# GEMM K-loops with all per-phase s_setprio flips deleted (A/B of the template's priority toggling)
# speedup vs baseline: 1.0123x; 1.0056x over previous
; #define PG8_STAGE(bufoff, gbase, voff) do { _Pragma("unroll") for (int _i = 0; _i < 2; ++_i) \
;         __builtin_amdgcn_global_load_lds((const unsigned*)((const char*)(gbase) + (voff)[_i]), (PG8_LAS unsigned*)(lds + (bufoff) + ldsw + _i * 8192), 16, 0, 0); } while (0)
; #define PG8_LDA(dst, b, h) do { _Pragma("unroll") for (int m = 0; m < 4; ++m) _Pragma("unroll") for (int k = 0; k < 2; ++k) dst[m][k] = *(const PG8_LAS bf16x8*)(lds + PG8_SA(b, h) + aoff + m * 2048 + k * 1024); } while (0)
; #define PG8_LDB(dst, b, h) do { _Pragma("unroll") for (int n = 0; n < 2; ++n) _Pragma("unroll") for (int k = 0; k < 2; ++k) dst[n][k] = *(const PG8_LAS bf16x8*)(lds + PG8_SB(b, h) + boff + n * 2048 + k * 1024); } while (0)
; #define PG8_MMA(ai, bj, At, Bt) do { __builtin_amdgcn_s_setprio(1); _Pragma("unroll") for (int m = 0; m < 4; ++m) _Pragma("unroll") for (int n = 0; n < 2; ++n) _Pragma("unroll") for (int k = 0; k < 2; ++k) \
;         acc[ai][bj][m][n] = mma16<F16>(Bt[n][k], At[m][k], acc[ai][bj][m][n]); __builtin_amdgcn_s_setprio(0); } while (0)
; #define PG8_WAIT_V(n) asm volatile("s_waitcnt vmcnt(" #n ")" ::: "memory")
; #define PG8_BAR __builtin_amdgcn_s_barrier()
; template <class Epi, class Sched, bool ALIGN_EPI = false, bool SP2 = false, bool F16 = false>
; __device__ __forceinline__ void gemm_phase(PG8_LAS unsigned char* lds, const Gemm g, const Sched& S, const Epi& E, const int wid_in) {
;     ...
;         for (int t = 0; t < nt; t += 2) {
;             const bool last = (t == nt - 2);
;             const char* a1 = cA + (size_t)(t + 1) * kstep;
;             const char* a2 = last ? nA : cA + (size_t)(t + 2) * kstep; const char* b2 = last ? nB : cB + (size_t)(t + 2) * kstep;
;             const char* a3 = a2 + kstep; const char* b3 = b2 + kstep;
;             if (last && has_next) S.a_ready(nxt);
;             if constexpr (SP2) {
;             PG8_LDB(B0, 0, 0); PG8_LDB(B1, 0, 1); PG8_SCHED; PG8_LDA(At, 0, 0); PG8_STAGE(PG8_SA(1, 1), a1 + hstep, voffA);
;             PG8_WAIT_V(8); PG8_WAIT_L(0); PG8_BAR; PG8_MMA(0, 0, At, B0); PG8_MMA(0, 1, At, B1); PG8_BAR; PG8_SCHED;
;             PG8_LDA(At, 0, 1); PG8_STAGE(PG8_SB(0, 0), b2, voffB); PG8_STAGE(PG8_SB(0, 1), b2 + hstep, voffB); PG8_STAGE(PG8_SA(0, 0), a2, voffA);
;             PG8_WAIT_V(8); PG8_WAIT_L(0); PG8_BAR; PG8_MMA(1, 0, At, B0); PG8_MMA(1, 1, At, B1); PG8_BAR; PG8_SCHED;
.LBB0_224:
	ds_read_b128 v[128:131], v184
	ds_read_b128 v[132:135], v184 offset:1024
	ds_read_b128 v[136:139], v184 offset:2048
	ds_read_b128 v[140:143], v184 offset:3072
	ds_read_b128 v[144:147], v185
	ds_read_b128 v[148:151], v185 offset:1024
	ds_read_b128 v[152:155], v185 offset:2048
	ds_read_b128 v[174:177], v185 offset:3072
	s_add_u32 s58, s56, 0xfffc0080
	s_addc_u32 s59, s57, -1
	s_cmp_eq_u32 s62, 12
	s_cselect_b32 s61, s9, s59
	s_cselect_b32 s60, s21, s58
	s_cselect_b32 s59, s42, s51
	s_cselect_b32 s58, s43, s49
	v_lshl_add_u64 v[178:179], s[56:57], 0, v[166:167]
	s_add_i32 m0, s83, 0xc000
	ds_read_b128 v[190:193], v186
	ds_read_b128 v[194:197], v186 offset:1024
	ds_read_b128 v[198:201], v186 offset:2048
	ds_read_b128 v[202:205], v186 offset:3072
	ds_read_b128 v[206:209], v186 offset:4096
	ds_read_b128 v[210:213], v186 offset:5120
	ds_read_b128 v[214:217], v186 offset:6144
	ds_read_b128 v[218:221], v186 offset:7168
	global_load_lds_dwordx4 v[178:179], off
	v_lshl_add_u64 v[178:179], s[56:57], 0, v[168:169]
	s_add_i32 m0, s83, 0xe000
	s_nop 0
	global_load_lds_dwordx4 v[178:179], off
	s_waitcnt vmcnt(8)
	s_waitcnt lgkmcnt(0)
	s_barrier
	s_waitcnt lgkmcnt(0)
	v_mfma_f32_16x16x32_f16 v[124:127], v[128:131], v[190:193], v[124:127]
	v_mfma_f32_16x16x32_f16 v[120:123], v[136:139], v[190:193], v[120:123]
	v_mfma_f32_16x16x32_f16 v[108:111], v[128:131], v[198:201], v[108:111]
	v_mfma_f32_16x16x32_f16 v[104:107], v[136:139], v[198:201], v[104:107]
	v_mfma_f32_16x16x32_f16 v[92:95], v[128:131], v[206:209], v[92:95]
	v_mfma_f32_16x16x32_f16 v[88:91], v[136:139], v[206:209], v[88:91]
	v_mfma_f32_16x16x32_f16 v[76:79], v[128:131], v[214:217], v[76:79]
	v_mfma_f32_16x16x32_f16 v[72:75], v[136:139], v[214:217], v[72:75]
	v_mfma_f32_16x16x32_f16 v[124:127], v[132:135], v[194:197], v[124:127]
	v_mfma_f32_16x16x32_f16 v[120:123], v[140:143], v[194:197], v[120:123]
	v_mfma_f32_16x16x32_f16 v[108:111], v[132:135], v[202:205], v[108:111]
	v_mfma_f32_16x16x32_f16 v[104:107], v[140:143], v[202:205], v[104:107]
	v_mfma_f32_16x16x32_f16 v[92:95], v[132:135], v[210:213], v[92:95]
	v_mfma_f32_16x16x32_f16 v[88:91], v[140:143], v[210:213], v[88:91]
	v_mfma_f32_16x16x32_f16 v[76:79], v[132:135], v[218:221], v[76:79]
	v_mfma_f32_16x16x32_f16 v[72:75], v[140:143], v[218:221], v[72:75]
	v_mfma_f32_16x16x32_f16 v[116:119], v[144:147], v[190:193], v[116:119]
	v_mfma_f32_16x16x32_f16 v[112:115], v[152:155], v[190:193], v[112:115]
	v_mfma_f32_16x16x32_f16 v[100:103], v[144:147], v[198:201], v[100:103]
	v_mfma_f32_16x16x32_f16 v[96:99], v[152:155], v[198:201], v[96:99]
	v_mfma_f32_16x16x32_f16 v[84:87], v[144:147], v[206:209], v[84:87]
	v_mfma_f32_16x16x32_f16 v[80:83], v[152:155], v[206:209], v[80:83]
	v_mfma_f32_16x16x32_f16 v[68:71], v[144:147], v[214:217], v[68:71]
	v_mfma_f32_16x16x32_f16 v[64:67], v[152:155], v[214:217], v[64:67]
	v_mfma_f32_16x16x32_f16 v[116:119], v[148:151], v[194:197], v[116:119]
	v_mfma_f32_16x16x32_f16 v[112:115], v[174:177], v[194:197], v[112:115]
	v_mfma_f32_16x16x32_f16 v[100:103], v[148:151], v[202:205], v[100:103]
	v_mfma_f32_16x16x32_f16 v[96:99], v[174:177], v[202:205], v[96:99]
	v_mfma_f32_16x16x32_f16 v[84:87], v[148:151], v[210:213], v[84:87]
	v_mfma_f32_16x16x32_f16 v[80:83], v[174:177], v[210:213], v[80:83]
	v_mfma_f32_16x16x32_f16 v[68:71], v[148:151], v[218:221], v[68:71]
	v_mfma_f32_16x16x32_f16 v[64:67], v[174:177], v[218:221], v[64:67]
	s_barrier
	s_add_i32 s63, s40, s68
	v_lshl_add_u64 v[178:179], s[58:59], 0, v[158:159]
	s_mov_b32 m0, s63
	ds_read_b128 v[190:193], v186 offset:16384
	ds_read_b128 v[194:197], v186 offset:17408
	ds_read_b128 v[198:201], v186 offset:18432
	ds_read_b128 v[202:205], v186 offset:19456
	ds_read_b128 v[206:209], v186 offset:20480
	ds_read_b128 v[210:213], v186 offset:21504
	ds_read_b128 v[214:217], v186 offset:22528
	ds_read_b128 v[218:221], v186 offset:23552
	global_load_lds_dwordx4 v[178:179], off
	s_add_i32 m0, s63, 0x2000
	s_add_u32 s64, s58, 0x40000
	v_lshl_add_u64 v[222:223], s[58:59], 0, v[162:163]
	s_addc_u32 s65, s59, 0
	s_add_i32 s63, s41, s68
	global_load_lds_dwordx4 v[222:223], off
	v_lshl_add_u64 v[224:225], s[64:65], 0, v[158:159]
	s_mov_b32 m0, s63
	v_lshl_add_u64 v[226:227], s[60:61], 0, v[160:161]
	global_load_lds_dwordx4 v[224:225], off
	v_lshl_add_u64 v[224:225], s[64:65], 0, v[162:163]
	s_add_i32 m0, s63, 0x2000
	s_nop 0
	global_load_lds_dwordx4 v[224:225], off
	v_lshl_add_u64 v[224:225], s[60:61], 0, v[156:157]
	s_mov_b32 m0, s83
	s_nop 0
	global_load_lds_dwordx4 v[224:225], off
	s_mov_b32 m0, s84
	s_nop 0
	global_load_lds_dwordx4 v[226:227], off
	s_waitcnt vmcnt(8)
	s_waitcnt lgkmcnt(0)
	s_barrier
; #define PG8_STAGE(bufoff, gbase, voff) do { _Pragma("unroll") for (int _i = 0; _i < 2; ++_i) \
;         __builtin_amdgcn_global_load_lds((const unsigned*)((const char*)(gbase) + (voff)[_i]), (PG8_LAS unsigned*)(lds + (bufoff) + ldsw + _i * 8192), 16, 0, 0); } while (0)
; #define PG8_LDA(dst, b, h) do { _Pragma("unroll") for (int m = 0; m < 4; ++m) _Pragma("unroll") for (int k = 0; k < 2; ++k) dst[m][k] = *(const PG8_LAS bf16x8*)(lds + PG8_SA(b, h) + aoff + m * 2048 + k * 1024); } while (0)
; #define PG8_LDB(dst, b, h) do { _Pragma("unroll") for (int n = 0; n < 2; ++n) _Pragma("unroll") for (int k = 0; k < 2; ++k) dst[n][k] = *(const PG8_LAS bf16x8*)(lds + PG8_SB(b, h) + boff + n * 2048 + k * 1024); } while (0)
; #define PG8_MMA(ai, bj, At, Bt) do { __builtin_amdgcn_s_setprio(1); _Pragma("unroll") for (int m = 0; m < 4; ++m) _Pragma("unroll") for (int n = 0; n < 2; ++n) _Pragma("unroll") for (int k = 0; k < 2; ++k) \
;         acc[ai][bj][m][n] = mma16<F16>(Bt[n][k], At[m][k], acc[ai][bj][m][n]); __builtin_amdgcn_s_setprio(0); } while (0)
; #define PG8_WAIT_V(n) asm volatile("s_waitcnt vmcnt(" #n ")" ::: "memory")
; #define PG8_WAIT_L(n) asm volatile("s_waitcnt lgkmcnt(" #n ")" ::: "memory")
; #define PG8_BAR __builtin_amdgcn_s_barrier()
; #define PG8_SCHED __builtin_amdgcn_sched_barrier(0)
; template <class Epi, class Sched, bool ALIGN_EPI = false, bool SP2 = false, bool F16 = false>
; __device__ __forceinline__ void gemm_phase(PG8_LAS unsigned char* lds, const Gemm g, const Sched& S, const Epi& E, const int wid_in) {
;     ...
;             PG8_WAIT_V(8); PG8_WAIT_L(0); PG8_BAR; PG8_MMA(1, 0, At, B0); PG8_MMA(1, 1, At, B1); PG8_BAR; PG8_SCHED;
;             PG8_LDB(B0, 1, 0); PG8_LDB(B1, 1, 1); PG8_SCHED; PG8_LDA(At, 1, 0); PG8_STAGE(PG8_SA(0, 1), a2 + hstep, voffA);
;             PG8_WAIT_V(8); PG8_WAIT_L(0); PG8_BAR; PG8_MMA(0, 0, At, B0); PG8_MMA(0, 1, At, B1); PG8_BAR; PG8_SCHED;
	s_waitcnt lgkmcnt(0)
	v_mfma_f32_16x16x32_f16 v[60:63], v[128:131], v[190:193], v[60:63]
	v_mfma_f32_16x16x32_f16 v[56:59], v[136:139], v[190:193], v[56:59]
	v_mfma_f32_16x16x32_f16 v[44:47], v[128:131], v[198:201], v[44:47]
	v_mfma_f32_16x16x32_f16 v[40:43], v[136:139], v[198:201], v[40:43]
	v_mfma_f32_16x16x32_f16 v[28:31], v[128:131], v[206:209], v[28:31]
	v_mfma_f32_16x16x32_f16 v[24:27], v[136:139], v[206:209], v[24:27]
	v_mfma_f32_16x16x32_f16 v[12:15], v[128:131], v[214:217], v[12:15]
	v_mfma_f32_16x16x32_f16 v[8:11], v[136:139], v[214:217], v[8:11]
	v_mfma_f32_16x16x32_f16 v[60:63], v[132:135], v[194:197], v[60:63]
	v_mfma_f32_16x16x32_f16 v[56:59], v[140:143], v[194:197], v[56:59]
	v_mfma_f32_16x16x32_f16 v[44:47], v[132:135], v[202:205], v[44:47]
	v_mfma_f32_16x16x32_f16 v[40:43], v[140:143], v[202:205], v[40:43]
	v_mfma_f32_16x16x32_f16 v[28:31], v[132:135], v[210:213], v[28:31]
	v_mfma_f32_16x16x32_f16 v[24:27], v[140:143], v[210:213], v[24:27]
	v_mfma_f32_16x16x32_f16 v[12:15], v[132:135], v[218:221], v[12:15]
	v_mfma_f32_16x16x32_f16 v[8:11], v[140:143], v[218:221], v[8:11]
	v_mfma_f32_16x16x32_f16 v[52:55], v[144:147], v[190:193], v[52:55]
	v_mfma_f32_16x16x32_f16 v[48:51], v[152:155], v[190:193], v[48:51]
	v_mfma_f32_16x16x32_f16 v[36:39], v[144:147], v[198:201], v[36:39]
	v_mfma_f32_16x16x32_f16 v[32:35], v[152:155], v[198:201], v[32:35]
	v_mfma_f32_16x16x32_f16 v[20:23], v[144:147], v[206:209], v[20:23]
	v_mfma_f32_16x16x32_f16 v[16:19], v[152:155], v[206:209], v[16:19]
	v_mfma_f32_16x16x32_f16 v[4:7], v[144:147], v[214:217], v[4:7]
	v_mfma_f32_16x16x32_f16 v[0:3], v[152:155], v[214:217], v[0:3]
	v_mfma_f32_16x16x32_f16 v[52:55], v[148:151], v[194:197], v[52:55]
	v_mfma_f32_16x16x32_f16 v[48:51], v[174:177], v[194:197], v[48:51]
	v_mfma_f32_16x16x32_f16 v[36:39], v[148:151], v[202:205], v[36:39]
	v_mfma_f32_16x16x32_f16 v[32:35], v[174:177], v[202:205], v[32:35]
	v_mfma_f32_16x16x32_f16 v[20:23], v[148:151], v[210:213], v[20:23]
	v_mfma_f32_16x16x32_f16 v[16:19], v[174:177], v[210:213], v[16:19]
	v_mfma_f32_16x16x32_f16 v[4:7], v[148:151], v[218:221], v[4:7]
	v_mfma_f32_16x16x32_f16 v[0:3], v[174:177], v[218:221], v[0:3]
	s_barrier
	s_add_i32 s63, 0, 0x18000
	s_add_i32 s64, 0, 0x1c000
	v_add_u32_e32 v140, s63, v183
	v_add_u32_e32 v165, s64, v183
	ds_read_b128 v[128:131], v140
	ds_read_b128 v[132:135], v140 offset:1024
	ds_read_b128 v[136:139], v140 offset:2048
	ds_read_b128 v[140:143], v140 offset:3072
	ds_read_b128 v[144:147], v165
	ds_read_b128 v[148:151], v165 offset:1024
	ds_read_b128 v[152:155], v165 offset:2048
	ds_read_b128 v[174:177], v165 offset:3072
	s_add_u32 s60, s60, 0x40000
	s_addc_u32 s61, s61, 0
	s_mov_b32 m0, s85
	v_lshl_add_u64 v[228:229], s[60:61], 0, v[156:157]
	ds_read_b128 v[190:193], v186 offset:32768
	ds_read_b128 v[194:197], v186 offset:33792
	ds_read_b128 v[198:201], v186 offset:34816
	ds_read_b128 v[202:205], v186 offset:35840
	ds_read_b128 v[206:209], v186 offset:36864
	ds_read_b128 v[210:213], v186 offset:37888
	ds_read_b128 v[214:217], v186 offset:38912
	ds_read_b128 v[218:221], v186 offset:39936
	global_load_lds_dwordx4 v[228:229], off
	v_lshl_add_u64 v[228:229], s[60:61], 0, v[160:161]
	s_mov_b32 m0, s86
	s_nop 0
	global_load_lds_dwordx4 v[228:229], off
	s_waitcnt vmcnt(8)
	s_waitcnt lgkmcnt(0)
	s_barrier
	s_waitcnt lgkmcnt(0)
	v_mfma_f32_16x16x32_f16 v[124:127], v[128:131], v[190:193], v[124:127]
	v_mfma_f32_16x16x32_f16 v[120:123], v[136:139], v[190:193], v[120:123]
	v_mfma_f32_16x16x32_f16 v[108:111], v[128:131], v[198:201], v[108:111]
	v_mfma_f32_16x16x32_f16 v[104:107], v[136:139], v[198:201], v[104:107]
	v_mfma_f32_16x16x32_f16 v[92:95], v[128:131], v[206:209], v[92:95]
	v_mfma_f32_16x16x32_f16 v[88:91], v[136:139], v[206:209], v[88:91]
	v_mfma_f32_16x16x32_f16 v[76:79], v[128:131], v[214:217], v[76:79]
	v_mfma_f32_16x16x32_f16 v[72:75], v[136:139], v[214:217], v[72:75]
	v_mfma_f32_16x16x32_f16 v[124:127], v[132:135], v[194:197], v[124:127]
	v_mfma_f32_16x16x32_f16 v[120:123], v[140:143], v[194:197], v[120:123]
	v_mfma_f32_16x16x32_f16 v[108:111], v[132:135], v[202:205], v[108:111]
	v_mfma_f32_16x16x32_f16 v[104:107], v[140:143], v[202:205], v[104:107]
	v_mfma_f32_16x16x32_f16 v[92:95], v[132:135], v[210:213], v[92:95]
	v_mfma_f32_16x16x32_f16 v[88:91], v[140:143], v[210:213], v[88:91]
	v_mfma_f32_16x16x32_f16 v[76:79], v[132:135], v[218:221], v[76:79]
	v_mfma_f32_16x16x32_f16 v[72:75], v[140:143], v[218:221], v[72:75]
	v_mfma_f32_16x16x32_f16 v[116:119], v[144:147], v[190:193], v[116:119]
	v_mfma_f32_16x16x32_f16 v[112:115], v[152:155], v[190:193], v[112:115]
	v_mfma_f32_16x16x32_f16 v[100:103], v[144:147], v[198:201], v[100:103]
	v_mfma_f32_16x16x32_f16 v[96:99], v[152:155], v[198:201], v[96:99]
	v_mfma_f32_16x16x32_f16 v[84:87], v[144:147], v[206:209], v[84:87]
	v_mfma_f32_16x16x32_f16 v[80:83], v[152:155], v[206:209], v[80:83]
	v_mfma_f32_16x16x32_f16 v[68:71], v[144:147], v[214:217], v[68:71]
	v_mfma_f32_16x16x32_f16 v[64:67], v[152:155], v[214:217], v[64:67]
	v_mfma_f32_16x16x32_f16 v[116:119], v[148:151], v[194:197], v[116:119]
	v_mfma_f32_16x16x32_f16 v[112:115], v[174:177], v[194:197], v[112:115]
	v_mfma_f32_16x16x32_f16 v[100:103], v[148:151], v[202:205], v[100:103]
	v_mfma_f32_16x16x32_f16 v[96:99], v[174:177], v[202:205], v[96:99]
	v_mfma_f32_16x16x32_f16 v[84:87], v[148:151], v[210:213], v[84:87]
	v_mfma_f32_16x16x32_f16 v[80:83], v[174:177], v[210:213], v[80:83]
	v_mfma_f32_16x16x32_f16 v[68:71], v[148:151], v[218:221], v[68:71]
	v_mfma_f32_16x16x32_f16 v[64:67], v[174:177], v[218:221], v[64:67]
	s_barrier
; #define PG8_STAGE(bufoff, gbase, voff) do { _Pragma("unroll") for (int _i = 0; _i < 2; ++_i) \
;         __builtin_amdgcn_global_load_lds((const unsigned*)((const char*)(gbase) + (voff)[_i]), (PG8_LAS unsigned*)(lds + (bufoff) + ldsw + _i * 8192), 16, 0, 0); } while (0)
; #define PG8_LDA(dst, b, h) do { _Pragma("unroll") for (int m = 0; m < 4; ++m) _Pragma("unroll") for (int k = 0; k < 2; ++k) dst[m][k] = *(const PG8_LAS bf16x8*)(lds + PG8_SA(b, h) + aoff + m * 2048 + k * 1024); } while (0)
; #define PG8_MMA(ai, bj, At, Bt) do { __builtin_amdgcn_s_setprio(1); _Pragma("unroll") for (int m = 0; m < 4; ++m) _Pragma("unroll") for (int n = 0; n < 2; ++n) _Pragma("unroll") for (int k = 0; k < 2; ++k) \
;         acc[ai][bj][m][n] = mma16<F16>(Bt[n][k], At[m][k], acc[ai][bj][m][n]); __builtin_amdgcn_s_setprio(0); } while (0)
; #define PG8_WAIT_V(n) asm volatile("s_waitcnt vmcnt(" #n ")" ::: "memory")
; #define PG8_WAIT_L(n) asm volatile("s_waitcnt lgkmcnt(" #n ")" ::: "memory")
; #define PG8_BAR __builtin_amdgcn_s_barrier()
; #define PG8_SCHED __builtin_amdgcn_sched_barrier(0)
; template <class Epi, class Sched, bool ALIGN_EPI = false, bool SP2 = false, bool F16 = false>
; __device__ __forceinline__ void gemm_phase(PG8_LAS unsigned char* lds, const Gemm g, const Sched& S, const Epi& E, const int wid_in) {
;     ...
;             PG8_LDA(At, 1, 1); PG8_STAGE(PG8_SB(1, 0), b3, voffB); PG8_STAGE(PG8_SB(1, 1), b3 + hstep, voffB); PG8_STAGE(PG8_SA(1, 0), a3, voffA);
;             PG8_WAIT_V(8); PG8_WAIT_L(0); PG8_BAR; PG8_MMA(1, 0, At, B0); PG8_MMA(1, 1, At, B1); PG8_BAR; PG8_SCHED;
;     ...
;         if constexpr (ALIGN_EPI) { if (wr == 0) PG8_BAR; }
	s_add_i32 s60, s63, s68
	v_lshl_add_u64 v[178:179], v[178:179], 0, s[24:25]
	s_mov_b32 m0, s60
	ds_read_b128 v[190:193], v186 offset:49152
	ds_read_b128 v[194:197], v186 offset:50176
	ds_read_b128 v[198:201], v186 offset:51200
	ds_read_b128 v[202:205], v186 offset:52224
	ds_read_b128 v[206:209], v186 offset:53248
	ds_read_b128 v[210:213], v186 offset:54272
	ds_read_b128 v[214:217], v186 offset:55296
	ds_read_b128 v[218:221], v186 offset:56320
	global_load_lds_dwordx4 v[178:179], off
	s_add_i32 m0, s60, 0x2000
	s_add_u32 s58, s58, 0x40080
	v_lshl_add_u64 v[178:179], v[222:223], 0, s[24:25]
	s_addc_u32 s59, s59, 0
	s_add_i32 s60, s64, s68
	global_load_lds_dwordx4 v[178:179], off
	v_lshl_add_u64 v[178:179], s[58:59], 0, v[158:159]
	s_mov_b32 m0, s60
	s_nop 0
	global_load_lds_dwordx4 v[178:179], off
	v_lshl_add_u64 v[178:179], s[58:59], 0, v[162:163]
	s_add_i32 m0, s60, 0x2000
	s_nop 0
	global_load_lds_dwordx4 v[178:179], off
	v_lshl_add_u64 v[178:179], v[224:225], 0, s[24:25]
	s_mov_b32 m0, s90
	s_nop 0
	global_load_lds_dwordx4 v[178:179], off
	v_lshl_add_u64 v[178:179], v[226:227], 0, s[24:25]
	s_mov_b32 m0, s91
	s_nop 0
	global_load_lds_dwordx4 v[178:179], off
	s_waitcnt vmcnt(8)
	s_waitcnt lgkmcnt(0)
	s_barrier
	s_waitcnt lgkmcnt(0)
	v_mfma_f32_16x16x32_f16 v[60:63], v[128:131], v[190:193], v[60:63]
	v_mfma_f32_16x16x32_f16 v[56:59], v[136:139], v[190:193], v[56:59]
	v_mfma_f32_16x16x32_f16 v[44:47], v[128:131], v[198:201], v[44:47]
	v_mfma_f32_16x16x32_f16 v[40:43], v[136:139], v[198:201], v[40:43]
	v_mfma_f32_16x16x32_f16 v[28:31], v[128:131], v[206:209], v[28:31]
	v_mfma_f32_16x16x32_f16 v[24:27], v[136:139], v[206:209], v[24:27]
	v_mfma_f32_16x16x32_f16 v[12:15], v[128:131], v[214:217], v[12:15]
	v_mfma_f32_16x16x32_f16 v[8:11], v[136:139], v[214:217], v[8:11]
	v_mfma_f32_16x16x32_f16 v[60:63], v[132:135], v[194:197], v[60:63]
	v_mfma_f32_16x16x32_f16 v[56:59], v[140:143], v[194:197], v[56:59]
	v_mfma_f32_16x16x32_f16 v[44:47], v[132:135], v[202:205], v[44:47]
	v_mfma_f32_16x16x32_f16 v[40:43], v[140:143], v[202:205], v[40:43]
	v_mfma_f32_16x16x32_f16 v[28:31], v[132:135], v[210:213], v[28:31]
	v_mfma_f32_16x16x32_f16 v[24:27], v[140:143], v[210:213], v[24:27]
	v_mfma_f32_16x16x32_f16 v[12:15], v[132:135], v[218:221], v[12:15]
	v_mfma_f32_16x16x32_f16 v[8:11], v[140:143], v[218:221], v[8:11]
	v_mfma_f32_16x16x32_f16 v[52:55], v[144:147], v[190:193], v[52:55]
	v_mfma_f32_16x16x32_f16 v[48:51], v[152:155], v[190:193], v[48:51]
	v_mfma_f32_16x16x32_f16 v[36:39], v[144:147], v[198:201], v[36:39]
	v_mfma_f32_16x16x32_f16 v[32:35], v[152:155], v[198:201], v[32:35]
	v_mfma_f32_16x16x32_f16 v[20:23], v[144:147], v[206:209], v[20:23]
	v_mfma_f32_16x16x32_f16 v[16:19], v[152:155], v[206:209], v[16:19]
	v_mfma_f32_16x16x32_f16 v[4:7], v[144:147], v[214:217], v[4:7]
	v_mfma_f32_16x16x32_f16 v[0:3], v[152:155], v[214:217], v[0:3]
	v_mfma_f32_16x16x32_f16 v[52:55], v[148:151], v[194:197], v[52:55]
	v_mfma_f32_16x16x32_f16 v[48:51], v[174:177], v[194:197], v[48:51]
	v_mfma_f32_16x16x32_f16 v[36:39], v[148:151], v[202:205], v[36:39]
	v_mfma_f32_16x16x32_f16 v[32:35], v[174:177], v[202:205], v[32:35]
	v_mfma_f32_16x16x32_f16 v[20:23], v[148:151], v[210:213], v[20:23]
	v_mfma_f32_16x16x32_f16 v[16:19], v[174:177], v[210:213], v[16:19]
	v_mfma_f32_16x16x32_f16 v[4:7], v[148:151], v[218:221], v[4:7]
	v_mfma_f32_16x16x32_f16 v[0:3], v[174:177], v[218:221], v[0:3]
	s_barrier
	s_add_i32 s62, s62, 2
	s_add_u32 s56, s56, 0x100
	s_addc_u32 s57, s57, 0
	s_add_u32 s49, s49, 0x100
	s_addc_u32 s51, s51, 0
	s_cmp_gt_u32 s62, 13
	s_cbranch_scc0 .LBB0_224
	s_and_b64 vcc, exec, s[26:27]
	s_cbranch_vccz .LBB0_227
	s_barrier

; #define PG8_STAGE(bufoff, gbase, voff) do { _Pragma("unroll") for (int _i = 0; _i < 2; ++_i) \
;         __builtin_amdgcn_global_load_lds((const unsigned*)((const char*)(gbase) + (voff)[_i]), (PG8_LAS unsigned*)(lds + (bufoff) + ldsw + _i * 8192), 16, 0, 0); } while (0)
; #define PG8_LDA(dst, b, h) do { _Pragma("unroll") for (int m = 0; m < 4; ++m) _Pragma("unroll") for (int k = 0; k < 2; ++k) dst[m][k] = *(const PG8_LAS bf16x8*)(lds + PG8_SA(b, h) + aoff + m * 2048 + k * 1024); } while (0)
; #define PG8_LDB(dst, b, h) do { _Pragma("unroll") for (int n = 0; n < 2; ++n) _Pragma("unroll") for (int k = 0; k < 2; ++k) dst[n][k] = *(const PG8_LAS bf16x8*)(lds + PG8_SB(b, h) + boff + n * 2048 + k * 1024); } while (0)
; #define PG8_MMA(ai, bj, At, Bt) do { __builtin_amdgcn_s_setprio(1); _Pragma("unroll") for (int m = 0; m < 4; ++m) _Pragma("unroll") for (int n = 0; n < 2; ++n) _Pragma("unroll") for (int k = 0; k < 2; ++k) \
;         acc[ai][bj][m][n] = mma16<F16>(Bt[n][k], At[m][k], acc[ai][bj][m][n]); __builtin_amdgcn_s_setprio(0); } while (0)
; #define PG8_WAIT_V(n) asm volatile("s_waitcnt vmcnt(" #n ")" ::: "memory")
; #define PG8_WAIT_L(n) asm volatile("s_waitcnt lgkmcnt(" #n ")" ::: "memory")
; template <class Epi, class Sched, bool ALIGN_EPI = false, bool SP2 = false, bool F16 = false>
; __device__ __forceinline__ void gemm_phase(PG8_LAS unsigned char* lds, const Gemm g, const Sched& S, const Epi& E, const int wid_in) {
;     ...
;             const bool last = (t == nt - 2);
;             const char* a1 = cA + (size_t)(t + 1) * kstep;
;             const char* a2 = last ? nA : cA + (size_t)(t + 2) * kstep; const char* b2 = last ? nB : cB + (size_t)(t + 2) * kstep;
;             const char* a3 = a2 + kstep; const char* b3 = b2 + kstep;
;             if (last && has_next) S.a_ready(nxt);
;             if constexpr (SP2) {
;             PG8_LDB(B0, 0, 0); PG8_LDB(B1, 0, 1); PG8_SCHED; PG8_LDA(At, 0, 0); PG8_STAGE(PG8_SA(1, 1), a1 + hstep, voffA);
;             PG8_WAIT_V(8); PG8_WAIT_L(0); PG8_BAR; PG8_MMA(0, 0, At, B0); PG8_MMA(0, 1, At, B1); PG8_BAR; PG8_SCHED;
;             PG8_LDA(At, 0, 1); PG8_STAGE(PG8_SB(0, 0), b2, voffB); PG8_STAGE(PG8_SB(0, 1), b2 + hstep, voffB); PG8_STAGE(PG8_SA(0, 0), a2, voffA);
;             PG8_WAIT_V(8); PG8_WAIT_L(0); PG8_BAR; PG8_MMA(1, 0, At, B0); PG8_MMA(1, 1, At, B1); PG8_BAR; PG8_SCHED;
.LBB0_508:
	ds_read_b128 v[128:131], v189
	ds_read_b128 v[132:135], v189 offset:1024
	ds_read_b128 v[136:139], v189 offset:2048
	ds_read_b128 v[140:143], v189 offset:3072
	ds_read_b128 v[144:147], v190
	ds_read_b128 v[148:151], v190 offset:1024
	ds_read_b128 v[168:171], v190 offset:2048
	ds_read_b128 v[172:175], v190 offset:3072
	s_add_u32 s46, s44, 0xfffc0080
	s_addc_u32 s47, s45, -1
	s_cmp_eq_u32 s43, 12
	s_cselect_b32 s49, s10, s47
	s_cselect_b32 s48, s27, s46
	s_cselect_b32 s47, s25, s42
	s_cselect_b32 s46, s35, s37
	v_lshl_add_u64 v[184:185], s[44:45], 0, v[160:161]
	s_add_i32 m0, s74, 0xc000
	ds_read_b128 v[176:179], v191
	ds_read_b128 v[180:183], v191 offset:1024
	ds_read_b128 v[192:195], v191 offset:2048
	ds_read_b128 v[196:199], v191 offset:3072
	ds_read_b128 v[200:203], v191 offset:4096
	ds_read_b128 v[204:207], v191 offset:5120
	ds_read_b128 v[208:211], v191 offset:6144
	ds_read_b128 v[212:215], v191 offset:7168
	global_load_lds_dwordx4 v[184:185], off
	v_lshl_add_u64 v[184:185], s[44:45], 0, v[162:163]
	s_add_i32 m0, s74, 0xe000
	s_nop 0
	global_load_lds_dwordx4 v[184:185], off
	s_waitcnt vmcnt(8)
	s_waitcnt lgkmcnt(0)
	s_barrier
	s_waitcnt lgkmcnt(0)
	v_mfma_f32_16x16x32_bf16 v[124:127], v[128:131], v[176:179], v[124:127]
	v_mfma_f32_16x16x32_bf16 v[120:123], v[136:139], v[176:179], v[120:123]
	v_mfma_f32_16x16x32_bf16 v[108:111], v[128:131], v[192:195], v[108:111]
	v_mfma_f32_16x16x32_bf16 v[104:107], v[136:139], v[192:195], v[104:107]
	v_mfma_f32_16x16x32_bf16 v[92:95], v[128:131], v[200:203], v[92:95]
	v_mfma_f32_16x16x32_bf16 v[88:91], v[136:139], v[200:203], v[88:91]
	v_mfma_f32_16x16x32_bf16 v[76:79], v[128:131], v[208:211], v[76:79]
	v_mfma_f32_16x16x32_bf16 v[72:75], v[136:139], v[208:211], v[72:75]
	v_mfma_f32_16x16x32_bf16 v[124:127], v[132:135], v[180:183], v[124:127]
	v_mfma_f32_16x16x32_bf16 v[120:123], v[140:143], v[180:183], v[120:123]
	v_mfma_f32_16x16x32_bf16 v[108:111], v[132:135], v[196:199], v[108:111]
	v_mfma_f32_16x16x32_bf16 v[104:107], v[140:143], v[196:199], v[104:107]
	v_mfma_f32_16x16x32_bf16 v[92:95], v[132:135], v[204:207], v[92:95]
	v_mfma_f32_16x16x32_bf16 v[88:91], v[140:143], v[204:207], v[88:91]
	v_mfma_f32_16x16x32_bf16 v[76:79], v[132:135], v[212:215], v[76:79]
	v_mfma_f32_16x16x32_bf16 v[72:75], v[140:143], v[212:215], v[72:75]
	v_mfma_f32_16x16x32_bf16 v[116:119], v[144:147], v[176:179], v[116:119]
	v_mfma_f32_16x16x32_bf16 v[112:115], v[168:171], v[176:179], v[112:115]
	v_mfma_f32_16x16x32_bf16 v[100:103], v[144:147], v[192:195], v[100:103]
	v_mfma_f32_16x16x32_bf16 v[96:99], v[168:171], v[192:195], v[96:99]
	v_mfma_f32_16x16x32_bf16 v[84:87], v[144:147], v[200:203], v[84:87]
	v_mfma_f32_16x16x32_bf16 v[80:83], v[168:171], v[200:203], v[80:83]
	v_mfma_f32_16x16x32_bf16 v[68:71], v[144:147], v[208:211], v[68:71]
	v_mfma_f32_16x16x32_bf16 v[64:67], v[168:171], v[208:211], v[64:67]
	v_mfma_f32_16x16x32_bf16 v[116:119], v[148:151], v[180:183], v[116:119]
	v_mfma_f32_16x16x32_bf16 v[112:115], v[172:175], v[180:183], v[112:115]
	v_mfma_f32_16x16x32_bf16 v[100:103], v[148:151], v[196:199], v[100:103]
	v_mfma_f32_16x16x32_bf16 v[96:99], v[172:175], v[196:199], v[96:99]
	v_mfma_f32_16x16x32_bf16 v[84:87], v[148:151], v[204:207], v[84:87]
	v_mfma_f32_16x16x32_bf16 v[80:83], v[172:175], v[204:207], v[80:83]
	v_mfma_f32_16x16x32_bf16 v[68:71], v[148:151], v[212:215], v[68:71]
	v_mfma_f32_16x16x32_bf16 v[64:67], v[172:175], v[212:215], v[64:67]
	s_barrier
	s_add_i32 s63, s60, s68
	v_lshl_add_u64 v[184:185], s[46:47], 0, v[154:155]
	s_mov_b32 m0, s63
	ds_read_b128 v[176:179], v191 offset:16384
	ds_read_b128 v[180:183], v191 offset:17408
	ds_read_b128 v[192:195], v191 offset:18432
	ds_read_b128 v[196:199], v191 offset:19456
	ds_read_b128 v[200:203], v191 offset:20480
	ds_read_b128 v[204:207], v191 offset:21504
	ds_read_b128 v[208:211], v191 offset:22528
	ds_read_b128 v[212:215], v191 offset:23552
	global_load_lds_dwordx4 v[184:185], off
	s_add_i32 m0, s63, 0x2000
	s_add_u32 s64, s46, 0x40000
	v_lshl_add_u64 v[216:217], s[46:47], 0, v[158:159]
	s_addc_u32 s65, s47, 0
	s_add_i32 s63, s61, s68
	global_load_lds_dwordx4 v[216:217], off
	v_lshl_add_u64 v[218:219], s[64:65], 0, v[154:155]
	s_mov_b32 m0, s63
	v_lshl_add_u64 v[220:221], s[48:49], 0, v[156:157]
	global_load_lds_dwordx4 v[218:219], off
	v_lshl_add_u64 v[218:219], s[64:65], 0, v[158:159]
	s_add_i32 m0, s63, 0x2000
	s_nop 0
	global_load_lds_dwordx4 v[218:219], off
	v_lshl_add_u64 v[218:219], s[48:49], 0, v[152:153]
	s_mov_b32 m0, s74
	s_nop 0
	global_load_lds_dwordx4 v[218:219], off
	s_mov_b32 m0, s51
	s_nop 0
	global_load_lds_dwordx4 v[220:221], off
	s_waitcnt vmcnt(8)
	s_waitcnt lgkmcnt(0)
	s_barrier
; #define PG8_STAGE(bufoff, gbase, voff) do { _Pragma("unroll") for (int _i = 0; _i < 2; ++_i) \
;         __builtin_amdgcn_global_load_lds((const unsigned*)((const char*)(gbase) + (voff)[_i]), (PG8_LAS unsigned*)(lds + (bufoff) + ldsw + _i * 8192), 16, 0, 0); } while (0)
; #define PG8_LDA(dst, b, h) do { _Pragma("unroll") for (int m = 0; m < 4; ++m) _Pragma("unroll") for (int k = 0; k < 2; ++k) dst[m][k] = *(const PG8_LAS bf16x8*)(lds + PG8_SA(b, h) + aoff + m * 2048 + k * 1024); } while (0)
; #define PG8_LDB(dst, b, h) do { _Pragma("unroll") for (int n = 0; n < 2; ++n) _Pragma("unroll") for (int k = 0; k < 2; ++k) dst[n][k] = *(const PG8_LAS bf16x8*)(lds + PG8_SB(b, h) + boff + n * 2048 + k * 1024); } while (0)
; #define PG8_MMA(ai, bj, At, Bt) do { __builtin_amdgcn_s_setprio(1); _Pragma("unroll") for (int m = 0; m < 4; ++m) _Pragma("unroll") for (int n = 0; n < 2; ++n) _Pragma("unroll") for (int k = 0; k < 2; ++k) \
;         acc[ai][bj][m][n] = mma16<F16>(Bt[n][k], At[m][k], acc[ai][bj][m][n]); __builtin_amdgcn_s_setprio(0); } while (0)
; #define PG8_WAIT_V(n) asm volatile("s_waitcnt vmcnt(" #n ")" ::: "memory")
; #define PG8_WAIT_L(n) asm volatile("s_waitcnt lgkmcnt(" #n ")" ::: "memory")
; #define PG8_BAR __builtin_amdgcn_s_barrier()
; #define PG8_SCHED __builtin_amdgcn_sched_barrier(0)
; template <class Epi, class Sched, bool ALIGN_EPI = false, bool SP2 = false, bool F16 = false>
; __device__ __forceinline__ void gemm_phase(PG8_LAS unsigned char* lds, const Gemm g, const Sched& S, const Epi& E, const int wid_in) {
;     ...
;             PG8_WAIT_V(8); PG8_WAIT_L(0); PG8_BAR; PG8_MMA(1, 0, At, B0); PG8_MMA(1, 1, At, B1); PG8_BAR; PG8_SCHED;
;             PG8_LDB(B0, 1, 0); PG8_LDB(B1, 1, 1); PG8_SCHED; PG8_LDA(At, 1, 0); PG8_STAGE(PG8_SA(0, 1), a2 + hstep, voffA);
;             PG8_WAIT_V(8); PG8_WAIT_L(0); PG8_BAR; PG8_MMA(0, 0, At, B0); PG8_MMA(0, 1, At, B1); PG8_BAR; PG8_SCHED;
	s_waitcnt lgkmcnt(0)
	v_mfma_f32_16x16x32_bf16 v[60:63], v[128:131], v[176:179], v[60:63]
	v_mfma_f32_16x16x32_bf16 v[56:59], v[136:139], v[176:179], v[56:59]
	v_mfma_f32_16x16x32_bf16 v[44:47], v[128:131], v[192:195], v[44:47]
	v_mfma_f32_16x16x32_bf16 v[40:43], v[136:139], v[192:195], v[40:43]
	v_mfma_f32_16x16x32_bf16 v[28:31], v[128:131], v[200:203], v[28:31]
	v_mfma_f32_16x16x32_bf16 v[24:27], v[136:139], v[200:203], v[24:27]
	v_mfma_f32_16x16x32_bf16 v[12:15], v[128:131], v[208:211], v[12:15]
	v_mfma_f32_16x16x32_bf16 v[8:11], v[136:139], v[208:211], v[8:11]
	v_mfma_f32_16x16x32_bf16 v[60:63], v[132:135], v[180:183], v[60:63]
	v_mfma_f32_16x16x32_bf16 v[56:59], v[140:143], v[180:183], v[56:59]
	v_mfma_f32_16x16x32_bf16 v[44:47], v[132:135], v[196:199], v[44:47]
	v_mfma_f32_16x16x32_bf16 v[40:43], v[140:143], v[196:199], v[40:43]
	v_mfma_f32_16x16x32_bf16 v[28:31], v[132:135], v[204:207], v[28:31]
	v_mfma_f32_16x16x32_bf16 v[24:27], v[140:143], v[204:207], v[24:27]
	v_mfma_f32_16x16x32_bf16 v[12:15], v[132:135], v[212:215], v[12:15]
	v_mfma_f32_16x16x32_bf16 v[8:11], v[140:143], v[212:215], v[8:11]
	v_mfma_f32_16x16x32_bf16 v[52:55], v[144:147], v[176:179], v[52:55]
	v_mfma_f32_16x16x32_bf16 v[48:51], v[168:171], v[176:179], v[48:51]
	v_mfma_f32_16x16x32_bf16 v[36:39], v[144:147], v[192:195], v[36:39]
	v_mfma_f32_16x16x32_bf16 v[32:35], v[168:171], v[192:195], v[32:35]
	v_mfma_f32_16x16x32_bf16 v[20:23], v[144:147], v[200:203], v[20:23]
	v_mfma_f32_16x16x32_bf16 v[16:19], v[168:171], v[200:203], v[16:19]
	v_mfma_f32_16x16x32_bf16 v[4:7], v[144:147], v[208:211], v[4:7]
	v_mfma_f32_16x16x32_bf16 v[0:3], v[168:171], v[208:211], v[0:3]
	v_mfma_f32_16x16x32_bf16 v[52:55], v[148:151], v[180:183], v[52:55]
	v_mfma_f32_16x16x32_bf16 v[48:51], v[172:175], v[180:183], v[48:51]
	v_mfma_f32_16x16x32_bf16 v[36:39], v[148:151], v[196:199], v[36:39]
	v_mfma_f32_16x16x32_bf16 v[32:35], v[172:175], v[196:199], v[32:35]
	v_mfma_f32_16x16x32_bf16 v[20:23], v[148:151], v[204:207], v[20:23]
	v_mfma_f32_16x16x32_bf16 v[16:19], v[172:175], v[204:207], v[16:19]
	v_mfma_f32_16x16x32_bf16 v[4:7], v[148:151], v[212:215], v[4:7]
	v_mfma_f32_16x16x32_bf16 v[0:3], v[172:175], v[212:215], v[0:3]
	s_barrier
	s_add_i32 s63, 0, 0x18000
	s_add_i32 s64, 0, 0x1c000
	v_add_u32_e32 v140, s63, v188
	v_add_u32_e32 v172, s64, v188
	ds_read_b128 v[128:131], v140
	ds_read_b128 v[132:135], v140 offset:1024
	ds_read_b128 v[136:139], v140 offset:2048
	ds_read_b128 v[140:143], v140 offset:3072
	ds_read_b128 v[144:147], v172
	ds_read_b128 v[148:151], v172 offset:1024
	ds_read_b128 v[168:171], v172 offset:2048
	ds_read_b128 v[172:175], v172 offset:3072
	s_add_u32 s48, s48, 0x40000
	s_addc_u32 s49, s49, 0
	s_mov_b32 m0, s52
	v_lshl_add_u64 v[222:223], s[48:49], 0, v[152:153]
	ds_read_b128 v[176:179], v191 offset:32768
	ds_read_b128 v[180:183], v191 offset:33792
	ds_read_b128 v[192:195], v191 offset:34816
	ds_read_b128 v[196:199], v191 offset:35840
	ds_read_b128 v[200:203], v191 offset:36864
	ds_read_b128 v[204:207], v191 offset:37888
	ds_read_b128 v[208:211], v191 offset:38912
	ds_read_b128 v[212:215], v191 offset:39936
	global_load_lds_dwordx4 v[222:223], off
	v_lshl_add_u64 v[222:223], s[48:49], 0, v[156:157]
	s_mov_b32 m0, s53
	s_nop 0
	global_load_lds_dwordx4 v[222:223], off
	s_waitcnt vmcnt(8)
	s_waitcnt lgkmcnt(0)
	s_barrier
	s_waitcnt lgkmcnt(0)
	v_mfma_f32_16x16x32_bf16 v[124:127], v[128:131], v[176:179], v[124:127]
	v_mfma_f32_16x16x32_bf16 v[120:123], v[136:139], v[176:179], v[120:123]
	v_mfma_f32_16x16x32_bf16 v[108:111], v[128:131], v[192:195], v[108:111]
	v_mfma_f32_16x16x32_bf16 v[104:107], v[136:139], v[192:195], v[104:107]
	v_mfma_f32_16x16x32_bf16 v[92:95], v[128:131], v[200:203], v[92:95]
	v_mfma_f32_16x16x32_bf16 v[88:91], v[136:139], v[200:203], v[88:91]
	v_mfma_f32_16x16x32_bf16 v[76:79], v[128:131], v[208:211], v[76:79]
	v_mfma_f32_16x16x32_bf16 v[72:75], v[136:139], v[208:211], v[72:75]
	v_mfma_f32_16x16x32_bf16 v[124:127], v[132:135], v[180:183], v[124:127]
	v_mfma_f32_16x16x32_bf16 v[120:123], v[140:143], v[180:183], v[120:123]
	v_mfma_f32_16x16x32_bf16 v[108:111], v[132:135], v[196:199], v[108:111]
	v_mfma_f32_16x16x32_bf16 v[104:107], v[140:143], v[196:199], v[104:107]
	v_mfma_f32_16x16x32_bf16 v[92:95], v[132:135], v[204:207], v[92:95]
	v_mfma_f32_16x16x32_bf16 v[88:91], v[140:143], v[204:207], v[88:91]
	v_mfma_f32_16x16x32_bf16 v[76:79], v[132:135], v[212:215], v[76:79]
	v_mfma_f32_16x16x32_bf16 v[72:75], v[140:143], v[212:215], v[72:75]
	v_mfma_f32_16x16x32_bf16 v[116:119], v[144:147], v[176:179], v[116:119]
	v_mfma_f32_16x16x32_bf16 v[112:115], v[168:171], v[176:179], v[112:115]
	v_mfma_f32_16x16x32_bf16 v[100:103], v[144:147], v[192:195], v[100:103]
	v_mfma_f32_16x16x32_bf16 v[96:99], v[168:171], v[192:195], v[96:99]
	v_mfma_f32_16x16x32_bf16 v[84:87], v[144:147], v[200:203], v[84:87]
	v_mfma_f32_16x16x32_bf16 v[80:83], v[168:171], v[200:203], v[80:83]
	v_mfma_f32_16x16x32_bf16 v[68:71], v[144:147], v[208:211], v[68:71]
	v_mfma_f32_16x16x32_bf16 v[64:67], v[168:171], v[208:211], v[64:67]
	v_mfma_f32_16x16x32_bf16 v[116:119], v[148:151], v[180:183], v[116:119]
	v_mfma_f32_16x16x32_bf16 v[112:115], v[172:175], v[180:183], v[112:115]
	v_mfma_f32_16x16x32_bf16 v[100:103], v[148:151], v[196:199], v[100:103]
	v_mfma_f32_16x16x32_bf16 v[96:99], v[172:175], v[196:199], v[96:99]
	v_mfma_f32_16x16x32_bf16 v[84:87], v[148:151], v[204:207], v[84:87]
	v_mfma_f32_16x16x32_bf16 v[80:83], v[172:175], v[204:207], v[80:83]
	v_mfma_f32_16x16x32_bf16 v[68:71], v[148:151], v[212:215], v[68:71]
	v_mfma_f32_16x16x32_bf16 v[64:67], v[172:175], v[212:215], v[64:67]
	s_barrier
; #define PG8_STAGE(bufoff, gbase, voff) do { _Pragma("unroll") for (int _i = 0; _i < 2; ++_i) \
;         __builtin_amdgcn_global_load_lds((const unsigned*)((const char*)(gbase) + (voff)[_i]), (PG8_LAS unsigned*)(lds + (bufoff) + ldsw + _i * 8192), 16, 0, 0); } while (0)
; #define PG8_LDA(dst, b, h) do { _Pragma("unroll") for (int m = 0; m < 4; ++m) _Pragma("unroll") for (int k = 0; k < 2; ++k) dst[m][k] = *(const PG8_LAS bf16x8*)(lds + PG8_SA(b, h) + aoff + m * 2048 + k * 1024); } while (0)
; #define PG8_MMA(ai, bj, At, Bt) do { __builtin_amdgcn_s_setprio(1); _Pragma("unroll") for (int m = 0; m < 4; ++m) _Pragma("unroll") for (int n = 0; n < 2; ++n) _Pragma("unroll") for (int k = 0; k < 2; ++k) \
;         acc[ai][bj][m][n] = mma16<F16>(Bt[n][k], At[m][k], acc[ai][bj][m][n]); __builtin_amdgcn_s_setprio(0); } while (0)
; #define PG8_WAIT_V(n) asm volatile("s_waitcnt vmcnt(" #n ")" ::: "memory")
; #define PG8_WAIT_L(n) asm volatile("s_waitcnt lgkmcnt(" #n ")" ::: "memory")
; #define PG8_BAR __builtin_amdgcn_s_barrier()
; #define PG8_SCHED __builtin_amdgcn_sched_barrier(0)
; template <class Epi, class Sched, bool ALIGN_EPI = false, bool SP2 = false, bool F16 = false>
; __device__ __forceinline__ void gemm_phase(PG8_LAS unsigned char* lds, const Gemm g, const Sched& S, const Epi& E, const int wid_in) {
;     ...
;             PG8_LDA(At, 1, 1); PG8_STAGE(PG8_SB(1, 0), b3, voffB); PG8_STAGE(PG8_SB(1, 1), b3 + hstep, voffB); PG8_STAGE(PG8_SA(1, 0), a3, voffA);
;             PG8_WAIT_V(8); PG8_WAIT_L(0); PG8_BAR; PG8_MMA(1, 0, At, B0); PG8_MMA(1, 1, At, B1); PG8_BAR; PG8_SCHED;
;     ...
;         if constexpr (ALIGN_EPI) { if (wr == 0) PG8_BAR; }
	s_add_i32 s48, s63, s68
	v_lshl_add_u64 v[184:185], v[184:185], 0, s[22:23]
	s_mov_b32 m0, s48
	ds_read_b128 v[176:179], v191 offset:49152
	ds_read_b128 v[180:183], v191 offset:50176
	ds_read_b128 v[192:195], v191 offset:51200
	ds_read_b128 v[196:199], v191 offset:52224
	ds_read_b128 v[200:203], v191 offset:53248
	ds_read_b128 v[204:207], v191 offset:54272
	ds_read_b128 v[208:211], v191 offset:55296
	ds_read_b128 v[212:215], v191 offset:56320
	global_load_lds_dwordx4 v[184:185], off
	s_add_i32 m0, s48, 0x2000
	s_add_u32 s46, s46, 0x40080
	v_lshl_add_u64 v[184:185], v[216:217], 0, s[22:23]
	s_addc_u32 s47, s47, 0
	s_add_i32 s48, s64, s68
	global_load_lds_dwordx4 v[184:185], off
	v_lshl_add_u64 v[184:185], s[46:47], 0, v[154:155]
	s_mov_b32 m0, s48
	s_nop 0
	global_load_lds_dwordx4 v[184:185], off
	v_lshl_add_u64 v[184:185], s[46:47], 0, v[158:159]
	s_add_i32 m0, s48, 0x2000
	s_nop 0
	global_load_lds_dwordx4 v[184:185], off
	v_lshl_add_u64 v[184:185], v[218:219], 0, s[22:23]
	s_mov_b32 m0, s75
	s_nop 0
	global_load_lds_dwordx4 v[184:185], off
	v_lshl_add_u64 v[184:185], v[220:221], 0, s[22:23]
	s_mov_b32 m0, s54
	s_nop 0
	global_load_lds_dwordx4 v[184:185], off
	s_waitcnt vmcnt(8)
	s_waitcnt lgkmcnt(0)
	s_barrier
	s_waitcnt lgkmcnt(0)
	v_mfma_f32_16x16x32_bf16 v[60:63], v[128:131], v[176:179], v[60:63]
	v_mfma_f32_16x16x32_bf16 v[56:59], v[136:139], v[176:179], v[56:59]
	v_mfma_f32_16x16x32_bf16 v[44:47], v[128:131], v[192:195], v[44:47]
	v_mfma_f32_16x16x32_bf16 v[40:43], v[136:139], v[192:195], v[40:43]
	v_mfma_f32_16x16x32_bf16 v[28:31], v[128:131], v[200:203], v[28:31]
	v_mfma_f32_16x16x32_bf16 v[24:27], v[136:139], v[200:203], v[24:27]
	v_mfma_f32_16x16x32_bf16 v[12:15], v[128:131], v[208:211], v[12:15]
	v_mfma_f32_16x16x32_bf16 v[8:11], v[136:139], v[208:211], v[8:11]
	v_mfma_f32_16x16x32_bf16 v[60:63], v[132:135], v[180:183], v[60:63]
	v_mfma_f32_16x16x32_bf16 v[56:59], v[140:143], v[180:183], v[56:59]
	v_mfma_f32_16x16x32_bf16 v[44:47], v[132:135], v[196:199], v[44:47]
	v_mfma_f32_16x16x32_bf16 v[40:43], v[140:143], v[196:199], v[40:43]
	v_mfma_f32_16x16x32_bf16 v[28:31], v[132:135], v[204:207], v[28:31]
	v_mfma_f32_16x16x32_bf16 v[24:27], v[140:143], v[204:207], v[24:27]
	v_mfma_f32_16x16x32_bf16 v[12:15], v[132:135], v[212:215], v[12:15]
	v_mfma_f32_16x16x32_bf16 v[8:11], v[140:143], v[212:215], v[8:11]
	v_mfma_f32_16x16x32_bf16 v[52:55], v[144:147], v[176:179], v[52:55]
	v_mfma_f32_16x16x32_bf16 v[48:51], v[168:171], v[176:179], v[48:51]
	v_mfma_f32_16x16x32_bf16 v[36:39], v[144:147], v[192:195], v[36:39]
	v_mfma_f32_16x16x32_bf16 v[32:35], v[168:171], v[192:195], v[32:35]
	v_mfma_f32_16x16x32_bf16 v[20:23], v[144:147], v[200:203], v[20:23]
	v_mfma_f32_16x16x32_bf16 v[16:19], v[168:171], v[200:203], v[16:19]
	v_mfma_f32_16x16x32_bf16 v[4:7], v[144:147], v[208:211], v[4:7]
	v_mfma_f32_16x16x32_bf16 v[0:3], v[168:171], v[208:211], v[0:3]
	v_mfma_f32_16x16x32_bf16 v[52:55], v[148:151], v[180:183], v[52:55]
	v_mfma_f32_16x16x32_bf16 v[48:51], v[172:175], v[180:183], v[48:51]
	v_mfma_f32_16x16x32_bf16 v[36:39], v[148:151], v[196:199], v[36:39]
	v_mfma_f32_16x16x32_bf16 v[32:35], v[172:175], v[196:199], v[32:35]
	v_mfma_f32_16x16x32_bf16 v[20:23], v[148:151], v[204:207], v[20:23]
	v_mfma_f32_16x16x32_bf16 v[16:19], v[172:175], v[204:207], v[16:19]
	v_mfma_f32_16x16x32_bf16 v[4:7], v[148:151], v[212:215], v[4:7]
	v_mfma_f32_16x16x32_bf16 v[0:3], v[172:175], v[212:215], v[0:3]
	s_barrier
	s_add_i32 s43, s43, 2
	s_add_u32 s44, s44, 0x100
	s_addc_u32 s45, s45, 0
	s_add_u32 s37, s37, 0x100
	s_addc_u32 s42, s42, 0
	s_cmp_gt_u32 s43, 13
	s_cbranch_scc0 .LBB0_508
	s_and_b64 vcc, exec, s[16:17]
	s_cbranch_vccz .LBB0_511
	s_barrier

; #define PG8_STAGE(bufoff, gbase, voff) do { _Pragma("unroll") for (int _i = 0; _i < 2; ++_i) \
;         __builtin_amdgcn_global_load_lds((const unsigned*)((const char*)(gbase) + (voff)[_i]), (PG8_LAS unsigned*)(lds + (bufoff) + ldsw + _i * 8192), 16, 0, 0); } while (0)
; #define PG8_LDA(dst, b, h) do { _Pragma("unroll") for (int m = 0; m < 4; ++m) _Pragma("unroll") for (int k = 0; k < 2; ++k) dst[m][k] = *(const PG8_LAS bf16x8*)(lds + PG8_SA(b, h) + aoff + m * 2048 + k * 1024); } while (0)
; #define PG8_LDB(dst, b, h) do { _Pragma("unroll") for (int n = 0; n < 2; ++n) _Pragma("unroll") for (int k = 0; k < 2; ++k) dst[n][k] = *(const PG8_LAS bf16x8*)(lds + PG8_SB(b, h) + boff + n * 2048 + k * 1024); } while (0)
; #define PG8_MMA(ai, bj, At, Bt) do { __builtin_amdgcn_s_setprio(1); _Pragma("unroll") for (int m = 0; m < 4; ++m) _Pragma("unroll") for (int n = 0; n < 2; ++n) _Pragma("unroll") for (int k = 0; k < 2; ++k) \
;         acc[ai][bj][m][n] = mma16<F16>(Bt[n][k], At[m][k], acc[ai][bj][m][n]); __builtin_amdgcn_s_setprio(0); } while (0)
; #define PG8_WAIT_V(n) asm volatile("s_waitcnt vmcnt(" #n ")" ::: "memory")
; #define PG8_WAIT_L(n) asm volatile("s_waitcnt lgkmcnt(" #n ")" ::: "memory")
; template <class Epi, class Sched, bool ALIGN_EPI = false, bool SP2 = false, bool F16 = false>
; __device__ __forceinline__ void gemm_phase(PG8_LAS unsigned char* lds, const Gemm g, const Sched& S, const Epi& E, const int wid_in) {
;     ...
;             const bool last = (t == nt - 2);
;             const char* a1 = cA + (size_t)(t + 1) * kstep;
;             const char* a2 = last ? nA : cA + (size_t)(t + 2) * kstep; const char* b2 = last ? nB : cB + (size_t)(t + 2) * kstep;
;             const char* a3 = a2 + kstep; const char* b3 = b2 + kstep;
;             if (last && has_next) S.a_ready(nxt);
;             if constexpr (SP2) {
;             PG8_LDB(B0, 0, 0); PG8_LDB(B1, 0, 1); PG8_SCHED; PG8_LDA(At, 0, 0); PG8_STAGE(PG8_SA(1, 1), a1 + hstep, voffA);
;             PG8_WAIT_V(8); PG8_WAIT_L(0); PG8_BAR; PG8_MMA(0, 0, At, B0); PG8_MMA(0, 1, At, B1); PG8_BAR; PG8_SCHED;
;             PG8_LDA(At, 0, 1); PG8_STAGE(PG8_SB(0, 0), b2, voffB); PG8_STAGE(PG8_SB(0, 1), b2 + hstep, voffB); PG8_STAGE(PG8_SA(0, 0), a2, voffA);
;             PG8_WAIT_V(8); PG8_WAIT_L(0); PG8_BAR; PG8_MMA(1, 0, At, B0); PG8_MMA(1, 1, At, B1); PG8_BAR; PG8_SCHED;
.LBB0_585:
	ds_read_b128 v[0:3], v193
	ds_read_b128 v[4:7], v193 offset:1024
	ds_read_b128 v[136:139], v193 offset:2048
	ds_read_b128 v[140:143], v193 offset:3072
	ds_read_b128 v[144:147], v194
	ds_read_b128 v[148:151], v194 offset:1024
	ds_read_b128 v[152:155], v194 offset:2048
	ds_read_b128 v[156:159], v194 offset:3072
	s_add_u32 s36, s34, 0xfffc0080
	s_addc_u32 s37, s35, -1
	s_cmp_eq_u32 s65, 12
	s_cselect_b32 s45, s23, s37
	s_cselect_b32 s44, s31, s36
	s_cselect_b32 s37, s21, s64
	s_cselect_b32 s36, s42, s43
	v_lshl_add_u64 v[188:189], s[34:35], 0, v[168:169]
	s_add_i32 m0, s74, 0xc000
	ds_read_b128 v[176:179], v195
	ds_read_b128 v[180:183], v195 offset:1024
	ds_read_b128 v[184:187], v195 offset:2048
	ds_read_b128 v[198:201], v195 offset:3072
	ds_read_b128 v[202:205], v195 offset:4096
	ds_read_b128 v[206:209], v195 offset:5120
	ds_read_b128 v[210:213], v195 offset:6144
	ds_read_b128 v[214:217], v195 offset:7168
	global_load_lds_dwordx4 v[188:189], off
	v_lshl_add_u64 v[188:189], s[34:35], 0, v[170:171]
	s_add_i32 m0, s74, 0xe000
	s_nop 0
	global_load_lds_dwordx4 v[188:189], off
	s_waitcnt vmcnt(8)
	s_waitcnt lgkmcnt(0)
	s_barrier
	s_waitcnt lgkmcnt(0)
	v_mfma_f32_16x16x32_f16 v[132:135], v[0:3], v[176:179], v[132:135]
	v_mfma_f32_16x16x32_f16 v[128:131], v[136:139], v[176:179], v[128:131]
	v_mfma_f32_16x16x32_f16 v[116:119], v[0:3], v[184:187], v[116:119]
	v_mfma_f32_16x16x32_f16 v[112:115], v[136:139], v[184:187], v[112:115]
	v_mfma_f32_16x16x32_f16 v[100:103], v[0:3], v[202:205], v[100:103]
	v_mfma_f32_16x16x32_f16 v[96:99], v[136:139], v[202:205], v[96:99]
	v_mfma_f32_16x16x32_f16 v[84:87], v[0:3], v[210:213], v[84:87]
	v_mfma_f32_16x16x32_f16 v[80:83], v[136:139], v[210:213], v[80:83]
	v_mfma_f32_16x16x32_f16 v[132:135], v[4:7], v[180:183], v[132:135]
	v_mfma_f32_16x16x32_f16 v[128:131], v[140:143], v[180:183], v[128:131]
	v_mfma_f32_16x16x32_f16 v[116:119], v[4:7], v[198:201], v[116:119]
	v_mfma_f32_16x16x32_f16 v[112:115], v[140:143], v[198:201], v[112:115]
	v_mfma_f32_16x16x32_f16 v[100:103], v[4:7], v[206:209], v[100:103]
	v_mfma_f32_16x16x32_f16 v[96:99], v[140:143], v[206:209], v[96:99]
	v_mfma_f32_16x16x32_f16 v[84:87], v[4:7], v[214:217], v[84:87]
	v_mfma_f32_16x16x32_f16 v[80:83], v[140:143], v[214:217], v[80:83]
	v_mfma_f32_16x16x32_f16 v[124:127], v[144:147], v[176:179], v[124:127]
	v_mfma_f32_16x16x32_f16 v[120:123], v[152:155], v[176:179], v[120:123]
	v_mfma_f32_16x16x32_f16 v[108:111], v[144:147], v[184:187], v[108:111]
	v_mfma_f32_16x16x32_f16 v[104:107], v[152:155], v[184:187], v[104:107]
	v_mfma_f32_16x16x32_f16 v[92:95], v[144:147], v[202:205], v[92:95]
	v_mfma_f32_16x16x32_f16 v[88:91], v[152:155], v[202:205], v[88:91]
	v_mfma_f32_16x16x32_f16 v[76:79], v[144:147], v[210:213], v[76:79]
	v_mfma_f32_16x16x32_f16 v[72:75], v[152:155], v[210:213], v[72:75]
	v_mfma_f32_16x16x32_f16 v[124:127], v[148:151], v[180:183], v[124:127]
	v_mfma_f32_16x16x32_f16 v[120:123], v[156:159], v[180:183], v[120:123]
	v_mfma_f32_16x16x32_f16 v[108:111], v[148:151], v[198:201], v[108:111]
	v_mfma_f32_16x16x32_f16 v[104:107], v[156:159], v[198:201], v[104:107]
	v_mfma_f32_16x16x32_f16 v[92:95], v[148:151], v[206:209], v[92:95]
	v_mfma_f32_16x16x32_f16 v[88:91], v[156:159], v[206:209], v[88:91]
	v_mfma_f32_16x16x32_f16 v[76:79], v[148:151], v[214:217], v[76:79]
	v_mfma_f32_16x16x32_f16 v[72:75], v[156:159], v[214:217], v[72:75]
	s_barrier
	s_add_i32 s66, s61, s68
	v_lshl_add_u64 v[188:189], s[36:37], 0, v[162:163]
	s_mov_b32 m0, s66
	ds_read_b128 v[176:179], v195 offset:16384
	ds_read_b128 v[180:183], v195 offset:17408
	ds_read_b128 v[184:187], v195 offset:18432
	ds_read_b128 v[198:201], v195 offset:19456
	ds_read_b128 v[202:205], v195 offset:20480
	ds_read_b128 v[206:209], v195 offset:21504
	ds_read_b128 v[210:213], v195 offset:22528
	ds_read_b128 v[214:217], v195 offset:23552
	global_load_lds_dwordx4 v[188:189], off
	s_add_i32 m0, s66, 0x2000
	s_add_u32 s66, s36, 0x40000
	v_lshl_add_u64 v[218:219], s[36:37], 0, v[166:167]
	s_addc_u32 s67, s37, 0
	s_add_i32 s76, s62, s68
	global_load_lds_dwordx4 v[218:219], off
	v_lshl_add_u64 v[220:221], s[66:67], 0, v[162:163]
	s_mov_b32 m0, s76
	v_lshl_add_u64 v[222:223], s[44:45], 0, v[164:165]
	global_load_lds_dwordx4 v[220:221], off
	v_lshl_add_u64 v[220:221], s[66:67], 0, v[166:167]
	s_add_i32 m0, s76, 0x2000
	s_nop 0
	global_load_lds_dwordx4 v[220:221], off
	v_lshl_add_u64 v[220:221], s[44:45], 0, v[160:161]
	s_mov_b32 m0, s74
	s_nop 0
	global_load_lds_dwordx4 v[220:221], off
	s_mov_b32 m0, s29
	s_nop 0
	global_load_lds_dwordx4 v[222:223], off
	s_waitcnt vmcnt(8)
	s_waitcnt lgkmcnt(0)
	s_barrier
; #define PG8_STAGE(bufoff, gbase, voff) do { _Pragma("unroll") for (int _i = 0; _i < 2; ++_i) \
;         __builtin_amdgcn_global_load_lds((const unsigned*)((const char*)(gbase) + (voff)[_i]), (PG8_LAS unsigned*)(lds + (bufoff) + ldsw + _i * 8192), 16, 0, 0); } while (0)
; #define PG8_LDA(dst, b, h) do { _Pragma("unroll") for (int m = 0; m < 4; ++m) _Pragma("unroll") for (int k = 0; k < 2; ++k) dst[m][k] = *(const PG8_LAS bf16x8*)(lds + PG8_SA(b, h) + aoff + m * 2048 + k * 1024); } while (0)
; #define PG8_LDB(dst, b, h) do { _Pragma("unroll") for (int n = 0; n < 2; ++n) _Pragma("unroll") for (int k = 0; k < 2; ++k) dst[n][k] = *(const PG8_LAS bf16x8*)(lds + PG8_SB(b, h) + boff + n * 2048 + k * 1024); } while (0)
; #define PG8_MMA(ai, bj, At, Bt) do { __builtin_amdgcn_s_setprio(1); _Pragma("unroll") for (int m = 0; m < 4; ++m) _Pragma("unroll") for (int n = 0; n < 2; ++n) _Pragma("unroll") for (int k = 0; k < 2; ++k) \
;         acc[ai][bj][m][n] = mma16<F16>(Bt[n][k], At[m][k], acc[ai][bj][m][n]); __builtin_amdgcn_s_setprio(0); } while (0)
; #define PG8_WAIT_V(n) asm volatile("s_waitcnt vmcnt(" #n ")" ::: "memory")
; #define PG8_WAIT_L(n) asm volatile("s_waitcnt lgkmcnt(" #n ")" ::: "memory")
; #define PG8_BAR __builtin_amdgcn_s_barrier()
; #define PG8_SCHED __builtin_amdgcn_sched_barrier(0)
; template <class Epi, class Sched, bool ALIGN_EPI = false, bool SP2 = false, bool F16 = false>
; __device__ __forceinline__ void gemm_phase(PG8_LAS unsigned char* lds, const Gemm g, const Sched& S, const Epi& E, const int wid_in) {
;     ...
;             PG8_WAIT_V(8); PG8_WAIT_L(0); PG8_BAR; PG8_MMA(1, 0, At, B0); PG8_MMA(1, 1, At, B1); PG8_BAR; PG8_SCHED;
;             PG8_LDB(B0, 1, 0); PG8_LDB(B1, 1, 1); PG8_SCHED; PG8_LDA(At, 1, 0); PG8_STAGE(PG8_SA(0, 1), a2 + hstep, voffA);
;             PG8_WAIT_V(8); PG8_WAIT_L(0); PG8_BAR; PG8_MMA(0, 0, At, B0); PG8_MMA(0, 1, At, B1); PG8_BAR; PG8_SCHED;
	s_waitcnt lgkmcnt(0)
	v_mfma_f32_16x16x32_f16 v[68:71], v[0:3], v[176:179], v[68:71]
	v_mfma_f32_16x16x32_f16 v[64:67], v[136:139], v[176:179], v[64:67]
	v_mfma_f32_16x16x32_f16 v[52:55], v[0:3], v[184:187], v[52:55]
	v_mfma_f32_16x16x32_f16 v[48:51], v[136:139], v[184:187], v[48:51]
	v_mfma_f32_16x16x32_f16 v[36:39], v[0:3], v[202:205], v[36:39]
	v_mfma_f32_16x16x32_f16 v[32:35], v[136:139], v[202:205], v[32:35]
	v_mfma_f32_16x16x32_f16 v[0:3], v[0:3], v[210:213], v[20:23]
	v_mfma_f32_16x16x32_f16 v[68:71], v[4:7], v[180:183], v[68:71]
	v_mfma_f32_16x16x32_f16 v[64:67], v[140:143], v[180:183], v[64:67]
	v_mfma_f32_16x16x32_f16 v[52:55], v[4:7], v[198:201], v[52:55]
	v_mfma_f32_16x16x32_f16 v[48:51], v[140:143], v[198:201], v[48:51]
	v_mfma_f32_16x16x32_f16 v[36:39], v[4:7], v[206:209], v[36:39]
	v_mfma_f32_16x16x32_f16 v[32:35], v[140:143], v[206:209], v[32:35]
	v_mfma_f32_16x16x32_f16 v[0:3], v[4:7], v[214:217], v[0:3]
	v_mfma_f32_16x16x32_f16 v[4:7], v[136:139], v[210:213], v[16:19]
	v_mfma_f32_16x16x32_f16 v[4:7], v[140:143], v[214:217], v[4:7]
	v_mfma_f32_16x16x32_f16 v[16:19], v[144:147], v[176:179], v[60:63]
	v_mfma_f32_16x16x32_f16 v[60:63], v[148:151], v[180:183], v[16:19]
	v_mfma_f32_16x16x32_f16 v[16:19], v[152:155], v[176:179], v[56:59]
	v_mfma_f32_16x16x32_f16 v[56:59], v[156:159], v[180:183], v[16:19]
	v_mfma_f32_16x16x32_f16 v[16:19], v[144:147], v[184:187], v[44:47]
	v_mfma_f32_16x16x32_f16 v[44:47], v[148:151], v[198:201], v[16:19]
	v_mfma_f32_16x16x32_f16 v[16:19], v[152:155], v[184:187], v[40:43]
	v_mfma_f32_16x16x32_f16 v[40:43], v[156:159], v[198:201], v[16:19]
	v_mfma_f32_16x16x32_f16 v[16:19], v[144:147], v[202:205], v[28:31]
	v_mfma_f32_16x16x32_f16 v[28:31], v[148:151], v[206:209], v[16:19]
	v_mfma_f32_16x16x32_f16 v[16:19], v[152:155], v[202:205], v[24:27]
	v_mfma_f32_16x16x32_f16 v[12:15], v[144:147], v[210:213], v[12:15]
	v_mfma_f32_16x16x32_f16 v[8:11], v[152:155], v[210:213], v[8:11]
	v_mfma_f32_16x16x32_f16 v[24:27], v[156:159], v[206:209], v[16:19]
	v_mfma_f32_16x16x32_f16 v[12:15], v[148:151], v[214:217], v[12:15]
	v_mfma_f32_16x16x32_f16 v[8:11], v[156:159], v[214:217], v[8:11]
	s_barrier
	s_add_i32 s66, 0, 0x18000
	s_add_i32 s67, 0, 0x1c000
	v_add_u32_e32 v140, s66, v192
	v_add_u32_e32 v156, s67, v192
	ds_read_b128 v[16:19], v140
	ds_read_b128 v[20:23], v140 offset:1024
	ds_read_b128 v[136:139], v140 offset:2048
	ds_read_b128 v[140:143], v140 offset:3072
	ds_read_b128 v[144:147], v156
	ds_read_b128 v[148:151], v156 offset:1024
	ds_read_b128 v[152:155], v156 offset:2048
	ds_read_b128 v[156:159], v156 offset:3072
	s_add_u32 s44, s44, 0x40000
	s_addc_u32 s45, s45, 0
	s_mov_b32 m0, s49
	v_lshl_add_u64 v[224:225], s[44:45], 0, v[160:161]
	ds_read_b128 v[176:179], v195 offset:32768
	ds_read_b128 v[180:183], v195 offset:33792
	ds_read_b128 v[184:187], v195 offset:34816
	ds_read_b128 v[198:201], v195 offset:35840
	ds_read_b128 v[202:205], v195 offset:36864
	ds_read_b128 v[206:209], v195 offset:37888
	ds_read_b128 v[210:213], v195 offset:38912
	ds_read_b128 v[214:217], v195 offset:39936
	global_load_lds_dwordx4 v[224:225], off
	v_lshl_add_u64 v[224:225], s[44:45], 0, v[164:165]
	s_mov_b32 m0, s50
	s_nop 0
	global_load_lds_dwordx4 v[224:225], off
	s_waitcnt vmcnt(8)
	s_waitcnt lgkmcnt(0)
	s_barrier
	s_waitcnt lgkmcnt(0)
	v_mfma_f32_16x16x32_f16 v[132:135], v[16:19], v[176:179], v[132:135]
	v_mfma_f32_16x16x32_f16 v[128:131], v[136:139], v[176:179], v[128:131]
	v_mfma_f32_16x16x32_f16 v[116:119], v[16:19], v[184:187], v[116:119]
	v_mfma_f32_16x16x32_f16 v[112:115], v[136:139], v[184:187], v[112:115]
	v_mfma_f32_16x16x32_f16 v[100:103], v[16:19], v[202:205], v[100:103]
	v_mfma_f32_16x16x32_f16 v[96:99], v[136:139], v[202:205], v[96:99]
	v_mfma_f32_16x16x32_f16 v[84:87], v[16:19], v[210:213], v[84:87]
	v_mfma_f32_16x16x32_f16 v[80:83], v[136:139], v[210:213], v[80:83]
	v_mfma_f32_16x16x32_f16 v[132:135], v[20:23], v[180:183], v[132:135]
	v_mfma_f32_16x16x32_f16 v[128:131], v[140:143], v[180:183], v[128:131]
	v_mfma_f32_16x16x32_f16 v[116:119], v[20:23], v[198:201], v[116:119]
	v_mfma_f32_16x16x32_f16 v[112:115], v[140:143], v[198:201], v[112:115]
	v_mfma_f32_16x16x32_f16 v[100:103], v[20:23], v[206:209], v[100:103]
	v_mfma_f32_16x16x32_f16 v[96:99], v[140:143], v[206:209], v[96:99]
	v_mfma_f32_16x16x32_f16 v[84:87], v[20:23], v[214:217], v[84:87]
	v_mfma_f32_16x16x32_f16 v[80:83], v[140:143], v[214:217], v[80:83]
	v_mfma_f32_16x16x32_f16 v[124:127], v[144:147], v[176:179], v[124:127]
	v_mfma_f32_16x16x32_f16 v[120:123], v[152:155], v[176:179], v[120:123]
	v_mfma_f32_16x16x32_f16 v[108:111], v[144:147], v[184:187], v[108:111]
	v_mfma_f32_16x16x32_f16 v[104:107], v[152:155], v[184:187], v[104:107]
	v_mfma_f32_16x16x32_f16 v[92:95], v[144:147], v[202:205], v[92:95]
	v_mfma_f32_16x16x32_f16 v[88:91], v[152:155], v[202:205], v[88:91]
	v_mfma_f32_16x16x32_f16 v[76:79], v[144:147], v[210:213], v[76:79]
	v_mfma_f32_16x16x32_f16 v[72:75], v[152:155], v[210:213], v[72:75]
	v_mfma_f32_16x16x32_f16 v[124:127], v[148:151], v[180:183], v[124:127]
	v_mfma_f32_16x16x32_f16 v[120:123], v[156:159], v[180:183], v[120:123]
	v_mfma_f32_16x16x32_f16 v[108:111], v[148:151], v[198:201], v[108:111]
	v_mfma_f32_16x16x32_f16 v[104:107], v[156:159], v[198:201], v[104:107]
	v_mfma_f32_16x16x32_f16 v[92:95], v[148:151], v[206:209], v[92:95]
	v_mfma_f32_16x16x32_f16 v[88:91], v[156:159], v[206:209], v[88:91]
	v_mfma_f32_16x16x32_f16 v[76:79], v[148:151], v[214:217], v[76:79]
	v_mfma_f32_16x16x32_f16 v[72:75], v[156:159], v[214:217], v[72:75]
	s_barrier
; #define PG8_STAGE(bufoff, gbase, voff) do { _Pragma("unroll") for (int _i = 0; _i < 2; ++_i) \
;         __builtin_amdgcn_global_load_lds((const unsigned*)((const char*)(gbase) + (voff)[_i]), (PG8_LAS unsigned*)(lds + (bufoff) + ldsw + _i * 8192), 16, 0, 0); } while (0)
; #define PG8_LDA(dst, b, h) do { _Pragma("unroll") for (int m = 0; m < 4; ++m) _Pragma("unroll") for (int k = 0; k < 2; ++k) dst[m][k] = *(const PG8_LAS bf16x8*)(lds + PG8_SA(b, h) + aoff + m * 2048 + k * 1024); } while (0)
; #define PG8_MMA(ai, bj, At, Bt) do { __builtin_amdgcn_s_setprio(1); _Pragma("unroll") for (int m = 0; m < 4; ++m) _Pragma("unroll") for (int n = 0; n < 2; ++n) _Pragma("unroll") for (int k = 0; k < 2; ++k) \
;         acc[ai][bj][m][n] = mma16<F16>(Bt[n][k], At[m][k], acc[ai][bj][m][n]); __builtin_amdgcn_s_setprio(0); } while (0)
; #define PG8_WAIT_V(n) asm volatile("s_waitcnt vmcnt(" #n ")" ::: "memory")
; #define PG8_WAIT_L(n) asm volatile("s_waitcnt lgkmcnt(" #n ")" ::: "memory")
; #define PG8_BAR __builtin_amdgcn_s_barrier()
; #define PG8_SCHED __builtin_amdgcn_sched_barrier(0)
; template <class Epi, class Sched, bool ALIGN_EPI = false, bool SP2 = false, bool F16 = false>
; __device__ __forceinline__ void gemm_phase(PG8_LAS unsigned char* lds, const Gemm g, const Sched& S, const Epi& E, const int wid_in) {
;     ...
;             PG8_LDA(At, 1, 1); PG8_STAGE(PG8_SB(1, 0), b3, voffB); PG8_STAGE(PG8_SB(1, 1), b3 + hstep, voffB); PG8_STAGE(PG8_SA(1, 0), a3, voffA);
;             PG8_WAIT_V(8); PG8_WAIT_L(0); PG8_BAR; PG8_MMA(1, 0, At, B0); PG8_MMA(1, 1, At, B1); PG8_BAR; PG8_SCHED;
;     ...
;         if constexpr (ALIGN_EPI) { if (wr == 0) PG8_BAR; }
	s_add_i32 s44, s66, s68
	v_lshl_add_u64 v[188:189], v[188:189], 0, s[18:19]
	s_mov_b32 m0, s44
	ds_read_b128 v[176:179], v195 offset:49152
	ds_read_b128 v[180:183], v195 offset:50176
	ds_read_b128 v[184:187], v195 offset:51200
	ds_read_b128 v[198:201], v195 offset:52224
	ds_read_b128 v[202:205], v195 offset:53248
	ds_read_b128 v[206:209], v195 offset:54272
	ds_read_b128 v[210:213], v195 offset:55296
	ds_read_b128 v[214:217], v195 offset:56320
	global_load_lds_dwordx4 v[188:189], off
	s_add_i32 m0, s44, 0x2000
	s_add_u32 s36, s36, 0x40080
	v_lshl_add_u64 v[188:189], v[218:219], 0, s[18:19]
	s_addc_u32 s37, s37, 0
	s_add_i32 s44, s67, s68
	global_load_lds_dwordx4 v[188:189], off
	v_lshl_add_u64 v[188:189], s[36:37], 0, v[162:163]
	s_mov_b32 m0, s44
	s_nop 0
	global_load_lds_dwordx4 v[188:189], off
	v_lshl_add_u64 v[188:189], s[36:37], 0, v[166:167]
	s_add_i32 m0, s44, 0x2000
	s_nop 0
	global_load_lds_dwordx4 v[188:189], off
	v_lshl_add_u64 v[188:189], v[220:221], 0, s[18:19]
	s_mov_b32 m0, s75
	s_nop 0
	global_load_lds_dwordx4 v[188:189], off
	v_lshl_add_u64 v[188:189], v[222:223], 0, s[18:19]
	s_mov_b32 m0, s53
	s_nop 0
	global_load_lds_dwordx4 v[188:189], off
	s_waitcnt vmcnt(8)
	s_waitcnt lgkmcnt(0)
	s_barrier
	s_waitcnt lgkmcnt(0)
	v_mfma_f32_16x16x32_f16 v[68:71], v[16:19], v[176:179], v[68:71]
	v_mfma_f32_16x16x32_f16 v[52:55], v[16:19], v[184:187], v[52:55]
	v_mfma_f32_16x16x32_f16 v[36:39], v[16:19], v[202:205], v[36:39]
	v_mfma_f32_16x16x32_f16 v[0:3], v[16:19], v[210:213], v[0:3]
	v_mfma_f32_16x16x32_f16 v[68:71], v[20:23], v[180:183], v[68:71]
	v_mfma_f32_16x16x32_f16 v[64:67], v[136:139], v[176:179], v[64:67]
	v_mfma_f32_16x16x32_f16 v[52:55], v[20:23], v[198:201], v[52:55]
	v_mfma_f32_16x16x32_f16 v[48:51], v[136:139], v[184:187], v[48:51]
	v_mfma_f32_16x16x32_f16 v[36:39], v[20:23], v[206:209], v[36:39]
	v_mfma_f32_16x16x32_f16 v[32:35], v[136:139], v[202:205], v[32:35]
	v_mfma_f32_16x16x32_f16 v[20:23], v[20:23], v[214:217], v[0:3]
	v_mfma_f32_16x16x32_f16 v[0:3], v[136:139], v[210:213], v[4:7]
	v_mfma_f32_16x16x32_f16 v[64:67], v[140:143], v[180:183], v[64:67]
	v_mfma_f32_16x16x32_f16 v[48:51], v[140:143], v[198:201], v[48:51]
	v_mfma_f32_16x16x32_f16 v[32:35], v[140:143], v[206:209], v[32:35]
	v_mfma_f32_16x16x32_f16 v[16:19], v[140:143], v[214:217], v[0:3]
	v_mfma_f32_16x16x32_f16 v[0:3], v[144:147], v[176:179], v[60:63]
	v_mfma_f32_16x16x32_f16 v[60:63], v[148:151], v[180:183], v[0:3]
	v_mfma_f32_16x16x32_f16 v[0:3], v[152:155], v[176:179], v[56:59]
	v_mfma_f32_16x16x32_f16 v[56:59], v[156:159], v[180:183], v[0:3]
	v_mfma_f32_16x16x32_f16 v[0:3], v[144:147], v[184:187], v[44:47]
	v_mfma_f32_16x16x32_f16 v[44:47], v[148:151], v[198:201], v[0:3]
	v_mfma_f32_16x16x32_f16 v[0:3], v[152:155], v[184:187], v[40:43]
	v_mfma_f32_16x16x32_f16 v[40:43], v[156:159], v[198:201], v[0:3]
	v_mfma_f32_16x16x32_f16 v[0:3], v[144:147], v[202:205], v[28:31]
	v_mfma_f32_16x16x32_f16 v[28:31], v[148:151], v[206:209], v[0:3]
	v_mfma_f32_16x16x32_f16 v[0:3], v[152:155], v[202:205], v[24:27]
	v_mfma_f32_16x16x32_f16 v[24:27], v[156:159], v[206:209], v[0:3]
	v_mfma_f32_16x16x32_f16 v[0:3], v[144:147], v[210:213], v[12:15]
	v_mfma_f32_16x16x32_f16 v[12:15], v[148:151], v[214:217], v[0:3]
	v_mfma_f32_16x16x32_f16 v[0:3], v[152:155], v[210:213], v[8:11]
	v_mfma_f32_16x16x32_f16 v[8:11], v[156:159], v[214:217], v[0:3]
	s_barrier
	s_add_i32 s65, s65, 2
	s_add_u32 s34, s34, 0x100
	s_addc_u32 s35, s35, 0
	s_add_u32 s43, s43, 0x100
	s_addc_u32 s64, s64, 0
	s_cmp_gt_u32 s65, 13
	s_cbranch_scc0 .LBB0_585
	s_and_b64 vcc, exec, s[16:17]
	s_cbranch_vccz .LBB0_588
	s_barrier

; #define PG8_STAGE(bufoff, gbase, voff) do { _Pragma("unroll") for (int _i = 0; _i < 2; ++_i) \
;         __builtin_amdgcn_global_load_lds((const unsigned*)((const char*)(gbase) + (voff)[_i]), (PG8_LAS unsigned*)(lds + (bufoff) + ldsw + _i * 8192), 16, 0, 0); } while (0)
; #define PG8_LDA(dst, b, h) do { _Pragma("unroll") for (int m = 0; m < 4; ++m) _Pragma("unroll") for (int k = 0; k < 2; ++k) dst[m][k] = *(const PG8_LAS bf16x8*)(lds + PG8_SA(b, h) + aoff + m * 2048 + k * 1024); } while (0)
; #define PG8_LDB(dst, b, h) do { _Pragma("unroll") for (int n = 0; n < 2; ++n) _Pragma("unroll") for (int k = 0; k < 2; ++k) dst[n][k] = *(const PG8_LAS bf16x8*)(lds + PG8_SB(b, h) + boff + n * 2048 + k * 1024); } while (0)
; #define PG8_MMA(ai, bj, At, Bt) do { __builtin_amdgcn_s_setprio(1); _Pragma("unroll") for (int m = 0; m < 4; ++m) _Pragma("unroll") for (int n = 0; n < 2; ++n) _Pragma("unroll") for (int k = 0; k < 2; ++k) \
;         acc[ai][bj][m][n] = mma16<F16>(Bt[n][k], At[m][k], acc[ai][bj][m][n]); __builtin_amdgcn_s_setprio(0); } while (0)
; #define PG8_WAIT_V(n) asm volatile("s_waitcnt vmcnt(" #n ")" ::: "memory")
; #define PG8_WAIT_L(n) asm volatile("s_waitcnt lgkmcnt(" #n ")" ::: "memory")
; template <class Epi, class Sched, bool ALIGN_EPI = false, bool SP2 = false, bool F16 = false>
; __device__ __forceinline__ void gemm_phase(PG8_LAS unsigned char* lds, const Gemm g, const Sched& S, const Epi& E, const int wid_in) {
;     ...
;             const bool last = (t == nt - 2);
;             const char* a1 = cA + (size_t)(t + 1) * kstep;
;             const char* a2 = last ? nA : cA + (size_t)(t + 2) * kstep; const char* b2 = last ? nB : cB + (size_t)(t + 2) * kstep;
;             const char* a3 = a2 + kstep; const char* b3 = b2 + kstep;
;             if (last && has_next) S.a_ready(nxt);
;             if constexpr (SP2) {
;             PG8_LDB(B0, 0, 0); PG8_LDB(B1, 0, 1); PG8_SCHED; PG8_LDA(At, 0, 0); PG8_STAGE(PG8_SA(1, 1), a1 + hstep, voffA);
;             PG8_WAIT_V(8); PG8_WAIT_L(0); PG8_BAR; PG8_MMA(0, 0, At, B0); PG8_MMA(0, 1, At, B1); PG8_BAR; PG8_SCHED;
;             PG8_LDA(At, 0, 1); PG8_STAGE(PG8_SB(0, 0), b2, voffB); PG8_STAGE(PG8_SB(0, 1), b2 + hstep, voffB); PG8_STAGE(PG8_SA(0, 0), a2, voffA);
;             PG8_WAIT_V(8); PG8_WAIT_L(0); PG8_BAR; PG8_MMA(1, 0, At, B0); PG8_MMA(1, 1, At, B1); PG8_BAR; PG8_SCHED;
.LBB0_716:
	ds_read_b128 v[128:131], v189
	ds_read_b128 v[132:135], v189 offset:1024
	ds_read_b128 v[136:139], v189 offset:2048
	ds_read_b128 v[140:143], v189 offset:3072
	ds_read_b128 v[144:147], v190
	ds_read_b128 v[148:151], v190 offset:1024
	ds_read_b128 v[168:171], v190 offset:2048
	ds_read_b128 v[172:175], v190 offset:3072
	s_add_u32 s30, s28, 0x100
	s_addc_u32 s31, s29, 0
	s_cmp_eq_u32 s60, 40
	s_cselect_b32 s37, s11, s31
	s_cselect_b32 s36, s10, s30
	s_cselect_b32 s35, s27, s59
	s_cselect_b32 s34, s26, s43
	v_lshl_add_u64 v[184:185], s[28:29], 0, v[160:161]
	s_add_i32 m0, s74, 0xc000
	ds_read_b128 v[176:179], v191
	ds_read_b128 v[180:183], v191 offset:1024
	ds_read_b128 v[192:195], v191 offset:2048
	ds_read_b128 v[196:199], v191 offset:3072
	ds_read_b128 v[200:203], v191 offset:4096
	ds_read_b128 v[204:207], v191 offset:5120
	ds_read_b128 v[208:211], v191 offset:6144
	ds_read_b128 v[212:215], v191 offset:7168
	global_load_lds_dwordx4 v[184:185], off
	v_lshl_add_u64 v[184:185], s[28:29], 0, v[162:163]
	s_add_i32 m0, s74, 0xe000
	s_nop 0
	global_load_lds_dwordx4 v[184:185], off
	s_waitcnt vmcnt(8)
	s_waitcnt lgkmcnt(0)
	s_barrier
	s_waitcnt lgkmcnt(0)
	v_mfma_f32_16x16x32_bf16 v[124:127], v[128:131], v[176:179], v[124:127]
	v_mfma_f32_16x16x32_bf16 v[120:123], v[136:139], v[176:179], v[120:123]
	v_mfma_f32_16x16x32_bf16 v[108:111], v[128:131], v[192:195], v[108:111]
	v_mfma_f32_16x16x32_bf16 v[104:107], v[136:139], v[192:195], v[104:107]
	v_mfma_f32_16x16x32_bf16 v[92:95], v[128:131], v[200:203], v[92:95]
	v_mfma_f32_16x16x32_bf16 v[88:91], v[136:139], v[200:203], v[88:91]
	v_mfma_f32_16x16x32_bf16 v[76:79], v[128:131], v[208:211], v[76:79]
	v_mfma_f32_16x16x32_bf16 v[72:75], v[136:139], v[208:211], v[72:75]
	v_mfma_f32_16x16x32_bf16 v[124:127], v[132:135], v[180:183], v[124:127]
	v_mfma_f32_16x16x32_bf16 v[120:123], v[140:143], v[180:183], v[120:123]
	v_mfma_f32_16x16x32_bf16 v[108:111], v[132:135], v[196:199], v[108:111]
	v_mfma_f32_16x16x32_bf16 v[104:107], v[140:143], v[196:199], v[104:107]
	v_mfma_f32_16x16x32_bf16 v[92:95], v[132:135], v[204:207], v[92:95]
	v_mfma_f32_16x16x32_bf16 v[88:91], v[140:143], v[204:207], v[88:91]
	v_mfma_f32_16x16x32_bf16 v[76:79], v[132:135], v[212:215], v[76:79]
	v_mfma_f32_16x16x32_bf16 v[72:75], v[140:143], v[212:215], v[72:75]
	v_mfma_f32_16x16x32_bf16 v[116:119], v[144:147], v[176:179], v[116:119]
	v_mfma_f32_16x16x32_bf16 v[112:115], v[168:171], v[176:179], v[112:115]
	v_mfma_f32_16x16x32_bf16 v[100:103], v[144:147], v[192:195], v[100:103]
	v_mfma_f32_16x16x32_bf16 v[96:99], v[168:171], v[192:195], v[96:99]
	v_mfma_f32_16x16x32_bf16 v[84:87], v[144:147], v[200:203], v[84:87]
	v_mfma_f32_16x16x32_bf16 v[80:83], v[168:171], v[200:203], v[80:83]
	v_mfma_f32_16x16x32_bf16 v[68:71], v[144:147], v[208:211], v[68:71]
	v_mfma_f32_16x16x32_bf16 v[64:67], v[168:171], v[208:211], v[64:67]
	v_mfma_f32_16x16x32_bf16 v[116:119], v[148:151], v[180:183], v[116:119]
	v_mfma_f32_16x16x32_bf16 v[112:115], v[172:175], v[180:183], v[112:115]
	v_mfma_f32_16x16x32_bf16 v[100:103], v[148:151], v[196:199], v[100:103]
	v_mfma_f32_16x16x32_bf16 v[96:99], v[172:175], v[196:199], v[96:99]
	v_mfma_f32_16x16x32_bf16 v[84:87], v[148:151], v[204:207], v[84:87]
	v_mfma_f32_16x16x32_bf16 v[80:83], v[172:175], v[204:207], v[80:83]
	v_mfma_f32_16x16x32_bf16 v[68:71], v[148:151], v[212:215], v[68:71]
	v_mfma_f32_16x16x32_bf16 v[64:67], v[172:175], v[212:215], v[64:67]
	s_barrier
	s_add_i32 s28, s52, s68
	v_lshl_add_u64 v[184:185], s[34:35], 0, v[154:155]
	s_mov_b32 m0, s28
	ds_read_b128 v[176:179], v191 offset:16384
	ds_read_b128 v[180:183], v191 offset:17408
	ds_read_b128 v[192:195], v191 offset:18432
	ds_read_b128 v[196:199], v191 offset:19456
	ds_read_b128 v[200:203], v191 offset:20480
	ds_read_b128 v[204:207], v191 offset:21504
	ds_read_b128 v[208:211], v191 offset:22528
	ds_read_b128 v[212:215], v191 offset:23552
	global_load_lds_dwordx4 v[184:185], off
	s_add_i32 m0, s28, 0x2000
	s_add_u32 s28, s34, 0xb0000
	v_lshl_add_u64 v[216:217], s[34:35], 0, v[158:159]
	s_addc_u32 s29, s35, 0
	s_add_i32 s61, s53, s68
	global_load_lds_dwordx4 v[216:217], off
	v_lshl_add_u64 v[218:219], s[28:29], 0, v[154:155]
	s_mov_b32 m0, s61
	v_lshl_add_u64 v[220:221], s[36:37], 0, v[156:157]
	global_load_lds_dwordx4 v[218:219], off
	v_lshl_add_u64 v[218:219], s[28:29], 0, v[158:159]
	s_add_i32 m0, s61, 0x2000
	s_nop 0
	global_load_lds_dwordx4 v[218:219], off
	v_lshl_add_u64 v[218:219], s[36:37], 0, v[152:153]
	s_mov_b32 m0, s74
	s_nop 0
	global_load_lds_dwordx4 v[218:219], off
	s_mov_b32 m0, s45
	s_nop 0
	global_load_lds_dwordx4 v[220:221], off
	s_waitcnt vmcnt(8)
	s_waitcnt lgkmcnt(0)
	s_barrier
; #define PG8_STAGE(bufoff, gbase, voff) do { _Pragma("unroll") for (int _i = 0; _i < 2; ++_i) \
;         __builtin_amdgcn_global_load_lds((const unsigned*)((const char*)(gbase) + (voff)[_i]), (PG8_LAS unsigned*)(lds + (bufoff) + ldsw + _i * 8192), 16, 0, 0); } while (0)
; #define PG8_LDA(dst, b, h) do { _Pragma("unroll") for (int m = 0; m < 4; ++m) _Pragma("unroll") for (int k = 0; k < 2; ++k) dst[m][k] = *(const PG8_LAS bf16x8*)(lds + PG8_SA(b, h) + aoff + m * 2048 + k * 1024); } while (0)
; #define PG8_LDB(dst, b, h) do { _Pragma("unroll") for (int n = 0; n < 2; ++n) _Pragma("unroll") for (int k = 0; k < 2; ++k) dst[n][k] = *(const PG8_LAS bf16x8*)(lds + PG8_SB(b, h) + boff + n * 2048 + k * 1024); } while (0)
; #define PG8_MMA(ai, bj, At, Bt) do { __builtin_amdgcn_s_setprio(1); _Pragma("unroll") for (int m = 0; m < 4; ++m) _Pragma("unroll") for (int n = 0; n < 2; ++n) _Pragma("unroll") for (int k = 0; k < 2; ++k) \
;         acc[ai][bj][m][n] = mma16<F16>(Bt[n][k], At[m][k], acc[ai][bj][m][n]); __builtin_amdgcn_s_setprio(0); } while (0)
; #define PG8_WAIT_V(n) asm volatile("s_waitcnt vmcnt(" #n ")" ::: "memory")
; #define PG8_WAIT_L(n) asm volatile("s_waitcnt lgkmcnt(" #n ")" ::: "memory")
; #define PG8_BAR __builtin_amdgcn_s_barrier()
; #define PG8_SCHED __builtin_amdgcn_sched_barrier(0)
; template <class Epi, class Sched, bool ALIGN_EPI = false, bool SP2 = false, bool F16 = false>
; __device__ __forceinline__ void gemm_phase(PG8_LAS unsigned char* lds, const Gemm g, const Sched& S, const Epi& E, const int wid_in) {
;     ...
;             PG8_WAIT_V(8); PG8_WAIT_L(0); PG8_BAR; PG8_MMA(1, 0, At, B0); PG8_MMA(1, 1, At, B1); PG8_BAR; PG8_SCHED;
;             PG8_LDB(B0, 1, 0); PG8_LDB(B1, 1, 1); PG8_SCHED; PG8_LDA(At, 1, 0); PG8_STAGE(PG8_SA(0, 1), a2 + hstep, voffA);
;             PG8_WAIT_V(8); PG8_WAIT_L(0); PG8_BAR; PG8_MMA(0, 0, At, B0); PG8_MMA(0, 1, At, B1); PG8_BAR; PG8_SCHED;
	s_waitcnt lgkmcnt(0)
	v_mfma_f32_16x16x32_bf16 v[60:63], v[128:131], v[176:179], v[60:63]
	v_mfma_f32_16x16x32_bf16 v[56:59], v[136:139], v[176:179], v[56:59]
	v_mfma_f32_16x16x32_bf16 v[44:47], v[128:131], v[192:195], v[44:47]
	v_mfma_f32_16x16x32_bf16 v[40:43], v[136:139], v[192:195], v[40:43]
	v_mfma_f32_16x16x32_bf16 v[28:31], v[128:131], v[200:203], v[28:31]
	v_mfma_f32_16x16x32_bf16 v[24:27], v[136:139], v[200:203], v[24:27]
	v_mfma_f32_16x16x32_bf16 v[12:15], v[128:131], v[208:211], v[12:15]
	v_mfma_f32_16x16x32_bf16 v[8:11], v[136:139], v[208:211], v[8:11]
	v_mfma_f32_16x16x32_bf16 v[60:63], v[132:135], v[180:183], v[60:63]
	v_mfma_f32_16x16x32_bf16 v[56:59], v[140:143], v[180:183], v[56:59]
	v_mfma_f32_16x16x32_bf16 v[44:47], v[132:135], v[196:199], v[44:47]
	v_mfma_f32_16x16x32_bf16 v[40:43], v[140:143], v[196:199], v[40:43]
	v_mfma_f32_16x16x32_bf16 v[28:31], v[132:135], v[204:207], v[28:31]
	v_mfma_f32_16x16x32_bf16 v[24:27], v[140:143], v[204:207], v[24:27]
	v_mfma_f32_16x16x32_bf16 v[12:15], v[132:135], v[212:215], v[12:15]
	v_mfma_f32_16x16x32_bf16 v[8:11], v[140:143], v[212:215], v[8:11]
	v_mfma_f32_16x16x32_bf16 v[52:55], v[144:147], v[176:179], v[52:55]
	v_mfma_f32_16x16x32_bf16 v[48:51], v[168:171], v[176:179], v[48:51]
	v_mfma_f32_16x16x32_bf16 v[36:39], v[144:147], v[192:195], v[36:39]
	v_mfma_f32_16x16x32_bf16 v[32:35], v[168:171], v[192:195], v[32:35]
	v_mfma_f32_16x16x32_bf16 v[20:23], v[144:147], v[200:203], v[20:23]
	v_mfma_f32_16x16x32_bf16 v[16:19], v[168:171], v[200:203], v[16:19]
	v_mfma_f32_16x16x32_bf16 v[4:7], v[144:147], v[208:211], v[4:7]
	v_mfma_f32_16x16x32_bf16 v[0:3], v[168:171], v[208:211], v[0:3]
	v_mfma_f32_16x16x32_bf16 v[52:55], v[148:151], v[180:183], v[52:55]
	v_mfma_f32_16x16x32_bf16 v[48:51], v[172:175], v[180:183], v[48:51]
	v_mfma_f32_16x16x32_bf16 v[36:39], v[148:151], v[196:199], v[36:39]
	v_mfma_f32_16x16x32_bf16 v[32:35], v[172:175], v[196:199], v[32:35]
	v_mfma_f32_16x16x32_bf16 v[20:23], v[148:151], v[204:207], v[20:23]
	v_mfma_f32_16x16x32_bf16 v[16:19], v[172:175], v[204:207], v[16:19]
	v_mfma_f32_16x16x32_bf16 v[4:7], v[148:151], v[212:215], v[4:7]
	v_mfma_f32_16x16x32_bf16 v[0:3], v[172:175], v[212:215], v[0:3]
	s_barrier
	s_add_i32 s61, 0, 0x18000
	s_add_i32 s62, 0, 0x1c000
	v_add_u32_e32 v140, s61, v188
	v_add_u32_e32 v172, s62, v188
	ds_read_b128 v[128:131], v140
	ds_read_b128 v[132:135], v140 offset:1024
	ds_read_b128 v[136:139], v140 offset:2048
	ds_read_b128 v[140:143], v140 offset:3072
	ds_read_b128 v[144:147], v172
	ds_read_b128 v[148:151], v172 offset:1024
	ds_read_b128 v[168:171], v172 offset:2048
	ds_read_b128 v[172:175], v172 offset:3072
	s_add_u32 s28, s36, 0xb0000
	s_addc_u32 s29, s37, 0
	s_mov_b32 m0, s46
	v_lshl_add_u64 v[222:223], s[28:29], 0, v[152:153]
	ds_read_b128 v[176:179], v191 offset:32768
	ds_read_b128 v[180:183], v191 offset:33792
	ds_read_b128 v[192:195], v191 offset:34816
	ds_read_b128 v[196:199], v191 offset:35840
	ds_read_b128 v[200:203], v191 offset:36864
	ds_read_b128 v[204:207], v191 offset:37888
	ds_read_b128 v[208:211], v191 offset:38912
	ds_read_b128 v[212:215], v191 offset:39936
	global_load_lds_dwordx4 v[222:223], off
	v_lshl_add_u64 v[222:223], s[28:29], 0, v[156:157]
	s_mov_b32 m0, s47
	s_nop 0
	global_load_lds_dwordx4 v[222:223], off
	s_waitcnt vmcnt(8)
	s_waitcnt lgkmcnt(0)
	s_barrier
	s_waitcnt lgkmcnt(0)
	v_mfma_f32_16x16x32_bf16 v[124:127], v[128:131], v[176:179], v[124:127]
	v_mfma_f32_16x16x32_bf16 v[120:123], v[136:139], v[176:179], v[120:123]
	v_mfma_f32_16x16x32_bf16 v[108:111], v[128:131], v[192:195], v[108:111]
	v_mfma_f32_16x16x32_bf16 v[104:107], v[136:139], v[192:195], v[104:107]
	v_mfma_f32_16x16x32_bf16 v[92:95], v[128:131], v[200:203], v[92:95]
	v_mfma_f32_16x16x32_bf16 v[88:91], v[136:139], v[200:203], v[88:91]
	v_mfma_f32_16x16x32_bf16 v[76:79], v[128:131], v[208:211], v[76:79]
	v_mfma_f32_16x16x32_bf16 v[72:75], v[136:139], v[208:211], v[72:75]
	v_mfma_f32_16x16x32_bf16 v[124:127], v[132:135], v[180:183], v[124:127]
	v_mfma_f32_16x16x32_bf16 v[120:123], v[140:143], v[180:183], v[120:123]
	v_mfma_f32_16x16x32_bf16 v[108:111], v[132:135], v[196:199], v[108:111]
	v_mfma_f32_16x16x32_bf16 v[104:107], v[140:143], v[196:199], v[104:107]
	v_mfma_f32_16x16x32_bf16 v[92:95], v[132:135], v[204:207], v[92:95]
	v_mfma_f32_16x16x32_bf16 v[88:91], v[140:143], v[204:207], v[88:91]
	v_mfma_f32_16x16x32_bf16 v[76:79], v[132:135], v[212:215], v[76:79]
	v_mfma_f32_16x16x32_bf16 v[72:75], v[140:143], v[212:215], v[72:75]
	v_mfma_f32_16x16x32_bf16 v[116:119], v[144:147], v[176:179], v[116:119]
	v_mfma_f32_16x16x32_bf16 v[112:115], v[168:171], v[176:179], v[112:115]
	v_mfma_f32_16x16x32_bf16 v[100:103], v[144:147], v[192:195], v[100:103]
	v_mfma_f32_16x16x32_bf16 v[96:99], v[168:171], v[192:195], v[96:99]
	v_mfma_f32_16x16x32_bf16 v[84:87], v[144:147], v[200:203], v[84:87]
	v_mfma_f32_16x16x32_bf16 v[80:83], v[168:171], v[200:203], v[80:83]
	v_mfma_f32_16x16x32_bf16 v[68:71], v[144:147], v[208:211], v[68:71]
	v_mfma_f32_16x16x32_bf16 v[64:67], v[168:171], v[208:211], v[64:67]
	v_mfma_f32_16x16x32_bf16 v[116:119], v[148:151], v[180:183], v[116:119]
	v_mfma_f32_16x16x32_bf16 v[112:115], v[172:175], v[180:183], v[112:115]
	v_mfma_f32_16x16x32_bf16 v[100:103], v[148:151], v[196:199], v[100:103]
	v_mfma_f32_16x16x32_bf16 v[96:99], v[172:175], v[196:199], v[96:99]
	v_mfma_f32_16x16x32_bf16 v[84:87], v[148:151], v[204:207], v[84:87]
	v_mfma_f32_16x16x32_bf16 v[80:83], v[172:175], v[204:207], v[80:83]
	v_mfma_f32_16x16x32_bf16 v[68:71], v[148:151], v[212:215], v[68:71]
	v_mfma_f32_16x16x32_bf16 v[64:67], v[172:175], v[212:215], v[64:67]
	s_barrier
; #define PG8_STAGE(bufoff, gbase, voff) do { _Pragma("unroll") for (int _i = 0; _i < 2; ++_i) \
;         __builtin_amdgcn_global_load_lds((const unsigned*)((const char*)(gbase) + (voff)[_i]), (PG8_LAS unsigned*)(lds + (bufoff) + ldsw + _i * 8192), 16, 0, 0); } while (0)
; #define PG8_LDA(dst, b, h) do { _Pragma("unroll") for (int m = 0; m < 4; ++m) _Pragma("unroll") for (int k = 0; k < 2; ++k) dst[m][k] = *(const PG8_LAS bf16x8*)(lds + PG8_SA(b, h) + aoff + m * 2048 + k * 1024); } while (0)
; #define PG8_MMA(ai, bj, At, Bt) do { __builtin_amdgcn_s_setprio(1); _Pragma("unroll") for (int m = 0; m < 4; ++m) _Pragma("unroll") for (int n = 0; n < 2; ++n) _Pragma("unroll") for (int k = 0; k < 2; ++k) \
;         acc[ai][bj][m][n] = mma16<F16>(Bt[n][k], At[m][k], acc[ai][bj][m][n]); __builtin_amdgcn_s_setprio(0); } while (0)
; #define PG8_WAIT_V(n) asm volatile("s_waitcnt vmcnt(" #n ")" ::: "memory")
; #define PG8_WAIT_L(n) asm volatile("s_waitcnt lgkmcnt(" #n ")" ::: "memory")
; #define PG8_BAR __builtin_amdgcn_s_barrier()
; #define PG8_SCHED __builtin_amdgcn_sched_barrier(0)
; template <class Epi, class Sched, bool ALIGN_EPI = false, bool SP2 = false, bool F16 = false>
; __device__ __forceinline__ void gemm_phase(PG8_LAS unsigned char* lds, const Gemm g, const Sched& S, const Epi& E, const int wid_in) {
;     ...
;             PG8_LDA(At, 1, 1); PG8_STAGE(PG8_SB(1, 0), b3, voffB); PG8_STAGE(PG8_SB(1, 1), b3 + hstep, voffB); PG8_STAGE(PG8_SA(1, 0), a3, voffA);
;             PG8_WAIT_V(8); PG8_WAIT_L(0); PG8_BAR; PG8_MMA(1, 0, At, B0); PG8_MMA(1, 1, At, B1); PG8_BAR; PG8_SCHED;
;     ...
;         if constexpr (ALIGN_EPI) { if (wr == 0) PG8_BAR; }
	s_add_i32 s28, s61, s68
	v_lshl_add_u64 v[184:185], v[184:185], 0, s[24:25]
	s_mov_b32 m0, s28
	ds_read_b128 v[176:179], v191 offset:49152
	ds_read_b128 v[180:183], v191 offset:50176
	ds_read_b128 v[192:195], v191 offset:51200
	ds_read_b128 v[196:199], v191 offset:52224
	ds_read_b128 v[200:203], v191 offset:53248
	ds_read_b128 v[204:207], v191 offset:54272
	ds_read_b128 v[208:211], v191 offset:55296
	ds_read_b128 v[212:215], v191 offset:56320
	global_load_lds_dwordx4 v[184:185], off
	s_add_i32 m0, s28, 0x2000
	s_add_u32 s28, s34, 0xb0080
	v_lshl_add_u64 v[184:185], v[216:217], 0, s[24:25]
	s_addc_u32 s29, s35, 0
	s_add_i32 s34, s62, s68
	global_load_lds_dwordx4 v[184:185], off
	v_lshl_add_u64 v[184:185], s[28:29], 0, v[154:155]
	s_mov_b32 m0, s34
	s_nop 0
	global_load_lds_dwordx4 v[184:185], off
	v_lshl_add_u64 v[184:185], s[28:29], 0, v[158:159]
	s_add_i32 m0, s34, 0x2000
	s_nop 0
	global_load_lds_dwordx4 v[184:185], off
	v_lshl_add_u64 v[184:185], v[218:219], 0, s[24:25]
	s_mov_b32 m0, s75
	s_nop 0
	global_load_lds_dwordx4 v[184:185], off
	v_lshl_add_u64 v[184:185], v[220:221], 0, s[24:25]
	s_mov_b32 m0, s48
	s_nop 0
	global_load_lds_dwordx4 v[184:185], off
	s_waitcnt vmcnt(8)
	s_waitcnt lgkmcnt(0)
	s_barrier
	s_waitcnt lgkmcnt(0)
	v_mfma_f32_16x16x32_bf16 v[60:63], v[128:131], v[176:179], v[60:63]
	v_mfma_f32_16x16x32_bf16 v[56:59], v[136:139], v[176:179], v[56:59]
	v_mfma_f32_16x16x32_bf16 v[44:47], v[128:131], v[192:195], v[44:47]
	v_mfma_f32_16x16x32_bf16 v[40:43], v[136:139], v[192:195], v[40:43]
	v_mfma_f32_16x16x32_bf16 v[28:31], v[128:131], v[200:203], v[28:31]
	v_mfma_f32_16x16x32_bf16 v[24:27], v[136:139], v[200:203], v[24:27]
	v_mfma_f32_16x16x32_bf16 v[12:15], v[128:131], v[208:211], v[12:15]
	v_mfma_f32_16x16x32_bf16 v[8:11], v[136:139], v[208:211], v[8:11]
	v_mfma_f32_16x16x32_bf16 v[60:63], v[132:135], v[180:183], v[60:63]
	v_mfma_f32_16x16x32_bf16 v[56:59], v[140:143], v[180:183], v[56:59]
	v_mfma_f32_16x16x32_bf16 v[44:47], v[132:135], v[196:199], v[44:47]
	v_mfma_f32_16x16x32_bf16 v[40:43], v[140:143], v[196:199], v[40:43]
	v_mfma_f32_16x16x32_bf16 v[28:31], v[132:135], v[204:207], v[28:31]
	v_mfma_f32_16x16x32_bf16 v[24:27], v[140:143], v[204:207], v[24:27]
	v_mfma_f32_16x16x32_bf16 v[12:15], v[132:135], v[212:215], v[12:15]
	v_mfma_f32_16x16x32_bf16 v[8:11], v[140:143], v[212:215], v[8:11]
	v_mfma_f32_16x16x32_bf16 v[52:55], v[144:147], v[176:179], v[52:55]
	v_mfma_f32_16x16x32_bf16 v[48:51], v[168:171], v[176:179], v[48:51]
	v_mfma_f32_16x16x32_bf16 v[36:39], v[144:147], v[192:195], v[36:39]
	v_mfma_f32_16x16x32_bf16 v[32:35], v[168:171], v[192:195], v[32:35]
	v_mfma_f32_16x16x32_bf16 v[20:23], v[144:147], v[200:203], v[20:23]
	v_mfma_f32_16x16x32_bf16 v[16:19], v[168:171], v[200:203], v[16:19]
	v_mfma_f32_16x16x32_bf16 v[4:7], v[144:147], v[208:211], v[4:7]
	v_mfma_f32_16x16x32_bf16 v[0:3], v[168:171], v[208:211], v[0:3]
	v_mfma_f32_16x16x32_bf16 v[52:55], v[148:151], v[180:183], v[52:55]
	v_mfma_f32_16x16x32_bf16 v[48:51], v[172:175], v[180:183], v[48:51]
	v_mfma_f32_16x16x32_bf16 v[36:39], v[148:151], v[196:199], v[36:39]
	v_mfma_f32_16x16x32_bf16 v[32:35], v[172:175], v[196:199], v[32:35]
	v_mfma_f32_16x16x32_bf16 v[20:23], v[148:151], v[204:207], v[20:23]
	v_mfma_f32_16x16x32_bf16 v[16:19], v[172:175], v[204:207], v[16:19]
	v_mfma_f32_16x16x32_bf16 v[4:7], v[148:151], v[212:215], v[4:7]
	v_mfma_f32_16x16x32_bf16 v[0:3], v[172:175], v[212:215], v[0:3]
	s_barrier
	s_add_i32 s60, s60, 2
	s_add_u32 s43, s43, 0x100
	s_addc_u32 s59, s59, 0
	s_cmp_gt_u32 s60, 41
	s_mov_b64 s[28:29], s[30:31]
	s_cbranch_scc0 .LBB0_716
	s_and_b64 vcc, exec, s[16:17]
	s_cbranch_vccz .LBB0_719
	s_barrier

; #define PG8_STAGE(bufoff, gbase, voff) do { _Pragma("unroll") for (int _i = 0; _i < 2; ++_i) \
;         __builtin_amdgcn_global_load_lds((const unsigned*)((const char*)(gbase) + (voff)[_i]), (PG8_LAS unsigned*)(lds + (bufoff) + ldsw + _i * 8192), 16, 0, 0); } while (0)
; #define PG8_LDA(dst, b, h) do { _Pragma("unroll") for (int m = 0; m < 4; ++m) _Pragma("unroll") for (int k = 0; k < 2; ++k) dst[m][k] = *(const PG8_LAS bf16x8*)(lds + PG8_SA(b, h) + aoff + m * 2048 + k * 1024); } while (0)
; #define PG8_LDB(dst, b, h) do { _Pragma("unroll") for (int n = 0; n < 2; ++n) _Pragma("unroll") for (int k = 0; k < 2; ++k) dst[n][k] = *(const PG8_LAS bf16x8*)(lds + PG8_SB(b, h) + boff + n * 2048 + k * 1024); } while (0)
; #define PG8_MMA(ai, bj, At, Bt) do { __builtin_amdgcn_s_setprio(1); _Pragma("unroll") for (int m = 0; m < 4; ++m) _Pragma("unroll") for (int n = 0; n < 2; ++n) _Pragma("unroll") for (int k = 0; k < 2; ++k) \
;         acc[ai][bj][m][n] = mma16<F16>(Bt[n][k], At[m][k], acc[ai][bj][m][n]); __builtin_amdgcn_s_setprio(0); } while (0)
; #define PG8_WAIT_V(n) asm volatile("s_waitcnt vmcnt(" #n ")" ::: "memory")
; #define PG8_WAIT_L(n) asm volatile("s_waitcnt lgkmcnt(" #n ")" ::: "memory")
; template <class Epi, class Sched, bool ALIGN_EPI = false, bool SP2 = false, bool F16 = false>
; __device__ __forceinline__ void gemm_phase(PG8_LAS unsigned char* lds, const Gemm g, const Sched& S, const Epi& E, const int wid_in) {
;     ...
;             const bool last = (t == nt - 2);
;             const char* a1 = cA + (size_t)(t + 1) * kstep;
;             const char* a2 = last ? nA : cA + (size_t)(t + 2) * kstep; const char* b2 = last ? nB : cB + (size_t)(t + 2) * kstep;
;             const char* a3 = a2 + kstep; const char* b3 = b2 + kstep;
;             if (last && has_next) S.a_ready(nxt);
;             if constexpr (SP2) {
;             PG8_LDB(B0, 0, 0); PG8_LDB(B1, 0, 1); PG8_SCHED; PG8_LDA(At, 0, 0); PG8_STAGE(PG8_SA(1, 1), a1 + hstep, voffA);
;             PG8_WAIT_V(8); PG8_WAIT_L(0); PG8_BAR; PG8_MMA(0, 0, At, B0); PG8_MMA(0, 1, At, B1); PG8_BAR; PG8_SCHED;
;             PG8_LDA(At, 0, 1); PG8_STAGE(PG8_SB(0, 0), b2, voffB); PG8_STAGE(PG8_SB(0, 1), b2 + hstep, voffB); PG8_STAGE(PG8_SA(0, 0), a2, voffA);
;             PG8_WAIT_V(8); PG8_WAIT_L(0); PG8_BAR; PG8_MMA(1, 0, At, B0); PG8_MMA(1, 1, At, B1); PG8_BAR; PG8_SCHED;
.LBB0_812:
	ds_read_b128 v[112:115], v235
	ds_read_b128 v[116:119], v235 offset:1024
	ds_read_b128 v[128:131], v235 offset:2048
	ds_read_b128 v[132:135], v235 offset:3072
	ds_read_b128 v[144:147], v236
	ds_read_b128 v[148:151], v236 offset:1024
	ds_read_b128 v[152:155], v236 offset:2048
	ds_read_b128 v[156:159], v236 offset:3072
	s_add_u32 s43, s46, 0xfffc0080
	s_addc_u32 s45, s47, -1
	s_cmp_eq_u32 s42, 12
	s_cselect_b32 s51, s14, s45
	s_cselect_b32 s50, s15, s43
	s_cselect_b32 s49, s29, s41
	s_cselect_b32 s48, s31, s40
	v_lshl_add_u64 v[192:193], s[46:47], 0, v[204:205]
	s_add_i32 m0, s74, 0xc000
	ds_read_b128 v[160:163], v237
	ds_read_b128 v[164:167], v237 offset:1024
	ds_read_b128 v[168:171], v237 offset:2048
	ds_read_b128 v[172:175], v237 offset:3072
	ds_read_b128 v[176:179], v237 offset:4096
	ds_read_b128 v[180:183], v237 offset:5120
	ds_read_b128 v[184:187], v237 offset:6144
	ds_read_b128 v[188:191], v237 offset:7168
	global_load_lds_dwordx4 v[192:193], off
	v_lshl_add_u64 v[192:193], s[46:47], 0, v[206:207]
	s_add_i32 m0, s74, 0xe000
	s_nop 0
	global_load_lds_dwordx4 v[192:193], off
	s_waitcnt vmcnt(8)
	s_waitcnt lgkmcnt(0)
	s_barrier
	s_waitcnt lgkmcnt(0)
	v_mfma_f32_16x16x32_f16 v[140:143], v[112:115], v[160:163], v[140:143]
	v_mfma_f32_16x16x32_f16 v[136:139], v[128:131], v[160:163], v[136:139]
	v_mfma_f32_16x16x32_f16 v[108:111], v[112:115], v[168:171], v[108:111]
	v_mfma_f32_16x16x32_f16 v[104:107], v[128:131], v[168:171], v[104:107]
	v_mfma_f32_16x16x32_f16 v[92:95], v[112:115], v[176:179], v[92:95]
	v_mfma_f32_16x16x32_f16 v[88:91], v[128:131], v[176:179], v[88:91]
	v_mfma_f32_16x16x32_f16 v[76:79], v[112:115], v[184:187], v[76:79]
	v_mfma_f32_16x16x32_f16 v[72:75], v[128:131], v[184:187], v[72:75]
	v_mfma_f32_16x16x32_f16 v[140:143], v[116:119], v[164:167], v[140:143]
	v_mfma_f32_16x16x32_f16 v[136:139], v[132:135], v[164:167], v[136:139]
	v_mfma_f32_16x16x32_f16 v[108:111], v[116:119], v[172:175], v[108:111]
	v_mfma_f32_16x16x32_f16 v[104:107], v[132:135], v[172:175], v[104:107]
	v_mfma_f32_16x16x32_f16 v[92:95], v[116:119], v[180:183], v[92:95]
	v_mfma_f32_16x16x32_f16 v[88:91], v[132:135], v[180:183], v[88:91]
	v_mfma_f32_16x16x32_f16 v[76:79], v[116:119], v[188:191], v[76:79]
	v_mfma_f32_16x16x32_f16 v[72:75], v[132:135], v[188:191], v[72:75]
	v_mfma_f32_16x16x32_f16 v[124:127], v[144:147], v[160:163], v[124:127]
	v_mfma_f32_16x16x32_f16 v[120:123], v[152:155], v[160:163], v[120:123]
	v_mfma_f32_16x16x32_f16 v[100:103], v[144:147], v[168:171], v[100:103]
	v_mfma_f32_16x16x32_f16 v[96:99], v[152:155], v[168:171], v[96:99]
	v_mfma_f32_16x16x32_f16 v[84:87], v[144:147], v[176:179], v[84:87]
	v_mfma_f32_16x16x32_f16 v[80:83], v[152:155], v[176:179], v[80:83]
	v_mfma_f32_16x16x32_f16 v[68:71], v[144:147], v[184:187], v[68:71]
	v_mfma_f32_16x16x32_f16 v[64:67], v[152:155], v[184:187], v[64:67]
	v_mfma_f32_16x16x32_f16 v[124:127], v[148:151], v[164:167], v[124:127]
	v_mfma_f32_16x16x32_f16 v[120:123], v[156:159], v[164:167], v[120:123]
	v_mfma_f32_16x16x32_f16 v[100:103], v[148:151], v[172:175], v[100:103]
	v_mfma_f32_16x16x32_f16 v[96:99], v[156:159], v[172:175], v[96:99]
	v_mfma_f32_16x16x32_f16 v[84:87], v[148:151], v[180:183], v[84:87]
	v_mfma_f32_16x16x32_f16 v[80:83], v[156:159], v[180:183], v[80:83]
	v_mfma_f32_16x16x32_f16 v[68:71], v[148:151], v[188:191], v[68:71]
	v_mfma_f32_16x16x32_f16 v[64:67], v[156:159], v[188:191], v[64:67]
	s_barrier
	s_add_i32 s43, s64, s68
	v_lshl_add_u64 v[192:193], s[48:49], 0, v[198:199]
	s_mov_b32 m0, s43
	ds_read_b128 v[160:163], v237 offset:16384
	ds_read_b128 v[164:167], v237 offset:17408
	ds_read_b128 v[168:171], v237 offset:18432
	ds_read_b128 v[172:175], v237 offset:19456
	ds_read_b128 v[176:179], v237 offset:20480
	ds_read_b128 v[180:183], v237 offset:21504
	ds_read_b128 v[184:187], v237 offset:22528
	ds_read_b128 v[188:191], v237 offset:23552
	global_load_lds_dwordx4 v[192:193], off
	s_add_i32 m0, s43, 0x2000
	s_add_u32 s86, s48, 0x40000
	v_lshl_add_u64 v[194:195], s[48:49], 0, v[202:203]
	s_addc_u32 s87, s49, 0
	s_add_i32 s43, s65, s68
	global_load_lds_dwordx4 v[194:195], off
	v_lshl_add_u64 v[212:213], s[86:87], 0, v[198:199]
	s_mov_b32 m0, s43
	v_lshl_add_u64 v[214:215], s[50:51], 0, v[200:201]
	global_load_lds_dwordx4 v[212:213], off
	v_lshl_add_u64 v[212:213], s[86:87], 0, v[202:203]
	s_add_i32 m0, s43, 0x2000
	s_nop 0
	global_load_lds_dwordx4 v[212:213], off
	v_lshl_add_u64 v[212:213], s[50:51], 0, v[196:197]
	s_mov_b32 m0, s74
	s_nop 0
	global_load_lds_dwordx4 v[212:213], off
	s_mov_b32 m0, s55
	s_nop 0
	global_load_lds_dwordx4 v[214:215], off
	s_waitcnt vmcnt(8)
	s_waitcnt lgkmcnt(0)
	s_barrier
; #define PG8_STAGE(bufoff, gbase, voff) do { _Pragma("unroll") for (int _i = 0; _i < 2; ++_i) \
;         __builtin_amdgcn_global_load_lds((const unsigned*)((const char*)(gbase) + (voff)[_i]), (PG8_LAS unsigned*)(lds + (bufoff) + ldsw + _i * 8192), 16, 0, 0); } while (0)
; #define PG8_LDA(dst, b, h) do { _Pragma("unroll") for (int m = 0; m < 4; ++m) _Pragma("unroll") for (int k = 0; k < 2; ++k) dst[m][k] = *(const PG8_LAS bf16x8*)(lds + PG8_SA(b, h) + aoff + m * 2048 + k * 1024); } while (0)
; #define PG8_LDB(dst, b, h) do { _Pragma("unroll") for (int n = 0; n < 2; ++n) _Pragma("unroll") for (int k = 0; k < 2; ++k) dst[n][k] = *(const PG8_LAS bf16x8*)(lds + PG8_SB(b, h) + boff + n * 2048 + k * 1024); } while (0)
; #define PG8_MMA(ai, bj, At, Bt) do { __builtin_amdgcn_s_setprio(1); _Pragma("unroll") for (int m = 0; m < 4; ++m) _Pragma("unroll") for (int n = 0; n < 2; ++n) _Pragma("unroll") for (int k = 0; k < 2; ++k) \
;         acc[ai][bj][m][n] = mma16<F16>(Bt[n][k], At[m][k], acc[ai][bj][m][n]); __builtin_amdgcn_s_setprio(0); } while (0)
; #define PG8_WAIT_V(n) asm volatile("s_waitcnt vmcnt(" #n ")" ::: "memory")
; #define PG8_WAIT_L(n) asm volatile("s_waitcnt lgkmcnt(" #n ")" ::: "memory")
; #define PG8_BAR __builtin_amdgcn_s_barrier()
; #define PG8_SCHED __builtin_amdgcn_sched_barrier(0)
; template <class Epi, class Sched, bool ALIGN_EPI = false, bool SP2 = false, bool F16 = false>
; __device__ __forceinline__ void gemm_phase(PG8_LAS unsigned char* lds, const Gemm g, const Sched& S, const Epi& E, const int wid_in) {
;     ...
;             PG8_WAIT_V(8); PG8_WAIT_L(0); PG8_BAR; PG8_MMA(1, 0, At, B0); PG8_MMA(1, 1, At, B1); PG8_BAR; PG8_SCHED;
;             PG8_LDB(B0, 1, 0); PG8_LDB(B1, 1, 1); PG8_SCHED; PG8_LDA(At, 1, 0); PG8_STAGE(PG8_SA(0, 1), a2 + hstep, voffA);
;             PG8_WAIT_V(8); PG8_WAIT_L(0); PG8_BAR; PG8_MMA(0, 0, At, B0); PG8_MMA(0, 1, At, B1); PG8_BAR; PG8_SCHED;
	s_waitcnt lgkmcnt(0)
	v_mfma_f32_16x16x32_f16 v[60:63], v[112:115], v[160:163], v[60:63]
	v_mfma_f32_16x16x32_f16 v[56:59], v[128:131], v[160:163], v[56:59]
	v_mfma_f32_16x16x32_f16 v[44:47], v[112:115], v[168:171], v[44:47]
	v_mfma_f32_16x16x32_f16 v[40:43], v[128:131], v[168:171], v[40:43]
	v_mfma_f32_16x16x32_f16 v[28:31], v[112:115], v[176:179], v[28:31]
	v_mfma_f32_16x16x32_f16 v[24:27], v[128:131], v[176:179], v[24:27]
	v_mfma_f32_16x16x32_f16 v[12:15], v[112:115], v[184:187], v[12:15]
	v_mfma_f32_16x16x32_f16 v[8:11], v[128:131], v[184:187], v[8:11]
	v_mfma_f32_16x16x32_f16 v[60:63], v[116:119], v[164:167], v[60:63]
	v_mfma_f32_16x16x32_f16 v[56:59], v[132:135], v[164:167], v[56:59]
	v_mfma_f32_16x16x32_f16 v[44:47], v[116:119], v[172:175], v[44:47]
	v_mfma_f32_16x16x32_f16 v[40:43], v[132:135], v[172:175], v[40:43]
	v_mfma_f32_16x16x32_f16 v[28:31], v[116:119], v[180:183], v[28:31]
	v_mfma_f32_16x16x32_f16 v[24:27], v[132:135], v[180:183], v[24:27]
	v_mfma_f32_16x16x32_f16 v[12:15], v[116:119], v[188:191], v[12:15]
	v_mfma_f32_16x16x32_f16 v[8:11], v[132:135], v[188:191], v[8:11]
	v_mfma_f32_16x16x32_f16 v[52:55], v[144:147], v[160:163], v[52:55]
	v_mfma_f32_16x16x32_f16 v[48:51], v[152:155], v[160:163], v[48:51]
	v_mfma_f32_16x16x32_f16 v[36:39], v[144:147], v[168:171], v[36:39]
	v_mfma_f32_16x16x32_f16 v[32:35], v[152:155], v[168:171], v[32:35]
	v_mfma_f32_16x16x32_f16 v[20:23], v[144:147], v[176:179], v[20:23]
	v_mfma_f32_16x16x32_f16 v[16:19], v[152:155], v[176:179], v[16:19]
	v_mfma_f32_16x16x32_f16 v[4:7], v[144:147], v[184:187], v[4:7]
	v_mfma_f32_16x16x32_f16 v[0:3], v[152:155], v[184:187], v[0:3]
	v_mfma_f32_16x16x32_f16 v[52:55], v[148:151], v[164:167], v[52:55]
	v_mfma_f32_16x16x32_f16 v[48:51], v[156:159], v[164:167], v[48:51]
	v_mfma_f32_16x16x32_f16 v[36:39], v[148:151], v[172:175], v[36:39]
	v_mfma_f32_16x16x32_f16 v[32:35], v[156:159], v[172:175], v[32:35]
	v_mfma_f32_16x16x32_f16 v[20:23], v[148:151], v[180:183], v[20:23]
	v_mfma_f32_16x16x32_f16 v[16:19], v[156:159], v[180:183], v[16:19]
	v_mfma_f32_16x16x32_f16 v[4:7], v[148:151], v[188:191], v[4:7]
	v_mfma_f32_16x16x32_f16 v[0:3], v[156:159], v[188:191], v[0:3]
	s_barrier
	s_add_i32 s43, 0, 0x18000
	s_add_i32 s45, 0, 0x1c000
	v_add_u32_e32 v132, s43, v234
	v_add_u32_e32 v156, s45, v234
	ds_read_b128 v[112:115], v132
	ds_read_b128 v[116:119], v132 offset:1024
	ds_read_b128 v[128:131], v132 offset:2048
	ds_read_b128 v[132:135], v132 offset:3072
	ds_read_b128 v[144:147], v156
	ds_read_b128 v[148:151], v156 offset:1024
	ds_read_b128 v[152:155], v156 offset:2048
	ds_read_b128 v[156:159], v156 offset:3072
	s_add_u32 s50, s50, 0x40000
	s_addc_u32 s51, s51, 0
	s_mov_b32 m0, s58
	v_lshl_add_u64 v[216:217], s[50:51], 0, v[196:197]
	ds_read_b128 v[160:163], v237 offset:32768
	ds_read_b128 v[164:167], v237 offset:33792
	ds_read_b128 v[168:171], v237 offset:34816
	ds_read_b128 v[172:175], v237 offset:35840
	ds_read_b128 v[176:179], v237 offset:36864
	ds_read_b128 v[180:183], v237 offset:37888
	ds_read_b128 v[184:187], v237 offset:38912
	ds_read_b128 v[188:191], v237 offset:39936
	global_load_lds_dwordx4 v[216:217], off
	v_lshl_add_u64 v[216:217], s[50:51], 0, v[200:201]
	s_mov_b32 m0, s59
	s_nop 0
	global_load_lds_dwordx4 v[216:217], off
	s_waitcnt vmcnt(8)
	s_waitcnt lgkmcnt(0)
	s_barrier
	s_waitcnt lgkmcnt(0)
	v_mfma_f32_16x16x32_f16 v[140:143], v[112:115], v[160:163], v[140:143]
	v_mfma_f32_16x16x32_f16 v[136:139], v[128:131], v[160:163], v[136:139]
	v_mfma_f32_16x16x32_f16 v[108:111], v[112:115], v[168:171], v[108:111]
	v_mfma_f32_16x16x32_f16 v[104:107], v[128:131], v[168:171], v[104:107]
	v_mfma_f32_16x16x32_f16 v[92:95], v[112:115], v[176:179], v[92:95]
	v_mfma_f32_16x16x32_f16 v[88:91], v[128:131], v[176:179], v[88:91]
	v_mfma_f32_16x16x32_f16 v[76:79], v[112:115], v[184:187], v[76:79]
	v_mfma_f32_16x16x32_f16 v[72:75], v[128:131], v[184:187], v[72:75]
	v_mfma_f32_16x16x32_f16 v[140:143], v[116:119], v[164:167], v[140:143]
	v_mfma_f32_16x16x32_f16 v[136:139], v[132:135], v[164:167], v[136:139]
	v_mfma_f32_16x16x32_f16 v[108:111], v[116:119], v[172:175], v[108:111]
	v_mfma_f32_16x16x32_f16 v[104:107], v[132:135], v[172:175], v[104:107]
	v_mfma_f32_16x16x32_f16 v[92:95], v[116:119], v[180:183], v[92:95]
	v_mfma_f32_16x16x32_f16 v[88:91], v[132:135], v[180:183], v[88:91]
	v_mfma_f32_16x16x32_f16 v[76:79], v[116:119], v[188:191], v[76:79]
	v_mfma_f32_16x16x32_f16 v[72:75], v[132:135], v[188:191], v[72:75]
	v_mfma_f32_16x16x32_f16 v[124:127], v[144:147], v[160:163], v[124:127]
	v_mfma_f32_16x16x32_f16 v[120:123], v[152:155], v[160:163], v[120:123]
	v_mfma_f32_16x16x32_f16 v[100:103], v[144:147], v[168:171], v[100:103]
	v_mfma_f32_16x16x32_f16 v[96:99], v[152:155], v[168:171], v[96:99]
	v_mfma_f32_16x16x32_f16 v[84:87], v[144:147], v[176:179], v[84:87]
	v_mfma_f32_16x16x32_f16 v[80:83], v[152:155], v[176:179], v[80:83]
	v_mfma_f32_16x16x32_f16 v[68:71], v[144:147], v[184:187], v[68:71]
	v_mfma_f32_16x16x32_f16 v[64:67], v[152:155], v[184:187], v[64:67]
	v_mfma_f32_16x16x32_f16 v[124:127], v[148:151], v[164:167], v[124:127]
	v_mfma_f32_16x16x32_f16 v[120:123], v[156:159], v[164:167], v[120:123]
	v_mfma_f32_16x16x32_f16 v[100:103], v[148:151], v[172:175], v[100:103]
	v_mfma_f32_16x16x32_f16 v[96:99], v[156:159], v[172:175], v[96:99]
	v_mfma_f32_16x16x32_f16 v[84:87], v[148:151], v[180:183], v[84:87]
	v_mfma_f32_16x16x32_f16 v[80:83], v[156:159], v[180:183], v[80:83]
	v_mfma_f32_16x16x32_f16 v[68:71], v[148:151], v[188:191], v[68:71]
	v_mfma_f32_16x16x32_f16 v[64:67], v[156:159], v[188:191], v[64:67]
	s_barrier
; #define PG8_STAGE(bufoff, gbase, voff) do { _Pragma("unroll") for (int _i = 0; _i < 2; ++_i) \
;         __builtin_amdgcn_global_load_lds((const unsigned*)((const char*)(gbase) + (voff)[_i]), (PG8_LAS unsigned*)(lds + (bufoff) + ldsw + _i * 8192), 16, 0, 0); } while (0)
; #define PG8_LDA(dst, b, h) do { _Pragma("unroll") for (int m = 0; m < 4; ++m) _Pragma("unroll") for (int k = 0; k < 2; ++k) dst[m][k] = *(const PG8_LAS bf16x8*)(lds + PG8_SA(b, h) + aoff + m * 2048 + k * 1024); } while (0)
; #define PG8_MMA(ai, bj, At, Bt) do { __builtin_amdgcn_s_setprio(1); _Pragma("unroll") for (int m = 0; m < 4; ++m) _Pragma("unroll") for (int n = 0; n < 2; ++n) _Pragma("unroll") for (int k = 0; k < 2; ++k) \
;         acc[ai][bj][m][n] = mma16<F16>(Bt[n][k], At[m][k], acc[ai][bj][m][n]); __builtin_amdgcn_s_setprio(0); } while (0)
; #define PG8_WAIT_V(n) asm volatile("s_waitcnt vmcnt(" #n ")" ::: "memory")
; #define PG8_WAIT_L(n) asm volatile("s_waitcnt lgkmcnt(" #n ")" ::: "memory")
; #define PG8_BAR __builtin_amdgcn_s_barrier()
; #define PG8_SCHED __builtin_amdgcn_sched_barrier(0)
; template <class Epi, class Sched, bool ALIGN_EPI = false, bool SP2 = false, bool F16 = false>
; __device__ __forceinline__ void gemm_phase(PG8_LAS unsigned char* lds, const Gemm g, const Sched& S, const Epi& E, const int wid_in) {
;     ...
;             PG8_LDA(At, 1, 1); PG8_STAGE(PG8_SB(1, 0), b3, voffB); PG8_STAGE(PG8_SB(1, 1), b3 + hstep, voffB); PG8_STAGE(PG8_SA(1, 0), a3, voffA);
;             PG8_WAIT_V(8); PG8_WAIT_L(0); PG8_BAR; PG8_MMA(1, 0, At, B0); PG8_MMA(1, 1, At, B1); PG8_BAR; PG8_SCHED;
;     ...
;         if constexpr (ALIGN_EPI) { if (wr == 0) PG8_BAR; }
	s_add_i32 s43, s43, s68
	v_lshl_add_u64 v[192:193], v[192:193], 0, s[26:27]
	s_mov_b32 m0, s43
	ds_read_b128 v[160:163], v237 offset:49152
	ds_read_b128 v[164:167], v237 offset:50176
	ds_read_b128 v[168:171], v237 offset:51200
	ds_read_b128 v[172:175], v237 offset:52224
	ds_read_b128 v[176:179], v237 offset:53248
	ds_read_b128 v[180:183], v237 offset:54272
	ds_read_b128 v[184:187], v237 offset:55296
	ds_read_b128 v[188:191], v237 offset:56320
	global_load_lds_dwordx4 v[192:193], off
	s_add_i32 m0, s43, 0x2000
	s_add_u32 s48, s48, 0x40080
	v_lshl_add_u64 v[192:193], v[194:195], 0, s[26:27]
	s_addc_u32 s49, s49, 0
	s_add_i32 s43, s45, s68
	global_load_lds_dwordx4 v[192:193], off
	v_lshl_add_u64 v[192:193], s[48:49], 0, v[198:199]
	s_mov_b32 m0, s43
	s_nop 0
	global_load_lds_dwordx4 v[192:193], off
	v_lshl_add_u64 v[192:193], s[48:49], 0, v[202:203]
	s_add_i32 m0, s43, 0x2000
	s_nop 0
	global_load_lds_dwordx4 v[192:193], off
	v_lshl_add_u64 v[192:193], v[212:213], 0, s[26:27]
	s_mov_b32 m0, s75
	s_nop 0
	global_load_lds_dwordx4 v[192:193], off
	v_lshl_add_u64 v[192:193], v[214:215], 0, s[26:27]
	s_mov_b32 m0, s60
	s_nop 0
	global_load_lds_dwordx4 v[192:193], off
	s_waitcnt vmcnt(8)
	s_waitcnt lgkmcnt(0)
	s_barrier
	s_waitcnt lgkmcnt(0)
	v_mfma_f32_16x16x32_f16 v[60:63], v[112:115], v[160:163], v[60:63]
	v_mfma_f32_16x16x32_f16 v[56:59], v[128:131], v[160:163], v[56:59]
	v_mfma_f32_16x16x32_f16 v[44:47], v[112:115], v[168:171], v[44:47]
	v_mfma_f32_16x16x32_f16 v[40:43], v[128:131], v[168:171], v[40:43]
	v_mfma_f32_16x16x32_f16 v[28:31], v[112:115], v[176:179], v[28:31]
	v_mfma_f32_16x16x32_f16 v[24:27], v[128:131], v[176:179], v[24:27]
	v_mfma_f32_16x16x32_f16 v[12:15], v[112:115], v[184:187], v[12:15]
	v_mfma_f32_16x16x32_f16 v[8:11], v[128:131], v[184:187], v[8:11]
	v_mfma_f32_16x16x32_f16 v[60:63], v[116:119], v[164:167], v[60:63]
	v_mfma_f32_16x16x32_f16 v[56:59], v[132:135], v[164:167], v[56:59]
	v_mfma_f32_16x16x32_f16 v[44:47], v[116:119], v[172:175], v[44:47]
	v_mfma_f32_16x16x32_f16 v[40:43], v[132:135], v[172:175], v[40:43]
	v_mfma_f32_16x16x32_f16 v[28:31], v[116:119], v[180:183], v[28:31]
	v_mfma_f32_16x16x32_f16 v[24:27], v[132:135], v[180:183], v[24:27]
	v_mfma_f32_16x16x32_f16 v[12:15], v[116:119], v[188:191], v[12:15]
	v_mfma_f32_16x16x32_f16 v[8:11], v[132:135], v[188:191], v[8:11]
	v_mfma_f32_16x16x32_f16 v[52:55], v[144:147], v[160:163], v[52:55]
	v_mfma_f32_16x16x32_f16 v[48:51], v[152:155], v[160:163], v[48:51]
	v_mfma_f32_16x16x32_f16 v[36:39], v[144:147], v[168:171], v[36:39]
	v_mfma_f32_16x16x32_f16 v[32:35], v[152:155], v[168:171], v[32:35]
	v_mfma_f32_16x16x32_f16 v[20:23], v[144:147], v[176:179], v[20:23]
	v_mfma_f32_16x16x32_f16 v[16:19], v[152:155], v[176:179], v[16:19]
	v_mfma_f32_16x16x32_f16 v[4:7], v[144:147], v[184:187], v[4:7]
	v_mfma_f32_16x16x32_f16 v[0:3], v[152:155], v[184:187], v[0:3]
	v_mfma_f32_16x16x32_f16 v[52:55], v[148:151], v[164:167], v[52:55]
	v_mfma_f32_16x16x32_f16 v[48:51], v[156:159], v[164:167], v[48:51]
	v_mfma_f32_16x16x32_f16 v[36:39], v[148:151], v[172:175], v[36:39]
	v_mfma_f32_16x16x32_f16 v[32:35], v[156:159], v[172:175], v[32:35]
	v_mfma_f32_16x16x32_f16 v[20:23], v[148:151], v[180:183], v[20:23]
	v_mfma_f32_16x16x32_f16 v[16:19], v[156:159], v[180:183], v[16:19]
	v_mfma_f32_16x16x32_f16 v[4:7], v[148:151], v[188:191], v[4:7]
	v_mfma_f32_16x16x32_f16 v[0:3], v[156:159], v[188:191], v[0:3]
	s_barrier
	s_add_i32 s42, s42, 2
	s_add_u32 s46, s46, 0x100
	s_addc_u32 s47, s47, 0
	s_add_u32 s40, s40, 0x100
	s_addc_u32 s41, s41, 0
	s_cmp_gt_u32 s42, 13
	s_cbranch_scc0 .LBB0_812
	s_and_b64 vcc, exec, s[16:17]
	s_cbranch_vccz .LBB0_815
	s_barrier

; #define PG8_STAGE(bufoff, gbase, voff) do { _Pragma("unroll") for (int _i = 0; _i < 2; ++_i) \
;         __builtin_amdgcn_global_load_lds((const unsigned*)((const char*)(gbase) + (voff)[_i]), (PG8_LAS unsigned*)(lds + (bufoff) + ldsw + _i * 8192), 16, 0, 0); } while (0)
; #define PG8_LDA(dst, b, h) do { _Pragma("unroll") for (int m = 0; m < 4; ++m) _Pragma("unroll") for (int k = 0; k < 2; ++k) dst[m][k] = *(const PG8_LAS bf16x8*)(lds + PG8_SA(b, h) + aoff + m * 2048 + k * 1024); } while (0)
; #define PG8_LDB(dst, b, h) do { _Pragma("unroll") for (int n = 0; n < 2; ++n) _Pragma("unroll") for (int k = 0; k < 2; ++k) dst[n][k] = *(const PG8_LAS bf16x8*)(lds + PG8_SB(b, h) + boff + n * 2048 + k * 1024); } while (0)
; #define PG8_MMA(ai, bj, At, Bt) do { __builtin_amdgcn_s_setprio(1); _Pragma("unroll") for (int m = 0; m < 4; ++m) _Pragma("unroll") for (int n = 0; n < 2; ++n) _Pragma("unroll") for (int k = 0; k < 2; ++k) \
;         acc[ai][bj][m][n] = mma16<F16>(Bt[n][k], At[m][k], acc[ai][bj][m][n]); __builtin_amdgcn_s_setprio(0); } while (0)
; #define PG8_WAIT_V(n) asm volatile("s_waitcnt vmcnt(" #n ")" ::: "memory")
; #define PG8_WAIT_L(n) asm volatile("s_waitcnt lgkmcnt(" #n ")" ::: "memory")
; template <class Epi, class Sched, bool ALIGN_EPI = false, bool SP2 = false, bool F16 = false>
; __device__ __forceinline__ void gemm_phase(PG8_LAS unsigned char* lds, const Gemm g, const Sched& S, const Epi& E, const int wid_in) {
;     ...
;             const bool last = (t == nt - 2);
;             const char* a1 = cA + (size_t)(t + 1) * kstep;
;             const char* a2 = last ? nA : cA + (size_t)(t + 2) * kstep; const char* b2 = last ? nB : cB + (size_t)(t + 2) * kstep;
;             const char* a3 = a2 + kstep; const char* b3 = b2 + kstep;
;             if (last && has_next) S.a_ready(nxt);
;             if constexpr (SP2) {
;             PG8_LDB(B0, 0, 0); PG8_LDB(B1, 0, 1); PG8_SCHED; PG8_LDA(At, 0, 0); PG8_STAGE(PG8_SA(1, 1), a1 + hstep, voffA);
;             PG8_WAIT_V(8); PG8_WAIT_L(0); PG8_BAR; PG8_MMA(0, 0, At, B0); PG8_MMA(0, 1, At, B1); PG8_BAR; PG8_SCHED;
;             PG8_LDA(At, 0, 1); PG8_STAGE(PG8_SB(0, 0), b2, voffB); PG8_STAGE(PG8_SB(0, 1), b2 + hstep, voffB); PG8_STAGE(PG8_SA(0, 0), a2, voffA);
;             PG8_WAIT_V(8); PG8_WAIT_L(0); PG8_BAR; PG8_MMA(1, 0, At, B0); PG8_MMA(1, 1, At, B1); PG8_BAR; PG8_SCHED;
.LBB0_902:
	ds_read_b128 v[128:131], v183
	ds_read_b128 v[132:135], v183 offset:1024
	ds_read_b128 v[136:139], v183 offset:2048
	ds_read_b128 v[140:143], v183 offset:3072
	ds_read_b128 v[144:147], v184
	ds_read_b128 v[148:151], v184 offset:1024
	ds_read_b128 v[152:155], v184 offset:2048
	ds_read_b128 v[174:177], v184 offset:3072
	s_add_u32 s48, s46, 0xfffc0080
	s_addc_u32 s49, s47, -1
	s_cmp_eq_u32 s52, 12
	s_cselect_b32 s51, s11, s49
	s_cselect_b32 s50, s13, s48
	s_cselect_b32 s49, s31, s43
	s_cselect_b32 s48, s35, s42
	v_lshl_add_u64 v[178:179], s[46:47], 0, v[166:167]
	s_add_i32 m0, s74, 0xc000
	ds_read_b128 v[188:191], v185
	ds_read_b128 v[192:195], v185 offset:1024
	ds_read_b128 v[196:199], v185 offset:2048
	ds_read_b128 v[200:203], v185 offset:3072
	ds_read_b128 v[204:207], v185 offset:4096
	ds_read_b128 v[208:211], v185 offset:5120
	ds_read_b128 v[212:215], v185 offset:6144
	ds_read_b128 v[216:219], v185 offset:7168
	global_load_lds_dwordx4 v[178:179], off
	v_lshl_add_u64 v[178:179], s[46:47], 0, v[168:169]
	s_add_i32 m0, s74, 0xe000
	s_nop 0
	global_load_lds_dwordx4 v[178:179], off
	s_waitcnt vmcnt(8)
	s_waitcnt lgkmcnt(0)
	s_barrier
	s_waitcnt lgkmcnt(0)
	v_mfma_f32_16x16x32_f16 v[124:127], v[128:131], v[188:191], v[124:127]
	v_mfma_f32_16x16x32_f16 v[120:123], v[136:139], v[188:191], v[120:123]
	v_mfma_f32_16x16x32_f16 v[108:111], v[128:131], v[196:199], v[108:111]
	v_mfma_f32_16x16x32_f16 v[104:107], v[136:139], v[196:199], v[104:107]
	v_mfma_f32_16x16x32_f16 v[92:95], v[128:131], v[204:207], v[92:95]
	v_mfma_f32_16x16x32_f16 v[88:91], v[136:139], v[204:207], v[88:91]
	v_mfma_f32_16x16x32_f16 v[76:79], v[128:131], v[212:215], v[76:79]
	v_mfma_f32_16x16x32_f16 v[72:75], v[136:139], v[212:215], v[72:75]
	v_mfma_f32_16x16x32_f16 v[124:127], v[132:135], v[192:195], v[124:127]
	v_mfma_f32_16x16x32_f16 v[120:123], v[140:143], v[192:195], v[120:123]
	v_mfma_f32_16x16x32_f16 v[108:111], v[132:135], v[200:203], v[108:111]
	v_mfma_f32_16x16x32_f16 v[104:107], v[140:143], v[200:203], v[104:107]
	v_mfma_f32_16x16x32_f16 v[92:95], v[132:135], v[208:211], v[92:95]
	v_mfma_f32_16x16x32_f16 v[88:91], v[140:143], v[208:211], v[88:91]
	v_mfma_f32_16x16x32_f16 v[76:79], v[132:135], v[216:219], v[76:79]
	v_mfma_f32_16x16x32_f16 v[72:75], v[140:143], v[216:219], v[72:75]
	v_mfma_f32_16x16x32_f16 v[116:119], v[144:147], v[188:191], v[116:119]
	v_mfma_f32_16x16x32_f16 v[112:115], v[152:155], v[188:191], v[112:115]
	v_mfma_f32_16x16x32_f16 v[100:103], v[144:147], v[196:199], v[100:103]
	v_mfma_f32_16x16x32_f16 v[96:99], v[152:155], v[196:199], v[96:99]
	v_mfma_f32_16x16x32_f16 v[84:87], v[144:147], v[204:207], v[84:87]
	v_mfma_f32_16x16x32_f16 v[80:83], v[152:155], v[204:207], v[80:83]
	v_mfma_f32_16x16x32_f16 v[68:71], v[144:147], v[212:215], v[68:71]
	v_mfma_f32_16x16x32_f16 v[64:67], v[152:155], v[212:215], v[64:67]
	v_mfma_f32_16x16x32_f16 v[116:119], v[148:151], v[192:195], v[116:119]
	v_mfma_f32_16x16x32_f16 v[112:115], v[174:177], v[192:195], v[112:115]
	v_mfma_f32_16x16x32_f16 v[100:103], v[148:151], v[200:203], v[100:103]
	v_mfma_f32_16x16x32_f16 v[96:99], v[174:177], v[200:203], v[96:99]
	v_mfma_f32_16x16x32_f16 v[84:87], v[148:151], v[208:211], v[84:87]
	v_mfma_f32_16x16x32_f16 v[80:83], v[174:177], v[208:211], v[80:83]
	v_mfma_f32_16x16x32_f16 v[68:71], v[148:151], v[216:219], v[68:71]
	v_mfma_f32_16x16x32_f16 v[64:67], v[174:177], v[216:219], v[64:67]
	s_barrier
	s_add_i32 s53, s40, s68
	v_lshl_add_u64 v[178:179], s[48:49], 0, v[158:159]
	s_mov_b32 m0, s53
	ds_read_b128 v[188:191], v185 offset:16384
	ds_read_b128 v[192:195], v185 offset:17408
	ds_read_b128 v[196:199], v185 offset:18432
	ds_read_b128 v[200:203], v185 offset:19456
	ds_read_b128 v[204:207], v185 offset:20480
	ds_read_b128 v[208:211], v185 offset:21504
	ds_read_b128 v[212:215], v185 offset:22528
	ds_read_b128 v[216:219], v185 offset:23552
	global_load_lds_dwordx4 v[178:179], off
	s_add_i32 m0, s53, 0x2000
	s_add_u32 s54, s48, 0x40000
	v_lshl_add_u64 v[220:221], s[48:49], 0, v[162:163]
	s_addc_u32 s55, s49, 0
	s_add_i32 s53, s41, s68
	global_load_lds_dwordx4 v[220:221], off
	v_lshl_add_u64 v[222:223], s[54:55], 0, v[158:159]
	s_mov_b32 m0, s53
	v_lshl_add_u64 v[224:225], s[50:51], 0, v[160:161]
	global_load_lds_dwordx4 v[222:223], off
	v_lshl_add_u64 v[222:223], s[54:55], 0, v[162:163]
	s_add_i32 m0, s53, 0x2000
	s_nop 0
	global_load_lds_dwordx4 v[222:223], off
	v_lshl_add_u64 v[222:223], s[50:51], 0, v[156:157]
	s_mov_b32 m0, s74
	s_nop 0
	global_load_lds_dwordx4 v[222:223], off
	s_mov_b32 m0, s65
	s_nop 0
	global_load_lds_dwordx4 v[224:225], off
	s_waitcnt vmcnt(8)
	s_waitcnt lgkmcnt(0)
	s_barrier
; #define PG8_STAGE(bufoff, gbase, voff) do { _Pragma("unroll") for (int _i = 0; _i < 2; ++_i) \
;         __builtin_amdgcn_global_load_lds((const unsigned*)((const char*)(gbase) + (voff)[_i]), (PG8_LAS unsigned*)(lds + (bufoff) + ldsw + _i * 8192), 16, 0, 0); } while (0)
; #define PG8_LDA(dst, b, h) do { _Pragma("unroll") for (int m = 0; m < 4; ++m) _Pragma("unroll") for (int k = 0; k < 2; ++k) dst[m][k] = *(const PG8_LAS bf16x8*)(lds + PG8_SA(b, h) + aoff + m * 2048 + k * 1024); } while (0)
; #define PG8_LDB(dst, b, h) do { _Pragma("unroll") for (int n = 0; n < 2; ++n) _Pragma("unroll") for (int k = 0; k < 2; ++k) dst[n][k] = *(const PG8_LAS bf16x8*)(lds + PG8_SB(b, h) + boff + n * 2048 + k * 1024); } while (0)
; #define PG8_MMA(ai, bj, At, Bt) do { __builtin_amdgcn_s_setprio(1); _Pragma("unroll") for (int m = 0; m < 4; ++m) _Pragma("unroll") for (int n = 0; n < 2; ++n) _Pragma("unroll") for (int k = 0; k < 2; ++k) \
;         acc[ai][bj][m][n] = mma16<F16>(Bt[n][k], At[m][k], acc[ai][bj][m][n]); __builtin_amdgcn_s_setprio(0); } while (0)
; #define PG8_WAIT_V(n) asm volatile("s_waitcnt vmcnt(" #n ")" ::: "memory")
; #define PG8_WAIT_L(n) asm volatile("s_waitcnt lgkmcnt(" #n ")" ::: "memory")
; #define PG8_BAR __builtin_amdgcn_s_barrier()
; #define PG8_SCHED __builtin_amdgcn_sched_barrier(0)
; template <class Epi, class Sched, bool ALIGN_EPI = false, bool SP2 = false, bool F16 = false>
; __device__ __forceinline__ void gemm_phase(PG8_LAS unsigned char* lds, const Gemm g, const Sched& S, const Epi& E, const int wid_in) {
;     ...
;             PG8_WAIT_V(8); PG8_WAIT_L(0); PG8_BAR; PG8_MMA(1, 0, At, B0); PG8_MMA(1, 1, At, B1); PG8_BAR; PG8_SCHED;
;             PG8_LDB(B0, 1, 0); PG8_LDB(B1, 1, 1); PG8_SCHED; PG8_LDA(At, 1, 0); PG8_STAGE(PG8_SA(0, 1), a2 + hstep, voffA);
;             PG8_WAIT_V(8); PG8_WAIT_L(0); PG8_BAR; PG8_MMA(0, 0, At, B0); PG8_MMA(0, 1, At, B1); PG8_BAR; PG8_SCHED;
	s_waitcnt lgkmcnt(0)
	v_mfma_f32_16x16x32_f16 v[60:63], v[128:131], v[188:191], v[60:63]
	v_mfma_f32_16x16x32_f16 v[56:59], v[136:139], v[188:191], v[56:59]
	v_mfma_f32_16x16x32_f16 v[44:47], v[128:131], v[196:199], v[44:47]
	v_mfma_f32_16x16x32_f16 v[40:43], v[136:139], v[196:199], v[40:43]
	v_mfma_f32_16x16x32_f16 v[28:31], v[128:131], v[204:207], v[28:31]
	v_mfma_f32_16x16x32_f16 v[24:27], v[136:139], v[204:207], v[24:27]
	v_mfma_f32_16x16x32_f16 v[12:15], v[128:131], v[212:215], v[12:15]
	v_mfma_f32_16x16x32_f16 v[8:11], v[136:139], v[212:215], v[8:11]
	v_mfma_f32_16x16x32_f16 v[60:63], v[132:135], v[192:195], v[60:63]
	v_mfma_f32_16x16x32_f16 v[56:59], v[140:143], v[192:195], v[56:59]
	v_mfma_f32_16x16x32_f16 v[44:47], v[132:135], v[200:203], v[44:47]
	v_mfma_f32_16x16x32_f16 v[40:43], v[140:143], v[200:203], v[40:43]
	v_mfma_f32_16x16x32_f16 v[28:31], v[132:135], v[208:211], v[28:31]
	v_mfma_f32_16x16x32_f16 v[24:27], v[140:143], v[208:211], v[24:27]
	v_mfma_f32_16x16x32_f16 v[12:15], v[132:135], v[216:219], v[12:15]
	v_mfma_f32_16x16x32_f16 v[8:11], v[140:143], v[216:219], v[8:11]
	v_mfma_f32_16x16x32_f16 v[52:55], v[144:147], v[188:191], v[52:55]
	v_mfma_f32_16x16x32_f16 v[48:51], v[152:155], v[188:191], v[48:51]
	v_mfma_f32_16x16x32_f16 v[36:39], v[144:147], v[196:199], v[36:39]
	v_mfma_f32_16x16x32_f16 v[32:35], v[152:155], v[196:199], v[32:35]
	v_mfma_f32_16x16x32_f16 v[20:23], v[144:147], v[204:207], v[20:23]
	v_mfma_f32_16x16x32_f16 v[16:19], v[152:155], v[204:207], v[16:19]
	v_mfma_f32_16x16x32_f16 v[4:7], v[144:147], v[212:215], v[4:7]
	v_mfma_f32_16x16x32_f16 v[0:3], v[152:155], v[212:215], v[0:3]
	v_mfma_f32_16x16x32_f16 v[52:55], v[148:151], v[192:195], v[52:55]
	v_mfma_f32_16x16x32_f16 v[48:51], v[174:177], v[192:195], v[48:51]
	v_mfma_f32_16x16x32_f16 v[36:39], v[148:151], v[200:203], v[36:39]
	v_mfma_f32_16x16x32_f16 v[32:35], v[174:177], v[200:203], v[32:35]
	v_mfma_f32_16x16x32_f16 v[20:23], v[148:151], v[208:211], v[20:23]
	v_mfma_f32_16x16x32_f16 v[16:19], v[174:177], v[208:211], v[16:19]
	v_mfma_f32_16x16x32_f16 v[4:7], v[148:151], v[216:219], v[4:7]
	v_mfma_f32_16x16x32_f16 v[0:3], v[174:177], v[216:219], v[0:3]
	s_barrier
	s_add_i32 s53, 0, 0x18000
	s_add_i32 s54, 0, 0x1c000
	v_add_u32_e32 v140, s53, v182
	v_add_u32_e32 v165, s54, v182
	ds_read_b128 v[128:131], v140
	ds_read_b128 v[132:135], v140 offset:1024
	ds_read_b128 v[136:139], v140 offset:2048
	ds_read_b128 v[140:143], v140 offset:3072
	ds_read_b128 v[144:147], v165
	ds_read_b128 v[148:151], v165 offset:1024
	ds_read_b128 v[152:155], v165 offset:2048
	ds_read_b128 v[174:177], v165 offset:3072
	s_add_u32 s50, s50, 0x40000
	s_addc_u32 s51, s51, 0
	s_mov_b32 m0, s66
	v_lshl_add_u64 v[226:227], s[50:51], 0, v[156:157]
	ds_read_b128 v[188:191], v185 offset:32768
	ds_read_b128 v[192:195], v185 offset:33792
	ds_read_b128 v[196:199], v185 offset:34816
	ds_read_b128 v[200:203], v185 offset:35840
	ds_read_b128 v[204:207], v185 offset:36864
	ds_read_b128 v[208:211], v185 offset:37888
	ds_read_b128 v[212:215], v185 offset:38912
	ds_read_b128 v[216:219], v185 offset:39936
	global_load_lds_dwordx4 v[226:227], off
	v_lshl_add_u64 v[226:227], s[50:51], 0, v[160:161]
	s_mov_b32 m0, s67
	s_nop 0
	global_load_lds_dwordx4 v[226:227], off
	s_waitcnt vmcnt(8)
	s_waitcnt lgkmcnt(0)
	s_barrier
	s_waitcnt lgkmcnt(0)
	v_mfma_f32_16x16x32_f16 v[124:127], v[128:131], v[188:191], v[124:127]
	v_mfma_f32_16x16x32_f16 v[120:123], v[136:139], v[188:191], v[120:123]
	v_mfma_f32_16x16x32_f16 v[108:111], v[128:131], v[196:199], v[108:111]
	v_mfma_f32_16x16x32_f16 v[104:107], v[136:139], v[196:199], v[104:107]
	v_mfma_f32_16x16x32_f16 v[92:95], v[128:131], v[204:207], v[92:95]
	v_mfma_f32_16x16x32_f16 v[88:91], v[136:139], v[204:207], v[88:91]
	v_mfma_f32_16x16x32_f16 v[76:79], v[128:131], v[212:215], v[76:79]
	v_mfma_f32_16x16x32_f16 v[72:75], v[136:139], v[212:215], v[72:75]
	v_mfma_f32_16x16x32_f16 v[124:127], v[132:135], v[192:195], v[124:127]
	v_mfma_f32_16x16x32_f16 v[120:123], v[140:143], v[192:195], v[120:123]
	v_mfma_f32_16x16x32_f16 v[108:111], v[132:135], v[200:203], v[108:111]
	v_mfma_f32_16x16x32_f16 v[104:107], v[140:143], v[200:203], v[104:107]
	v_mfma_f32_16x16x32_f16 v[92:95], v[132:135], v[208:211], v[92:95]
	v_mfma_f32_16x16x32_f16 v[88:91], v[140:143], v[208:211], v[88:91]
	v_mfma_f32_16x16x32_f16 v[76:79], v[132:135], v[216:219], v[76:79]
	v_mfma_f32_16x16x32_f16 v[72:75], v[140:143], v[216:219], v[72:75]
	v_mfma_f32_16x16x32_f16 v[116:119], v[144:147], v[188:191], v[116:119]
	v_mfma_f32_16x16x32_f16 v[112:115], v[152:155], v[188:191], v[112:115]
	v_mfma_f32_16x16x32_f16 v[100:103], v[144:147], v[196:199], v[100:103]
	v_mfma_f32_16x16x32_f16 v[96:99], v[152:155], v[196:199], v[96:99]
	v_mfma_f32_16x16x32_f16 v[84:87], v[144:147], v[204:207], v[84:87]
	v_mfma_f32_16x16x32_f16 v[80:83], v[152:155], v[204:207], v[80:83]
	v_mfma_f32_16x16x32_f16 v[68:71], v[144:147], v[212:215], v[68:71]
	v_mfma_f32_16x16x32_f16 v[64:67], v[152:155], v[212:215], v[64:67]
	v_mfma_f32_16x16x32_f16 v[116:119], v[148:151], v[192:195], v[116:119]
	v_mfma_f32_16x16x32_f16 v[112:115], v[174:177], v[192:195], v[112:115]
	v_mfma_f32_16x16x32_f16 v[100:103], v[148:151], v[200:203], v[100:103]
	v_mfma_f32_16x16x32_f16 v[96:99], v[174:177], v[200:203], v[96:99]
	v_mfma_f32_16x16x32_f16 v[84:87], v[148:151], v[208:211], v[84:87]
	v_mfma_f32_16x16x32_f16 v[80:83], v[174:177], v[208:211], v[80:83]
	v_mfma_f32_16x16x32_f16 v[68:71], v[148:151], v[216:219], v[68:71]
	v_mfma_f32_16x16x32_f16 v[64:67], v[174:177], v[216:219], v[64:67]
	s_barrier
; #define PG8_STAGE(bufoff, gbase, voff) do { _Pragma("unroll") for (int _i = 0; _i < 2; ++_i) \
;         __builtin_amdgcn_global_load_lds((const unsigned*)((const char*)(gbase) + (voff)[_i]), (PG8_LAS unsigned*)(lds + (bufoff) + ldsw + _i * 8192), 16, 0, 0); } while (0)
; #define PG8_LDA(dst, b, h) do { _Pragma("unroll") for (int m = 0; m < 4; ++m) _Pragma("unroll") for (int k = 0; k < 2; ++k) dst[m][k] = *(const PG8_LAS bf16x8*)(lds + PG8_SA(b, h) + aoff + m * 2048 + k * 1024); } while (0)
; #define PG8_MMA(ai, bj, At, Bt) do { __builtin_amdgcn_s_setprio(1); _Pragma("unroll") for (int m = 0; m < 4; ++m) _Pragma("unroll") for (int n = 0; n < 2; ++n) _Pragma("unroll") for (int k = 0; k < 2; ++k) \
;         acc[ai][bj][m][n] = mma16<F16>(Bt[n][k], At[m][k], acc[ai][bj][m][n]); __builtin_amdgcn_s_setprio(0); } while (0)
; #define PG8_WAIT_V(n) asm volatile("s_waitcnt vmcnt(" #n ")" ::: "memory")
; #define PG8_WAIT_L(n) asm volatile("s_waitcnt lgkmcnt(" #n ")" ::: "memory")
; #define PG8_BAR __builtin_amdgcn_s_barrier()
; #define PG8_SCHED __builtin_amdgcn_sched_barrier(0)
; template <class Epi, class Sched, bool ALIGN_EPI = false, bool SP2 = false, bool F16 = false>
; __device__ __forceinline__ void gemm_phase(PG8_LAS unsigned char* lds, const Gemm g, const Sched& S, const Epi& E, const int wid_in) {
;     ...
;             PG8_LDA(At, 1, 1); PG8_STAGE(PG8_SB(1, 0), b3, voffB); PG8_STAGE(PG8_SB(1, 1), b3 + hstep, voffB); PG8_STAGE(PG8_SA(1, 0), a3, voffA);
;             PG8_WAIT_V(8); PG8_WAIT_L(0); PG8_BAR; PG8_MMA(1, 0, At, B0); PG8_MMA(1, 1, At, B1); PG8_BAR; PG8_SCHED;
;     ...
;         if constexpr (ALIGN_EPI) { if (wr == 0) PG8_BAR; }
	s_add_i32 s50, s53, s68
	v_lshl_add_u64 v[178:179], v[178:179], 0, s[20:21]
	s_mov_b32 m0, s50
	ds_read_b128 v[188:191], v185 offset:49152
	ds_read_b128 v[192:195], v185 offset:50176
	ds_read_b128 v[196:199], v185 offset:51200
	ds_read_b128 v[200:203], v185 offset:52224
	ds_read_b128 v[204:207], v185 offset:53248
	ds_read_b128 v[208:211], v185 offset:54272
	ds_read_b128 v[212:215], v185 offset:55296
	ds_read_b128 v[216:219], v185 offset:56320
	global_load_lds_dwordx4 v[178:179], off
	s_add_i32 m0, s50, 0x2000
	s_add_u32 s48, s48, 0x40080
	v_lshl_add_u64 v[178:179], v[220:221], 0, s[20:21]
	s_addc_u32 s49, s49, 0
	s_add_i32 s50, s54, s68
	global_load_lds_dwordx4 v[178:179], off
	v_lshl_add_u64 v[178:179], s[48:49], 0, v[158:159]
	s_mov_b32 m0, s50
	s_nop 0
	global_load_lds_dwordx4 v[178:179], off
	v_lshl_add_u64 v[178:179], s[48:49], 0, v[162:163]
	s_add_i32 m0, s50, 0x2000
	s_nop 0
	global_load_lds_dwordx4 v[178:179], off
	v_lshl_add_u64 v[178:179], v[222:223], 0, s[20:21]
	s_mov_b32 m0, s75
	s_nop 0
	global_load_lds_dwordx4 v[178:179], off
	v_lshl_add_u64 v[178:179], v[224:225], 0, s[20:21]
	s_mov_b32 m0, s89
	s_nop 0
	global_load_lds_dwordx4 v[178:179], off
	s_waitcnt vmcnt(8)
	s_waitcnt lgkmcnt(0)
	s_barrier
	s_waitcnt lgkmcnt(0)
	v_mfma_f32_16x16x32_f16 v[60:63], v[128:131], v[188:191], v[60:63]
	v_mfma_f32_16x16x32_f16 v[56:59], v[136:139], v[188:191], v[56:59]
	v_mfma_f32_16x16x32_f16 v[44:47], v[128:131], v[196:199], v[44:47]
	v_mfma_f32_16x16x32_f16 v[40:43], v[136:139], v[196:199], v[40:43]
	v_mfma_f32_16x16x32_f16 v[28:31], v[128:131], v[204:207], v[28:31]
	v_mfma_f32_16x16x32_f16 v[24:27], v[136:139], v[204:207], v[24:27]
	v_mfma_f32_16x16x32_f16 v[12:15], v[128:131], v[212:215], v[12:15]
	v_mfma_f32_16x16x32_f16 v[8:11], v[136:139], v[212:215], v[8:11]
	v_mfma_f32_16x16x32_f16 v[60:63], v[132:135], v[192:195], v[60:63]
	v_mfma_f32_16x16x32_f16 v[56:59], v[140:143], v[192:195], v[56:59]
	v_mfma_f32_16x16x32_f16 v[44:47], v[132:135], v[200:203], v[44:47]
	v_mfma_f32_16x16x32_f16 v[40:43], v[140:143], v[200:203], v[40:43]
	v_mfma_f32_16x16x32_f16 v[28:31], v[132:135], v[208:211], v[28:31]
	v_mfma_f32_16x16x32_f16 v[24:27], v[140:143], v[208:211], v[24:27]
	v_mfma_f32_16x16x32_f16 v[12:15], v[132:135], v[216:219], v[12:15]
	v_mfma_f32_16x16x32_f16 v[8:11], v[140:143], v[216:219], v[8:11]
	v_mfma_f32_16x16x32_f16 v[52:55], v[144:147], v[188:191], v[52:55]
	v_mfma_f32_16x16x32_f16 v[48:51], v[152:155], v[188:191], v[48:51]
	v_mfma_f32_16x16x32_f16 v[36:39], v[144:147], v[196:199], v[36:39]
	v_mfma_f32_16x16x32_f16 v[32:35], v[152:155], v[196:199], v[32:35]
	v_mfma_f32_16x16x32_f16 v[20:23], v[144:147], v[204:207], v[20:23]
	v_mfma_f32_16x16x32_f16 v[16:19], v[152:155], v[204:207], v[16:19]
	v_mfma_f32_16x16x32_f16 v[4:7], v[144:147], v[212:215], v[4:7]
	v_mfma_f32_16x16x32_f16 v[0:3], v[152:155], v[212:215], v[0:3]
	v_mfma_f32_16x16x32_f16 v[52:55], v[148:151], v[192:195], v[52:55]
	v_mfma_f32_16x16x32_f16 v[48:51], v[174:177], v[192:195], v[48:51]
	v_mfma_f32_16x16x32_f16 v[36:39], v[148:151], v[200:203], v[36:39]
	v_mfma_f32_16x16x32_f16 v[32:35], v[174:177], v[200:203], v[32:35]
	v_mfma_f32_16x16x32_f16 v[20:23], v[148:151], v[208:211], v[20:23]
	v_mfma_f32_16x16x32_f16 v[16:19], v[174:177], v[208:211], v[16:19]
	v_mfma_f32_16x16x32_f16 v[4:7], v[148:151], v[216:219], v[4:7]
	v_mfma_f32_16x16x32_f16 v[0:3], v[174:177], v[216:219], v[0:3]
	s_barrier
	s_add_i32 s52, s52, 2
	s_add_u32 s46, s46, 0x100
	s_addc_u32 s47, s47, 0
	s_add_u32 s42, s42, 0x100
	s_addc_u32 s43, s43, 0
	s_cmp_gt_u32 s52, 13
	s_cbranch_scc0 .LBB0_902
	s_and_b64 vcc, exec, s[16:17]
	s_cbranch_vccz .LBB0_905
	s_barrier

; #define PG8_STAGE(bufoff, gbase, voff) do { _Pragma("unroll") for (int _i = 0; _i < 2; ++_i) \
;         __builtin_amdgcn_global_load_lds((const unsigned*)((const char*)(gbase) + (voff)[_i]), (PG8_LAS unsigned*)(lds + (bufoff) + ldsw + _i * 8192), 16, 0, 0); } while (0)
; #define PG8_LDA(dst, b, h) do { _Pragma("unroll") for (int m = 0; m < 4; ++m) _Pragma("unroll") for (int k = 0; k < 2; ++k) dst[m][k] = *(const PG8_LAS bf16x8*)(lds + PG8_SA(b, h) + aoff + m * 2048 + k * 1024); } while (0)
; #define PG8_LDB(dst, b, h) do { _Pragma("unroll") for (int n = 0; n < 2; ++n) _Pragma("unroll") for (int k = 0; k < 2; ++k) dst[n][k] = *(const PG8_LAS bf16x8*)(lds + PG8_SB(b, h) + boff + n * 2048 + k * 1024); } while (0)
; #define PG8_MMA(ai, bj, At, Bt) do { __builtin_amdgcn_s_setprio(1); _Pragma("unroll") for (int m = 0; m < 4; ++m) _Pragma("unroll") for (int n = 0; n < 2; ++n) _Pragma("unroll") for (int k = 0; k < 2; ++k) \
;         acc[ai][bj][m][n] = mma16<F16>(Bt[n][k], At[m][k], acc[ai][bj][m][n]); __builtin_amdgcn_s_setprio(0); } while (0)
; #define PG8_WAIT_V(n) asm volatile("s_waitcnt vmcnt(" #n ")" ::: "memory")
; #define PG8_WAIT_L(n) asm volatile("s_waitcnt lgkmcnt(" #n ")" ::: "memory")
; template <class Epi, class Sched, bool ALIGN_EPI = false, bool SP2 = false, bool F16 = false>
; __device__ __forceinline__ void gemm_phase(PG8_LAS unsigned char* lds, const Gemm g, const Sched& S, const Epi& E, const int wid_in) {
;     ...
;             const bool last = (t == nt - 2);
;             const char* a1 = cA + (size_t)(t + 1) * kstep;
;             const char* a2 = last ? nA : cA + (size_t)(t + 2) * kstep; const char* b2 = last ? nB : cB + (size_t)(t + 2) * kstep;
;             const char* a3 = a2 + kstep; const char* b3 = b2 + kstep;
;             if (last && has_next) S.a_ready(nxt);
;             if constexpr (SP2) {
;             PG8_LDB(B0, 0, 0); PG8_LDB(B1, 0, 1); PG8_SCHED; PG8_LDA(At, 0, 0); PG8_STAGE(PG8_SA(1, 1), a1 + hstep, voffA);
;             PG8_WAIT_V(8); PG8_WAIT_L(0); PG8_BAR; PG8_MMA(0, 0, At, B0); PG8_MMA(0, 1, At, B1); PG8_BAR; PG8_SCHED;
;             PG8_LDA(At, 0, 1); PG8_STAGE(PG8_SB(0, 0), b2, voffB); PG8_STAGE(PG8_SB(0, 1), b2 + hstep, voffB); PG8_STAGE(PG8_SA(0, 0), a2, voffA);
;             PG8_WAIT_V(8); PG8_WAIT_L(0); PG8_BAR; PG8_MMA(1, 0, At, B0); PG8_MMA(1, 1, At, B1); PG8_BAR; PG8_SCHED;
.LBB0_1165:
	ds_read_b128 v[128:131], v189
	ds_read_b128 v[132:135], v189 offset:1024
	ds_read_b128 v[136:139], v189 offset:2048
	ds_read_b128 v[140:143], v189 offset:3072
	ds_read_b128 v[144:147], v190
	ds_read_b128 v[148:151], v190 offset:1024
	ds_read_b128 v[168:171], v190 offset:2048
	ds_read_b128 v[172:175], v190 offset:3072
	s_add_u32 s50, s48, 0xfffc0080
	s_addc_u32 s51, s49, -1
	s_cmp_eq_u32 s64, 12
	s_cselect_b32 s53, s35, s51
	s_cselect_b32 s52, s42, s50
	s_cselect_b32 s51, s31, s63
	s_cselect_b32 s50, s43, s47
	v_lshl_add_u64 v[184:185], s[48:49], 0, v[160:161]
	s_add_i32 m0, s74, 0xc000
	ds_read_b128 v[176:179], v191
	ds_read_b128 v[180:183], v191 offset:1024
	ds_read_b128 v[192:195], v191 offset:2048
	ds_read_b128 v[196:199], v191 offset:3072
	ds_read_b128 v[200:203], v191 offset:4096
	ds_read_b128 v[204:207], v191 offset:5120
	ds_read_b128 v[208:211], v191 offset:6144
	ds_read_b128 v[212:215], v191 offset:7168
	global_load_lds_dwordx4 v[184:185], off
	v_lshl_add_u64 v[184:185], s[48:49], 0, v[162:163]
	s_add_i32 m0, s74, 0xe000
	s_nop 0
	global_load_lds_dwordx4 v[184:185], off
	s_waitcnt vmcnt(8)
	s_waitcnt lgkmcnt(0)
	s_barrier
	s_waitcnt lgkmcnt(0)
	v_mfma_f32_16x16x32_bf16 v[124:127], v[128:131], v[176:179], v[124:127]
	v_mfma_f32_16x16x32_bf16 v[120:123], v[136:139], v[176:179], v[120:123]
	v_mfma_f32_16x16x32_bf16 v[108:111], v[128:131], v[192:195], v[108:111]
	v_mfma_f32_16x16x32_bf16 v[104:107], v[136:139], v[192:195], v[104:107]
	v_mfma_f32_16x16x32_bf16 v[92:95], v[128:131], v[200:203], v[92:95]
	v_mfma_f32_16x16x32_bf16 v[88:91], v[136:139], v[200:203], v[88:91]
	v_mfma_f32_16x16x32_bf16 v[76:79], v[128:131], v[208:211], v[76:79]
	v_mfma_f32_16x16x32_bf16 v[72:75], v[136:139], v[208:211], v[72:75]
	v_mfma_f32_16x16x32_bf16 v[124:127], v[132:135], v[180:183], v[124:127]
	v_mfma_f32_16x16x32_bf16 v[120:123], v[140:143], v[180:183], v[120:123]
	v_mfma_f32_16x16x32_bf16 v[108:111], v[132:135], v[196:199], v[108:111]
	v_mfma_f32_16x16x32_bf16 v[104:107], v[140:143], v[196:199], v[104:107]
	v_mfma_f32_16x16x32_bf16 v[92:95], v[132:135], v[204:207], v[92:95]
	v_mfma_f32_16x16x32_bf16 v[88:91], v[140:143], v[204:207], v[88:91]
	v_mfma_f32_16x16x32_bf16 v[76:79], v[132:135], v[212:215], v[76:79]
	v_mfma_f32_16x16x32_bf16 v[72:75], v[140:143], v[212:215], v[72:75]
	v_mfma_f32_16x16x32_bf16 v[116:119], v[144:147], v[176:179], v[116:119]
	v_mfma_f32_16x16x32_bf16 v[112:115], v[168:171], v[176:179], v[112:115]
	v_mfma_f32_16x16x32_bf16 v[100:103], v[144:147], v[192:195], v[100:103]
	v_mfma_f32_16x16x32_bf16 v[96:99], v[168:171], v[192:195], v[96:99]
	v_mfma_f32_16x16x32_bf16 v[84:87], v[144:147], v[200:203], v[84:87]
	v_mfma_f32_16x16x32_bf16 v[80:83], v[168:171], v[200:203], v[80:83]
	v_mfma_f32_16x16x32_bf16 v[68:71], v[144:147], v[208:211], v[68:71]
	v_mfma_f32_16x16x32_bf16 v[64:67], v[168:171], v[208:211], v[64:67]
	v_mfma_f32_16x16x32_bf16 v[116:119], v[148:151], v[180:183], v[116:119]
	v_mfma_f32_16x16x32_bf16 v[112:115], v[172:175], v[180:183], v[112:115]
	v_mfma_f32_16x16x32_bf16 v[100:103], v[148:151], v[196:199], v[100:103]
	v_mfma_f32_16x16x32_bf16 v[96:99], v[172:175], v[196:199], v[96:99]
	v_mfma_f32_16x16x32_bf16 v[84:87], v[148:151], v[204:207], v[84:87]
	v_mfma_f32_16x16x32_bf16 v[80:83], v[172:175], v[204:207], v[80:83]
	v_mfma_f32_16x16x32_bf16 v[68:71], v[148:151], v[212:215], v[68:71]
	v_mfma_f32_16x16x32_bf16 v[64:67], v[172:175], v[212:215], v[64:67]
	s_barrier
	s_add_i32 s65, s60, s68
	v_lshl_add_u64 v[184:185], s[50:51], 0, v[154:155]
	s_mov_b32 m0, s65
	ds_read_b128 v[176:179], v191 offset:16384
	ds_read_b128 v[180:183], v191 offset:17408
	ds_read_b128 v[192:195], v191 offset:18432
	ds_read_b128 v[196:199], v191 offset:19456
	ds_read_b128 v[200:203], v191 offset:20480
	ds_read_b128 v[204:207], v191 offset:21504
	ds_read_b128 v[208:211], v191 offset:22528
	ds_read_b128 v[212:215], v191 offset:23552
	global_load_lds_dwordx4 v[184:185], off
	s_add_i32 m0, s65, 0x2000
	s_add_u32 s66, s50, 0x40000
	v_lshl_add_u64 v[216:217], s[50:51], 0, v[158:159]
	s_addc_u32 s67, s51, 0
	s_add_i32 s65, s61, s68
	global_load_lds_dwordx4 v[216:217], off
	v_lshl_add_u64 v[218:219], s[66:67], 0, v[154:155]
	s_mov_b32 m0, s65
	v_lshl_add_u64 v[220:221], s[52:53], 0, v[156:157]
	global_load_lds_dwordx4 v[218:219], off
	v_lshl_add_u64 v[218:219], s[66:67], 0, v[158:159]
	s_add_i32 m0, s65, 0x2000
	s_nop 0
	global_load_lds_dwordx4 v[218:219], off
	v_lshl_add_u64 v[218:219], s[52:53], 0, v[152:153]
	s_mov_b32 m0, s74
	s_nop 0
	global_load_lds_dwordx4 v[218:219], off
	s_mov_b32 m0, s41
	s_nop 0
	global_load_lds_dwordx4 v[220:221], off
	s_waitcnt vmcnt(8)
	s_waitcnt lgkmcnt(0)
	s_barrier
; #define PG8_STAGE(bufoff, gbase, voff) do { _Pragma("unroll") for (int _i = 0; _i < 2; ++_i) \
;         __builtin_amdgcn_global_load_lds((const unsigned*)((const char*)(gbase) + (voff)[_i]), (PG8_LAS unsigned*)(lds + (bufoff) + ldsw + _i * 8192), 16, 0, 0); } while (0)
; #define PG8_LDA(dst, b, h) do { _Pragma("unroll") for (int m = 0; m < 4; ++m) _Pragma("unroll") for (int k = 0; k < 2; ++k) dst[m][k] = *(const PG8_LAS bf16x8*)(lds + PG8_SA(b, h) + aoff + m * 2048 + k * 1024); } while (0)
; #define PG8_LDB(dst, b, h) do { _Pragma("unroll") for (int n = 0; n < 2; ++n) _Pragma("unroll") for (int k = 0; k < 2; ++k) dst[n][k] = *(const PG8_LAS bf16x8*)(lds + PG8_SB(b, h) + boff + n * 2048 + k * 1024); } while (0)
; #define PG8_MMA(ai, bj, At, Bt) do { __builtin_amdgcn_s_setprio(1); _Pragma("unroll") for (int m = 0; m < 4; ++m) _Pragma("unroll") for (int n = 0; n < 2; ++n) _Pragma("unroll") for (int k = 0; k < 2; ++k) \
;         acc[ai][bj][m][n] = mma16<F16>(Bt[n][k], At[m][k], acc[ai][bj][m][n]); __builtin_amdgcn_s_setprio(0); } while (0)
; #define PG8_WAIT_V(n) asm volatile("s_waitcnt vmcnt(" #n ")" ::: "memory")
; #define PG8_WAIT_L(n) asm volatile("s_waitcnt lgkmcnt(" #n ")" ::: "memory")
; #define PG8_BAR __builtin_amdgcn_s_barrier()
; #define PG8_SCHED __builtin_amdgcn_sched_barrier(0)
; template <class Epi, class Sched, bool ALIGN_EPI = false, bool SP2 = false, bool F16 = false>
; __device__ __forceinline__ void gemm_phase(PG8_LAS unsigned char* lds, const Gemm g, const Sched& S, const Epi& E, const int wid_in) {
;     ...
;             PG8_WAIT_V(8); PG8_WAIT_L(0); PG8_BAR; PG8_MMA(1, 0, At, B0); PG8_MMA(1, 1, At, B1); PG8_BAR; PG8_SCHED;
;             PG8_LDB(B0, 1, 0); PG8_LDB(B1, 1, 1); PG8_SCHED; PG8_LDA(At, 1, 0); PG8_STAGE(PG8_SA(0, 1), a2 + hstep, voffA);
;             PG8_WAIT_V(8); PG8_WAIT_L(0); PG8_BAR; PG8_MMA(0, 0, At, B0); PG8_MMA(0, 1, At, B1); PG8_BAR; PG8_SCHED;
	s_waitcnt lgkmcnt(0)
	v_mfma_f32_16x16x32_bf16 v[60:63], v[128:131], v[176:179], v[60:63]
	v_mfma_f32_16x16x32_bf16 v[56:59], v[136:139], v[176:179], v[56:59]
	v_mfma_f32_16x16x32_bf16 v[44:47], v[128:131], v[192:195], v[44:47]
	v_mfma_f32_16x16x32_bf16 v[40:43], v[136:139], v[192:195], v[40:43]
	v_mfma_f32_16x16x32_bf16 v[28:31], v[128:131], v[200:203], v[28:31]
	v_mfma_f32_16x16x32_bf16 v[24:27], v[136:139], v[200:203], v[24:27]
	v_mfma_f32_16x16x32_bf16 v[12:15], v[128:131], v[208:211], v[12:15]
	v_mfma_f32_16x16x32_bf16 v[8:11], v[136:139], v[208:211], v[8:11]
	v_mfma_f32_16x16x32_bf16 v[60:63], v[132:135], v[180:183], v[60:63]
	v_mfma_f32_16x16x32_bf16 v[56:59], v[140:143], v[180:183], v[56:59]
	v_mfma_f32_16x16x32_bf16 v[44:47], v[132:135], v[196:199], v[44:47]
	v_mfma_f32_16x16x32_bf16 v[40:43], v[140:143], v[196:199], v[40:43]
	v_mfma_f32_16x16x32_bf16 v[28:31], v[132:135], v[204:207], v[28:31]
	v_mfma_f32_16x16x32_bf16 v[24:27], v[140:143], v[204:207], v[24:27]
	v_mfma_f32_16x16x32_bf16 v[12:15], v[132:135], v[212:215], v[12:15]
	v_mfma_f32_16x16x32_bf16 v[8:11], v[140:143], v[212:215], v[8:11]
	v_mfma_f32_16x16x32_bf16 v[52:55], v[144:147], v[176:179], v[52:55]
	v_mfma_f32_16x16x32_bf16 v[48:51], v[168:171], v[176:179], v[48:51]
	v_mfma_f32_16x16x32_bf16 v[36:39], v[144:147], v[192:195], v[36:39]
	v_mfma_f32_16x16x32_bf16 v[32:35], v[168:171], v[192:195], v[32:35]
	v_mfma_f32_16x16x32_bf16 v[20:23], v[144:147], v[200:203], v[20:23]
	v_mfma_f32_16x16x32_bf16 v[16:19], v[168:171], v[200:203], v[16:19]
	v_mfma_f32_16x16x32_bf16 v[4:7], v[144:147], v[208:211], v[4:7]
	v_mfma_f32_16x16x32_bf16 v[0:3], v[168:171], v[208:211], v[0:3]
	v_mfma_f32_16x16x32_bf16 v[52:55], v[148:151], v[180:183], v[52:55]
	v_mfma_f32_16x16x32_bf16 v[48:51], v[172:175], v[180:183], v[48:51]
	v_mfma_f32_16x16x32_bf16 v[36:39], v[148:151], v[196:199], v[36:39]
	v_mfma_f32_16x16x32_bf16 v[32:35], v[172:175], v[196:199], v[32:35]
	v_mfma_f32_16x16x32_bf16 v[20:23], v[148:151], v[204:207], v[20:23]
	v_mfma_f32_16x16x32_bf16 v[16:19], v[172:175], v[204:207], v[16:19]
	v_mfma_f32_16x16x32_bf16 v[4:7], v[148:151], v[212:215], v[4:7]
	v_mfma_f32_16x16x32_bf16 v[0:3], v[172:175], v[212:215], v[0:3]
	s_barrier
	s_add_i32 s65, 0, 0x18000
	s_add_i32 s66, 0, 0x1c000
	v_add_u32_e32 v140, s65, v188
	v_add_u32_e32 v172, s66, v188
	ds_read_b128 v[128:131], v140
	ds_read_b128 v[132:135], v140 offset:1024
	ds_read_b128 v[136:139], v140 offset:2048
	ds_read_b128 v[140:143], v140 offset:3072
	ds_read_b128 v[144:147], v172
	ds_read_b128 v[148:151], v172 offset:1024
	ds_read_b128 v[168:171], v172 offset:2048
	ds_read_b128 v[172:175], v172 offset:3072
	s_add_u32 s52, s52, 0x40000
	s_addc_u32 s53, s53, 0
	s_mov_b32 m0, s54
	v_lshl_add_u64 v[222:223], s[52:53], 0, v[152:153]
	ds_read_b128 v[176:179], v191 offset:32768
	ds_read_b128 v[180:183], v191 offset:33792
	ds_read_b128 v[192:195], v191 offset:34816
	ds_read_b128 v[196:199], v191 offset:35840
	ds_read_b128 v[200:203], v191 offset:36864
	ds_read_b128 v[204:207], v191 offset:37888
	ds_read_b128 v[208:211], v191 offset:38912
	ds_read_b128 v[212:215], v191 offset:39936
	global_load_lds_dwordx4 v[222:223], off
	v_lshl_add_u64 v[222:223], s[52:53], 0, v[156:157]
	s_mov_b32 m0, s55
	s_nop 0
	global_load_lds_dwordx4 v[222:223], off
	s_waitcnt vmcnt(8)
	s_waitcnt lgkmcnt(0)
	s_barrier
	s_waitcnt lgkmcnt(0)
	v_mfma_f32_16x16x32_bf16 v[124:127], v[128:131], v[176:179], v[124:127]
	v_mfma_f32_16x16x32_bf16 v[120:123], v[136:139], v[176:179], v[120:123]
	v_mfma_f32_16x16x32_bf16 v[108:111], v[128:131], v[192:195], v[108:111]
	v_mfma_f32_16x16x32_bf16 v[104:107], v[136:139], v[192:195], v[104:107]
	v_mfma_f32_16x16x32_bf16 v[92:95], v[128:131], v[200:203], v[92:95]
	v_mfma_f32_16x16x32_bf16 v[88:91], v[136:139], v[200:203], v[88:91]
	v_mfma_f32_16x16x32_bf16 v[76:79], v[128:131], v[208:211], v[76:79]
	v_mfma_f32_16x16x32_bf16 v[72:75], v[136:139], v[208:211], v[72:75]
	v_mfma_f32_16x16x32_bf16 v[124:127], v[132:135], v[180:183], v[124:127]
	v_mfma_f32_16x16x32_bf16 v[120:123], v[140:143], v[180:183], v[120:123]
	v_mfma_f32_16x16x32_bf16 v[108:111], v[132:135], v[196:199], v[108:111]
	v_mfma_f32_16x16x32_bf16 v[104:107], v[140:143], v[196:199], v[104:107]
	v_mfma_f32_16x16x32_bf16 v[92:95], v[132:135], v[204:207], v[92:95]
	v_mfma_f32_16x16x32_bf16 v[88:91], v[140:143], v[204:207], v[88:91]
	v_mfma_f32_16x16x32_bf16 v[76:79], v[132:135], v[212:215], v[76:79]
	v_mfma_f32_16x16x32_bf16 v[72:75], v[140:143], v[212:215], v[72:75]
	v_mfma_f32_16x16x32_bf16 v[116:119], v[144:147], v[176:179], v[116:119]
	v_mfma_f32_16x16x32_bf16 v[112:115], v[168:171], v[176:179], v[112:115]
	v_mfma_f32_16x16x32_bf16 v[100:103], v[144:147], v[192:195], v[100:103]
	v_mfma_f32_16x16x32_bf16 v[96:99], v[168:171], v[192:195], v[96:99]
	v_mfma_f32_16x16x32_bf16 v[84:87], v[144:147], v[200:203], v[84:87]
	v_mfma_f32_16x16x32_bf16 v[80:83], v[168:171], v[200:203], v[80:83]
	v_mfma_f32_16x16x32_bf16 v[68:71], v[144:147], v[208:211], v[68:71]
	v_mfma_f32_16x16x32_bf16 v[64:67], v[168:171], v[208:211], v[64:67]
	v_mfma_f32_16x16x32_bf16 v[116:119], v[148:151], v[180:183], v[116:119]
	v_mfma_f32_16x16x32_bf16 v[112:115], v[172:175], v[180:183], v[112:115]
	v_mfma_f32_16x16x32_bf16 v[100:103], v[148:151], v[196:199], v[100:103]
	v_mfma_f32_16x16x32_bf16 v[96:99], v[172:175], v[196:199], v[96:99]
	v_mfma_f32_16x16x32_bf16 v[84:87], v[148:151], v[204:207], v[84:87]
	v_mfma_f32_16x16x32_bf16 v[80:83], v[172:175], v[204:207], v[80:83]
	v_mfma_f32_16x16x32_bf16 v[68:71], v[148:151], v[212:215], v[68:71]
	v_mfma_f32_16x16x32_bf16 v[64:67], v[172:175], v[212:215], v[64:67]
	s_barrier
; #define PG8_STAGE(bufoff, gbase, voff) do { _Pragma("unroll") for (int _i = 0; _i < 2; ++_i) \
;         __builtin_amdgcn_global_load_lds((const unsigned*)((const char*)(gbase) + (voff)[_i]), (PG8_LAS unsigned*)(lds + (bufoff) + ldsw + _i * 8192), 16, 0, 0); } while (0)
; #define PG8_LDA(dst, b, h) do { _Pragma("unroll") for (int m = 0; m < 4; ++m) _Pragma("unroll") for (int k = 0; k < 2; ++k) dst[m][k] = *(const PG8_LAS bf16x8*)(lds + PG8_SA(b, h) + aoff + m * 2048 + k * 1024); } while (0)
; #define PG8_MMA(ai, bj, At, Bt) do { __builtin_amdgcn_s_setprio(1); _Pragma("unroll") for (int m = 0; m < 4; ++m) _Pragma("unroll") for (int n = 0; n < 2; ++n) _Pragma("unroll") for (int k = 0; k < 2; ++k) \
;         acc[ai][bj][m][n] = mma16<F16>(Bt[n][k], At[m][k], acc[ai][bj][m][n]); __builtin_amdgcn_s_setprio(0); } while (0)
; #define PG8_WAIT_V(n) asm volatile("s_waitcnt vmcnt(" #n ")" ::: "memory")
; #define PG8_WAIT_L(n) asm volatile("s_waitcnt lgkmcnt(" #n ")" ::: "memory")
; #define PG8_BAR __builtin_amdgcn_s_barrier()
; #define PG8_SCHED __builtin_amdgcn_sched_barrier(0)
; template <class Epi, class Sched, bool ALIGN_EPI = false, bool SP2 = false, bool F16 = false>
; __device__ __forceinline__ void gemm_phase(PG8_LAS unsigned char* lds, const Gemm g, const Sched& S, const Epi& E, const int wid_in) {
;     ...
;             PG8_LDA(At, 1, 1); PG8_STAGE(PG8_SB(1, 0), b3, voffB); PG8_STAGE(PG8_SB(1, 1), b3 + hstep, voffB); PG8_STAGE(PG8_SA(1, 0), a3, voffA);
;             PG8_WAIT_V(8); PG8_WAIT_L(0); PG8_BAR; PG8_MMA(1, 0, At, B0); PG8_MMA(1, 1, At, B1); PG8_BAR; PG8_SCHED;
;     ...
;         if constexpr (ALIGN_EPI) { if (wr == 0) PG8_BAR; }
	s_add_i32 s52, s65, s68
	v_lshl_add_u64 v[184:185], v[184:185], 0, s[28:29]
	s_mov_b32 m0, s52
	ds_read_b128 v[176:179], v191 offset:49152
	ds_read_b128 v[180:183], v191 offset:50176
	ds_read_b128 v[192:195], v191 offset:51200
	ds_read_b128 v[196:199], v191 offset:52224
	ds_read_b128 v[200:203], v191 offset:53248
	ds_read_b128 v[204:207], v191 offset:54272
	ds_read_b128 v[208:211], v191 offset:55296
	ds_read_b128 v[212:215], v191 offset:56320
	global_load_lds_dwordx4 v[184:185], off
	s_add_i32 m0, s52, 0x2000
	s_add_u32 s50, s50, 0x40080
	v_lshl_add_u64 v[184:185], v[216:217], 0, s[28:29]
	s_addc_u32 s51, s51, 0
	s_add_i32 s52, s66, s68
	global_load_lds_dwordx4 v[184:185], off
	v_lshl_add_u64 v[184:185], s[50:51], 0, v[154:155]
	s_mov_b32 m0, s52
	s_nop 0
	global_load_lds_dwordx4 v[184:185], off
	v_lshl_add_u64 v[184:185], s[50:51], 0, v[158:159]
	s_add_i32 m0, s52, 0x2000
	s_nop 0
	global_load_lds_dwordx4 v[184:185], off
	v_lshl_add_u64 v[184:185], v[218:219], 0, s[28:29]
	s_mov_b32 m0, s75
	s_nop 0
	global_load_lds_dwordx4 v[184:185], off
	v_lshl_add_u64 v[184:185], v[220:221], 0, s[28:29]
	s_mov_b32 m0, s56
	s_nop 0
	global_load_lds_dwordx4 v[184:185], off
	s_waitcnt vmcnt(8)
	s_waitcnt lgkmcnt(0)
	s_barrier
	s_waitcnt lgkmcnt(0)
	v_mfma_f32_16x16x32_bf16 v[60:63], v[128:131], v[176:179], v[60:63]
	v_mfma_f32_16x16x32_bf16 v[56:59], v[136:139], v[176:179], v[56:59]
	v_mfma_f32_16x16x32_bf16 v[44:47], v[128:131], v[192:195], v[44:47]
	v_mfma_f32_16x16x32_bf16 v[40:43], v[136:139], v[192:195], v[40:43]
	v_mfma_f32_16x16x32_bf16 v[28:31], v[128:131], v[200:203], v[28:31]
	v_mfma_f32_16x16x32_bf16 v[24:27], v[136:139], v[200:203], v[24:27]
	v_mfma_f32_16x16x32_bf16 v[12:15], v[128:131], v[208:211], v[12:15]
	v_mfma_f32_16x16x32_bf16 v[8:11], v[136:139], v[208:211], v[8:11]
	v_mfma_f32_16x16x32_bf16 v[60:63], v[132:135], v[180:183], v[60:63]
	v_mfma_f32_16x16x32_bf16 v[56:59], v[140:143], v[180:183], v[56:59]
	v_mfma_f32_16x16x32_bf16 v[44:47], v[132:135], v[196:199], v[44:47]
	v_mfma_f32_16x16x32_bf16 v[40:43], v[140:143], v[196:199], v[40:43]
	v_mfma_f32_16x16x32_bf16 v[28:31], v[132:135], v[204:207], v[28:31]
	v_mfma_f32_16x16x32_bf16 v[24:27], v[140:143], v[204:207], v[24:27]
	v_mfma_f32_16x16x32_bf16 v[12:15], v[132:135], v[212:215], v[12:15]
	v_mfma_f32_16x16x32_bf16 v[8:11], v[140:143], v[212:215], v[8:11]
	v_mfma_f32_16x16x32_bf16 v[52:55], v[144:147], v[176:179], v[52:55]
	v_mfma_f32_16x16x32_bf16 v[48:51], v[168:171], v[176:179], v[48:51]
	v_mfma_f32_16x16x32_bf16 v[36:39], v[144:147], v[192:195], v[36:39]
	v_mfma_f32_16x16x32_bf16 v[32:35], v[168:171], v[192:195], v[32:35]
	v_mfma_f32_16x16x32_bf16 v[20:23], v[144:147], v[200:203], v[20:23]
	v_mfma_f32_16x16x32_bf16 v[16:19], v[168:171], v[200:203], v[16:19]
	v_mfma_f32_16x16x32_bf16 v[4:7], v[144:147], v[208:211], v[4:7]
	v_mfma_f32_16x16x32_bf16 v[0:3], v[168:171], v[208:211], v[0:3]
	v_mfma_f32_16x16x32_bf16 v[52:55], v[148:151], v[180:183], v[52:55]
	v_mfma_f32_16x16x32_bf16 v[48:51], v[172:175], v[180:183], v[48:51]
	v_mfma_f32_16x16x32_bf16 v[36:39], v[148:151], v[196:199], v[36:39]
	v_mfma_f32_16x16x32_bf16 v[32:35], v[172:175], v[196:199], v[32:35]
	v_mfma_f32_16x16x32_bf16 v[20:23], v[148:151], v[204:207], v[20:23]
	v_mfma_f32_16x16x32_bf16 v[16:19], v[172:175], v[204:207], v[16:19]
	v_mfma_f32_16x16x32_bf16 v[4:7], v[148:151], v[212:215], v[4:7]
	v_mfma_f32_16x16x32_bf16 v[0:3], v[172:175], v[212:215], v[0:3]
	s_barrier
	s_add_i32 s64, s64, 2
	s_add_u32 s48, s48, 0x100
	s_addc_u32 s49, s49, 0
	s_add_u32 s47, s47, 0x100
	s_addc_u32 s63, s63, 0
	s_cmp_gt_u32 s64, 13
	s_cbranch_scc0 .LBB0_1165
	s_and_b64 vcc, exec, s[16:17]
	s_cbranch_vccz .LBB0_1168
	s_barrier

; #define PG8_STAGE(bufoff, gbase, voff) do { _Pragma("unroll") for (int _i = 0; _i < 2; ++_i) \
;         __builtin_amdgcn_global_load_lds((const unsigned*)((const char*)(gbase) + (voff)[_i]), (PG8_LAS unsigned*)(lds + (bufoff) + ldsw + _i * 8192), 16, 0, 0); } while (0)
; #define PG8_LDA(dst, b, h) do { _Pragma("unroll") for (int m = 0; m < 4; ++m) _Pragma("unroll") for (int k = 0; k < 2; ++k) dst[m][k] = *(const PG8_LAS bf16x8*)(lds + PG8_SA(b, h) + aoff + m * 2048 + k * 1024); } while (0)
; #define PG8_LDB(dst, b, h) do { _Pragma("unroll") for (int n = 0; n < 2; ++n) _Pragma("unroll") for (int k = 0; k < 2; ++k) dst[n][k] = *(const PG8_LAS bf16x8*)(lds + PG8_SB(b, h) + boff + n * 2048 + k * 1024); } while (0)
; #define PG8_MMA(ai, bj, At, Bt) do { __builtin_amdgcn_s_setprio(1); _Pragma("unroll") for (int m = 0; m < 4; ++m) _Pragma("unroll") for (int n = 0; n < 2; ++n) _Pragma("unroll") for (int k = 0; k < 2; ++k) \
;         acc[ai][bj][m][n] = mma16<F16>(Bt[n][k], At[m][k], acc[ai][bj][m][n]); __builtin_amdgcn_s_setprio(0); } while (0)
; #define PG8_WAIT_V(n) asm volatile("s_waitcnt vmcnt(" #n ")" ::: "memory")
; #define PG8_WAIT_L(n) asm volatile("s_waitcnt lgkmcnt(" #n ")" ::: "memory")
; template <class Epi, class Sched, bool ALIGN_EPI = false, bool SP2 = false, bool F16 = false>
; __device__ __forceinline__ void gemm_phase(PG8_LAS unsigned char* lds, const Gemm g, const Sched& S, const Epi& E, const int wid_in) {
;     ...
;             const bool last = (t == nt - 2);
;             const char* a1 = cA + (size_t)(t + 1) * kstep;
;             const char* a2 = last ? nA : cA + (size_t)(t + 2) * kstep; const char* b2 = last ? nB : cB + (size_t)(t + 2) * kstep;
;             const char* a3 = a2 + kstep; const char* b3 = b2 + kstep;
;             if (last && has_next) S.a_ready(nxt);
;             if constexpr (SP2) {
;             PG8_LDB(B0, 0, 0); PG8_LDB(B1, 0, 1); PG8_SCHED; PG8_LDA(At, 0, 0); PG8_STAGE(PG8_SA(1, 1), a1 + hstep, voffA);
;             PG8_WAIT_V(8); PG8_WAIT_L(0); PG8_BAR; PG8_MMA(0, 0, At, B0); PG8_MMA(0, 1, At, B1); PG8_BAR; PG8_SCHED;
;             PG8_LDA(At, 0, 1); PG8_STAGE(PG8_SB(0, 0), b2, voffB); PG8_STAGE(PG8_SB(0, 1), b2 + hstep, voffB); PG8_STAGE(PG8_SA(0, 0), a2, voffA);
;             PG8_WAIT_V(8); PG8_WAIT_L(0); PG8_BAR; PG8_MMA(1, 0, At, B0); PG8_MMA(1, 1, At, B1); PG8_BAR; PG8_SCHED;
.LBB0_1242:
	ds_read_b128 v[0:3], v193
	ds_read_b128 v[4:7], v193 offset:1024
	ds_read_b128 v[136:139], v193 offset:2048
	ds_read_b128 v[140:143], v193 offset:3072
	ds_read_b128 v[144:147], v194
	ds_read_b128 v[148:151], v194 offset:1024
	ds_read_b128 v[152:155], v194 offset:2048
	ds_read_b128 v[156:159], v194 offset:3072
	s_add_u32 s48, s46, 0xfffc0080
	s_addc_u32 s49, s47, -1
	s_cmp_eq_u32 s67, 12
	s_cselect_b32 s51, s29, s49
	s_cselect_b32 s50, s42, s48
	s_cselect_b32 s49, s27, s66
	s_cselect_b32 s48, s43, s45
	v_lshl_add_u64 v[188:189], s[46:47], 0, v[168:169]
	s_add_i32 m0, s74, 0xc000
	ds_read_b128 v[176:179], v195
	ds_read_b128 v[180:183], v195 offset:1024
	ds_read_b128 v[184:187], v195 offset:2048
	ds_read_b128 v[198:201], v195 offset:3072
	ds_read_b128 v[202:205], v195 offset:4096
	ds_read_b128 v[206:209], v195 offset:5120
	ds_read_b128 v[210:213], v195 offset:6144
	ds_read_b128 v[214:217], v195 offset:7168
	global_load_lds_dwordx4 v[188:189], off
	v_lshl_add_u64 v[188:189], s[46:47], 0, v[170:171]
	s_add_i32 m0, s74, 0xe000
	s_nop 0
	global_load_lds_dwordx4 v[188:189], off
	s_waitcnt vmcnt(8)
	s_waitcnt lgkmcnt(0)
	s_barrier
	s_waitcnt lgkmcnt(0)
	v_mfma_f32_16x16x32_f16 v[132:135], v[0:3], v[176:179], v[132:135]
	v_mfma_f32_16x16x32_f16 v[128:131], v[136:139], v[176:179], v[128:131]
	v_mfma_f32_16x16x32_f16 v[116:119], v[0:3], v[184:187], v[116:119]
	v_mfma_f32_16x16x32_f16 v[112:115], v[136:139], v[184:187], v[112:115]
	v_mfma_f32_16x16x32_f16 v[100:103], v[0:3], v[202:205], v[100:103]
	v_mfma_f32_16x16x32_f16 v[96:99], v[136:139], v[202:205], v[96:99]
	v_mfma_f32_16x16x32_f16 v[84:87], v[0:3], v[210:213], v[84:87]
	v_mfma_f32_16x16x32_f16 v[80:83], v[136:139], v[210:213], v[80:83]
	v_mfma_f32_16x16x32_f16 v[132:135], v[4:7], v[180:183], v[132:135]
	v_mfma_f32_16x16x32_f16 v[128:131], v[140:143], v[180:183], v[128:131]
	v_mfma_f32_16x16x32_f16 v[116:119], v[4:7], v[198:201], v[116:119]
	v_mfma_f32_16x16x32_f16 v[112:115], v[140:143], v[198:201], v[112:115]
	v_mfma_f32_16x16x32_f16 v[100:103], v[4:7], v[206:209], v[100:103]
	v_mfma_f32_16x16x32_f16 v[96:99], v[140:143], v[206:209], v[96:99]
	v_mfma_f32_16x16x32_f16 v[84:87], v[4:7], v[214:217], v[84:87]
	v_mfma_f32_16x16x32_f16 v[80:83], v[140:143], v[214:217], v[80:83]
	v_mfma_f32_16x16x32_f16 v[124:127], v[144:147], v[176:179], v[124:127]
	v_mfma_f32_16x16x32_f16 v[120:123], v[152:155], v[176:179], v[120:123]
	v_mfma_f32_16x16x32_f16 v[108:111], v[144:147], v[184:187], v[108:111]
	v_mfma_f32_16x16x32_f16 v[104:107], v[152:155], v[184:187], v[104:107]
	v_mfma_f32_16x16x32_f16 v[92:95], v[144:147], v[202:205], v[92:95]
	v_mfma_f32_16x16x32_f16 v[88:91], v[152:155], v[202:205], v[88:91]
	v_mfma_f32_16x16x32_f16 v[76:79], v[144:147], v[210:213], v[76:79]
	v_mfma_f32_16x16x32_f16 v[72:75], v[152:155], v[210:213], v[72:75]
	v_mfma_f32_16x16x32_f16 v[124:127], v[148:151], v[180:183], v[124:127]
	v_mfma_f32_16x16x32_f16 v[120:123], v[156:159], v[180:183], v[120:123]
	v_mfma_f32_16x16x32_f16 v[108:111], v[148:151], v[198:201], v[108:111]
	v_mfma_f32_16x16x32_f16 v[104:107], v[156:159], v[198:201], v[104:107]
	v_mfma_f32_16x16x32_f16 v[92:95], v[148:151], v[206:209], v[92:95]
	v_mfma_f32_16x16x32_f16 v[88:91], v[156:159], v[206:209], v[88:91]
	v_mfma_f32_16x16x32_f16 v[76:79], v[148:151], v[214:217], v[76:79]
	v_mfma_f32_16x16x32_f16 v[72:75], v[156:159], v[214:217], v[72:75]
	s_barrier
	s_add_i32 s76, s63, s68
	v_lshl_add_u64 v[188:189], s[48:49], 0, v[162:163]
	s_mov_b32 m0, s76
	ds_read_b128 v[176:179], v195 offset:16384
	ds_read_b128 v[180:183], v195 offset:17408
	ds_read_b128 v[184:187], v195 offset:18432
	ds_read_b128 v[198:201], v195 offset:19456
	ds_read_b128 v[202:205], v195 offset:20480
	ds_read_b128 v[206:209], v195 offset:21504
	ds_read_b128 v[210:213], v195 offset:22528
	ds_read_b128 v[214:217], v195 offset:23552
	global_load_lds_dwordx4 v[188:189], off
	s_add_i32 m0, s76, 0x2000
	s_add_u32 s90, s48, 0x40000
	v_lshl_add_u64 v[218:219], s[48:49], 0, v[166:167]
	s_addc_u32 s91, s49, 0
	s_add_i32 s76, s64, s68
	global_load_lds_dwordx4 v[218:219], off
	v_lshl_add_u64 v[220:221], s[90:91], 0, v[162:163]
	s_mov_b32 m0, s76
	v_lshl_add_u64 v[222:223], s[50:51], 0, v[164:165]
	global_load_lds_dwordx4 v[220:221], off
	v_lshl_add_u64 v[220:221], s[90:91], 0, v[166:167]
	s_add_i32 m0, s76, 0x2000
	s_nop 0
	global_load_lds_dwordx4 v[220:221], off
	v_lshl_add_u64 v[220:221], s[50:51], 0, v[160:161]
	s_mov_b32 m0, s74
	s_nop 0
	global_load_lds_dwordx4 v[220:221], off
	s_mov_b32 m0, s37
	s_nop 0
	global_load_lds_dwordx4 v[222:223], off
	s_waitcnt vmcnt(8)
	s_waitcnt lgkmcnt(0)
	s_barrier
; #define PG8_STAGE(bufoff, gbase, voff) do { _Pragma("unroll") for (int _i = 0; _i < 2; ++_i) \
;         __builtin_amdgcn_global_load_lds((const unsigned*)((const char*)(gbase) + (voff)[_i]), (PG8_LAS unsigned*)(lds + (bufoff) + ldsw + _i * 8192), 16, 0, 0); } while (0)
; #define PG8_LDA(dst, b, h) do { _Pragma("unroll") for (int m = 0; m < 4; ++m) _Pragma("unroll") for (int k = 0; k < 2; ++k) dst[m][k] = *(const PG8_LAS bf16x8*)(lds + PG8_SA(b, h) + aoff + m * 2048 + k * 1024); } while (0)
; #define PG8_LDB(dst, b, h) do { _Pragma("unroll") for (int n = 0; n < 2; ++n) _Pragma("unroll") for (int k = 0; k < 2; ++k) dst[n][k] = *(const PG8_LAS bf16x8*)(lds + PG8_SB(b, h) + boff + n * 2048 + k * 1024); } while (0)
; #define PG8_MMA(ai, bj, At, Bt) do { __builtin_amdgcn_s_setprio(1); _Pragma("unroll") for (int m = 0; m < 4; ++m) _Pragma("unroll") for (int n = 0; n < 2; ++n) _Pragma("unroll") for (int k = 0; k < 2; ++k) \
;         acc[ai][bj][m][n] = mma16<F16>(Bt[n][k], At[m][k], acc[ai][bj][m][n]); __builtin_amdgcn_s_setprio(0); } while (0)
; #define PG8_WAIT_V(n) asm volatile("s_waitcnt vmcnt(" #n ")" ::: "memory")
; #define PG8_WAIT_L(n) asm volatile("s_waitcnt lgkmcnt(" #n ")" ::: "memory")
; #define PG8_BAR __builtin_amdgcn_s_barrier()
; #define PG8_SCHED __builtin_amdgcn_sched_barrier(0)
; template <class Epi, class Sched, bool ALIGN_EPI = false, bool SP2 = false, bool F16 = false>
; __device__ __forceinline__ void gemm_phase(PG8_LAS unsigned char* lds, const Gemm g, const Sched& S, const Epi& E, const int wid_in) {
;     ...
;             PG8_WAIT_V(8); PG8_WAIT_L(0); PG8_BAR; PG8_MMA(1, 0, At, B0); PG8_MMA(1, 1, At, B1); PG8_BAR; PG8_SCHED;
;             PG8_LDB(B0, 1, 0); PG8_LDB(B1, 1, 1); PG8_SCHED; PG8_LDA(At, 1, 0); PG8_STAGE(PG8_SA(0, 1), a2 + hstep, voffA);
;             PG8_WAIT_V(8); PG8_WAIT_L(0); PG8_BAR; PG8_MMA(0, 0, At, B0); PG8_MMA(0, 1, At, B1); PG8_BAR; PG8_SCHED;
	s_waitcnt lgkmcnt(0)
	v_mfma_f32_16x16x32_f16 v[68:71], v[0:3], v[176:179], v[68:71]
	v_mfma_f32_16x16x32_f16 v[64:67], v[136:139], v[176:179], v[64:67]
	v_mfma_f32_16x16x32_f16 v[52:55], v[0:3], v[184:187], v[52:55]
	v_mfma_f32_16x16x32_f16 v[48:51], v[136:139], v[184:187], v[48:51]
	v_mfma_f32_16x16x32_f16 v[36:39], v[0:3], v[202:205], v[36:39]
	v_mfma_f32_16x16x32_f16 v[32:35], v[136:139], v[202:205], v[32:35]
	v_mfma_f32_16x16x32_f16 v[0:3], v[0:3], v[210:213], v[20:23]
	v_mfma_f32_16x16x32_f16 v[68:71], v[4:7], v[180:183], v[68:71]
	v_mfma_f32_16x16x32_f16 v[64:67], v[140:143], v[180:183], v[64:67]
	v_mfma_f32_16x16x32_f16 v[52:55], v[4:7], v[198:201], v[52:55]
	v_mfma_f32_16x16x32_f16 v[48:51], v[140:143], v[198:201], v[48:51]
	v_mfma_f32_16x16x32_f16 v[36:39], v[4:7], v[206:209], v[36:39]
	v_mfma_f32_16x16x32_f16 v[32:35], v[140:143], v[206:209], v[32:35]
	v_mfma_f32_16x16x32_f16 v[0:3], v[4:7], v[214:217], v[0:3]
	v_mfma_f32_16x16x32_f16 v[4:7], v[136:139], v[210:213], v[16:19]
	v_mfma_f32_16x16x32_f16 v[4:7], v[140:143], v[214:217], v[4:7]
	v_mfma_f32_16x16x32_f16 v[16:19], v[144:147], v[176:179], v[60:63]
	v_mfma_f32_16x16x32_f16 v[60:63], v[148:151], v[180:183], v[16:19]
	v_mfma_f32_16x16x32_f16 v[16:19], v[152:155], v[176:179], v[56:59]
	v_mfma_f32_16x16x32_f16 v[56:59], v[156:159], v[180:183], v[16:19]
	v_mfma_f32_16x16x32_f16 v[16:19], v[144:147], v[184:187], v[44:47]
	v_mfma_f32_16x16x32_f16 v[44:47], v[148:151], v[198:201], v[16:19]
	v_mfma_f32_16x16x32_f16 v[16:19], v[152:155], v[184:187], v[40:43]
	v_mfma_f32_16x16x32_f16 v[40:43], v[156:159], v[198:201], v[16:19]
	v_mfma_f32_16x16x32_f16 v[16:19], v[144:147], v[202:205], v[28:31]
	v_mfma_f32_16x16x32_f16 v[28:31], v[148:151], v[206:209], v[16:19]
	v_mfma_f32_16x16x32_f16 v[16:19], v[152:155], v[202:205], v[24:27]
	v_mfma_f32_16x16x32_f16 v[12:15], v[144:147], v[210:213], v[12:15]
	v_mfma_f32_16x16x32_f16 v[8:11], v[152:155], v[210:213], v[8:11]
	v_mfma_f32_16x16x32_f16 v[24:27], v[156:159], v[206:209], v[16:19]
	v_mfma_f32_16x16x32_f16 v[12:15], v[148:151], v[214:217], v[12:15]
	v_mfma_f32_16x16x32_f16 v[8:11], v[156:159], v[214:217], v[8:11]
	s_barrier
	s_add_i32 s76, 0, 0x18000
	s_add_i32 s83, 0, 0x1c000
	v_add_u32_e32 v140, s76, v192
	v_add_u32_e32 v156, s83, v192
	ds_read_b128 v[16:19], v140
	ds_read_b128 v[20:23], v140 offset:1024
	ds_read_b128 v[136:139], v140 offset:2048
	ds_read_b128 v[140:143], v140 offset:3072
	ds_read_b128 v[144:147], v156
	ds_read_b128 v[148:151], v156 offset:1024
	ds_read_b128 v[152:155], v156 offset:2048
	ds_read_b128 v[156:159], v156 offset:3072
	s_add_u32 s50, s50, 0x40000
	s_addc_u32 s51, s51, 0
	s_mov_b32 m0, s53
	v_lshl_add_u64 v[224:225], s[50:51], 0, v[160:161]
	ds_read_b128 v[176:179], v195 offset:32768
	ds_read_b128 v[180:183], v195 offset:33792
	ds_read_b128 v[184:187], v195 offset:34816
	ds_read_b128 v[198:201], v195 offset:35840
	ds_read_b128 v[202:205], v195 offset:36864
	ds_read_b128 v[206:209], v195 offset:37888
	ds_read_b128 v[210:213], v195 offset:38912
	ds_read_b128 v[214:217], v195 offset:39936
	global_load_lds_dwordx4 v[224:225], off
	v_lshl_add_u64 v[224:225], s[50:51], 0, v[164:165]
	s_mov_b32 m0, s54
	s_nop 0
	global_load_lds_dwordx4 v[224:225], off
	s_waitcnt vmcnt(8)
	s_waitcnt lgkmcnt(0)
	s_barrier
	s_waitcnt lgkmcnt(0)
	v_mfma_f32_16x16x32_f16 v[132:135], v[16:19], v[176:179], v[132:135]
	v_mfma_f32_16x16x32_f16 v[128:131], v[136:139], v[176:179], v[128:131]
	v_mfma_f32_16x16x32_f16 v[116:119], v[16:19], v[184:187], v[116:119]
	v_mfma_f32_16x16x32_f16 v[112:115], v[136:139], v[184:187], v[112:115]
	v_mfma_f32_16x16x32_f16 v[100:103], v[16:19], v[202:205], v[100:103]
	v_mfma_f32_16x16x32_f16 v[96:99], v[136:139], v[202:205], v[96:99]
	v_mfma_f32_16x16x32_f16 v[84:87], v[16:19], v[210:213], v[84:87]
	v_mfma_f32_16x16x32_f16 v[80:83], v[136:139], v[210:213], v[80:83]
	v_mfma_f32_16x16x32_f16 v[132:135], v[20:23], v[180:183], v[132:135]
	v_mfma_f32_16x16x32_f16 v[128:131], v[140:143], v[180:183], v[128:131]
	v_mfma_f32_16x16x32_f16 v[116:119], v[20:23], v[198:201], v[116:119]
	v_mfma_f32_16x16x32_f16 v[112:115], v[140:143], v[198:201], v[112:115]
	v_mfma_f32_16x16x32_f16 v[100:103], v[20:23], v[206:209], v[100:103]
	v_mfma_f32_16x16x32_f16 v[96:99], v[140:143], v[206:209], v[96:99]
	v_mfma_f32_16x16x32_f16 v[84:87], v[20:23], v[214:217], v[84:87]
	v_mfma_f32_16x16x32_f16 v[80:83], v[140:143], v[214:217], v[80:83]
	v_mfma_f32_16x16x32_f16 v[124:127], v[144:147], v[176:179], v[124:127]
	v_mfma_f32_16x16x32_f16 v[120:123], v[152:155], v[176:179], v[120:123]
	v_mfma_f32_16x16x32_f16 v[108:111], v[144:147], v[184:187], v[108:111]
	v_mfma_f32_16x16x32_f16 v[104:107], v[152:155], v[184:187], v[104:107]
	v_mfma_f32_16x16x32_f16 v[92:95], v[144:147], v[202:205], v[92:95]
	v_mfma_f32_16x16x32_f16 v[88:91], v[152:155], v[202:205], v[88:91]
	v_mfma_f32_16x16x32_f16 v[76:79], v[144:147], v[210:213], v[76:79]
	v_mfma_f32_16x16x32_f16 v[72:75], v[152:155], v[210:213], v[72:75]
	v_mfma_f32_16x16x32_f16 v[124:127], v[148:151], v[180:183], v[124:127]
	v_mfma_f32_16x16x32_f16 v[120:123], v[156:159], v[180:183], v[120:123]
	v_mfma_f32_16x16x32_f16 v[108:111], v[148:151], v[198:201], v[108:111]
	v_mfma_f32_16x16x32_f16 v[104:107], v[156:159], v[198:201], v[104:107]
	v_mfma_f32_16x16x32_f16 v[92:95], v[148:151], v[206:209], v[92:95]
	v_mfma_f32_16x16x32_f16 v[88:91], v[156:159], v[206:209], v[88:91]
	v_mfma_f32_16x16x32_f16 v[76:79], v[148:151], v[214:217], v[76:79]
	v_mfma_f32_16x16x32_f16 v[72:75], v[156:159], v[214:217], v[72:75]
	s_barrier
; #define PG8_STAGE(bufoff, gbase, voff) do { _Pragma("unroll") for (int _i = 0; _i < 2; ++_i) \
;         __builtin_amdgcn_global_load_lds((const unsigned*)((const char*)(gbase) + (voff)[_i]), (PG8_LAS unsigned*)(lds + (bufoff) + ldsw + _i * 8192), 16, 0, 0); } while (0)
; #define PG8_LDA(dst, b, h) do { _Pragma("unroll") for (int m = 0; m < 4; ++m) _Pragma("unroll") for (int k = 0; k < 2; ++k) dst[m][k] = *(const PG8_LAS bf16x8*)(lds + PG8_SA(b, h) + aoff + m * 2048 + k * 1024); } while (0)
; #define PG8_MMA(ai, bj, At, Bt) do { __builtin_amdgcn_s_setprio(1); _Pragma("unroll") for (int m = 0; m < 4; ++m) _Pragma("unroll") for (int n = 0; n < 2; ++n) _Pragma("unroll") for (int k = 0; k < 2; ++k) \
;         acc[ai][bj][m][n] = mma16<F16>(Bt[n][k], At[m][k], acc[ai][bj][m][n]); __builtin_amdgcn_s_setprio(0); } while (0)
; #define PG8_WAIT_V(n) asm volatile("s_waitcnt vmcnt(" #n ")" ::: "memory")
; #define PG8_WAIT_L(n) asm volatile("s_waitcnt lgkmcnt(" #n ")" ::: "memory")
; #define PG8_BAR __builtin_amdgcn_s_barrier()
; #define PG8_SCHED __builtin_amdgcn_sched_barrier(0)
; template <class Epi, class Sched, bool ALIGN_EPI = false, bool SP2 = false, bool F16 = false>
; __device__ __forceinline__ void gemm_phase(PG8_LAS unsigned char* lds, const Gemm g, const Sched& S, const Epi& E, const int wid_in) {
;     ...
;             PG8_LDA(At, 1, 1); PG8_STAGE(PG8_SB(1, 0), b3, voffB); PG8_STAGE(PG8_SB(1, 1), b3 + hstep, voffB); PG8_STAGE(PG8_SA(1, 0), a3, voffA);
;             PG8_WAIT_V(8); PG8_WAIT_L(0); PG8_BAR; PG8_MMA(1, 0, At, B0); PG8_MMA(1, 1, At, B1); PG8_BAR; PG8_SCHED;
;     ...
;         if constexpr (ALIGN_EPI) { if (wr == 0) PG8_BAR; }
	s_add_i32 s50, s76, s68
	v_lshl_add_u64 v[188:189], v[188:189], 0, s[24:25]
	s_mov_b32 m0, s50
	ds_read_b128 v[176:179], v195 offset:49152
	ds_read_b128 v[180:183], v195 offset:50176
	ds_read_b128 v[184:187], v195 offset:51200
	ds_read_b128 v[198:201], v195 offset:52224
	ds_read_b128 v[202:205], v195 offset:53248
	ds_read_b128 v[206:209], v195 offset:54272
	ds_read_b128 v[210:213], v195 offset:55296
	ds_read_b128 v[214:217], v195 offset:56320
	global_load_lds_dwordx4 v[188:189], off
	s_add_i32 m0, s50, 0x2000
	s_add_u32 s48, s48, 0x40080
	v_lshl_add_u64 v[188:189], v[218:219], 0, s[24:25]
	s_addc_u32 s49, s49, 0
	s_add_i32 s50, s83, s68
	global_load_lds_dwordx4 v[188:189], off
	v_lshl_add_u64 v[188:189], s[48:49], 0, v[162:163]
	s_mov_b32 m0, s50
	s_nop 0
	global_load_lds_dwordx4 v[188:189], off
	v_lshl_add_u64 v[188:189], s[48:49], 0, v[166:167]
	s_add_i32 m0, s50, 0x2000
	s_nop 0
	global_load_lds_dwordx4 v[188:189], off
	v_lshl_add_u64 v[188:189], v[220:221], 0, s[24:25]
	s_mov_b32 m0, s75
	s_nop 0
	global_load_lds_dwordx4 v[188:189], off
	v_lshl_add_u64 v[188:189], v[222:223], 0, s[24:25]
	s_mov_b32 m0, s57
	s_nop 0
	global_load_lds_dwordx4 v[188:189], off
	s_waitcnt vmcnt(8)
	s_waitcnt lgkmcnt(0)
	s_barrier
	s_waitcnt lgkmcnt(0)
	v_mfma_f32_16x16x32_f16 v[68:71], v[16:19], v[176:179], v[68:71]
	v_mfma_f32_16x16x32_f16 v[52:55], v[16:19], v[184:187], v[52:55]
	v_mfma_f32_16x16x32_f16 v[36:39], v[16:19], v[202:205], v[36:39]
	v_mfma_f32_16x16x32_f16 v[0:3], v[16:19], v[210:213], v[0:3]
	v_mfma_f32_16x16x32_f16 v[68:71], v[20:23], v[180:183], v[68:71]
	v_mfma_f32_16x16x32_f16 v[64:67], v[136:139], v[176:179], v[64:67]
	v_mfma_f32_16x16x32_f16 v[52:55], v[20:23], v[198:201], v[52:55]
	v_mfma_f32_16x16x32_f16 v[48:51], v[136:139], v[184:187], v[48:51]
	v_mfma_f32_16x16x32_f16 v[36:39], v[20:23], v[206:209], v[36:39]
	v_mfma_f32_16x16x32_f16 v[32:35], v[136:139], v[202:205], v[32:35]
	v_mfma_f32_16x16x32_f16 v[20:23], v[20:23], v[214:217], v[0:3]
	v_mfma_f32_16x16x32_f16 v[0:3], v[136:139], v[210:213], v[4:7]
	v_mfma_f32_16x16x32_f16 v[64:67], v[140:143], v[180:183], v[64:67]
	v_mfma_f32_16x16x32_f16 v[48:51], v[140:143], v[198:201], v[48:51]
	v_mfma_f32_16x16x32_f16 v[32:35], v[140:143], v[206:209], v[32:35]
	v_mfma_f32_16x16x32_f16 v[16:19], v[140:143], v[214:217], v[0:3]
	v_mfma_f32_16x16x32_f16 v[0:3], v[144:147], v[176:179], v[60:63]
	v_mfma_f32_16x16x32_f16 v[60:63], v[148:151], v[180:183], v[0:3]
	v_mfma_f32_16x16x32_f16 v[0:3], v[152:155], v[176:179], v[56:59]
	v_mfma_f32_16x16x32_f16 v[56:59], v[156:159], v[180:183], v[0:3]
	v_mfma_f32_16x16x32_f16 v[0:3], v[144:147], v[184:187], v[44:47]
	v_mfma_f32_16x16x32_f16 v[44:47], v[148:151], v[198:201], v[0:3]
	v_mfma_f32_16x16x32_f16 v[0:3], v[152:155], v[184:187], v[40:43]
	v_mfma_f32_16x16x32_f16 v[40:43], v[156:159], v[198:201], v[0:3]
	v_mfma_f32_16x16x32_f16 v[0:3], v[144:147], v[202:205], v[28:31]
	v_mfma_f32_16x16x32_f16 v[28:31], v[148:151], v[206:209], v[0:3]
	v_mfma_f32_16x16x32_f16 v[0:3], v[152:155], v[202:205], v[24:27]
	v_mfma_f32_16x16x32_f16 v[24:27], v[156:159], v[206:209], v[0:3]
	v_mfma_f32_16x16x32_f16 v[0:3], v[144:147], v[210:213], v[12:15]
	v_mfma_f32_16x16x32_f16 v[12:15], v[148:151], v[214:217], v[0:3]
	v_mfma_f32_16x16x32_f16 v[0:3], v[152:155], v[210:213], v[8:11]
	v_mfma_f32_16x16x32_f16 v[8:11], v[156:159], v[214:217], v[0:3]
	s_barrier
	s_add_i32 s67, s67, 2
	s_add_u32 s46, s46, 0x100
	s_addc_u32 s47, s47, 0
	s_add_u32 s45, s45, 0x100
	s_addc_u32 s66, s66, 0
	s_cmp_gt_u32 s67, 13
	s_cbranch_scc0 .LBB0_1242
	s_and_b64 vcc, exec, s[16:17]
	s_cbranch_vccz .LBB0_1245
	s_barrier

; #define PG8_STAGE(bufoff, gbase, voff) do { _Pragma("unroll") for (int _i = 0; _i < 2; ++_i) \
;         __builtin_amdgcn_global_load_lds((const unsigned*)((const char*)(gbase) + (voff)[_i]), (PG8_LAS unsigned*)(lds + (bufoff) + ldsw + _i * 8192), 16, 0, 0); } while (0)
; #define PG8_LDA(dst, b, h) do { _Pragma("unroll") for (int m = 0; m < 4; ++m) _Pragma("unroll") for (int k = 0; k < 2; ++k) dst[m][k] = *(const PG8_LAS bf16x8*)(lds + PG8_SA(b, h) + aoff + m * 2048 + k * 1024); } while (0)
; #define PG8_LDB(dst, b, h) do { _Pragma("unroll") for (int n = 0; n < 2; ++n) _Pragma("unroll") for (int k = 0; k < 2; ++k) dst[n][k] = *(const PG8_LAS bf16x8*)(lds + PG8_SB(b, h) + boff + n * 2048 + k * 1024); } while (0)
; #define PG8_MMA(ai, bj, At, Bt) do { __builtin_amdgcn_s_setprio(1); _Pragma("unroll") for (int m = 0; m < 4; ++m) _Pragma("unroll") for (int n = 0; n < 2; ++n) _Pragma("unroll") for (int k = 0; k < 2; ++k) \
;         acc[ai][bj][m][n] = mma16<F16>(Bt[n][k], At[m][k], acc[ai][bj][m][n]); __builtin_amdgcn_s_setprio(0); } while (0)
; #define PG8_WAIT_V(n) asm volatile("s_waitcnt vmcnt(" #n ")" ::: "memory")
; #define PG8_WAIT_L(n) asm volatile("s_waitcnt lgkmcnt(" #n ")" ::: "memory")
; template <class Epi, class Sched, bool ALIGN_EPI = false, bool SP2 = false, bool F16 = false>
; __device__ __forceinline__ void gemm_phase(PG8_LAS unsigned char* lds, const Gemm g, const Sched& S, const Epi& E, const int wid_in) {
;     ...
;             const bool last = (t == nt - 2);
;             const char* a1 = cA + (size_t)(t + 1) * kstep;
;             const char* a2 = last ? nA : cA + (size_t)(t + 2) * kstep; const char* b2 = last ? nB : cB + (size_t)(t + 2) * kstep;
;             const char* a3 = a2 + kstep; const char* b3 = b2 + kstep;
;             if (last && has_next) S.a_ready(nxt);
;             if constexpr (SP2) {
;             PG8_LDB(B0, 0, 0); PG8_LDB(B1, 0, 1); PG8_SCHED; PG8_LDA(At, 0, 0); PG8_STAGE(PG8_SA(1, 1), a1 + hstep, voffA);
;             PG8_WAIT_V(8); PG8_WAIT_L(0); PG8_BAR; PG8_MMA(0, 0, At, B0); PG8_MMA(0, 1, At, B1); PG8_BAR; PG8_SCHED;
;             PG8_LDA(At, 0, 1); PG8_STAGE(PG8_SB(0, 0), b2, voffB); PG8_STAGE(PG8_SB(0, 1), b2 + hstep, voffB); PG8_STAGE(PG8_SA(0, 0), a2, voffA);
;             PG8_WAIT_V(8); PG8_WAIT_L(0); PG8_BAR; PG8_MMA(1, 0, At, B0); PG8_MMA(1, 1, At, B1); PG8_BAR; PG8_SCHED;
.LBB0_1373:
	ds_read_b128 v[128:131], v189
	ds_read_b128 v[132:135], v189 offset:1024
	ds_read_b128 v[136:139], v189 offset:2048
	ds_read_b128 v[140:143], v189 offset:3072
	ds_read_b128 v[144:147], v190
	ds_read_b128 v[148:151], v190 offset:1024
	ds_read_b128 v[168:171], v190 offset:2048
	ds_read_b128 v[172:175], v190 offset:3072
	s_add_u32 s44, s36, 0x100
	s_addc_u32 s45, s37, 0
	s_cmp_eq_u32 s62, 40
	s_cselect_b32 s49, s13, s45
	s_cselect_b32 s48, s12, s44
	s_cselect_b32 s47, s35, s61
	s_cselect_b32 s46, s34, s43
	v_lshl_add_u64 v[184:185], s[36:37], 0, v[160:161]
	s_add_i32 m0, s74, 0xc000
	ds_read_b128 v[176:179], v191
	ds_read_b128 v[180:183], v191 offset:1024
	ds_read_b128 v[192:195], v191 offset:2048
	ds_read_b128 v[196:199], v191 offset:3072
	ds_read_b128 v[200:203], v191 offset:4096
	ds_read_b128 v[204:207], v191 offset:5120
	ds_read_b128 v[208:211], v191 offset:6144
	ds_read_b128 v[212:215], v191 offset:7168
	global_load_lds_dwordx4 v[184:185], off
	v_lshl_add_u64 v[184:185], s[36:37], 0, v[162:163]
	s_add_i32 m0, s74, 0xe000
	s_nop 0
	global_load_lds_dwordx4 v[184:185], off
	s_waitcnt vmcnt(8)
	s_waitcnt lgkmcnt(0)
	s_barrier
	s_waitcnt lgkmcnt(0)
	v_mfma_f32_16x16x32_bf16 v[124:127], v[128:131], v[176:179], v[124:127]
	v_mfma_f32_16x16x32_bf16 v[120:123], v[136:139], v[176:179], v[120:123]
	v_mfma_f32_16x16x32_bf16 v[108:111], v[128:131], v[192:195], v[108:111]
	v_mfma_f32_16x16x32_bf16 v[104:107], v[136:139], v[192:195], v[104:107]
	v_mfma_f32_16x16x32_bf16 v[92:95], v[128:131], v[200:203], v[92:95]
	v_mfma_f32_16x16x32_bf16 v[88:91], v[136:139], v[200:203], v[88:91]
	v_mfma_f32_16x16x32_bf16 v[76:79], v[128:131], v[208:211], v[76:79]
	v_mfma_f32_16x16x32_bf16 v[72:75], v[136:139], v[208:211], v[72:75]
	v_mfma_f32_16x16x32_bf16 v[124:127], v[132:135], v[180:183], v[124:127]
	v_mfma_f32_16x16x32_bf16 v[120:123], v[140:143], v[180:183], v[120:123]
	v_mfma_f32_16x16x32_bf16 v[108:111], v[132:135], v[196:199], v[108:111]
	v_mfma_f32_16x16x32_bf16 v[104:107], v[140:143], v[196:199], v[104:107]
	v_mfma_f32_16x16x32_bf16 v[92:95], v[132:135], v[204:207], v[92:95]
	v_mfma_f32_16x16x32_bf16 v[88:91], v[140:143], v[204:207], v[88:91]
	v_mfma_f32_16x16x32_bf16 v[76:79], v[132:135], v[212:215], v[76:79]
	v_mfma_f32_16x16x32_bf16 v[72:75], v[140:143], v[212:215], v[72:75]
	v_mfma_f32_16x16x32_bf16 v[116:119], v[144:147], v[176:179], v[116:119]
	v_mfma_f32_16x16x32_bf16 v[112:115], v[168:171], v[176:179], v[112:115]
	v_mfma_f32_16x16x32_bf16 v[100:103], v[144:147], v[192:195], v[100:103]
	v_mfma_f32_16x16x32_bf16 v[96:99], v[168:171], v[192:195], v[96:99]
	v_mfma_f32_16x16x32_bf16 v[84:87], v[144:147], v[200:203], v[84:87]
	v_mfma_f32_16x16x32_bf16 v[80:83], v[168:171], v[200:203], v[80:83]
	v_mfma_f32_16x16x32_bf16 v[68:71], v[144:147], v[208:211], v[68:71]
	v_mfma_f32_16x16x32_bf16 v[64:67], v[168:171], v[208:211], v[64:67]
	v_mfma_f32_16x16x32_bf16 v[116:119], v[148:151], v[180:183], v[116:119]
	v_mfma_f32_16x16x32_bf16 v[112:115], v[172:175], v[180:183], v[112:115]
	v_mfma_f32_16x16x32_bf16 v[100:103], v[148:151], v[196:199], v[100:103]
	v_mfma_f32_16x16x32_bf16 v[96:99], v[172:175], v[196:199], v[96:99]
	v_mfma_f32_16x16x32_bf16 v[84:87], v[148:151], v[204:207], v[84:87]
	v_mfma_f32_16x16x32_bf16 v[80:83], v[172:175], v[204:207], v[80:83]
	v_mfma_f32_16x16x32_bf16 v[68:71], v[148:151], v[212:215], v[68:71]
	v_mfma_f32_16x16x32_bf16 v[64:67], v[172:175], v[212:215], v[64:67]
	s_barrier
	s_add_i32 s36, s56, s68
	v_lshl_add_u64 v[184:185], s[46:47], 0, v[154:155]
	s_mov_b32 m0, s36
	ds_read_b128 v[176:179], v191 offset:16384
	ds_read_b128 v[180:183], v191 offset:17408
	ds_read_b128 v[192:195], v191 offset:18432
	ds_read_b128 v[196:199], v191 offset:19456
	ds_read_b128 v[200:203], v191 offset:20480
	ds_read_b128 v[204:207], v191 offset:21504
	ds_read_b128 v[208:211], v191 offset:22528
	ds_read_b128 v[212:215], v191 offset:23552
	global_load_lds_dwordx4 v[184:185], off
	s_add_i32 m0, s36, 0x2000
	s_add_u32 s36, s46, 0xb0000
	v_lshl_add_u64 v[216:217], s[46:47], 0, v[158:159]
	s_addc_u32 s37, s47, 0
	s_add_i32 s63, s57, s68
	global_load_lds_dwordx4 v[216:217], off
	v_lshl_add_u64 v[218:219], s[36:37], 0, v[154:155]
	s_mov_b32 m0, s63
	v_lshl_add_u64 v[220:221], s[48:49], 0, v[156:157]
	global_load_lds_dwordx4 v[218:219], off
	v_lshl_add_u64 v[218:219], s[36:37], 0, v[158:159]
	s_add_i32 m0, s63, 0x2000
	s_nop 0
	global_load_lds_dwordx4 v[218:219], off
	v_lshl_add_u64 v[218:219], s[48:49], 0, v[152:153]
	s_mov_b32 m0, s74
	s_nop 0
	global_load_lds_dwordx4 v[218:219], off
	s_mov_b32 m0, s41
	s_nop 0
	global_load_lds_dwordx4 v[220:221], off
	s_waitcnt vmcnt(8)
	s_waitcnt lgkmcnt(0)
	s_barrier
; #define PG8_STAGE(bufoff, gbase, voff) do { _Pragma("unroll") for (int _i = 0; _i < 2; ++_i) \
;         __builtin_amdgcn_global_load_lds((const unsigned*)((const char*)(gbase) + (voff)[_i]), (PG8_LAS unsigned*)(lds + (bufoff) + ldsw + _i * 8192), 16, 0, 0); } while (0)
; #define PG8_LDA(dst, b, h) do { _Pragma("unroll") for (int m = 0; m < 4; ++m) _Pragma("unroll") for (int k = 0; k < 2; ++k) dst[m][k] = *(const PG8_LAS bf16x8*)(lds + PG8_SA(b, h) + aoff + m * 2048 + k * 1024); } while (0)
; #define PG8_LDB(dst, b, h) do { _Pragma("unroll") for (int n = 0; n < 2; ++n) _Pragma("unroll") for (int k = 0; k < 2; ++k) dst[n][k] = *(const PG8_LAS bf16x8*)(lds + PG8_SB(b, h) + boff + n * 2048 + k * 1024); } while (0)
; #define PG8_MMA(ai, bj, At, Bt) do { __builtin_amdgcn_s_setprio(1); _Pragma("unroll") for (int m = 0; m < 4; ++m) _Pragma("unroll") for (int n = 0; n < 2; ++n) _Pragma("unroll") for (int k = 0; k < 2; ++k) \
;         acc[ai][bj][m][n] = mma16<F16>(Bt[n][k], At[m][k], acc[ai][bj][m][n]); __builtin_amdgcn_s_setprio(0); } while (0)
; #define PG8_WAIT_V(n) asm volatile("s_waitcnt vmcnt(" #n ")" ::: "memory")
; #define PG8_WAIT_L(n) asm volatile("s_waitcnt lgkmcnt(" #n ")" ::: "memory")
; #define PG8_BAR __builtin_amdgcn_s_barrier()
; #define PG8_SCHED __builtin_amdgcn_sched_barrier(0)
; template <class Epi, class Sched, bool ALIGN_EPI = false, bool SP2 = false, bool F16 = false>
; __device__ __forceinline__ void gemm_phase(PG8_LAS unsigned char* lds, const Gemm g, const Sched& S, const Epi& E, const int wid_in) {
;     ...
;             PG8_WAIT_V(8); PG8_WAIT_L(0); PG8_BAR; PG8_MMA(1, 0, At, B0); PG8_MMA(1, 1, At, B1); PG8_BAR; PG8_SCHED;
;             PG8_LDB(B0, 1, 0); PG8_LDB(B1, 1, 1); PG8_SCHED; PG8_LDA(At, 1, 0); PG8_STAGE(PG8_SA(0, 1), a2 + hstep, voffA);
;             PG8_WAIT_V(8); PG8_WAIT_L(0); PG8_BAR; PG8_MMA(0, 0, At, B0); PG8_MMA(0, 1, At, B1); PG8_BAR; PG8_SCHED;
	s_waitcnt lgkmcnt(0)
	v_mfma_f32_16x16x32_bf16 v[60:63], v[128:131], v[176:179], v[60:63]
	v_mfma_f32_16x16x32_bf16 v[56:59], v[136:139], v[176:179], v[56:59]
	v_mfma_f32_16x16x32_bf16 v[44:47], v[128:131], v[192:195], v[44:47]
	v_mfma_f32_16x16x32_bf16 v[40:43], v[136:139], v[192:195], v[40:43]
	v_mfma_f32_16x16x32_bf16 v[28:31], v[128:131], v[200:203], v[28:31]
	v_mfma_f32_16x16x32_bf16 v[24:27], v[136:139], v[200:203], v[24:27]
	v_mfma_f32_16x16x32_bf16 v[12:15], v[128:131], v[208:211], v[12:15]
	v_mfma_f32_16x16x32_bf16 v[8:11], v[136:139], v[208:211], v[8:11]
	v_mfma_f32_16x16x32_bf16 v[60:63], v[132:135], v[180:183], v[60:63]
	v_mfma_f32_16x16x32_bf16 v[56:59], v[140:143], v[180:183], v[56:59]
	v_mfma_f32_16x16x32_bf16 v[44:47], v[132:135], v[196:199], v[44:47]
	v_mfma_f32_16x16x32_bf16 v[40:43], v[140:143], v[196:199], v[40:43]
	v_mfma_f32_16x16x32_bf16 v[28:31], v[132:135], v[204:207], v[28:31]
	v_mfma_f32_16x16x32_bf16 v[24:27], v[140:143], v[204:207], v[24:27]
	v_mfma_f32_16x16x32_bf16 v[12:15], v[132:135], v[212:215], v[12:15]
	v_mfma_f32_16x16x32_bf16 v[8:11], v[140:143], v[212:215], v[8:11]
	v_mfma_f32_16x16x32_bf16 v[52:55], v[144:147], v[176:179], v[52:55]
	v_mfma_f32_16x16x32_bf16 v[48:51], v[168:171], v[176:179], v[48:51]
	v_mfma_f32_16x16x32_bf16 v[36:39], v[144:147], v[192:195], v[36:39]
	v_mfma_f32_16x16x32_bf16 v[32:35], v[168:171], v[192:195], v[32:35]
	v_mfma_f32_16x16x32_bf16 v[20:23], v[144:147], v[200:203], v[20:23]
	v_mfma_f32_16x16x32_bf16 v[16:19], v[168:171], v[200:203], v[16:19]
	v_mfma_f32_16x16x32_bf16 v[4:7], v[144:147], v[208:211], v[4:7]
	v_mfma_f32_16x16x32_bf16 v[0:3], v[168:171], v[208:211], v[0:3]
	v_mfma_f32_16x16x32_bf16 v[52:55], v[148:151], v[180:183], v[52:55]
	v_mfma_f32_16x16x32_bf16 v[48:51], v[172:175], v[180:183], v[48:51]
	v_mfma_f32_16x16x32_bf16 v[36:39], v[148:151], v[196:199], v[36:39]
	v_mfma_f32_16x16x32_bf16 v[32:35], v[172:175], v[196:199], v[32:35]
	v_mfma_f32_16x16x32_bf16 v[20:23], v[148:151], v[204:207], v[20:23]
	v_mfma_f32_16x16x32_bf16 v[16:19], v[172:175], v[204:207], v[16:19]
	v_mfma_f32_16x16x32_bf16 v[4:7], v[148:151], v[212:215], v[4:7]
	v_mfma_f32_16x16x32_bf16 v[0:3], v[172:175], v[212:215], v[0:3]
	s_barrier
	s_add_i32 s63, 0, 0x18000
	s_add_i32 s64, 0, 0x1c000
	v_add_u32_e32 v140, s63, v188
	v_add_u32_e32 v172, s64, v188
	ds_read_b128 v[128:131], v140
	ds_read_b128 v[132:135], v140 offset:1024
	ds_read_b128 v[136:139], v140 offset:2048
	ds_read_b128 v[140:143], v140 offset:3072
	ds_read_b128 v[144:147], v172
	ds_read_b128 v[148:151], v172 offset:1024
	ds_read_b128 v[168:171], v172 offset:2048
	ds_read_b128 v[172:175], v172 offset:3072
	s_add_u32 s36, s48, 0xb0000
	s_addc_u32 s37, s49, 0
	s_mov_b32 m0, s50
	v_lshl_add_u64 v[222:223], s[36:37], 0, v[152:153]
	ds_read_b128 v[176:179], v191 offset:32768
	ds_read_b128 v[180:183], v191 offset:33792
	ds_read_b128 v[192:195], v191 offset:34816
	ds_read_b128 v[196:199], v191 offset:35840
	ds_read_b128 v[200:203], v191 offset:36864
	ds_read_b128 v[204:207], v191 offset:37888
	ds_read_b128 v[208:211], v191 offset:38912
	ds_read_b128 v[212:215], v191 offset:39936
	global_load_lds_dwordx4 v[222:223], off
	v_lshl_add_u64 v[222:223], s[36:37], 0, v[156:157]
	s_mov_b32 m0, s51
	s_nop 0
	global_load_lds_dwordx4 v[222:223], off
	s_waitcnt vmcnt(8)
	s_waitcnt lgkmcnt(0)
	s_barrier
	s_waitcnt lgkmcnt(0)
	v_mfma_f32_16x16x32_bf16 v[124:127], v[128:131], v[176:179], v[124:127]
	v_mfma_f32_16x16x32_bf16 v[120:123], v[136:139], v[176:179], v[120:123]
	v_mfma_f32_16x16x32_bf16 v[108:111], v[128:131], v[192:195], v[108:111]
	v_mfma_f32_16x16x32_bf16 v[104:107], v[136:139], v[192:195], v[104:107]
	v_mfma_f32_16x16x32_bf16 v[92:95], v[128:131], v[200:203], v[92:95]
	v_mfma_f32_16x16x32_bf16 v[88:91], v[136:139], v[200:203], v[88:91]
	v_mfma_f32_16x16x32_bf16 v[76:79], v[128:131], v[208:211], v[76:79]
	v_mfma_f32_16x16x32_bf16 v[72:75], v[136:139], v[208:211], v[72:75]
	v_mfma_f32_16x16x32_bf16 v[124:127], v[132:135], v[180:183], v[124:127]
	v_mfma_f32_16x16x32_bf16 v[120:123], v[140:143], v[180:183], v[120:123]
	v_mfma_f32_16x16x32_bf16 v[108:111], v[132:135], v[196:199], v[108:111]
	v_mfma_f32_16x16x32_bf16 v[104:107], v[140:143], v[196:199], v[104:107]
	v_mfma_f32_16x16x32_bf16 v[92:95], v[132:135], v[204:207], v[92:95]
	v_mfma_f32_16x16x32_bf16 v[88:91], v[140:143], v[204:207], v[88:91]
	v_mfma_f32_16x16x32_bf16 v[76:79], v[132:135], v[212:215], v[76:79]
	v_mfma_f32_16x16x32_bf16 v[72:75], v[140:143], v[212:215], v[72:75]
	v_mfma_f32_16x16x32_bf16 v[116:119], v[144:147], v[176:179], v[116:119]
	v_mfma_f32_16x16x32_bf16 v[112:115], v[168:171], v[176:179], v[112:115]
	v_mfma_f32_16x16x32_bf16 v[100:103], v[144:147], v[192:195], v[100:103]
	v_mfma_f32_16x16x32_bf16 v[96:99], v[168:171], v[192:195], v[96:99]
	v_mfma_f32_16x16x32_bf16 v[84:87], v[144:147], v[200:203], v[84:87]
	v_mfma_f32_16x16x32_bf16 v[80:83], v[168:171], v[200:203], v[80:83]
	v_mfma_f32_16x16x32_bf16 v[68:71], v[144:147], v[208:211], v[68:71]
	v_mfma_f32_16x16x32_bf16 v[64:67], v[168:171], v[208:211], v[64:67]
	v_mfma_f32_16x16x32_bf16 v[116:119], v[148:151], v[180:183], v[116:119]
	v_mfma_f32_16x16x32_bf16 v[112:115], v[172:175], v[180:183], v[112:115]
	v_mfma_f32_16x16x32_bf16 v[100:103], v[148:151], v[196:199], v[100:103]
	v_mfma_f32_16x16x32_bf16 v[96:99], v[172:175], v[196:199], v[96:99]
	v_mfma_f32_16x16x32_bf16 v[84:87], v[148:151], v[204:207], v[84:87]
	v_mfma_f32_16x16x32_bf16 v[80:83], v[172:175], v[204:207], v[80:83]
	v_mfma_f32_16x16x32_bf16 v[68:71], v[148:151], v[212:215], v[68:71]
	v_mfma_f32_16x16x32_bf16 v[64:67], v[172:175], v[212:215], v[64:67]
	s_barrier
; #define PG8_STAGE(bufoff, gbase, voff) do { _Pragma("unroll") for (int _i = 0; _i < 2; ++_i) \
;         __builtin_amdgcn_global_load_lds((const unsigned*)((const char*)(gbase) + (voff)[_i]), (PG8_LAS unsigned*)(lds + (bufoff) + ldsw + _i * 8192), 16, 0, 0); } while (0)
; #define PG8_LDA(dst, b, h) do { _Pragma("unroll") for (int m = 0; m < 4; ++m) _Pragma("unroll") for (int k = 0; k < 2; ++k) dst[m][k] = *(const PG8_LAS bf16x8*)(lds + PG8_SA(b, h) + aoff + m * 2048 + k * 1024); } while (0)
; #define PG8_MMA(ai, bj, At, Bt) do { __builtin_amdgcn_s_setprio(1); _Pragma("unroll") for (int m = 0; m < 4; ++m) _Pragma("unroll") for (int n = 0; n < 2; ++n) _Pragma("unroll") for (int k = 0; k < 2; ++k) \
;         acc[ai][bj][m][n] = mma16<F16>(Bt[n][k], At[m][k], acc[ai][bj][m][n]); __builtin_amdgcn_s_setprio(0); } while (0)
; #define PG8_WAIT_V(n) asm volatile("s_waitcnt vmcnt(" #n ")" ::: "memory")
; #define PG8_WAIT_L(n) asm volatile("s_waitcnt lgkmcnt(" #n ")" ::: "memory")
; #define PG8_BAR __builtin_amdgcn_s_barrier()
; #define PG8_SCHED __builtin_amdgcn_sched_barrier(0)
; template <class Epi, class Sched, bool ALIGN_EPI = false, bool SP2 = false, bool F16 = false>
; __device__ __forceinline__ void gemm_phase(PG8_LAS unsigned char* lds, const Gemm g, const Sched& S, const Epi& E, const int wid_in) {
;     ...
;             PG8_LDA(At, 1, 1); PG8_STAGE(PG8_SB(1, 0), b3, voffB); PG8_STAGE(PG8_SB(1, 1), b3 + hstep, voffB); PG8_STAGE(PG8_SA(1, 0), a3, voffA);
;             PG8_WAIT_V(8); PG8_WAIT_L(0); PG8_BAR; PG8_MMA(1, 0, At, B0); PG8_MMA(1, 1, At, B1); PG8_BAR; PG8_SCHED;
;     ...
;         if constexpr (ALIGN_EPI) { if (wr == 0) PG8_BAR; }
	s_add_i32 s36, s63, s68
	v_lshl_add_u64 v[184:185], v[184:185], 0, s[30:31]
	s_mov_b32 m0, s36
	ds_read_b128 v[176:179], v191 offset:49152
	ds_read_b128 v[180:183], v191 offset:50176
	ds_read_b128 v[192:195], v191 offset:51200
	ds_read_b128 v[196:199], v191 offset:52224
	ds_read_b128 v[200:203], v191 offset:53248
	ds_read_b128 v[204:207], v191 offset:54272
	ds_read_b128 v[208:211], v191 offset:55296
	ds_read_b128 v[212:215], v191 offset:56320
	global_load_lds_dwordx4 v[184:185], off
	s_add_i32 m0, s36, 0x2000
	s_add_u32 s36, s46, 0xb0080
	v_lshl_add_u64 v[184:185], v[216:217], 0, s[30:31]
	s_addc_u32 s37, s47, 0
	s_add_i32 s46, s64, s68
	global_load_lds_dwordx4 v[184:185], off
	v_lshl_add_u64 v[184:185], s[36:37], 0, v[154:155]
	s_mov_b32 m0, s46
	s_nop 0
	global_load_lds_dwordx4 v[184:185], off
	v_lshl_add_u64 v[184:185], s[36:37], 0, v[158:159]
	s_add_i32 m0, s46, 0x2000
	s_nop 0
	global_load_lds_dwordx4 v[184:185], off
	v_lshl_add_u64 v[184:185], v[218:219], 0, s[30:31]
	s_mov_b32 m0, s75
	s_nop 0
	global_load_lds_dwordx4 v[184:185], off
	v_lshl_add_u64 v[184:185], v[220:221], 0, s[30:31]
	s_mov_b32 m0, s52
	s_nop 0
	global_load_lds_dwordx4 v[184:185], off
	s_waitcnt vmcnt(8)
	s_waitcnt lgkmcnt(0)
	s_barrier
	s_waitcnt lgkmcnt(0)
	v_mfma_f32_16x16x32_bf16 v[60:63], v[128:131], v[176:179], v[60:63]
	v_mfma_f32_16x16x32_bf16 v[56:59], v[136:139], v[176:179], v[56:59]
	v_mfma_f32_16x16x32_bf16 v[44:47], v[128:131], v[192:195], v[44:47]
	v_mfma_f32_16x16x32_bf16 v[40:43], v[136:139], v[192:195], v[40:43]
	v_mfma_f32_16x16x32_bf16 v[28:31], v[128:131], v[200:203], v[28:31]
	v_mfma_f32_16x16x32_bf16 v[24:27], v[136:139], v[200:203], v[24:27]
	v_mfma_f32_16x16x32_bf16 v[12:15], v[128:131], v[208:211], v[12:15]
	v_mfma_f32_16x16x32_bf16 v[8:11], v[136:139], v[208:211], v[8:11]
	v_mfma_f32_16x16x32_bf16 v[60:63], v[132:135], v[180:183], v[60:63]
	v_mfma_f32_16x16x32_bf16 v[56:59], v[140:143], v[180:183], v[56:59]
	v_mfma_f32_16x16x32_bf16 v[44:47], v[132:135], v[196:199], v[44:47]
	v_mfma_f32_16x16x32_bf16 v[40:43], v[140:143], v[196:199], v[40:43]
	v_mfma_f32_16x16x32_bf16 v[28:31], v[132:135], v[204:207], v[28:31]
	v_mfma_f32_16x16x32_bf16 v[24:27], v[140:143], v[204:207], v[24:27]
	v_mfma_f32_16x16x32_bf16 v[12:15], v[132:135], v[212:215], v[12:15]
	v_mfma_f32_16x16x32_bf16 v[8:11], v[140:143], v[212:215], v[8:11]
	v_mfma_f32_16x16x32_bf16 v[52:55], v[144:147], v[176:179], v[52:55]
	v_mfma_f32_16x16x32_bf16 v[48:51], v[168:171], v[176:179], v[48:51]
	v_mfma_f32_16x16x32_bf16 v[36:39], v[144:147], v[192:195], v[36:39]
	v_mfma_f32_16x16x32_bf16 v[32:35], v[168:171], v[192:195], v[32:35]
	v_mfma_f32_16x16x32_bf16 v[20:23], v[144:147], v[200:203], v[20:23]
	v_mfma_f32_16x16x32_bf16 v[16:19], v[168:171], v[200:203], v[16:19]
	v_mfma_f32_16x16x32_bf16 v[4:7], v[144:147], v[208:211], v[4:7]
	v_mfma_f32_16x16x32_bf16 v[0:3], v[168:171], v[208:211], v[0:3]
	v_mfma_f32_16x16x32_bf16 v[52:55], v[148:151], v[180:183], v[52:55]
	v_mfma_f32_16x16x32_bf16 v[48:51], v[172:175], v[180:183], v[48:51]
	v_mfma_f32_16x16x32_bf16 v[36:39], v[148:151], v[196:199], v[36:39]
	v_mfma_f32_16x16x32_bf16 v[32:35], v[172:175], v[196:199], v[32:35]
	v_mfma_f32_16x16x32_bf16 v[20:23], v[148:151], v[204:207], v[20:23]
	v_mfma_f32_16x16x32_bf16 v[16:19], v[172:175], v[204:207], v[16:19]
	v_mfma_f32_16x16x32_bf16 v[4:7], v[148:151], v[212:215], v[4:7]
	v_mfma_f32_16x16x32_bf16 v[0:3], v[172:175], v[212:215], v[0:3]
	s_barrier
	s_add_i32 s62, s62, 2
	s_add_u32 s43, s43, 0x100
	s_addc_u32 s61, s61, 0
	s_cmp_gt_u32 s62, 41
	s_mov_b64 s[36:37], s[44:45]
	s_cbranch_scc0 .LBB0_1373
	s_and_b64 vcc, exec, s[16:17]
	s_cbranch_vccz .LBB0_1376
	s_barrier

; #define PG8_STAGE(bufoff, gbase, voff) do { _Pragma("unroll") for (int _i = 0; _i < 2; ++_i) \
;         __builtin_amdgcn_global_load_lds((const unsigned*)((const char*)(gbase) + (voff)[_i]), (PG8_LAS unsigned*)(lds + (bufoff) + ldsw + _i * 8192), 16, 0, 0); } while (0)
; #define PG8_LDA(dst, b, h) do { _Pragma("unroll") for (int m = 0; m < 4; ++m) _Pragma("unroll") for (int k = 0; k < 2; ++k) dst[m][k] = *(const PG8_LAS bf16x8*)(lds + PG8_SA(b, h) + aoff + m * 2048 + k * 1024); } while (0)
; #define PG8_LDB(dst, b, h) do { _Pragma("unroll") for (int n = 0; n < 2; ++n) _Pragma("unroll") for (int k = 0; k < 2; ++k) dst[n][k] = *(const PG8_LAS bf16x8*)(lds + PG8_SB(b, h) + boff + n * 2048 + k * 1024); } while (0)
; #define PG8_MMA(ai, bj, At, Bt) do { __builtin_amdgcn_s_setprio(1); _Pragma("unroll") for (int m = 0; m < 4; ++m) _Pragma("unroll") for (int n = 0; n < 2; ++n) _Pragma("unroll") for (int k = 0; k < 2; ++k) \
;         acc[ai][bj][m][n] = mma16<F16>(Bt[n][k], At[m][k], acc[ai][bj][m][n]); __builtin_amdgcn_s_setprio(0); } while (0)
; #define PG8_WAIT_V(n) asm volatile("s_waitcnt vmcnt(" #n ")" ::: "memory")
; #define PG8_WAIT_L(n) asm volatile("s_waitcnt lgkmcnt(" #n ")" ::: "memory")
; template <class Epi, class Sched, bool ALIGN_EPI = false, bool SP2 = false, bool F16 = false>
; __device__ __forceinline__ void gemm_phase(PG8_LAS unsigned char* lds, const Gemm g, const Sched& S, const Epi& E, const int wid_in) {
;     ...
;             const bool last = (t == nt - 2);
;             const char* a1 = cA + (size_t)(t + 1) * kstep;
;             const char* a2 = last ? nA : cA + (size_t)(t + 2) * kstep; const char* b2 = last ? nB : cB + (size_t)(t + 2) * kstep;
;             const char* a3 = a2 + kstep; const char* b3 = b2 + kstep;
;             if (last && has_next) S.a_ready(nxt);
;             if constexpr (SP2) {
;             PG8_LDB(B0, 0, 0); PG8_LDB(B1, 0, 1); PG8_SCHED; PG8_LDA(At, 0, 0); PG8_STAGE(PG8_SA(1, 1), a1 + hstep, voffA);
;             PG8_WAIT_V(8); PG8_WAIT_L(0); PG8_BAR; PG8_MMA(0, 0, At, B0); PG8_MMA(0, 1, At, B1); PG8_BAR; PG8_SCHED;
;             PG8_LDA(At, 0, 1); PG8_STAGE(PG8_SB(0, 0), b2, voffB); PG8_STAGE(PG8_SB(0, 1), b2 + hstep, voffB); PG8_STAGE(PG8_SA(0, 0), a2, voffA);
;             PG8_WAIT_V(8); PG8_WAIT_L(0); PG8_BAR; PG8_MMA(1, 0, At, B0); PG8_MMA(1, 1, At, B1); PG8_BAR; PG8_SCHED;
.LBB0_1469:
	ds_read_b128 v[112:115], v235
	ds_read_b128 v[116:119], v235 offset:1024
	ds_read_b128 v[128:131], v235 offset:2048
	ds_read_b128 v[132:135], v235 offset:3072
	ds_read_b128 v[144:147], v236
	ds_read_b128 v[148:151], v236 offset:1024
	ds_read_b128 v[152:155], v236 offset:2048
	ds_read_b128 v[156:159], v236 offset:3072
	s_add_u32 s45, s52, 0xfffc0080
	s_addc_u32 s51, s53, -1
	s_cmp_eq_u32 s43, 12
	s_cselect_b32 s57, s14, s51
	s_cselect_b32 s56, s15, s45
	s_cselect_b32 s55, s37, s42
	s_cselect_b32 s54, s40, s41
	v_lshl_add_u64 v[192:193], s[52:53], 0, v[204:205]
	s_add_i32 m0, s74, 0xc000
	ds_read_b128 v[160:163], v237
	ds_read_b128 v[164:167], v237 offset:1024
	ds_read_b128 v[168:171], v237 offset:2048
	ds_read_b128 v[172:175], v237 offset:3072
	ds_read_b128 v[176:179], v237 offset:4096
	ds_read_b128 v[180:183], v237 offset:5120
	ds_read_b128 v[184:187], v237 offset:6144
	ds_read_b128 v[188:191], v237 offset:7168
	global_load_lds_dwordx4 v[192:193], off
	v_lshl_add_u64 v[192:193], s[52:53], 0, v[206:207]
	s_add_i32 m0, s74, 0xe000
	s_nop 0
	global_load_lds_dwordx4 v[192:193], off
	s_waitcnt vmcnt(8)
	s_waitcnt lgkmcnt(0)
	s_barrier
	s_waitcnt lgkmcnt(0)
	v_mfma_f32_16x16x32_f16 v[140:143], v[112:115], v[160:163], v[140:143]
	v_mfma_f32_16x16x32_f16 v[136:139], v[128:131], v[160:163], v[136:139]
	v_mfma_f32_16x16x32_f16 v[108:111], v[112:115], v[168:171], v[108:111]
	v_mfma_f32_16x16x32_f16 v[104:107], v[128:131], v[168:171], v[104:107]
	v_mfma_f32_16x16x32_f16 v[92:95], v[112:115], v[176:179], v[92:95]
	v_mfma_f32_16x16x32_f16 v[88:91], v[128:131], v[176:179], v[88:91]
	v_mfma_f32_16x16x32_f16 v[76:79], v[112:115], v[184:187], v[76:79]
	v_mfma_f32_16x16x32_f16 v[72:75], v[128:131], v[184:187], v[72:75]
	v_mfma_f32_16x16x32_f16 v[140:143], v[116:119], v[164:167], v[140:143]
	v_mfma_f32_16x16x32_f16 v[136:139], v[132:135], v[164:167], v[136:139]
	v_mfma_f32_16x16x32_f16 v[108:111], v[116:119], v[172:175], v[108:111]
	v_mfma_f32_16x16x32_f16 v[104:107], v[132:135], v[172:175], v[104:107]
	v_mfma_f32_16x16x32_f16 v[92:95], v[116:119], v[180:183], v[92:95]
	v_mfma_f32_16x16x32_f16 v[88:91], v[132:135], v[180:183], v[88:91]
	v_mfma_f32_16x16x32_f16 v[76:79], v[116:119], v[188:191], v[76:79]
	v_mfma_f32_16x16x32_f16 v[72:75], v[132:135], v[188:191], v[72:75]
	v_mfma_f32_16x16x32_f16 v[124:127], v[144:147], v[160:163], v[124:127]
	v_mfma_f32_16x16x32_f16 v[120:123], v[152:155], v[160:163], v[120:123]
	v_mfma_f32_16x16x32_f16 v[100:103], v[144:147], v[168:171], v[100:103]
	v_mfma_f32_16x16x32_f16 v[96:99], v[152:155], v[168:171], v[96:99]
	v_mfma_f32_16x16x32_f16 v[84:87], v[144:147], v[176:179], v[84:87]
	v_mfma_f32_16x16x32_f16 v[80:83], v[152:155], v[176:179], v[80:83]
	v_mfma_f32_16x16x32_f16 v[68:71], v[144:147], v[184:187], v[68:71]
	v_mfma_f32_16x16x32_f16 v[64:67], v[152:155], v[184:187], v[64:67]
	v_mfma_f32_16x16x32_f16 v[124:127], v[148:151], v[164:167], v[124:127]
	v_mfma_f32_16x16x32_f16 v[120:123], v[156:159], v[164:167], v[120:123]
	v_mfma_f32_16x16x32_f16 v[100:103], v[148:151], v[172:175], v[100:103]
	v_mfma_f32_16x16x32_f16 v[96:99], v[156:159], v[172:175], v[96:99]
	v_mfma_f32_16x16x32_f16 v[84:87], v[148:151], v[180:183], v[84:87]
	v_mfma_f32_16x16x32_f16 v[80:83], v[156:159], v[180:183], v[80:83]
	v_mfma_f32_16x16x32_f16 v[68:71], v[148:151], v[188:191], v[68:71]
	v_mfma_f32_16x16x32_f16 v[64:67], v[156:159], v[188:191], v[64:67]
	s_barrier
	s_add_i32 s45, s66, s68
	v_lshl_add_u64 v[192:193], s[54:55], 0, v[198:199]
	s_mov_b32 m0, s45
	ds_read_b128 v[160:163], v237 offset:16384
	ds_read_b128 v[164:167], v237 offset:17408
	ds_read_b128 v[168:171], v237 offset:18432
	ds_read_b128 v[172:175], v237 offset:19456
	ds_read_b128 v[176:179], v237 offset:20480
	ds_read_b128 v[180:183], v237 offset:21504
	ds_read_b128 v[184:187], v237 offset:22528
	ds_read_b128 v[188:191], v237 offset:23552
	global_load_lds_dwordx4 v[192:193], off
	s_add_i32 m0, s45, 0x2000
	s_add_u32 s94, s54, 0x40000
	v_lshl_add_u64 v[194:195], s[54:55], 0, v[202:203]
	s_addc_u32 s95, s55, 0
	s_add_i32 s45, s67, s68
	global_load_lds_dwordx4 v[194:195], off
	v_lshl_add_u64 v[212:213], s[94:95], 0, v[198:199]
	s_mov_b32 m0, s45
	v_lshl_add_u64 v[214:215], s[56:57], 0, v[200:201]
	global_load_lds_dwordx4 v[212:213], off
	v_lshl_add_u64 v[212:213], s[94:95], 0, v[202:203]
	s_add_i32 m0, s45, 0x2000
	s_nop 0
	global_load_lds_dwordx4 v[212:213], off
	v_lshl_add_u64 v[212:213], s[56:57], 0, v[196:197]
	s_mov_b32 m0, s74
	s_nop 0
	global_load_lds_dwordx4 v[212:213], off
	s_mov_b32 m0, s59
	s_nop 0
	global_load_lds_dwordx4 v[214:215], off
	s_waitcnt vmcnt(8)
	s_waitcnt lgkmcnt(0)
	s_barrier
; #define PG8_STAGE(bufoff, gbase, voff) do { _Pragma("unroll") for (int _i = 0; _i < 2; ++_i) \
;         __builtin_amdgcn_global_load_lds((const unsigned*)((const char*)(gbase) + (voff)[_i]), (PG8_LAS unsigned*)(lds + (bufoff) + ldsw + _i * 8192), 16, 0, 0); } while (0)
; #define PG8_LDA(dst, b, h) do { _Pragma("unroll") for (int m = 0; m < 4; ++m) _Pragma("unroll") for (int k = 0; k < 2; ++k) dst[m][k] = *(const PG8_LAS bf16x8*)(lds + PG8_SA(b, h) + aoff + m * 2048 + k * 1024); } while (0)
; #define PG8_LDB(dst, b, h) do { _Pragma("unroll") for (int n = 0; n < 2; ++n) _Pragma("unroll") for (int k = 0; k < 2; ++k) dst[n][k] = *(const PG8_LAS bf16x8*)(lds + PG8_SB(b, h) + boff + n * 2048 + k * 1024); } while (0)
; #define PG8_MMA(ai, bj, At, Bt) do { __builtin_amdgcn_s_setprio(1); _Pragma("unroll") for (int m = 0; m < 4; ++m) _Pragma("unroll") for (int n = 0; n < 2; ++n) _Pragma("unroll") for (int k = 0; k < 2; ++k) \
;         acc[ai][bj][m][n] = mma16<F16>(Bt[n][k], At[m][k], acc[ai][bj][m][n]); __builtin_amdgcn_s_setprio(0); } while (0)
; #define PG8_WAIT_V(n) asm volatile("s_waitcnt vmcnt(" #n ")" ::: "memory")
; #define PG8_WAIT_L(n) asm volatile("s_waitcnt lgkmcnt(" #n ")" ::: "memory")
; #define PG8_BAR __builtin_amdgcn_s_barrier()
; #define PG8_SCHED __builtin_amdgcn_sched_barrier(0)
; template <class Epi, class Sched, bool ALIGN_EPI = false, bool SP2 = false, bool F16 = false>
; __device__ __forceinline__ void gemm_phase(PG8_LAS unsigned char* lds, const Gemm g, const Sched& S, const Epi& E, const int wid_in) {
;     ...
;             PG8_WAIT_V(8); PG8_WAIT_L(0); PG8_BAR; PG8_MMA(1, 0, At, B0); PG8_MMA(1, 1, At, B1); PG8_BAR; PG8_SCHED;
;             PG8_LDB(B0, 1, 0); PG8_LDB(B1, 1, 1); PG8_SCHED; PG8_LDA(At, 1, 0); PG8_STAGE(PG8_SA(0, 1), a2 + hstep, voffA);
;             PG8_WAIT_V(8); PG8_WAIT_L(0); PG8_BAR; PG8_MMA(0, 0, At, B0); PG8_MMA(0, 1, At, B1); PG8_BAR; PG8_SCHED;
	s_waitcnt lgkmcnt(0)
	v_mfma_f32_16x16x32_f16 v[60:63], v[112:115], v[160:163], v[60:63]
	v_mfma_f32_16x16x32_f16 v[56:59], v[128:131], v[160:163], v[56:59]
	v_mfma_f32_16x16x32_f16 v[44:47], v[112:115], v[168:171], v[44:47]
	v_mfma_f32_16x16x32_f16 v[40:43], v[128:131], v[168:171], v[40:43]
	v_mfma_f32_16x16x32_f16 v[28:31], v[112:115], v[176:179], v[28:31]
	v_mfma_f32_16x16x32_f16 v[24:27], v[128:131], v[176:179], v[24:27]
	v_mfma_f32_16x16x32_f16 v[12:15], v[112:115], v[184:187], v[12:15]
	v_mfma_f32_16x16x32_f16 v[8:11], v[128:131], v[184:187], v[8:11]
	v_mfma_f32_16x16x32_f16 v[60:63], v[116:119], v[164:167], v[60:63]
	v_mfma_f32_16x16x32_f16 v[56:59], v[132:135], v[164:167], v[56:59]
	v_mfma_f32_16x16x32_f16 v[44:47], v[116:119], v[172:175], v[44:47]
	v_mfma_f32_16x16x32_f16 v[40:43], v[132:135], v[172:175], v[40:43]
	v_mfma_f32_16x16x32_f16 v[28:31], v[116:119], v[180:183], v[28:31]
	v_mfma_f32_16x16x32_f16 v[24:27], v[132:135], v[180:183], v[24:27]
	v_mfma_f32_16x16x32_f16 v[12:15], v[116:119], v[188:191], v[12:15]
	v_mfma_f32_16x16x32_f16 v[8:11], v[132:135], v[188:191], v[8:11]
	v_mfma_f32_16x16x32_f16 v[52:55], v[144:147], v[160:163], v[52:55]
	v_mfma_f32_16x16x32_f16 v[48:51], v[152:155], v[160:163], v[48:51]
	v_mfma_f32_16x16x32_f16 v[36:39], v[144:147], v[168:171], v[36:39]
	v_mfma_f32_16x16x32_f16 v[32:35], v[152:155], v[168:171], v[32:35]
	v_mfma_f32_16x16x32_f16 v[20:23], v[144:147], v[176:179], v[20:23]
	v_mfma_f32_16x16x32_f16 v[16:19], v[152:155], v[176:179], v[16:19]
	v_mfma_f32_16x16x32_f16 v[4:7], v[144:147], v[184:187], v[4:7]
	v_mfma_f32_16x16x32_f16 v[0:3], v[152:155], v[184:187], v[0:3]
	v_mfma_f32_16x16x32_f16 v[52:55], v[148:151], v[164:167], v[52:55]
	v_mfma_f32_16x16x32_f16 v[48:51], v[156:159], v[164:167], v[48:51]
	v_mfma_f32_16x16x32_f16 v[36:39], v[148:151], v[172:175], v[36:39]
	v_mfma_f32_16x16x32_f16 v[32:35], v[156:159], v[172:175], v[32:35]
	v_mfma_f32_16x16x32_f16 v[20:23], v[148:151], v[180:183], v[20:23]
	v_mfma_f32_16x16x32_f16 v[16:19], v[156:159], v[180:183], v[16:19]
	v_mfma_f32_16x16x32_f16 v[4:7], v[148:151], v[188:191], v[4:7]
	v_mfma_f32_16x16x32_f16 v[0:3], v[156:159], v[188:191], v[0:3]
	s_barrier
	s_add_i32 s45, 0, 0x18000
	s_add_i32 s51, 0, 0x1c000
	v_add_u32_e32 v132, s45, v234
	v_add_u32_e32 v156, s51, v234
	ds_read_b128 v[112:115], v132
	ds_read_b128 v[116:119], v132 offset:1024
	ds_read_b128 v[128:131], v132 offset:2048
	ds_read_b128 v[132:135], v132 offset:3072
	ds_read_b128 v[144:147], v156
	ds_read_b128 v[148:151], v156 offset:1024
	ds_read_b128 v[152:155], v156 offset:2048
	ds_read_b128 v[156:159], v156 offset:3072
	s_add_u32 s56, s56, 0x40000
	s_addc_u32 s57, s57, 0
	s_mov_b32 m0, s60
	v_lshl_add_u64 v[216:217], s[56:57], 0, v[196:197]
	ds_read_b128 v[160:163], v237 offset:32768
	ds_read_b128 v[164:167], v237 offset:33792
	ds_read_b128 v[168:171], v237 offset:34816
	ds_read_b128 v[172:175], v237 offset:35840
	ds_read_b128 v[176:179], v237 offset:36864
	ds_read_b128 v[180:183], v237 offset:37888
	ds_read_b128 v[184:187], v237 offset:38912
	ds_read_b128 v[188:191], v237 offset:39936
	global_load_lds_dwordx4 v[216:217], off
	v_lshl_add_u64 v[216:217], s[56:57], 0, v[200:201]
	s_mov_b32 m0, s61
	s_nop 0
	global_load_lds_dwordx4 v[216:217], off
	s_waitcnt vmcnt(8)
	s_waitcnt lgkmcnt(0)
	s_barrier
	s_waitcnt lgkmcnt(0)
	v_mfma_f32_16x16x32_f16 v[140:143], v[112:115], v[160:163], v[140:143]
	v_mfma_f32_16x16x32_f16 v[136:139], v[128:131], v[160:163], v[136:139]
	v_mfma_f32_16x16x32_f16 v[108:111], v[112:115], v[168:171], v[108:111]
	v_mfma_f32_16x16x32_f16 v[104:107], v[128:131], v[168:171], v[104:107]
	v_mfma_f32_16x16x32_f16 v[92:95], v[112:115], v[176:179], v[92:95]
	v_mfma_f32_16x16x32_f16 v[88:91], v[128:131], v[176:179], v[88:91]
	v_mfma_f32_16x16x32_f16 v[76:79], v[112:115], v[184:187], v[76:79]
	v_mfma_f32_16x16x32_f16 v[72:75], v[128:131], v[184:187], v[72:75]
	v_mfma_f32_16x16x32_f16 v[140:143], v[116:119], v[164:167], v[140:143]
	v_mfma_f32_16x16x32_f16 v[136:139], v[132:135], v[164:167], v[136:139]
	v_mfma_f32_16x16x32_f16 v[108:111], v[116:119], v[172:175], v[108:111]
	v_mfma_f32_16x16x32_f16 v[104:107], v[132:135], v[172:175], v[104:107]
	v_mfma_f32_16x16x32_f16 v[92:95], v[116:119], v[180:183], v[92:95]
	v_mfma_f32_16x16x32_f16 v[88:91], v[132:135], v[180:183], v[88:91]
	v_mfma_f32_16x16x32_f16 v[76:79], v[116:119], v[188:191], v[76:79]
	v_mfma_f32_16x16x32_f16 v[72:75], v[132:135], v[188:191], v[72:75]
	v_mfma_f32_16x16x32_f16 v[124:127], v[144:147], v[160:163], v[124:127]
	v_mfma_f32_16x16x32_f16 v[120:123], v[152:155], v[160:163], v[120:123]
	v_mfma_f32_16x16x32_f16 v[100:103], v[144:147], v[168:171], v[100:103]
	v_mfma_f32_16x16x32_f16 v[96:99], v[152:155], v[168:171], v[96:99]
	v_mfma_f32_16x16x32_f16 v[84:87], v[144:147], v[176:179], v[84:87]
	v_mfma_f32_16x16x32_f16 v[80:83], v[152:155], v[176:179], v[80:83]
	v_mfma_f32_16x16x32_f16 v[68:71], v[144:147], v[184:187], v[68:71]
	v_mfma_f32_16x16x32_f16 v[64:67], v[152:155], v[184:187], v[64:67]
	v_mfma_f32_16x16x32_f16 v[124:127], v[148:151], v[164:167], v[124:127]
	v_mfma_f32_16x16x32_f16 v[120:123], v[156:159], v[164:167], v[120:123]
	v_mfma_f32_16x16x32_f16 v[100:103], v[148:151], v[172:175], v[100:103]
	v_mfma_f32_16x16x32_f16 v[96:99], v[156:159], v[172:175], v[96:99]
	v_mfma_f32_16x16x32_f16 v[84:87], v[148:151], v[180:183], v[84:87]
	v_mfma_f32_16x16x32_f16 v[80:83], v[156:159], v[180:183], v[80:83]
	v_mfma_f32_16x16x32_f16 v[68:71], v[148:151], v[188:191], v[68:71]
	v_mfma_f32_16x16x32_f16 v[64:67], v[156:159], v[188:191], v[64:67]
	s_barrier
; #define PG8_STAGE(bufoff, gbase, voff) do { _Pragma("unroll") for (int _i = 0; _i < 2; ++_i) \
;         __builtin_amdgcn_global_load_lds((const unsigned*)((const char*)(gbase) + (voff)[_i]), (PG8_LAS unsigned*)(lds + (bufoff) + ldsw + _i * 8192), 16, 0, 0); } while (0)
; #define PG8_LDA(dst, b, h) do { _Pragma("unroll") for (int m = 0; m < 4; ++m) _Pragma("unroll") for (int k = 0; k < 2; ++k) dst[m][k] = *(const PG8_LAS bf16x8*)(lds + PG8_SA(b, h) + aoff + m * 2048 + k * 1024); } while (0)
; #define PG8_MMA(ai, bj, At, Bt) do { __builtin_amdgcn_s_setprio(1); _Pragma("unroll") for (int m = 0; m < 4; ++m) _Pragma("unroll") for (int n = 0; n < 2; ++n) _Pragma("unroll") for (int k = 0; k < 2; ++k) \
;         acc[ai][bj][m][n] = mma16<F16>(Bt[n][k], At[m][k], acc[ai][bj][m][n]); __builtin_amdgcn_s_setprio(0); } while (0)
; #define PG8_WAIT_V(n) asm volatile("s_waitcnt vmcnt(" #n ")" ::: "memory")
; #define PG8_WAIT_L(n) asm volatile("s_waitcnt lgkmcnt(" #n ")" ::: "memory")
; #define PG8_BAR __builtin_amdgcn_s_barrier()
; #define PG8_SCHED __builtin_amdgcn_sched_barrier(0)
; template <class Epi, class Sched, bool ALIGN_EPI = false, bool SP2 = false, bool F16 = false>
; __device__ __forceinline__ void gemm_phase(PG8_LAS unsigned char* lds, const Gemm g, const Sched& S, const Epi& E, const int wid_in) {
;     ...
;             PG8_LDA(At, 1, 1); PG8_STAGE(PG8_SB(1, 0), b3, voffB); PG8_STAGE(PG8_SB(1, 1), b3 + hstep, voffB); PG8_STAGE(PG8_SA(1, 0), a3, voffA);
;             PG8_WAIT_V(8); PG8_WAIT_L(0); PG8_BAR; PG8_MMA(1, 0, At, B0); PG8_MMA(1, 1, At, B1); PG8_BAR; PG8_SCHED;
;     ...
;         if constexpr (ALIGN_EPI) { if (wr == 0) PG8_BAR; }
	s_add_i32 s45, s45, s68
	v_lshl_add_u64 v[192:193], v[192:193], 0, s[34:35]
	s_mov_b32 m0, s45
	ds_read_b128 v[160:163], v237 offset:49152
	ds_read_b128 v[164:167], v237 offset:50176
	ds_read_b128 v[168:171], v237 offset:51200
	ds_read_b128 v[172:175], v237 offset:52224
	ds_read_b128 v[176:179], v237 offset:53248
	ds_read_b128 v[180:183], v237 offset:54272
	ds_read_b128 v[184:187], v237 offset:55296
	ds_read_b128 v[188:191], v237 offset:56320
	global_load_lds_dwordx4 v[192:193], off
	s_add_i32 m0, s45, 0x2000
	s_add_u32 s54, s54, 0x40080
	v_lshl_add_u64 v[192:193], v[194:195], 0, s[34:35]
	s_addc_u32 s55, s55, 0
	s_add_i32 s45, s51, s68
	global_load_lds_dwordx4 v[192:193], off
	v_lshl_add_u64 v[192:193], s[54:55], 0, v[198:199]
	s_mov_b32 m0, s45
	s_nop 0
	global_load_lds_dwordx4 v[192:193], off
	v_lshl_add_u64 v[192:193], s[54:55], 0, v[202:203]
	s_add_i32 m0, s45, 0x2000
	s_nop 0
	global_load_lds_dwordx4 v[192:193], off
	v_lshl_add_u64 v[192:193], v[212:213], 0, s[34:35]
	s_mov_b32 m0, s75
	s_nop 0
	global_load_lds_dwordx4 v[192:193], off
	v_lshl_add_u64 v[192:193], v[214:215], 0, s[34:35]
	s_mov_b32 m0, s62
	s_nop 0
	global_load_lds_dwordx4 v[192:193], off
	s_waitcnt vmcnt(8)
	s_waitcnt lgkmcnt(0)
	s_barrier
	s_waitcnt lgkmcnt(0)
	v_mfma_f32_16x16x32_f16 v[60:63], v[112:115], v[160:163], v[60:63]
	v_mfma_f32_16x16x32_f16 v[56:59], v[128:131], v[160:163], v[56:59]
	v_mfma_f32_16x16x32_f16 v[44:47], v[112:115], v[168:171], v[44:47]
	v_mfma_f32_16x16x32_f16 v[40:43], v[128:131], v[168:171], v[40:43]
	v_mfma_f32_16x16x32_f16 v[28:31], v[112:115], v[176:179], v[28:31]
	v_mfma_f32_16x16x32_f16 v[24:27], v[128:131], v[176:179], v[24:27]
	v_mfma_f32_16x16x32_f16 v[12:15], v[112:115], v[184:187], v[12:15]
	v_mfma_f32_16x16x32_f16 v[8:11], v[128:131], v[184:187], v[8:11]
	v_mfma_f32_16x16x32_f16 v[60:63], v[116:119], v[164:167], v[60:63]
	v_mfma_f32_16x16x32_f16 v[56:59], v[132:135], v[164:167], v[56:59]
	v_mfma_f32_16x16x32_f16 v[44:47], v[116:119], v[172:175], v[44:47]
	v_mfma_f32_16x16x32_f16 v[40:43], v[132:135], v[172:175], v[40:43]
	v_mfma_f32_16x16x32_f16 v[28:31], v[116:119], v[180:183], v[28:31]
	v_mfma_f32_16x16x32_f16 v[24:27], v[132:135], v[180:183], v[24:27]
	v_mfma_f32_16x16x32_f16 v[12:15], v[116:119], v[188:191], v[12:15]
	v_mfma_f32_16x16x32_f16 v[8:11], v[132:135], v[188:191], v[8:11]
	v_mfma_f32_16x16x32_f16 v[52:55], v[144:147], v[160:163], v[52:55]
	v_mfma_f32_16x16x32_f16 v[48:51], v[152:155], v[160:163], v[48:51]
	v_mfma_f32_16x16x32_f16 v[36:39], v[144:147], v[168:171], v[36:39]
	v_mfma_f32_16x16x32_f16 v[32:35], v[152:155], v[168:171], v[32:35]
	v_mfma_f32_16x16x32_f16 v[20:23], v[144:147], v[176:179], v[20:23]
	v_mfma_f32_16x16x32_f16 v[16:19], v[152:155], v[176:179], v[16:19]
	v_mfma_f32_16x16x32_f16 v[4:7], v[144:147], v[184:187], v[4:7]
	v_mfma_f32_16x16x32_f16 v[0:3], v[152:155], v[184:187], v[0:3]
	v_mfma_f32_16x16x32_f16 v[52:55], v[148:151], v[164:167], v[52:55]
	v_mfma_f32_16x16x32_f16 v[48:51], v[156:159], v[164:167], v[48:51]
	v_mfma_f32_16x16x32_f16 v[36:39], v[148:151], v[172:175], v[36:39]
	v_mfma_f32_16x16x32_f16 v[32:35], v[156:159], v[172:175], v[32:35]
	v_mfma_f32_16x16x32_f16 v[20:23], v[148:151], v[180:183], v[20:23]
	v_mfma_f32_16x16x32_f16 v[16:19], v[156:159], v[180:183], v[16:19]
	v_mfma_f32_16x16x32_f16 v[4:7], v[148:151], v[188:191], v[4:7]
	v_mfma_f32_16x16x32_f16 v[0:3], v[156:159], v[188:191], v[0:3]
	s_barrier
	s_add_i32 s43, s43, 2
	s_add_u32 s52, s52, 0x100
	s_addc_u32 s53, s53, 0
	s_add_u32 s41, s41, 0x100
	s_addc_u32 s42, s42, 0
	s_cmp_gt_u32 s43, 13
	s_cbranch_scc0 .LBB0_1469
	s_and_b64 vcc, exec, s[16:17]
	s_cbranch_vccz .LBB0_1472
	s_barrier

; #define PG8_STAGE(bufoff, gbase, voff) do { _Pragma("unroll") for (int _i = 0; _i < 2; ++_i) \
;         __builtin_amdgcn_global_load_lds((const unsigned*)((const char*)(gbase) + (voff)[_i]), (PG8_LAS unsigned*)(lds + (bufoff) + ldsw + _i * 8192), 16, 0, 0); } while (0)
; #define PG8_LDA(dst, b, h) do { _Pragma("unroll") for (int m = 0; m < 4; ++m) _Pragma("unroll") for (int k = 0; k < 2; ++k) dst[m][k] = *(const PG8_LAS bf16x8*)(lds + PG8_SA(b, h) + aoff + m * 2048 + k * 1024); } while (0)
; #define PG8_LDB(dst, b, h) do { _Pragma("unroll") for (int n = 0; n < 2; ++n) _Pragma("unroll") for (int k = 0; k < 2; ++k) dst[n][k] = *(const PG8_LAS bf16x8*)(lds + PG8_SB(b, h) + boff + n * 2048 + k * 1024); } while (0)
; #define PG8_MMA(ai, bj, At, Bt) do { __builtin_amdgcn_s_setprio(1); _Pragma("unroll") for (int m = 0; m < 4; ++m) _Pragma("unroll") for (int n = 0; n < 2; ++n) _Pragma("unroll") for (int k = 0; k < 2; ++k) \
;         acc[ai][bj][m][n] = mma16<F16>(Bt[n][k], At[m][k], acc[ai][bj][m][n]); __builtin_amdgcn_s_setprio(0); } while (0)
; #define PG8_WAIT_V(n) asm volatile("s_waitcnt vmcnt(" #n ")" ::: "memory")
; #define PG8_BAR __builtin_amdgcn_s_barrier()
; template <class Epi, class Sched, bool ALIGN_EPI = false, bool SP2 = false, bool F16 = false>
; __device__ __forceinline__ void gemm_phase(PG8_LAS unsigned char* lds, const Gemm g, const Sched& S, const Epi& E, const int wid_in) {
;     ...
;         for (int t = 0; t < nt; t += 2) {
;             const bool last = (t == nt - 2);
;             const char* a1 = cA + (size_t)(t + 1) * kstep;
;             const char* a2 = last ? nA : cA + (size_t)(t + 2) * kstep; const char* b2 = last ? nB : cB + (size_t)(t + 2) * kstep;
;             const char* a3 = a2 + kstep; const char* b3 = b2 + kstep;
;             if (last && has_next) S.a_ready(nxt);
;             if constexpr (SP2) {
;             PG8_LDB(B0, 0, 0); PG8_LDB(B1, 0, 1); PG8_SCHED; PG8_LDA(At, 0, 0); PG8_STAGE(PG8_SA(1, 1), a1 + hstep, voffA);
;             PG8_WAIT_V(8); PG8_WAIT_L(0); PG8_BAR; PG8_MMA(0, 0, At, B0); PG8_MMA(0, 1, At, B1); PG8_BAR; PG8_SCHED;
;             PG8_LDA(At, 0, 1); PG8_STAGE(PG8_SB(0, 0), b2, voffB); PG8_STAGE(PG8_SB(0, 1), b2 + hstep, voffB); PG8_STAGE(PG8_SA(0, 0), a2, voffA);
;             PG8_WAIT_V(8); PG8_WAIT_L(0); PG8_BAR; PG8_MMA(1, 0, At, B0); PG8_MMA(1, 1, At, B1); PG8_BAR; PG8_SCHED;
.LBB0_1548:
	ds_read_b128 v[128:131], v184
	ds_read_b128 v[132:135], v184 offset:1024
	ds_read_b128 v[136:139], v184 offset:2048
	ds_read_b128 v[140:143], v184 offset:3072
	ds_read_b128 v[144:147], v185
	ds_read_b128 v[148:151], v185 offset:1024
	ds_read_b128 v[152:155], v185 offset:2048
	ds_read_b128 v[174:177], v185 offset:3072
	s_add_u32 s45, s50, 0xfffc0080
	s_addc_u32 s52, s51, -1
	s_cmp_eq_u32 s43, 12
	s_cselect_b32 s55, s13, s52
	s_cselect_b32 s54, s31, s45
	s_cselect_b32 s53, s37, s42
	s_cselect_b32 s52, s40, s41
	v_lshl_add_u64 v[178:179], s[50:51], 0, v[166:167]
	s_add_i32 m0, s74, 0xc000
	ds_read_b128 v[190:193], v186
	ds_read_b128 v[194:197], v186 offset:1024
	ds_read_b128 v[198:201], v186 offset:2048
	ds_read_b128 v[202:205], v186 offset:3072
	ds_read_b128 v[206:209], v186 offset:4096
	ds_read_b128 v[210:213], v186 offset:5120
	ds_read_b128 v[214:217], v186 offset:6144
	ds_read_b128 v[218:221], v186 offset:7168
	global_load_lds_dwordx4 v[178:179], off
	v_lshl_add_u64 v[178:179], s[50:51], 0, v[168:169]
	s_add_i32 m0, s74, 0xe000
	s_nop 0
	global_load_lds_dwordx4 v[178:179], off
	s_waitcnt vmcnt(8)
	s_waitcnt lgkmcnt(0)
	s_barrier
	s_waitcnt lgkmcnt(0)
	v_mfma_f32_16x16x32_f16 v[124:127], v[128:131], v[190:193], v[124:127]
	v_mfma_f32_16x16x32_f16 v[120:123], v[136:139], v[190:193], v[120:123]
	v_mfma_f32_16x16x32_f16 v[108:111], v[128:131], v[198:201], v[108:111]
	v_mfma_f32_16x16x32_f16 v[104:107], v[136:139], v[198:201], v[104:107]
	v_mfma_f32_16x16x32_f16 v[92:95], v[128:131], v[206:209], v[92:95]
	v_mfma_f32_16x16x32_f16 v[88:91], v[136:139], v[206:209], v[88:91]
	v_mfma_f32_16x16x32_f16 v[76:79], v[128:131], v[214:217], v[76:79]
	v_mfma_f32_16x16x32_f16 v[72:75], v[136:139], v[214:217], v[72:75]
	v_mfma_f32_16x16x32_f16 v[124:127], v[132:135], v[194:197], v[124:127]
	v_mfma_f32_16x16x32_f16 v[120:123], v[140:143], v[194:197], v[120:123]
	v_mfma_f32_16x16x32_f16 v[108:111], v[132:135], v[202:205], v[108:111]
	v_mfma_f32_16x16x32_f16 v[104:107], v[140:143], v[202:205], v[104:107]
	v_mfma_f32_16x16x32_f16 v[92:95], v[132:135], v[210:213], v[92:95]
	v_mfma_f32_16x16x32_f16 v[88:91], v[140:143], v[210:213], v[88:91]
	v_mfma_f32_16x16x32_f16 v[76:79], v[132:135], v[218:221], v[76:79]
	v_mfma_f32_16x16x32_f16 v[72:75], v[140:143], v[218:221], v[72:75]
	v_mfma_f32_16x16x32_f16 v[116:119], v[144:147], v[190:193], v[116:119]
	v_mfma_f32_16x16x32_f16 v[112:115], v[152:155], v[190:193], v[112:115]
	v_mfma_f32_16x16x32_f16 v[100:103], v[144:147], v[198:201], v[100:103]
	v_mfma_f32_16x16x32_f16 v[96:99], v[152:155], v[198:201], v[96:99]
	v_mfma_f32_16x16x32_f16 v[84:87], v[144:147], v[206:209], v[84:87]
	v_mfma_f32_16x16x32_f16 v[80:83], v[152:155], v[206:209], v[80:83]
	v_mfma_f32_16x16x32_f16 v[68:71], v[144:147], v[214:217], v[68:71]
	v_mfma_f32_16x16x32_f16 v[64:67], v[152:155], v[214:217], v[64:67]
	v_mfma_f32_16x16x32_f16 v[116:119], v[148:151], v[194:197], v[116:119]
	v_mfma_f32_16x16x32_f16 v[112:115], v[174:177], v[194:197], v[112:115]
	v_mfma_f32_16x16x32_f16 v[100:103], v[148:151], v[202:205], v[100:103]
	v_mfma_f32_16x16x32_f16 v[96:99], v[174:177], v[202:205], v[96:99]
	v_mfma_f32_16x16x32_f16 v[84:87], v[148:151], v[210:213], v[84:87]
	v_mfma_f32_16x16x32_f16 v[80:83], v[174:177], v[210:213], v[80:83]
	v_mfma_f32_16x16x32_f16 v[68:71], v[148:151], v[218:221], v[68:71]
	v_mfma_f32_16x16x32_f16 v[64:67], v[174:177], v[218:221], v[64:67]
	s_barrier
	s_add_i32 s45, s90, s68
	v_lshl_add_u64 v[178:179], s[52:53], 0, v[158:159]
	s_mov_b32 m0, s45
	ds_read_b128 v[190:193], v186 offset:16384
	ds_read_b128 v[194:197], v186 offset:17408
	ds_read_b128 v[198:201], v186 offset:18432
	ds_read_b128 v[202:205], v186 offset:19456
	ds_read_b128 v[206:209], v186 offset:20480
	ds_read_b128 v[210:213], v186 offset:21504
	ds_read_b128 v[214:217], v186 offset:22528
	ds_read_b128 v[218:221], v186 offset:23552
	global_load_lds_dwordx4 v[178:179], off
	s_add_i32 m0, s45, 0x2000
	s_add_u32 s56, s52, 0x40000
	v_lshl_add_u64 v[222:223], s[52:53], 0, v[162:163]
	s_addc_u32 s57, s53, 0
	s_add_i32 s45, s84, s68
	global_load_lds_dwordx4 v[222:223], off
	v_lshl_add_u64 v[224:225], s[56:57], 0, v[158:159]
	s_mov_b32 m0, s45
	v_lshl_add_u64 v[226:227], s[54:55], 0, v[160:161]
	global_load_lds_dwordx4 v[224:225], off
	v_lshl_add_u64 v[224:225], s[56:57], 0, v[162:163]
	s_add_i32 m0, s45, 0x2000
	s_nop 0
	global_load_lds_dwordx4 v[224:225], off
	v_lshl_add_u64 v[224:225], s[54:55], 0, v[156:157]
	s_mov_b32 m0, s74
	s_nop 0
	global_load_lds_dwordx4 v[224:225], off
	s_mov_b32 m0, s66
	s_nop 0
	global_load_lds_dwordx4 v[226:227], off
	s_waitcnt vmcnt(8)
	s_waitcnt lgkmcnt(0)
	s_barrier
; #define PG8_STAGE(bufoff, gbase, voff) do { _Pragma("unroll") for (int _i = 0; _i < 2; ++_i) \
;         __builtin_amdgcn_global_load_lds((const unsigned*)((const char*)(gbase) + (voff)[_i]), (PG8_LAS unsigned*)(lds + (bufoff) + ldsw + _i * 8192), 16, 0, 0); } while (0)
; #define PG8_LDA(dst, b, h) do { _Pragma("unroll") for (int m = 0; m < 4; ++m) _Pragma("unroll") for (int k = 0; k < 2; ++k) dst[m][k] = *(const PG8_LAS bf16x8*)(lds + PG8_SA(b, h) + aoff + m * 2048 + k * 1024); } while (0)
; #define PG8_LDB(dst, b, h) do { _Pragma("unroll") for (int n = 0; n < 2; ++n) _Pragma("unroll") for (int k = 0; k < 2; ++k) dst[n][k] = *(const PG8_LAS bf16x8*)(lds + PG8_SB(b, h) + boff + n * 2048 + k * 1024); } while (0)
; #define PG8_MMA(ai, bj, At, Bt) do { __builtin_amdgcn_s_setprio(1); _Pragma("unroll") for (int m = 0; m < 4; ++m) _Pragma("unroll") for (int n = 0; n < 2; ++n) _Pragma("unroll") for (int k = 0; k < 2; ++k) \
;         acc[ai][bj][m][n] = mma16<F16>(Bt[n][k], At[m][k], acc[ai][bj][m][n]); __builtin_amdgcn_s_setprio(0); } while (0)
; #define PG8_WAIT_V(n) asm volatile("s_waitcnt vmcnt(" #n ")" ::: "memory")
; #define PG8_WAIT_L(n) asm volatile("s_waitcnt lgkmcnt(" #n ")" ::: "memory")
; #define PG8_BAR __builtin_amdgcn_s_barrier()
; #define PG8_SCHED __builtin_amdgcn_sched_barrier(0)
; template <class Epi, class Sched, bool ALIGN_EPI = false, bool SP2 = false, bool F16 = false>
; __device__ __forceinline__ void gemm_phase(PG8_LAS unsigned char* lds, const Gemm g, const Sched& S, const Epi& E, const int wid_in) {
;     ...
;             PG8_WAIT_V(8); PG8_WAIT_L(0); PG8_BAR; PG8_MMA(1, 0, At, B0); PG8_MMA(1, 1, At, B1); PG8_BAR; PG8_SCHED;
;             PG8_LDB(B0, 1, 0); PG8_LDB(B1, 1, 1); PG8_SCHED; PG8_LDA(At, 1, 0); PG8_STAGE(PG8_SA(0, 1), a2 + hstep, voffA);
;             PG8_WAIT_V(8); PG8_WAIT_L(0); PG8_BAR; PG8_MMA(0, 0, At, B0); PG8_MMA(0, 1, At, B1); PG8_BAR; PG8_SCHED;
	s_waitcnt lgkmcnt(0)
	v_mfma_f32_16x16x32_f16 v[60:63], v[128:131], v[190:193], v[60:63]
	v_mfma_f32_16x16x32_f16 v[56:59], v[136:139], v[190:193], v[56:59]
	v_mfma_f32_16x16x32_f16 v[44:47], v[128:131], v[198:201], v[44:47]
	v_mfma_f32_16x16x32_f16 v[40:43], v[136:139], v[198:201], v[40:43]
	v_mfma_f32_16x16x32_f16 v[28:31], v[128:131], v[206:209], v[28:31]
	v_mfma_f32_16x16x32_f16 v[24:27], v[136:139], v[206:209], v[24:27]
	v_mfma_f32_16x16x32_f16 v[12:15], v[128:131], v[214:217], v[12:15]
	v_mfma_f32_16x16x32_f16 v[8:11], v[136:139], v[214:217], v[8:11]
	v_mfma_f32_16x16x32_f16 v[60:63], v[132:135], v[194:197], v[60:63]
	v_mfma_f32_16x16x32_f16 v[56:59], v[140:143], v[194:197], v[56:59]
	v_mfma_f32_16x16x32_f16 v[44:47], v[132:135], v[202:205], v[44:47]
	v_mfma_f32_16x16x32_f16 v[40:43], v[140:143], v[202:205], v[40:43]
	v_mfma_f32_16x16x32_f16 v[28:31], v[132:135], v[210:213], v[28:31]
	v_mfma_f32_16x16x32_f16 v[24:27], v[140:143], v[210:213], v[24:27]
	v_mfma_f32_16x16x32_f16 v[12:15], v[132:135], v[218:221], v[12:15]
	v_mfma_f32_16x16x32_f16 v[8:11], v[140:143], v[218:221], v[8:11]
	v_mfma_f32_16x16x32_f16 v[52:55], v[144:147], v[190:193], v[52:55]
	v_mfma_f32_16x16x32_f16 v[48:51], v[152:155], v[190:193], v[48:51]
	v_mfma_f32_16x16x32_f16 v[36:39], v[144:147], v[198:201], v[36:39]
	v_mfma_f32_16x16x32_f16 v[32:35], v[152:155], v[198:201], v[32:35]
	v_mfma_f32_16x16x32_f16 v[20:23], v[144:147], v[206:209], v[20:23]
	v_mfma_f32_16x16x32_f16 v[16:19], v[152:155], v[206:209], v[16:19]
	v_mfma_f32_16x16x32_f16 v[4:7], v[144:147], v[214:217], v[4:7]
	v_mfma_f32_16x16x32_f16 v[0:3], v[152:155], v[214:217], v[0:3]
	v_mfma_f32_16x16x32_f16 v[52:55], v[148:151], v[194:197], v[52:55]
	v_mfma_f32_16x16x32_f16 v[48:51], v[174:177], v[194:197], v[48:51]
	v_mfma_f32_16x16x32_f16 v[36:39], v[148:151], v[202:205], v[36:39]
	v_mfma_f32_16x16x32_f16 v[32:35], v[174:177], v[202:205], v[32:35]
	v_mfma_f32_16x16x32_f16 v[20:23], v[148:151], v[210:213], v[20:23]
	v_mfma_f32_16x16x32_f16 v[16:19], v[174:177], v[210:213], v[16:19]
	v_mfma_f32_16x16x32_f16 v[4:7], v[148:151], v[218:221], v[4:7]
	v_mfma_f32_16x16x32_f16 v[0:3], v[174:177], v[218:221], v[0:3]
	s_barrier
	s_add_i32 s45, 0, 0x18000
	s_add_i32 s56, 0, 0x1c000
	v_add_u32_e32 v140, s45, v183
	v_add_u32_e32 v165, s56, v183
	ds_read_b128 v[128:131], v140
	ds_read_b128 v[132:135], v140 offset:1024
	ds_read_b128 v[136:139], v140 offset:2048
	ds_read_b128 v[140:143], v140 offset:3072
	ds_read_b128 v[144:147], v165
	ds_read_b128 v[148:151], v165 offset:1024
	ds_read_b128 v[152:155], v165 offset:2048
	ds_read_b128 v[174:177], v165 offset:3072
	s_add_u32 s54, s54, 0x40000
	s_addc_u32 s55, s55, 0
	s_mov_b32 m0, s67
	v_lshl_add_u64 v[228:229], s[54:55], 0, v[156:157]
	ds_read_b128 v[190:193], v186 offset:32768
	ds_read_b128 v[194:197], v186 offset:33792
	ds_read_b128 v[198:201], v186 offset:34816
	ds_read_b128 v[202:205], v186 offset:35840
	ds_read_b128 v[206:209], v186 offset:36864
	ds_read_b128 v[210:213], v186 offset:37888
	ds_read_b128 v[214:217], v186 offset:38912
	ds_read_b128 v[218:221], v186 offset:39936
	global_load_lds_dwordx4 v[228:229], off
	v_lshl_add_u64 v[228:229], s[54:55], 0, v[160:161]
	s_mov_b32 m0, s91
	s_nop 0
	global_load_lds_dwordx4 v[228:229], off
	s_waitcnt vmcnt(8)
	s_waitcnt lgkmcnt(0)
	s_barrier
	s_waitcnt lgkmcnt(0)
	v_mfma_f32_16x16x32_f16 v[124:127], v[128:131], v[190:193], v[124:127]
	v_mfma_f32_16x16x32_f16 v[120:123], v[136:139], v[190:193], v[120:123]
	v_mfma_f32_16x16x32_f16 v[108:111], v[128:131], v[198:201], v[108:111]
	v_mfma_f32_16x16x32_f16 v[104:107], v[136:139], v[198:201], v[104:107]
	v_mfma_f32_16x16x32_f16 v[92:95], v[128:131], v[206:209], v[92:95]
	v_mfma_f32_16x16x32_f16 v[88:91], v[136:139], v[206:209], v[88:91]
	v_mfma_f32_16x16x32_f16 v[76:79], v[128:131], v[214:217], v[76:79]
	v_mfma_f32_16x16x32_f16 v[72:75], v[136:139], v[214:217], v[72:75]
	v_mfma_f32_16x16x32_f16 v[124:127], v[132:135], v[194:197], v[124:127]
	v_mfma_f32_16x16x32_f16 v[120:123], v[140:143], v[194:197], v[120:123]
	v_mfma_f32_16x16x32_f16 v[108:111], v[132:135], v[202:205], v[108:111]
	v_mfma_f32_16x16x32_f16 v[104:107], v[140:143], v[202:205], v[104:107]
	v_mfma_f32_16x16x32_f16 v[92:95], v[132:135], v[210:213], v[92:95]
	v_mfma_f32_16x16x32_f16 v[88:91], v[140:143], v[210:213], v[88:91]
	v_mfma_f32_16x16x32_f16 v[76:79], v[132:135], v[218:221], v[76:79]
	v_mfma_f32_16x16x32_f16 v[72:75], v[140:143], v[218:221], v[72:75]
	v_mfma_f32_16x16x32_f16 v[116:119], v[144:147], v[190:193], v[116:119]
	v_mfma_f32_16x16x32_f16 v[112:115], v[152:155], v[190:193], v[112:115]
	v_mfma_f32_16x16x32_f16 v[100:103], v[144:147], v[198:201], v[100:103]
	v_mfma_f32_16x16x32_f16 v[96:99], v[152:155], v[198:201], v[96:99]
	v_mfma_f32_16x16x32_f16 v[84:87], v[144:147], v[206:209], v[84:87]
	v_mfma_f32_16x16x32_f16 v[80:83], v[152:155], v[206:209], v[80:83]
	v_mfma_f32_16x16x32_f16 v[68:71], v[144:147], v[214:217], v[68:71]
	v_mfma_f32_16x16x32_f16 v[64:67], v[152:155], v[214:217], v[64:67]
	v_mfma_f32_16x16x32_f16 v[116:119], v[148:151], v[194:197], v[116:119]
	v_mfma_f32_16x16x32_f16 v[112:115], v[174:177], v[194:197], v[112:115]
	v_mfma_f32_16x16x32_f16 v[100:103], v[148:151], v[202:205], v[100:103]
	v_mfma_f32_16x16x32_f16 v[96:99], v[174:177], v[202:205], v[96:99]
	v_mfma_f32_16x16x32_f16 v[84:87], v[148:151], v[210:213], v[84:87]
	v_mfma_f32_16x16x32_f16 v[80:83], v[174:177], v[210:213], v[80:83]
	v_mfma_f32_16x16x32_f16 v[68:71], v[148:151], v[218:221], v[68:71]
	v_mfma_f32_16x16x32_f16 v[64:67], v[174:177], v[218:221], v[64:67]
	s_barrier
; #define PG8_STAGE(bufoff, gbase, voff) do { _Pragma("unroll") for (int _i = 0; _i < 2; ++_i) \
;         __builtin_amdgcn_global_load_lds((const unsigned*)((const char*)(gbase) + (voff)[_i]), (PG8_LAS unsigned*)(lds + (bufoff) + ldsw + _i * 8192), 16, 0, 0); } while (0)
; #define PG8_LDA(dst, b, h) do { _Pragma("unroll") for (int m = 0; m < 4; ++m) _Pragma("unroll") for (int k = 0; k < 2; ++k) dst[m][k] = *(const PG8_LAS bf16x8*)(lds + PG8_SA(b, h) + aoff + m * 2048 + k * 1024); } while (0)
; #define PG8_MMA(ai, bj, At, Bt) do { __builtin_amdgcn_s_setprio(1); _Pragma("unroll") for (int m = 0; m < 4; ++m) _Pragma("unroll") for (int n = 0; n < 2; ++n) _Pragma("unroll") for (int k = 0; k < 2; ++k) \
;         acc[ai][bj][m][n] = mma16<F16>(Bt[n][k], At[m][k], acc[ai][bj][m][n]); __builtin_amdgcn_s_setprio(0); } while (0)
; #define PG8_WAIT_V(n) asm volatile("s_waitcnt vmcnt(" #n ")" ::: "memory")
; #define PG8_WAIT_L(n) asm volatile("s_waitcnt lgkmcnt(" #n ")" ::: "memory")
; #define PG8_BAR __builtin_amdgcn_s_barrier()
; #define PG8_SCHED __builtin_amdgcn_sched_barrier(0)
; template <class Epi, class Sched, bool ALIGN_EPI = false, bool SP2 = false, bool F16 = false>
; __device__ __forceinline__ void gemm_phase(PG8_LAS unsigned char* lds, const Gemm g, const Sched& S, const Epi& E, const int wid_in) {
;     ...
;             PG8_LDA(At, 1, 1); PG8_STAGE(PG8_SB(1, 0), b3, voffB); PG8_STAGE(PG8_SB(1, 1), b3 + hstep, voffB); PG8_STAGE(PG8_SA(1, 0), a3, voffA);
;             PG8_WAIT_V(8); PG8_WAIT_L(0); PG8_BAR; PG8_MMA(1, 0, At, B0); PG8_MMA(1, 1, At, B1); PG8_BAR; PG8_SCHED;
;     ...
;         if constexpr (ALIGN_EPI) { if (wr == 0) PG8_BAR; }
	s_add_i32 s45, s45, s68
	v_lshl_add_u64 v[178:179], v[178:179], 0, s[34:35]
	s_mov_b32 m0, s45
	ds_read_b128 v[190:193], v186 offset:49152
	ds_read_b128 v[194:197], v186 offset:50176
	ds_read_b128 v[198:201], v186 offset:51200
	ds_read_b128 v[202:205], v186 offset:52224
	ds_read_b128 v[206:209], v186 offset:53248
	ds_read_b128 v[210:213], v186 offset:54272
	ds_read_b128 v[214:217], v186 offset:55296
	ds_read_b128 v[218:221], v186 offset:56320
	global_load_lds_dwordx4 v[178:179], off
	s_add_i32 m0, s45, 0x2000
	s_add_u32 s52, s52, 0x40080
	v_lshl_add_u64 v[178:179], v[222:223], 0, s[34:35]
	s_addc_u32 s53, s53, 0
	s_add_i32 s45, s56, s68
	global_load_lds_dwordx4 v[178:179], off
	v_lshl_add_u64 v[178:179], s[52:53], 0, v[158:159]
	s_mov_b32 m0, s45
	s_nop 0
	global_load_lds_dwordx4 v[178:179], off
	v_lshl_add_u64 v[178:179], s[52:53], 0, v[162:163]
	s_add_i32 m0, s45, 0x2000
	s_nop 0
	global_load_lds_dwordx4 v[178:179], off
	v_lshl_add_u64 v[178:179], v[224:225], 0, s[34:35]
	s_mov_b32 m0, s75
	s_nop 0
	global_load_lds_dwordx4 v[178:179], off
	v_lshl_add_u64 v[178:179], v[226:227], 0, s[34:35]
	s_mov_b32 m0, s97
	s_nop 0
	global_load_lds_dwordx4 v[178:179], off
	s_waitcnt vmcnt(8)
	s_waitcnt lgkmcnt(0)
	s_barrier
	s_waitcnt lgkmcnt(0)
	v_mfma_f32_16x16x32_f16 v[60:63], v[128:131], v[190:193], v[60:63]
	v_mfma_f32_16x16x32_f16 v[56:59], v[136:139], v[190:193], v[56:59]
	v_mfma_f32_16x16x32_f16 v[44:47], v[128:131], v[198:201], v[44:47]
	v_mfma_f32_16x16x32_f16 v[40:43], v[136:139], v[198:201], v[40:43]
	v_mfma_f32_16x16x32_f16 v[28:31], v[128:131], v[206:209], v[28:31]
	v_mfma_f32_16x16x32_f16 v[24:27], v[136:139], v[206:209], v[24:27]
	v_mfma_f32_16x16x32_f16 v[12:15], v[128:131], v[214:217], v[12:15]
	v_mfma_f32_16x16x32_f16 v[8:11], v[136:139], v[214:217], v[8:11]
	v_mfma_f32_16x16x32_f16 v[60:63], v[132:135], v[194:197], v[60:63]
	v_mfma_f32_16x16x32_f16 v[56:59], v[140:143], v[194:197], v[56:59]
	v_mfma_f32_16x16x32_f16 v[44:47], v[132:135], v[202:205], v[44:47]
	v_mfma_f32_16x16x32_f16 v[40:43], v[140:143], v[202:205], v[40:43]
	v_mfma_f32_16x16x32_f16 v[28:31], v[132:135], v[210:213], v[28:31]
	v_mfma_f32_16x16x32_f16 v[24:27], v[140:143], v[210:213], v[24:27]
	v_mfma_f32_16x16x32_f16 v[12:15], v[132:135], v[218:221], v[12:15]
	v_mfma_f32_16x16x32_f16 v[8:11], v[140:143], v[218:221], v[8:11]
	v_mfma_f32_16x16x32_f16 v[52:55], v[144:147], v[190:193], v[52:55]
	v_mfma_f32_16x16x32_f16 v[48:51], v[152:155], v[190:193], v[48:51]
	v_mfma_f32_16x16x32_f16 v[36:39], v[144:147], v[198:201], v[36:39]
	v_mfma_f32_16x16x32_f16 v[32:35], v[152:155], v[198:201], v[32:35]
	v_mfma_f32_16x16x32_f16 v[20:23], v[144:147], v[206:209], v[20:23]
	v_mfma_f32_16x16x32_f16 v[16:19], v[152:155], v[206:209], v[16:19]
	v_mfma_f32_16x16x32_f16 v[4:7], v[144:147], v[214:217], v[4:7]
	v_mfma_f32_16x16x32_f16 v[0:3], v[152:155], v[214:217], v[0:3]
	v_mfma_f32_16x16x32_f16 v[52:55], v[148:151], v[194:197], v[52:55]
	v_mfma_f32_16x16x32_f16 v[48:51], v[174:177], v[194:197], v[48:51]
	v_mfma_f32_16x16x32_f16 v[36:39], v[148:151], v[202:205], v[36:39]
	v_mfma_f32_16x16x32_f16 v[32:35], v[174:177], v[202:205], v[32:35]
	v_mfma_f32_16x16x32_f16 v[20:23], v[148:151], v[210:213], v[20:23]
	v_mfma_f32_16x16x32_f16 v[16:19], v[174:177], v[210:213], v[16:19]
	v_mfma_f32_16x16x32_f16 v[4:7], v[148:151], v[218:221], v[4:7]
	v_mfma_f32_16x16x32_f16 v[0:3], v[174:177], v[218:221], v[0:3]
	s_barrier
	s_add_i32 s43, s43, 2
	s_add_u32 s50, s50, 0x100
	s_addc_u32 s51, s51, 0
	s_add_u32 s41, s41, 0x100
	s_addc_u32 s42, s42, 0
	s_cmp_gt_u32 s43, 13
	s_cbranch_scc0 .LBB0_1548
	s_and_b64 vcc, exec, s[16:17]
	s_cbranch_vccz .LBB0_1551
	s_barrier

; #define PG8_STAGE(bufoff, gbase, voff) do { _Pragma("unroll") for (int _i = 0; _i < 2; ++_i) \
;         __builtin_amdgcn_global_load_lds((const unsigned*)((const char*)(gbase) + (voff)[_i]), (PG8_LAS unsigned*)(lds + (bufoff) + ldsw + _i * 8192), 16, 0, 0); } while (0)
; #define PG8_LDA(dst, b, h) do { _Pragma("unroll") for (int m = 0; m < 4; ++m) _Pragma("unroll") for (int k = 0; k < 2; ++k) dst[m][k] = *(const PG8_LAS bf16x8*)(lds + PG8_SA(b, h) + aoff + m * 2048 + k * 1024); } while (0)
; #define PG8_LDB(dst, b, h) do { _Pragma("unroll") for (int n = 0; n < 2; ++n) _Pragma("unroll") for (int k = 0; k < 2; ++k) dst[n][k] = *(const PG8_LAS bf16x8*)(lds + PG8_SB(b, h) + boff + n * 2048 + k * 1024); } while (0)
; #define PG8_MMA(ai, bj, At, Bt) do { __builtin_amdgcn_s_setprio(1); _Pragma("unroll") for (int m = 0; m < 4; ++m) _Pragma("unroll") for (int n = 0; n < 2; ++n) _Pragma("unroll") for (int k = 0; k < 2; ++k) \
;         acc[ai][bj][m][n] = mma16<F16>(Bt[n][k], At[m][k], acc[ai][bj][m][n]); __builtin_amdgcn_s_setprio(0); } while (0)
; #define PG8_WAIT_V(n) asm volatile("s_waitcnt vmcnt(" #n ")" ::: "memory")
; #define PG8_BAR __builtin_amdgcn_s_barrier()
; template <class Epi, class Sched, bool ALIGN_EPI = false, bool SP2 = false, bool F16 = false>
; __device__ __forceinline__ void gemm_phase(PG8_LAS unsigned char* lds, const Gemm g, const Sched& S, const Epi& E, const int wid_in) {
;     ...
;         for (int t = 0; t < nt; t += 2) {
;             const bool last = (t == nt - 2);
;             const char* a1 = cA + (size_t)(t + 1) * kstep;
;             const char* a2 = last ? nA : cA + (size_t)(t + 2) * kstep; const char* b2 = last ? nB : cB + (size_t)(t + 2) * kstep;
;             const char* a3 = a2 + kstep; const char* b3 = b2 + kstep;
;             if (last && has_next) S.a_ready(nxt);
;             if constexpr (SP2) {
;             PG8_LDB(B0, 0, 0); PG8_LDB(B1, 0, 1); PG8_SCHED; PG8_LDA(At, 0, 0); PG8_STAGE(PG8_SA(1, 1), a1 + hstep, voffA);
;             PG8_WAIT_V(8); PG8_WAIT_L(0); PG8_BAR; PG8_MMA(0, 0, At, B0); PG8_MMA(0, 1, At, B1); PG8_BAR; PG8_SCHED;
;             PG8_LDA(At, 0, 1); PG8_STAGE(PG8_SB(0, 0), b2, voffB); PG8_STAGE(PG8_SB(0, 1), b2 + hstep, voffB); PG8_STAGE(PG8_SA(0, 0), a2, voffA);
;             PG8_WAIT_V(8); PG8_WAIT_L(0); PG8_BAR; PG8_MMA(1, 0, At, B0); PG8_MMA(1, 1, At, B1); PG8_BAR; PG8_SCHED;
.LBB0_1832:
	ds_read_b128 v[128:131], v189
	ds_read_b128 v[132:135], v189 offset:1024
	ds_read_b128 v[136:139], v189 offset:2048
	ds_read_b128 v[140:143], v189 offset:3072
	ds_read_b128 v[144:147], v190
	ds_read_b128 v[148:151], v190 offset:1024
	ds_read_b128 v[168:171], v190 offset:2048
	ds_read_b128 v[172:175], v190 offset:3072
	s_add_u32 s50, s48, 0xfffc0080
	s_addc_u32 s51, s49, -1
	s_cmp_eq_u32 s61, 12
	s_cselect_b32 s53, s35, s51
	s_cselect_b32 s52, s42, s50
	s_cselect_b32 s51, s31, s60
	s_cselect_b32 s50, s43, s47
	s_mov_b32 m0, s91
	v_lshl_add_u64 v[184:185], s[48:49], 0, v[160:161]
	ds_read_b128 v[176:179], v191
	ds_read_b128 v[180:183], v191 offset:1024
	ds_read_b128 v[192:195], v191 offset:2048
	ds_read_b128 v[196:199], v191 offset:3072
	ds_read_b128 v[200:203], v191 offset:4096
	ds_read_b128 v[204:207], v191 offset:5120
	ds_read_b128 v[208:211], v191 offset:6144
	ds_read_b128 v[212:215], v191 offset:7168
	global_load_lds_dwordx4 v[184:185], off
	v_lshl_add_u64 v[184:185], s[48:49], 0, v[162:163]
	s_add_i32 m0, s74, 0xe000
	s_nop 0
	global_load_lds_dwordx4 v[184:185], off
	s_waitcnt vmcnt(8)
	s_waitcnt lgkmcnt(0)
	s_barrier
	s_waitcnt lgkmcnt(0)
	v_mfma_f32_16x16x32_bf16 v[124:127], v[128:131], v[176:179], v[124:127]
	v_mfma_f32_16x16x32_bf16 v[120:123], v[136:139], v[176:179], v[120:123]
	v_mfma_f32_16x16x32_bf16 v[108:111], v[128:131], v[192:195], v[108:111]
	v_mfma_f32_16x16x32_bf16 v[104:107], v[136:139], v[192:195], v[104:107]
	v_mfma_f32_16x16x32_bf16 v[92:95], v[128:131], v[200:203], v[92:95]
	v_mfma_f32_16x16x32_bf16 v[88:91], v[136:139], v[200:203], v[88:91]
	v_mfma_f32_16x16x32_bf16 v[76:79], v[128:131], v[208:211], v[76:79]
	v_mfma_f32_16x16x32_bf16 v[72:75], v[136:139], v[208:211], v[72:75]
	v_mfma_f32_16x16x32_bf16 v[124:127], v[132:135], v[180:183], v[124:127]
	v_mfma_f32_16x16x32_bf16 v[120:123], v[140:143], v[180:183], v[120:123]
	v_mfma_f32_16x16x32_bf16 v[108:111], v[132:135], v[196:199], v[108:111]
	v_mfma_f32_16x16x32_bf16 v[104:107], v[140:143], v[196:199], v[104:107]
	v_mfma_f32_16x16x32_bf16 v[92:95], v[132:135], v[204:207], v[92:95]
	v_mfma_f32_16x16x32_bf16 v[88:91], v[140:143], v[204:207], v[88:91]
	v_mfma_f32_16x16x32_bf16 v[76:79], v[132:135], v[212:215], v[76:79]
	v_mfma_f32_16x16x32_bf16 v[72:75], v[140:143], v[212:215], v[72:75]
	v_mfma_f32_16x16x32_bf16 v[116:119], v[144:147], v[176:179], v[116:119]
	v_mfma_f32_16x16x32_bf16 v[112:115], v[168:171], v[176:179], v[112:115]
	v_mfma_f32_16x16x32_bf16 v[100:103], v[144:147], v[192:195], v[100:103]
	v_mfma_f32_16x16x32_bf16 v[96:99], v[168:171], v[192:195], v[96:99]
	v_mfma_f32_16x16x32_bf16 v[84:87], v[144:147], v[200:203], v[84:87]
	v_mfma_f32_16x16x32_bf16 v[80:83], v[168:171], v[200:203], v[80:83]
	v_mfma_f32_16x16x32_bf16 v[68:71], v[144:147], v[208:211], v[68:71]
	v_mfma_f32_16x16x32_bf16 v[64:67], v[168:171], v[208:211], v[64:67]
	v_mfma_f32_16x16x32_bf16 v[116:119], v[148:151], v[180:183], v[116:119]
	v_mfma_f32_16x16x32_bf16 v[112:115], v[172:175], v[180:183], v[112:115]
	v_mfma_f32_16x16x32_bf16 v[100:103], v[148:151], v[196:199], v[100:103]
	v_mfma_f32_16x16x32_bf16 v[96:99], v[172:175], v[196:199], v[96:99]
	v_mfma_f32_16x16x32_bf16 v[84:87], v[148:151], v[204:207], v[84:87]
	v_mfma_f32_16x16x32_bf16 v[80:83], v[172:175], v[204:207], v[80:83]
	v_mfma_f32_16x16x32_bf16 v[68:71], v[148:151], v[212:215], v[68:71]
	v_mfma_f32_16x16x32_bf16 v[64:67], v[172:175], v[212:215], v[64:67]
	s_barrier
	s_add_i32 s62, s57, s68
	v_lshl_add_u64 v[184:185], s[50:51], 0, v[154:155]
	s_mov_b32 m0, s62
	ds_read_b128 v[176:179], v191 offset:16384
	ds_read_b128 v[180:183], v191 offset:17408
	ds_read_b128 v[192:195], v191 offset:18432
	ds_read_b128 v[196:199], v191 offset:19456
	ds_read_b128 v[200:203], v191 offset:20480
	ds_read_b128 v[204:207], v191 offset:21504
	ds_read_b128 v[208:211], v191 offset:22528
	ds_read_b128 v[212:215], v191 offset:23552
	global_load_lds_dwordx4 v[184:185], off
	s_add_i32 m0, s62, 0x2000
	s_add_u32 s62, s50, 0x40000
	v_lshl_add_u64 v[216:217], s[50:51], 0, v[158:159]
	s_addc_u32 s63, s51, 0
	s_add_i32 s64, s58, s68
	global_load_lds_dwordx4 v[216:217], off
	v_lshl_add_u64 v[218:219], s[62:63], 0, v[154:155]
	s_mov_b32 m0, s64
	v_lshl_add_u64 v[220:221], s[52:53], 0, v[156:157]
	global_load_lds_dwordx4 v[218:219], off
	v_lshl_add_u64 v[218:219], s[62:63], 0, v[158:159]
	s_add_i32 m0, s64, 0x2000
	s_nop 0
	global_load_lds_dwordx4 v[218:219], off
	v_lshl_add_u64 v[218:219], s[52:53], 0, v[152:153]
	s_mov_b32 m0, s74
	s_nop 0
	global_load_lds_dwordx4 v[218:219], off
	s_mov_b32 m0, s66
	s_nop 0
	global_load_lds_dwordx4 v[220:221], off
	s_waitcnt vmcnt(8)
	s_waitcnt lgkmcnt(0)
	s_barrier
; #define PG8_STAGE(bufoff, gbase, voff) do { _Pragma("unroll") for (int _i = 0; _i < 2; ++_i) \
;         __builtin_amdgcn_global_load_lds((const unsigned*)((const char*)(gbase) + (voff)[_i]), (PG8_LAS unsigned*)(lds + (bufoff) + ldsw + _i * 8192), 16, 0, 0); } while (0)
; #define PG8_LDA(dst, b, h) do { _Pragma("unroll") for (int m = 0; m < 4; ++m) _Pragma("unroll") for (int k = 0; k < 2; ++k) dst[m][k] = *(const PG8_LAS bf16x8*)(lds + PG8_SA(b, h) + aoff + m * 2048 + k * 1024); } while (0)
; #define PG8_LDB(dst, b, h) do { _Pragma("unroll") for (int n = 0; n < 2; ++n) _Pragma("unroll") for (int k = 0; k < 2; ++k) dst[n][k] = *(const PG8_LAS bf16x8*)(lds + PG8_SB(b, h) + boff + n * 2048 + k * 1024); } while (0)
; #define PG8_MMA(ai, bj, At, Bt) do { __builtin_amdgcn_s_setprio(1); _Pragma("unroll") for (int m = 0; m < 4; ++m) _Pragma("unroll") for (int n = 0; n < 2; ++n) _Pragma("unroll") for (int k = 0; k < 2; ++k) \
;         acc[ai][bj][m][n] = mma16<F16>(Bt[n][k], At[m][k], acc[ai][bj][m][n]); __builtin_amdgcn_s_setprio(0); } while (0)
; #define PG8_WAIT_V(n) asm volatile("s_waitcnt vmcnt(" #n ")" ::: "memory")
; #define PG8_WAIT_L(n) asm volatile("s_waitcnt lgkmcnt(" #n ")" ::: "memory")
; #define PG8_BAR __builtin_amdgcn_s_barrier()
; #define PG8_SCHED __builtin_amdgcn_sched_barrier(0)
; template <class Epi, class Sched, bool ALIGN_EPI = false, bool SP2 = false, bool F16 = false>
; __device__ __forceinline__ void gemm_phase(PG8_LAS unsigned char* lds, const Gemm g, const Sched& S, const Epi& E, const int wid_in) {
;     ...
;             PG8_WAIT_V(8); PG8_WAIT_L(0); PG8_BAR; PG8_MMA(1, 0, At, B0); PG8_MMA(1, 1, At, B1); PG8_BAR; PG8_SCHED;
;             PG8_LDB(B0, 1, 0); PG8_LDB(B1, 1, 1); PG8_SCHED; PG8_LDA(At, 1, 0); PG8_STAGE(PG8_SA(0, 1), a2 + hstep, voffA);
;             PG8_WAIT_V(8); PG8_WAIT_L(0); PG8_BAR; PG8_MMA(0, 0, At, B0); PG8_MMA(0, 1, At, B1); PG8_BAR; PG8_SCHED;
	s_waitcnt lgkmcnt(0)
	v_mfma_f32_16x16x32_bf16 v[60:63], v[128:131], v[176:179], v[60:63]
	v_mfma_f32_16x16x32_bf16 v[56:59], v[136:139], v[176:179], v[56:59]
	v_mfma_f32_16x16x32_bf16 v[44:47], v[128:131], v[192:195], v[44:47]
	v_mfma_f32_16x16x32_bf16 v[40:43], v[136:139], v[192:195], v[40:43]
	v_mfma_f32_16x16x32_bf16 v[28:31], v[128:131], v[200:203], v[28:31]
	v_mfma_f32_16x16x32_bf16 v[24:27], v[136:139], v[200:203], v[24:27]
	v_mfma_f32_16x16x32_bf16 v[12:15], v[128:131], v[208:211], v[12:15]
	v_mfma_f32_16x16x32_bf16 v[8:11], v[136:139], v[208:211], v[8:11]
	v_mfma_f32_16x16x32_bf16 v[60:63], v[132:135], v[180:183], v[60:63]
	v_mfma_f32_16x16x32_bf16 v[56:59], v[140:143], v[180:183], v[56:59]
	v_mfma_f32_16x16x32_bf16 v[44:47], v[132:135], v[196:199], v[44:47]
	v_mfma_f32_16x16x32_bf16 v[40:43], v[140:143], v[196:199], v[40:43]
	v_mfma_f32_16x16x32_bf16 v[28:31], v[132:135], v[204:207], v[28:31]
	v_mfma_f32_16x16x32_bf16 v[24:27], v[140:143], v[204:207], v[24:27]
	v_mfma_f32_16x16x32_bf16 v[12:15], v[132:135], v[212:215], v[12:15]
	v_mfma_f32_16x16x32_bf16 v[8:11], v[140:143], v[212:215], v[8:11]
	v_mfma_f32_16x16x32_bf16 v[52:55], v[144:147], v[176:179], v[52:55]
	v_mfma_f32_16x16x32_bf16 v[48:51], v[168:171], v[176:179], v[48:51]
	v_mfma_f32_16x16x32_bf16 v[36:39], v[144:147], v[192:195], v[36:39]
	v_mfma_f32_16x16x32_bf16 v[32:35], v[168:171], v[192:195], v[32:35]
	v_mfma_f32_16x16x32_bf16 v[20:23], v[144:147], v[200:203], v[20:23]
	v_mfma_f32_16x16x32_bf16 v[16:19], v[168:171], v[200:203], v[16:19]
	v_mfma_f32_16x16x32_bf16 v[4:7], v[144:147], v[208:211], v[4:7]
	v_mfma_f32_16x16x32_bf16 v[0:3], v[168:171], v[208:211], v[0:3]
	v_mfma_f32_16x16x32_bf16 v[52:55], v[148:151], v[180:183], v[52:55]
	v_mfma_f32_16x16x32_bf16 v[48:51], v[172:175], v[180:183], v[48:51]
	v_mfma_f32_16x16x32_bf16 v[36:39], v[148:151], v[196:199], v[36:39]
	v_mfma_f32_16x16x32_bf16 v[32:35], v[172:175], v[196:199], v[32:35]
	v_mfma_f32_16x16x32_bf16 v[20:23], v[148:151], v[204:207], v[20:23]
	v_mfma_f32_16x16x32_bf16 v[16:19], v[172:175], v[204:207], v[16:19]
	v_mfma_f32_16x16x32_bf16 v[4:7], v[148:151], v[212:215], v[4:7]
	v_mfma_f32_16x16x32_bf16 v[0:3], v[172:175], v[212:215], v[0:3]
	s_barrier
	s_add_i32 s62, 0, 0x18000
	s_add_i32 s63, 0, 0x1c000
	v_add_u32_e32 v140, s62, v188
	v_add_u32_e32 v172, s63, v188
	ds_read_b128 v[128:131], v140
	ds_read_b128 v[132:135], v140 offset:1024
	ds_read_b128 v[136:139], v140 offset:2048
	ds_read_b128 v[140:143], v140 offset:3072
	ds_read_b128 v[144:147], v172
	ds_read_b128 v[148:151], v172 offset:1024
	ds_read_b128 v[168:171], v172 offset:2048
	ds_read_b128 v[172:175], v172 offset:3072
	s_add_u32 s52, s52, 0x40000
	s_addc_u32 s53, s53, 0
	s_mov_b32 m0, s90
	v_lshl_add_u64 v[222:223], s[52:53], 0, v[152:153]
	ds_read_b128 v[176:179], v191 offset:32768
	ds_read_b128 v[180:183], v191 offset:33792
	ds_read_b128 v[192:195], v191 offset:34816
	ds_read_b128 v[196:199], v191 offset:35840
	ds_read_b128 v[200:203], v191 offset:36864
	ds_read_b128 v[204:207], v191 offset:37888
	ds_read_b128 v[208:211], v191 offset:38912
	ds_read_b128 v[212:215], v191 offset:39936
	global_load_lds_dwordx4 v[222:223], off
	v_lshl_add_u64 v[222:223], s[52:53], 0, v[156:157]
	s_mov_b32 m0, s41
	s_nop 0
	global_load_lds_dwordx4 v[222:223], off
	s_waitcnt vmcnt(8)
	s_waitcnt lgkmcnt(0)
	s_barrier
	s_waitcnt lgkmcnt(0)
	v_mfma_f32_16x16x32_bf16 v[124:127], v[128:131], v[176:179], v[124:127]
	v_mfma_f32_16x16x32_bf16 v[120:123], v[136:139], v[176:179], v[120:123]
	v_mfma_f32_16x16x32_bf16 v[108:111], v[128:131], v[192:195], v[108:111]
	v_mfma_f32_16x16x32_bf16 v[104:107], v[136:139], v[192:195], v[104:107]
	v_mfma_f32_16x16x32_bf16 v[92:95], v[128:131], v[200:203], v[92:95]
	v_mfma_f32_16x16x32_bf16 v[88:91], v[136:139], v[200:203], v[88:91]
	v_mfma_f32_16x16x32_bf16 v[76:79], v[128:131], v[208:211], v[76:79]
	v_mfma_f32_16x16x32_bf16 v[72:75], v[136:139], v[208:211], v[72:75]
	v_mfma_f32_16x16x32_bf16 v[124:127], v[132:135], v[180:183], v[124:127]
	v_mfma_f32_16x16x32_bf16 v[120:123], v[140:143], v[180:183], v[120:123]
	v_mfma_f32_16x16x32_bf16 v[108:111], v[132:135], v[196:199], v[108:111]
	v_mfma_f32_16x16x32_bf16 v[104:107], v[140:143], v[196:199], v[104:107]
	v_mfma_f32_16x16x32_bf16 v[92:95], v[132:135], v[204:207], v[92:95]
	v_mfma_f32_16x16x32_bf16 v[88:91], v[140:143], v[204:207], v[88:91]
	v_mfma_f32_16x16x32_bf16 v[76:79], v[132:135], v[212:215], v[76:79]
	v_mfma_f32_16x16x32_bf16 v[72:75], v[140:143], v[212:215], v[72:75]
	v_mfma_f32_16x16x32_bf16 v[116:119], v[144:147], v[176:179], v[116:119]
	v_mfma_f32_16x16x32_bf16 v[112:115], v[168:171], v[176:179], v[112:115]
	v_mfma_f32_16x16x32_bf16 v[100:103], v[144:147], v[192:195], v[100:103]
	v_mfma_f32_16x16x32_bf16 v[96:99], v[168:171], v[192:195], v[96:99]
	v_mfma_f32_16x16x32_bf16 v[84:87], v[144:147], v[200:203], v[84:87]
	v_mfma_f32_16x16x32_bf16 v[80:83], v[168:171], v[200:203], v[80:83]
	v_mfma_f32_16x16x32_bf16 v[68:71], v[144:147], v[208:211], v[68:71]
	v_mfma_f32_16x16x32_bf16 v[64:67], v[168:171], v[208:211], v[64:67]
	v_mfma_f32_16x16x32_bf16 v[116:119], v[148:151], v[180:183], v[116:119]
	v_mfma_f32_16x16x32_bf16 v[112:115], v[172:175], v[180:183], v[112:115]
	v_mfma_f32_16x16x32_bf16 v[100:103], v[148:151], v[196:199], v[100:103]
	v_mfma_f32_16x16x32_bf16 v[96:99], v[172:175], v[196:199], v[96:99]
	v_mfma_f32_16x16x32_bf16 v[84:87], v[148:151], v[204:207], v[84:87]
	v_mfma_f32_16x16x32_bf16 v[80:83], v[172:175], v[204:207], v[80:83]
	v_mfma_f32_16x16x32_bf16 v[68:71], v[148:151], v[212:215], v[68:71]
	v_mfma_f32_16x16x32_bf16 v[64:67], v[172:175], v[212:215], v[64:67]
	s_barrier
; #define PG8_STAGE(bufoff, gbase, voff) do { _Pragma("unroll") for (int _i = 0; _i < 2; ++_i) \
;         __builtin_amdgcn_global_load_lds((const unsigned*)((const char*)(gbase) + (voff)[_i]), (PG8_LAS unsigned*)(lds + (bufoff) + ldsw + _i * 8192), 16, 0, 0); } while (0)
; #define PG8_LDA(dst, b, h) do { _Pragma("unroll") for (int m = 0; m < 4; ++m) _Pragma("unroll") for (int k = 0; k < 2; ++k) dst[m][k] = *(const PG8_LAS bf16x8*)(lds + PG8_SA(b, h) + aoff + m * 2048 + k * 1024); } while (0)
; #define PG8_MMA(ai, bj, At, Bt) do { __builtin_amdgcn_s_setprio(1); _Pragma("unroll") for (int m = 0; m < 4; ++m) _Pragma("unroll") for (int n = 0; n < 2; ++n) _Pragma("unroll") for (int k = 0; k < 2; ++k) \
;         acc[ai][bj][m][n] = mma16<F16>(Bt[n][k], At[m][k], acc[ai][bj][m][n]); __builtin_amdgcn_s_setprio(0); } while (0)
; #define PG8_WAIT_V(n) asm volatile("s_waitcnt vmcnt(" #n ")" ::: "memory")
; #define PG8_WAIT_L(n) asm volatile("s_waitcnt lgkmcnt(" #n ")" ::: "memory")
; #define PG8_BAR __builtin_amdgcn_s_barrier()
; #define PG8_SCHED __builtin_amdgcn_sched_barrier(0)
; template <class Epi, class Sched, bool ALIGN_EPI = false, bool SP2 = false, bool F16 = false>
; __device__ __forceinline__ void gemm_phase(PG8_LAS unsigned char* lds, const Gemm g, const Sched& S, const Epi& E, const int wid_in) {
;     ...
;             PG8_LDA(At, 1, 1); PG8_STAGE(PG8_SB(1, 0), b3, voffB); PG8_STAGE(PG8_SB(1, 1), b3 + hstep, voffB); PG8_STAGE(PG8_SA(1, 0), a3, voffA);
;             PG8_WAIT_V(8); PG8_WAIT_L(0); PG8_BAR; PG8_MMA(1, 0, At, B0); PG8_MMA(1, 1, At, B1); PG8_BAR; PG8_SCHED;
;     ...
;         if constexpr (ALIGN_EPI) { if (wr == 0) PG8_BAR; }
	s_add_i32 s52, s62, s68
	v_lshl_add_u64 v[184:185], v[184:185], 0, s[28:29]
	s_mov_b32 m0, s52
	ds_read_b128 v[176:179], v191 offset:49152
	ds_read_b128 v[180:183], v191 offset:50176
	ds_read_b128 v[192:195], v191 offset:51200
	ds_read_b128 v[196:199], v191 offset:52224
	ds_read_b128 v[200:203], v191 offset:53248
	ds_read_b128 v[204:207], v191 offset:54272
	ds_read_b128 v[208:211], v191 offset:55296
	ds_read_b128 v[212:215], v191 offset:56320
	global_load_lds_dwordx4 v[184:185], off
	s_add_i32 m0, s52, 0x2000
	s_add_u32 s50, s50, 0x40080
	v_lshl_add_u64 v[184:185], v[216:217], 0, s[28:29]
	s_addc_u32 s51, s51, 0
	s_add_i32 s52, s63, s68
	global_load_lds_dwordx4 v[184:185], off
	v_lshl_add_u64 v[184:185], s[50:51], 0, v[154:155]
	s_mov_b32 m0, s52
	s_nop 0
	global_load_lds_dwordx4 v[184:185], off
	v_lshl_add_u64 v[184:185], s[50:51], 0, v[158:159]
	s_add_i32 m0, s52, 0x2000
	s_nop 0
	global_load_lds_dwordx4 v[184:185], off
	v_lshl_add_u64 v[184:185], v[218:219], 0, s[28:29]
	s_mov_b32 m0, s75
	s_nop 0
	global_load_lds_dwordx4 v[184:185], off
	v_lshl_add_u64 v[184:185], v[220:221], 0, s[28:29]
	s_mov_b32 m0, s67
	s_nop 0
	global_load_lds_dwordx4 v[184:185], off
	s_waitcnt vmcnt(8)
	s_waitcnt lgkmcnt(0)
	s_barrier
	s_waitcnt lgkmcnt(0)
	v_mfma_f32_16x16x32_bf16 v[60:63], v[128:131], v[176:179], v[60:63]
	v_mfma_f32_16x16x32_bf16 v[56:59], v[136:139], v[176:179], v[56:59]
	v_mfma_f32_16x16x32_bf16 v[44:47], v[128:131], v[192:195], v[44:47]
	v_mfma_f32_16x16x32_bf16 v[40:43], v[136:139], v[192:195], v[40:43]
	v_mfma_f32_16x16x32_bf16 v[28:31], v[128:131], v[200:203], v[28:31]
	v_mfma_f32_16x16x32_bf16 v[24:27], v[136:139], v[200:203], v[24:27]
	v_mfma_f32_16x16x32_bf16 v[12:15], v[128:131], v[208:211], v[12:15]
	v_mfma_f32_16x16x32_bf16 v[8:11], v[136:139], v[208:211], v[8:11]
	v_mfma_f32_16x16x32_bf16 v[60:63], v[132:135], v[180:183], v[60:63]
	v_mfma_f32_16x16x32_bf16 v[56:59], v[140:143], v[180:183], v[56:59]
	v_mfma_f32_16x16x32_bf16 v[44:47], v[132:135], v[196:199], v[44:47]
	v_mfma_f32_16x16x32_bf16 v[40:43], v[140:143], v[196:199], v[40:43]
	v_mfma_f32_16x16x32_bf16 v[28:31], v[132:135], v[204:207], v[28:31]
	v_mfma_f32_16x16x32_bf16 v[24:27], v[140:143], v[204:207], v[24:27]
	v_mfma_f32_16x16x32_bf16 v[12:15], v[132:135], v[212:215], v[12:15]
	v_mfma_f32_16x16x32_bf16 v[8:11], v[140:143], v[212:215], v[8:11]
	v_mfma_f32_16x16x32_bf16 v[52:55], v[144:147], v[176:179], v[52:55]
	v_mfma_f32_16x16x32_bf16 v[48:51], v[168:171], v[176:179], v[48:51]
	v_mfma_f32_16x16x32_bf16 v[36:39], v[144:147], v[192:195], v[36:39]
	v_mfma_f32_16x16x32_bf16 v[32:35], v[168:171], v[192:195], v[32:35]
	v_mfma_f32_16x16x32_bf16 v[20:23], v[144:147], v[200:203], v[20:23]
	v_mfma_f32_16x16x32_bf16 v[16:19], v[168:171], v[200:203], v[16:19]
	v_mfma_f32_16x16x32_bf16 v[4:7], v[144:147], v[208:211], v[4:7]
	v_mfma_f32_16x16x32_bf16 v[0:3], v[168:171], v[208:211], v[0:3]
	v_mfma_f32_16x16x32_bf16 v[52:55], v[148:151], v[180:183], v[52:55]
	v_mfma_f32_16x16x32_bf16 v[48:51], v[172:175], v[180:183], v[48:51]
	v_mfma_f32_16x16x32_bf16 v[36:39], v[148:151], v[196:199], v[36:39]
	v_mfma_f32_16x16x32_bf16 v[32:35], v[172:175], v[196:199], v[32:35]
	v_mfma_f32_16x16x32_bf16 v[20:23], v[148:151], v[204:207], v[20:23]
	v_mfma_f32_16x16x32_bf16 v[16:19], v[172:175], v[204:207], v[16:19]
	v_mfma_f32_16x16x32_bf16 v[4:7], v[148:151], v[212:215], v[4:7]
	v_mfma_f32_16x16x32_bf16 v[0:3], v[172:175], v[212:215], v[0:3]
	s_barrier
	s_add_i32 s61, s61, 2
	s_add_u32 s48, s48, 0x100
	s_addc_u32 s49, s49, 0
	s_add_u32 s47, s47, 0x100
	s_addc_u32 s60, s60, 0
	s_cmp_gt_u32 s61, 13
	s_cbranch_scc0 .LBB0_1832
	s_and_b64 vcc, exec, s[16:17]
	s_cbranch_vccz .LBB0_1835
	s_barrier

; #define PG8_STAGE(bufoff, gbase, voff) do { _Pragma("unroll") for (int _i = 0; _i < 2; ++_i) \
;         __builtin_amdgcn_global_load_lds((const unsigned*)((const char*)(gbase) + (voff)[_i]), (PG8_LAS unsigned*)(lds + (bufoff) + ldsw + _i * 8192), 16, 0, 0); } while (0)
; #define PG8_LDA(dst, b, h) do { _Pragma("unroll") for (int m = 0; m < 4; ++m) _Pragma("unroll") for (int k = 0; k < 2; ++k) dst[m][k] = *(const PG8_LAS bf16x8*)(lds + PG8_SA(b, h) + aoff + m * 2048 + k * 1024); } while (0)
; #define PG8_LDB(dst, b, h) do { _Pragma("unroll") for (int n = 0; n < 2; ++n) _Pragma("unroll") for (int k = 0; k < 2; ++k) dst[n][k] = *(const PG8_LAS bf16x8*)(lds + PG8_SB(b, h) + boff + n * 2048 + k * 1024); } while (0)
; #define PG8_MMA(ai, bj, At, Bt) do { __builtin_amdgcn_s_setprio(1); _Pragma("unroll") for (int m = 0; m < 4; ++m) _Pragma("unroll") for (int n = 0; n < 2; ++n) _Pragma("unroll") for (int k = 0; k < 2; ++k) \
;         acc[ai][bj][m][n] = mma16<F16>(Bt[n][k], At[m][k], acc[ai][bj][m][n]); __builtin_amdgcn_s_setprio(0); } while (0)
; #define PG8_WAIT_V(n) asm volatile("s_waitcnt vmcnt(" #n ")" ::: "memory")
; #define PG8_BAR __builtin_amdgcn_s_barrier()
; template <class Epi, class Sched, bool ALIGN_EPI = false, bool SP2 = false, bool F16 = false>
; __device__ __forceinline__ void gemm_phase(PG8_LAS unsigned char* lds, const Gemm g, const Sched& S, const Epi& E, const int wid_in) {
;     ...
;         for (int t = 0; t < nt; t += 2) {
;             const bool last = (t == nt - 2);
;             const char* a1 = cA + (size_t)(t + 1) * kstep;
;             const char* a2 = last ? nA : cA + (size_t)(t + 2) * kstep; const char* b2 = last ? nB : cB + (size_t)(t + 2) * kstep;
;             const char* a3 = a2 + kstep; const char* b3 = b2 + kstep;
;             if (last && has_next) S.a_ready(nxt);
;             if constexpr (SP2) {
;             PG8_LDB(B0, 0, 0); PG8_LDB(B1, 0, 1); PG8_SCHED; PG8_LDA(At, 0, 0); PG8_STAGE(PG8_SA(1, 1), a1 + hstep, voffA);
;             PG8_WAIT_V(8); PG8_WAIT_L(0); PG8_BAR; PG8_MMA(0, 0, At, B0); PG8_MMA(0, 1, At, B1); PG8_BAR; PG8_SCHED;
;             PG8_LDA(At, 0, 1); PG8_STAGE(PG8_SB(0, 0), b2, voffB); PG8_STAGE(PG8_SB(0, 1), b2 + hstep, voffB); PG8_STAGE(PG8_SA(0, 0), a2, voffA);
;             PG8_WAIT_V(8); PG8_WAIT_L(0); PG8_BAR; PG8_MMA(1, 0, At, B0); PG8_MMA(1, 1, At, B1); PG8_BAR; PG8_SCHED;
.LBB0_1909:
	ds_read_b128 v[0:3], v193
	ds_read_b128 v[4:7], v193 offset:1024
	ds_read_b128 v[136:139], v193 offset:2048
	ds_read_b128 v[140:143], v193 offset:3072
	ds_read_b128 v[144:147], v194
	ds_read_b128 v[148:151], v194 offset:1024
	ds_read_b128 v[152:155], v194 offset:2048
	ds_read_b128 v[156:159], v194 offset:3072
	s_add_u32 s48, s46, 0xfffc0080
	s_addc_u32 s49, s47, -1
	s_cmp_eq_u32 s64, 12
	s_cselect_b32 s51, s29, s49
	s_cselect_b32 s50, s42, s48
	s_cselect_b32 s49, s27, s63
	s_cselect_b32 s48, s43, s45
	s_mov_b32 m0, s91
	v_lshl_add_u64 v[188:189], s[46:47], 0, v[168:169]
	ds_read_b128 v[176:179], v195
	ds_read_b128 v[180:183], v195 offset:1024
	ds_read_b128 v[184:187], v195 offset:2048
	ds_read_b128 v[198:201], v195 offset:3072
	ds_read_b128 v[202:205], v195 offset:4096
	ds_read_b128 v[206:209], v195 offset:5120
	ds_read_b128 v[210:213], v195 offset:6144
	ds_read_b128 v[214:217], v195 offset:7168
	global_load_lds_dwordx4 v[188:189], off
	v_lshl_add_u64 v[188:189], s[46:47], 0, v[170:171]
	s_add_i32 m0, s74, 0xe000
	s_nop 0
	global_load_lds_dwordx4 v[188:189], off
	s_waitcnt vmcnt(8)
	s_waitcnt lgkmcnt(0)
	s_barrier
	s_waitcnt lgkmcnt(0)
	v_mfma_f32_16x16x32_f16 v[132:135], v[0:3], v[176:179], v[132:135]
	v_mfma_f32_16x16x32_f16 v[128:131], v[136:139], v[176:179], v[128:131]
	v_mfma_f32_16x16x32_f16 v[116:119], v[0:3], v[184:187], v[116:119]
	v_mfma_f32_16x16x32_f16 v[112:115], v[136:139], v[184:187], v[112:115]
	v_mfma_f32_16x16x32_f16 v[100:103], v[0:3], v[202:205], v[100:103]
	v_mfma_f32_16x16x32_f16 v[96:99], v[136:139], v[202:205], v[96:99]
	v_mfma_f32_16x16x32_f16 v[84:87], v[0:3], v[210:213], v[84:87]
	v_mfma_f32_16x16x32_f16 v[80:83], v[136:139], v[210:213], v[80:83]
	v_mfma_f32_16x16x32_f16 v[132:135], v[4:7], v[180:183], v[132:135]
	v_mfma_f32_16x16x32_f16 v[128:131], v[140:143], v[180:183], v[128:131]
	v_mfma_f32_16x16x32_f16 v[116:119], v[4:7], v[198:201], v[116:119]
	v_mfma_f32_16x16x32_f16 v[112:115], v[140:143], v[198:201], v[112:115]
	v_mfma_f32_16x16x32_f16 v[100:103], v[4:7], v[206:209], v[100:103]
	v_mfma_f32_16x16x32_f16 v[96:99], v[140:143], v[206:209], v[96:99]
	v_mfma_f32_16x16x32_f16 v[84:87], v[4:7], v[214:217], v[84:87]
	v_mfma_f32_16x16x32_f16 v[80:83], v[140:143], v[214:217], v[80:83]
	v_mfma_f32_16x16x32_f16 v[124:127], v[144:147], v[176:179], v[124:127]
	v_mfma_f32_16x16x32_f16 v[120:123], v[152:155], v[176:179], v[120:123]
	v_mfma_f32_16x16x32_f16 v[108:111], v[144:147], v[184:187], v[108:111]
	v_mfma_f32_16x16x32_f16 v[104:107], v[152:155], v[184:187], v[104:107]
	v_mfma_f32_16x16x32_f16 v[92:95], v[144:147], v[202:205], v[92:95]
	v_mfma_f32_16x16x32_f16 v[88:91], v[152:155], v[202:205], v[88:91]
	v_mfma_f32_16x16x32_f16 v[76:79], v[144:147], v[210:213], v[76:79]
	v_mfma_f32_16x16x32_f16 v[72:75], v[152:155], v[210:213], v[72:75]
	v_mfma_f32_16x16x32_f16 v[124:127], v[148:151], v[180:183], v[124:127]
	v_mfma_f32_16x16x32_f16 v[120:123], v[156:159], v[180:183], v[120:123]
	v_mfma_f32_16x16x32_f16 v[108:111], v[148:151], v[198:201], v[108:111]
	v_mfma_f32_16x16x32_f16 v[104:107], v[156:159], v[198:201], v[104:107]
	v_mfma_f32_16x16x32_f16 v[92:95], v[148:151], v[206:209], v[92:95]
	v_mfma_f32_16x16x32_f16 v[88:91], v[156:159], v[206:209], v[88:91]
	v_mfma_f32_16x16x32_f16 v[76:79], v[148:151], v[214:217], v[76:79]
	v_mfma_f32_16x16x32_f16 v[72:75], v[156:159], v[214:217], v[72:75]
	s_barrier
	s_add_i32 s65, s60, s68
	v_lshl_add_u64 v[188:189], s[48:49], 0, v[162:163]
	s_mov_b32 m0, s65
	ds_read_b128 v[176:179], v195 offset:16384
	ds_read_b128 v[180:183], v195 offset:17408
	ds_read_b128 v[184:187], v195 offset:18432
	ds_read_b128 v[198:201], v195 offset:19456
	ds_read_b128 v[202:205], v195 offset:20480
	ds_read_b128 v[206:209], v195 offset:21504
	ds_read_b128 v[210:213], v195 offset:22528
	ds_read_b128 v[214:217], v195 offset:23552
	global_load_lds_dwordx4 v[188:189], off
	s_add_i32 m0, s65, 0x2000
	s_add_u32 s84, s48, 0x40000
	v_lshl_add_u64 v[218:219], s[48:49], 0, v[166:167]
	s_addc_u32 s85, s49, 0
	s_add_i32 s65, s61, s68
	global_load_lds_dwordx4 v[218:219], off
	v_lshl_add_u64 v[220:221], s[84:85], 0, v[162:163]
	s_mov_b32 m0, s65
	v_lshl_add_u64 v[222:223], s[50:51], 0, v[164:165]
	global_load_lds_dwordx4 v[220:221], off
	v_lshl_add_u64 v[220:221], s[84:85], 0, v[166:167]
	s_add_i32 m0, s65, 0x2000
	s_nop 0
	global_load_lds_dwordx4 v[220:221], off
	v_lshl_add_u64 v[220:221], s[50:51], 0, v[160:161]
	s_mov_b32 m0, s74
	s_nop 0
	global_load_lds_dwordx4 v[220:221], off
	s_mov_b32 m0, s66
	s_nop 0
	global_load_lds_dwordx4 v[222:223], off
	s_waitcnt vmcnt(8)
	s_waitcnt lgkmcnt(0)
	s_barrier
; #define PG8_STAGE(bufoff, gbase, voff) do { _Pragma("unroll") for (int _i = 0; _i < 2; ++_i) \
;         __builtin_amdgcn_global_load_lds((const unsigned*)((const char*)(gbase) + (voff)[_i]), (PG8_LAS unsigned*)(lds + (bufoff) + ldsw + _i * 8192), 16, 0, 0); } while (0)
; #define PG8_LDA(dst, b, h) do { _Pragma("unroll") for (int m = 0; m < 4; ++m) _Pragma("unroll") for (int k = 0; k < 2; ++k) dst[m][k] = *(const PG8_LAS bf16x8*)(lds + PG8_SA(b, h) + aoff + m * 2048 + k * 1024); } while (0)
; #define PG8_LDB(dst, b, h) do { _Pragma("unroll") for (int n = 0; n < 2; ++n) _Pragma("unroll") for (int k = 0; k < 2; ++k) dst[n][k] = *(const PG8_LAS bf16x8*)(lds + PG8_SB(b, h) + boff + n * 2048 + k * 1024); } while (0)
; #define PG8_MMA(ai, bj, At, Bt) do { __builtin_amdgcn_s_setprio(1); _Pragma("unroll") for (int m = 0; m < 4; ++m) _Pragma("unroll") for (int n = 0; n < 2; ++n) _Pragma("unroll") for (int k = 0; k < 2; ++k) \
;         acc[ai][bj][m][n] = mma16<F16>(Bt[n][k], At[m][k], acc[ai][bj][m][n]); __builtin_amdgcn_s_setprio(0); } while (0)
; #define PG8_WAIT_V(n) asm volatile("s_waitcnt vmcnt(" #n ")" ::: "memory")
; #define PG8_WAIT_L(n) asm volatile("s_waitcnt lgkmcnt(" #n ")" ::: "memory")
; #define PG8_BAR __builtin_amdgcn_s_barrier()
; #define PG8_SCHED __builtin_amdgcn_sched_barrier(0)
; template <class Epi, class Sched, bool ALIGN_EPI = false, bool SP2 = false, bool F16 = false>
; __device__ __forceinline__ void gemm_phase(PG8_LAS unsigned char* lds, const Gemm g, const Sched& S, const Epi& E, const int wid_in) {
;     ...
;             PG8_WAIT_V(8); PG8_WAIT_L(0); PG8_BAR; PG8_MMA(1, 0, At, B0); PG8_MMA(1, 1, At, B1); PG8_BAR; PG8_SCHED;
;             PG8_LDB(B0, 1, 0); PG8_LDB(B1, 1, 1); PG8_SCHED; PG8_LDA(At, 1, 0); PG8_STAGE(PG8_SA(0, 1), a2 + hstep, voffA);
;             PG8_WAIT_V(8); PG8_WAIT_L(0); PG8_BAR; PG8_MMA(0, 0, At, B0); PG8_MMA(0, 1, At, B1); PG8_BAR; PG8_SCHED;
	s_waitcnt lgkmcnt(0)
	v_mfma_f32_16x16x32_f16 v[68:71], v[0:3], v[176:179], v[68:71]
	v_mfma_f32_16x16x32_f16 v[64:67], v[136:139], v[176:179], v[64:67]
	v_mfma_f32_16x16x32_f16 v[52:55], v[0:3], v[184:187], v[52:55]
	v_mfma_f32_16x16x32_f16 v[48:51], v[136:139], v[184:187], v[48:51]
	v_mfma_f32_16x16x32_f16 v[36:39], v[0:3], v[202:205], v[36:39]
	v_mfma_f32_16x16x32_f16 v[32:35], v[136:139], v[202:205], v[32:35]
	v_mfma_f32_16x16x32_f16 v[0:3], v[0:3], v[210:213], v[20:23]
	v_mfma_f32_16x16x32_f16 v[68:71], v[4:7], v[180:183], v[68:71]
	v_mfma_f32_16x16x32_f16 v[64:67], v[140:143], v[180:183], v[64:67]
	v_mfma_f32_16x16x32_f16 v[52:55], v[4:7], v[198:201], v[52:55]
	v_mfma_f32_16x16x32_f16 v[48:51], v[140:143], v[198:201], v[48:51]
	v_mfma_f32_16x16x32_f16 v[36:39], v[4:7], v[206:209], v[36:39]
	v_mfma_f32_16x16x32_f16 v[32:35], v[140:143], v[206:209], v[32:35]
	v_mfma_f32_16x16x32_f16 v[0:3], v[4:7], v[214:217], v[0:3]
	v_mfma_f32_16x16x32_f16 v[4:7], v[136:139], v[210:213], v[16:19]
	v_mfma_f32_16x16x32_f16 v[4:7], v[140:143], v[214:217], v[4:7]
	v_mfma_f32_16x16x32_f16 v[16:19], v[144:147], v[176:179], v[60:63]
	v_mfma_f32_16x16x32_f16 v[60:63], v[148:151], v[180:183], v[16:19]
	v_mfma_f32_16x16x32_f16 v[16:19], v[152:155], v[176:179], v[56:59]
	v_mfma_f32_16x16x32_f16 v[56:59], v[156:159], v[180:183], v[16:19]
	v_mfma_f32_16x16x32_f16 v[16:19], v[144:147], v[184:187], v[44:47]
	v_mfma_f32_16x16x32_f16 v[44:47], v[148:151], v[198:201], v[16:19]
	v_mfma_f32_16x16x32_f16 v[16:19], v[152:155], v[184:187], v[40:43]
	v_mfma_f32_16x16x32_f16 v[40:43], v[156:159], v[198:201], v[16:19]
	v_mfma_f32_16x16x32_f16 v[16:19], v[144:147], v[202:205], v[28:31]
	v_mfma_f32_16x16x32_f16 v[28:31], v[148:151], v[206:209], v[16:19]
	v_mfma_f32_16x16x32_f16 v[16:19], v[152:155], v[202:205], v[24:27]
	v_mfma_f32_16x16x32_f16 v[12:15], v[144:147], v[210:213], v[12:15]
	v_mfma_f32_16x16x32_f16 v[8:11], v[152:155], v[210:213], v[8:11]
	v_mfma_f32_16x16x32_f16 v[24:27], v[156:159], v[206:209], v[16:19]
	v_mfma_f32_16x16x32_f16 v[12:15], v[148:151], v[214:217], v[12:15]
	v_mfma_f32_16x16x32_f16 v[8:11], v[156:159], v[214:217], v[8:11]
	s_barrier
	s_add_i32 s65, 0, 0x18000
	s_add_i32 s76, 0, 0x1c000
	v_add_u32_e32 v140, s65, v192
	v_add_u32_e32 v156, s76, v192
	ds_read_b128 v[16:19], v140
	ds_read_b128 v[20:23], v140 offset:1024
	ds_read_b128 v[136:139], v140 offset:2048
	ds_read_b128 v[140:143], v140 offset:3072
	ds_read_b128 v[144:147], v156
	ds_read_b128 v[148:151], v156 offset:1024
	ds_read_b128 v[152:155], v156 offset:2048
	ds_read_b128 v[156:159], v156 offset:3072
	s_add_u32 s50, s50, 0x40000
	s_addc_u32 s51, s51, 0
	s_mov_b32 m0, s90
	v_lshl_add_u64 v[224:225], s[50:51], 0, v[160:161]
	ds_read_b128 v[176:179], v195 offset:32768
	ds_read_b128 v[180:183], v195 offset:33792
	ds_read_b128 v[184:187], v195 offset:34816
	ds_read_b128 v[198:201], v195 offset:35840
	ds_read_b128 v[202:205], v195 offset:36864
	ds_read_b128 v[206:209], v195 offset:37888
	ds_read_b128 v[210:213], v195 offset:38912
	ds_read_b128 v[214:217], v195 offset:39936
	global_load_lds_dwordx4 v[224:225], off
	v_lshl_add_u64 v[224:225], s[50:51], 0, v[164:165]
	s_mov_b32 m0, s37
	s_nop 0
	global_load_lds_dwordx4 v[224:225], off
	s_waitcnt vmcnt(8)
	s_waitcnt lgkmcnt(0)
	s_barrier
	s_waitcnt lgkmcnt(0)
	v_mfma_f32_16x16x32_f16 v[132:135], v[16:19], v[176:179], v[132:135]
	v_mfma_f32_16x16x32_f16 v[128:131], v[136:139], v[176:179], v[128:131]
	v_mfma_f32_16x16x32_f16 v[116:119], v[16:19], v[184:187], v[116:119]
	v_mfma_f32_16x16x32_f16 v[112:115], v[136:139], v[184:187], v[112:115]
	v_mfma_f32_16x16x32_f16 v[100:103], v[16:19], v[202:205], v[100:103]
	v_mfma_f32_16x16x32_f16 v[96:99], v[136:139], v[202:205], v[96:99]
	v_mfma_f32_16x16x32_f16 v[84:87], v[16:19], v[210:213], v[84:87]
	v_mfma_f32_16x16x32_f16 v[80:83], v[136:139], v[210:213], v[80:83]
	v_mfma_f32_16x16x32_f16 v[132:135], v[20:23], v[180:183], v[132:135]
	v_mfma_f32_16x16x32_f16 v[128:131], v[140:143], v[180:183], v[128:131]
	v_mfma_f32_16x16x32_f16 v[116:119], v[20:23], v[198:201], v[116:119]
	v_mfma_f32_16x16x32_f16 v[112:115], v[140:143], v[198:201], v[112:115]
	v_mfma_f32_16x16x32_f16 v[100:103], v[20:23], v[206:209], v[100:103]
	v_mfma_f32_16x16x32_f16 v[96:99], v[140:143], v[206:209], v[96:99]
	v_mfma_f32_16x16x32_f16 v[84:87], v[20:23], v[214:217], v[84:87]
	v_mfma_f32_16x16x32_f16 v[80:83], v[140:143], v[214:217], v[80:83]
	v_mfma_f32_16x16x32_f16 v[124:127], v[144:147], v[176:179], v[124:127]
	v_mfma_f32_16x16x32_f16 v[120:123], v[152:155], v[176:179], v[120:123]
	v_mfma_f32_16x16x32_f16 v[108:111], v[144:147], v[184:187], v[108:111]
	v_mfma_f32_16x16x32_f16 v[104:107], v[152:155], v[184:187], v[104:107]
	v_mfma_f32_16x16x32_f16 v[92:95], v[144:147], v[202:205], v[92:95]
	v_mfma_f32_16x16x32_f16 v[88:91], v[152:155], v[202:205], v[88:91]
	v_mfma_f32_16x16x32_f16 v[76:79], v[144:147], v[210:213], v[76:79]
	v_mfma_f32_16x16x32_f16 v[72:75], v[152:155], v[210:213], v[72:75]
	v_mfma_f32_16x16x32_f16 v[124:127], v[148:151], v[180:183], v[124:127]
	v_mfma_f32_16x16x32_f16 v[120:123], v[156:159], v[180:183], v[120:123]
	v_mfma_f32_16x16x32_f16 v[108:111], v[148:151], v[198:201], v[108:111]
	v_mfma_f32_16x16x32_f16 v[104:107], v[156:159], v[198:201], v[104:107]
	v_mfma_f32_16x16x32_f16 v[92:95], v[148:151], v[206:209], v[92:95]
	v_mfma_f32_16x16x32_f16 v[88:91], v[156:159], v[206:209], v[88:91]
	v_mfma_f32_16x16x32_f16 v[76:79], v[148:151], v[214:217], v[76:79]
	v_mfma_f32_16x16x32_f16 v[72:75], v[156:159], v[214:217], v[72:75]
	s_barrier
; #define PG8_STAGE(bufoff, gbase, voff) do { _Pragma("unroll") for (int _i = 0; _i < 2; ++_i) \
;         __builtin_amdgcn_global_load_lds((const unsigned*)((const char*)(gbase) + (voff)[_i]), (PG8_LAS unsigned*)(lds + (bufoff) + ldsw + _i * 8192), 16, 0, 0); } while (0)
; #define PG8_LDA(dst, b, h) do { _Pragma("unroll") for (int m = 0; m < 4; ++m) _Pragma("unroll") for (int k = 0; k < 2; ++k) dst[m][k] = *(const PG8_LAS bf16x8*)(lds + PG8_SA(b, h) + aoff + m * 2048 + k * 1024); } while (0)
; #define PG8_MMA(ai, bj, At, Bt) do { __builtin_amdgcn_s_setprio(1); _Pragma("unroll") for (int m = 0; m < 4; ++m) _Pragma("unroll") for (int n = 0; n < 2; ++n) _Pragma("unroll") for (int k = 0; k < 2; ++k) \
;         acc[ai][bj][m][n] = mma16<F16>(Bt[n][k], At[m][k], acc[ai][bj][m][n]); __builtin_amdgcn_s_setprio(0); } while (0)
; #define PG8_WAIT_V(n) asm volatile("s_waitcnt vmcnt(" #n ")" ::: "memory")
; #define PG8_WAIT_L(n) asm volatile("s_waitcnt lgkmcnt(" #n ")" ::: "memory")
; #define PG8_BAR __builtin_amdgcn_s_barrier()
; #define PG8_SCHED __builtin_amdgcn_sched_barrier(0)
; template <class Epi, class Sched, bool ALIGN_EPI = false, bool SP2 = false, bool F16 = false>
; __device__ __forceinline__ void gemm_phase(PG8_LAS unsigned char* lds, const Gemm g, const Sched& S, const Epi& E, const int wid_in) {
;     ...
;             PG8_LDA(At, 1, 1); PG8_STAGE(PG8_SB(1, 0), b3, voffB); PG8_STAGE(PG8_SB(1, 1), b3 + hstep, voffB); PG8_STAGE(PG8_SA(1, 0), a3, voffA);
;             PG8_WAIT_V(8); PG8_WAIT_L(0); PG8_BAR; PG8_MMA(1, 0, At, B0); PG8_MMA(1, 1, At, B1); PG8_BAR; PG8_SCHED;
;     ...
;         if constexpr (ALIGN_EPI) { if (wr == 0) PG8_BAR; }
	s_add_i32 s50, s65, s68
	v_lshl_add_u64 v[188:189], v[188:189], 0, s[24:25]
	s_mov_b32 m0, s50
	ds_read_b128 v[176:179], v195 offset:49152
	ds_read_b128 v[180:183], v195 offset:50176
	ds_read_b128 v[184:187], v195 offset:51200
	ds_read_b128 v[198:201], v195 offset:52224
	ds_read_b128 v[202:205], v195 offset:53248
	ds_read_b128 v[206:209], v195 offset:54272
	ds_read_b128 v[210:213], v195 offset:55296
	ds_read_b128 v[214:217], v195 offset:56320
	global_load_lds_dwordx4 v[188:189], off
	s_add_i32 m0, s50, 0x2000
	s_add_u32 s48, s48, 0x40080
	v_lshl_add_u64 v[188:189], v[218:219], 0, s[24:25]
	s_addc_u32 s49, s49, 0
	s_add_i32 s50, s76, s68
	global_load_lds_dwordx4 v[188:189], off
	v_lshl_add_u64 v[188:189], s[48:49], 0, v[162:163]
	s_mov_b32 m0, s50
	s_nop 0
	global_load_lds_dwordx4 v[188:189], off
	v_lshl_add_u64 v[188:189], s[48:49], 0, v[166:167]
	s_add_i32 m0, s50, 0x2000
	s_nop 0
	global_load_lds_dwordx4 v[188:189], off
	v_lshl_add_u64 v[188:189], v[220:221], 0, s[24:25]
	s_mov_b32 m0, s75
	s_nop 0
	global_load_lds_dwordx4 v[188:189], off
	v_lshl_add_u64 v[188:189], v[222:223], 0, s[24:25]
	s_mov_b32 m0, s67
	s_nop 0
	global_load_lds_dwordx4 v[188:189], off
	s_waitcnt vmcnt(8)
	s_waitcnt lgkmcnt(0)
	s_barrier
	s_waitcnt lgkmcnt(0)
	v_mfma_f32_16x16x32_f16 v[68:71], v[16:19], v[176:179], v[68:71]
	v_mfma_f32_16x16x32_f16 v[52:55], v[16:19], v[184:187], v[52:55]
	v_mfma_f32_16x16x32_f16 v[36:39], v[16:19], v[202:205], v[36:39]
	v_mfma_f32_16x16x32_f16 v[0:3], v[16:19], v[210:213], v[0:3]
	v_mfma_f32_16x16x32_f16 v[68:71], v[20:23], v[180:183], v[68:71]
	v_mfma_f32_16x16x32_f16 v[64:67], v[136:139], v[176:179], v[64:67]
	v_mfma_f32_16x16x32_f16 v[52:55], v[20:23], v[198:201], v[52:55]
	v_mfma_f32_16x16x32_f16 v[48:51], v[136:139], v[184:187], v[48:51]
	v_mfma_f32_16x16x32_f16 v[36:39], v[20:23], v[206:209], v[36:39]
	v_mfma_f32_16x16x32_f16 v[32:35], v[136:139], v[202:205], v[32:35]
	v_mfma_f32_16x16x32_f16 v[20:23], v[20:23], v[214:217], v[0:3]
	v_mfma_f32_16x16x32_f16 v[0:3], v[136:139], v[210:213], v[4:7]
	v_mfma_f32_16x16x32_f16 v[64:67], v[140:143], v[180:183], v[64:67]
	v_mfma_f32_16x16x32_f16 v[48:51], v[140:143], v[198:201], v[48:51]
	v_mfma_f32_16x16x32_f16 v[32:35], v[140:143], v[206:209], v[32:35]
	v_mfma_f32_16x16x32_f16 v[16:19], v[140:143], v[214:217], v[0:3]
	v_mfma_f32_16x16x32_f16 v[0:3], v[144:147], v[176:179], v[60:63]
	v_mfma_f32_16x16x32_f16 v[60:63], v[148:151], v[180:183], v[0:3]
	v_mfma_f32_16x16x32_f16 v[0:3], v[152:155], v[176:179], v[56:59]
	v_mfma_f32_16x16x32_f16 v[56:59], v[156:159], v[180:183], v[0:3]
	v_mfma_f32_16x16x32_f16 v[0:3], v[144:147], v[184:187], v[44:47]
	v_mfma_f32_16x16x32_f16 v[44:47], v[148:151], v[198:201], v[0:3]
	v_mfma_f32_16x16x32_f16 v[0:3], v[152:155], v[184:187], v[40:43]
	v_mfma_f32_16x16x32_f16 v[40:43], v[156:159], v[198:201], v[0:3]
	v_mfma_f32_16x16x32_f16 v[0:3], v[144:147], v[202:205], v[28:31]
	v_mfma_f32_16x16x32_f16 v[28:31], v[148:151], v[206:209], v[0:3]
	v_mfma_f32_16x16x32_f16 v[0:3], v[152:155], v[202:205], v[24:27]
	v_mfma_f32_16x16x32_f16 v[24:27], v[156:159], v[206:209], v[0:3]
	v_mfma_f32_16x16x32_f16 v[0:3], v[144:147], v[210:213], v[12:15]
	v_mfma_f32_16x16x32_f16 v[12:15], v[148:151], v[214:217], v[0:3]
	v_mfma_f32_16x16x32_f16 v[0:3], v[152:155], v[210:213], v[8:11]
	v_mfma_f32_16x16x32_f16 v[8:11], v[156:159], v[214:217], v[0:3]
	s_barrier
	s_add_i32 s64, s64, 2
	s_add_u32 s46, s46, 0x100
	s_addc_u32 s47, s47, 0
	s_add_u32 s45, s45, 0x100
	s_addc_u32 s63, s63, 0
	s_cmp_gt_u32 s64, 13
	s_cbranch_scc0 .LBB0_1909
	s_and_b64 vcc, exec, s[16:17]
	s_cbranch_vccz .LBB0_1912
	s_barrier

; #define PG8_STAGE(bufoff, gbase, voff) do { _Pragma("unroll") for (int _i = 0; _i < 2; ++_i) \
;         __builtin_amdgcn_global_load_lds((const unsigned*)((const char*)(gbase) + (voff)[_i]), (PG8_LAS unsigned*)(lds + (bufoff) + ldsw + _i * 8192), 16, 0, 0); } while (0)
; #define PG8_LDA(dst, b, h) do { _Pragma("unroll") for (int m = 0; m < 4; ++m) _Pragma("unroll") for (int k = 0; k < 2; ++k) dst[m][k] = *(const PG8_LAS bf16x8*)(lds + PG8_SA(b, h) + aoff + m * 2048 + k * 1024); } while (0)
; #define PG8_LDB(dst, b, h) do { _Pragma("unroll") for (int n = 0; n < 2; ++n) _Pragma("unroll") for (int k = 0; k < 2; ++k) dst[n][k] = *(const PG8_LAS bf16x8*)(lds + PG8_SB(b, h) + boff + n * 2048 + k * 1024); } while (0)
; #define PG8_MMA(ai, bj, At, Bt) do { __builtin_amdgcn_s_setprio(1); _Pragma("unroll") for (int m = 0; m < 4; ++m) _Pragma("unroll") for (int n = 0; n < 2; ++n) _Pragma("unroll") for (int k = 0; k < 2; ++k) \
;         acc[ai][bj][m][n] = mma16<F16>(Bt[n][k], At[m][k], acc[ai][bj][m][n]); __builtin_amdgcn_s_setprio(0); } while (0)
; #define PG8_WAIT_V(n) asm volatile("s_waitcnt vmcnt(" #n ")" ::: "memory")
; #define PG8_BAR __builtin_amdgcn_s_barrier()
; template <class Epi, class Sched, bool ALIGN_EPI = false, bool SP2 = false, bool F16 = false>
; __device__ __forceinline__ void gemm_phase(PG8_LAS unsigned char* lds, const Gemm g, const Sched& S, const Epi& E, const int wid_in) {
;     ...
;         for (int t = 0; t < nt; t += 2) {
;             const bool last = (t == nt - 2);
;             const char* a1 = cA + (size_t)(t + 1) * kstep;
;             const char* a2 = last ? nA : cA + (size_t)(t + 2) * kstep; const char* b2 = last ? nB : cB + (size_t)(t + 2) * kstep;
;             const char* a3 = a2 + kstep; const char* b3 = b2 + kstep;
;             if (last && has_next) S.a_ready(nxt);
;             if constexpr (SP2) {
;             PG8_LDB(B0, 0, 0); PG8_LDB(B1, 0, 1); PG8_SCHED; PG8_LDA(At, 0, 0); PG8_STAGE(PG8_SA(1, 1), a1 + hstep, voffA);
;             PG8_WAIT_V(8); PG8_WAIT_L(0); PG8_BAR; PG8_MMA(0, 0, At, B0); PG8_MMA(0, 1, At, B1); PG8_BAR; PG8_SCHED;
;             PG8_LDA(At, 0, 1); PG8_STAGE(PG8_SB(0, 0), b2, voffB); PG8_STAGE(PG8_SB(0, 1), b2 + hstep, voffB); PG8_STAGE(PG8_SA(0, 0), a2, voffA);
;             PG8_WAIT_V(8); PG8_WAIT_L(0); PG8_BAR; PG8_MMA(1, 0, At, B0); PG8_MMA(1, 1, At, B1); PG8_BAR; PG8_SCHED;
.LBB0_2040:
	ds_read_b128 v[128:131], v189
	ds_read_b128 v[132:135], v189 offset:1024
	ds_read_b128 v[136:139], v189 offset:2048
	ds_read_b128 v[140:143], v189 offset:3072
	ds_read_b128 v[144:147], v190
	ds_read_b128 v[148:151], v190 offset:1024
	ds_read_b128 v[168:171], v190 offset:2048
	ds_read_b128 v[172:175], v190 offset:3072
	s_add_u32 s44, s36, 0x100
	s_addc_u32 s45, s37, 0
	s_cmp_eq_u32 s59, 40
	s_cselect_b32 s49, s13, s45
	s_cselect_b32 s48, s12, s44
	s_cselect_b32 s47, s35, s58
	s_cselect_b32 s46, s34, s43
	s_mov_b32 m0, s91
	v_lshl_add_u64 v[184:185], s[36:37], 0, v[160:161]
	ds_read_b128 v[176:179], v191
	ds_read_b128 v[180:183], v191 offset:1024
	ds_read_b128 v[192:195], v191 offset:2048
	ds_read_b128 v[196:199], v191 offset:3072
	ds_read_b128 v[200:203], v191 offset:4096
	ds_read_b128 v[204:207], v191 offset:5120
	ds_read_b128 v[208:211], v191 offset:6144
	ds_read_b128 v[212:215], v191 offset:7168
	global_load_lds_dwordx4 v[184:185], off
	v_lshl_add_u64 v[184:185], s[36:37], 0, v[162:163]
	s_add_i32 m0, s74, 0xe000
	s_nop 0
	global_load_lds_dwordx4 v[184:185], off
	s_waitcnt vmcnt(8)
	s_waitcnt lgkmcnt(0)
	s_barrier
	s_waitcnt lgkmcnt(0)
	v_mfma_f32_16x16x32_bf16 v[124:127], v[128:131], v[176:179], v[124:127]
	v_mfma_f32_16x16x32_bf16 v[120:123], v[136:139], v[176:179], v[120:123]
	v_mfma_f32_16x16x32_bf16 v[108:111], v[128:131], v[192:195], v[108:111]
	v_mfma_f32_16x16x32_bf16 v[104:107], v[136:139], v[192:195], v[104:107]
	v_mfma_f32_16x16x32_bf16 v[92:95], v[128:131], v[200:203], v[92:95]
	v_mfma_f32_16x16x32_bf16 v[88:91], v[136:139], v[200:203], v[88:91]
	v_mfma_f32_16x16x32_bf16 v[76:79], v[128:131], v[208:211], v[76:79]
	v_mfma_f32_16x16x32_bf16 v[72:75], v[136:139], v[208:211], v[72:75]
	v_mfma_f32_16x16x32_bf16 v[124:127], v[132:135], v[180:183], v[124:127]
	v_mfma_f32_16x16x32_bf16 v[120:123], v[140:143], v[180:183], v[120:123]
	v_mfma_f32_16x16x32_bf16 v[108:111], v[132:135], v[196:199], v[108:111]
	v_mfma_f32_16x16x32_bf16 v[104:107], v[140:143], v[196:199], v[104:107]
	v_mfma_f32_16x16x32_bf16 v[92:95], v[132:135], v[204:207], v[92:95]
	v_mfma_f32_16x16x32_bf16 v[88:91], v[140:143], v[204:207], v[88:91]
	v_mfma_f32_16x16x32_bf16 v[76:79], v[132:135], v[212:215], v[76:79]
	v_mfma_f32_16x16x32_bf16 v[72:75], v[140:143], v[212:215], v[72:75]
	v_mfma_f32_16x16x32_bf16 v[116:119], v[144:147], v[176:179], v[116:119]
	v_mfma_f32_16x16x32_bf16 v[112:115], v[168:171], v[176:179], v[112:115]
	v_mfma_f32_16x16x32_bf16 v[100:103], v[144:147], v[192:195], v[100:103]
	v_mfma_f32_16x16x32_bf16 v[96:99], v[168:171], v[192:195], v[96:99]
	v_mfma_f32_16x16x32_bf16 v[84:87], v[144:147], v[200:203], v[84:87]
	v_mfma_f32_16x16x32_bf16 v[80:83], v[168:171], v[200:203], v[80:83]
	v_mfma_f32_16x16x32_bf16 v[68:71], v[144:147], v[208:211], v[68:71]
	v_mfma_f32_16x16x32_bf16 v[64:67], v[168:171], v[208:211], v[64:67]
	v_mfma_f32_16x16x32_bf16 v[116:119], v[148:151], v[180:183], v[116:119]
	v_mfma_f32_16x16x32_bf16 v[112:115], v[172:175], v[180:183], v[112:115]
	v_mfma_f32_16x16x32_bf16 v[100:103], v[148:151], v[196:199], v[100:103]
	v_mfma_f32_16x16x32_bf16 v[96:99], v[172:175], v[196:199], v[96:99]
	v_mfma_f32_16x16x32_bf16 v[84:87], v[148:151], v[204:207], v[84:87]
	v_mfma_f32_16x16x32_bf16 v[80:83], v[172:175], v[204:207], v[80:83]
	v_mfma_f32_16x16x32_bf16 v[68:71], v[148:151], v[212:215], v[68:71]
	v_mfma_f32_16x16x32_bf16 v[64:67], v[172:175], v[212:215], v[64:67]
	s_barrier
	s_add_i32 s36, s53, s68
	v_lshl_add_u64 v[184:185], s[46:47], 0, v[154:155]
	s_mov_b32 m0, s36
	ds_read_b128 v[176:179], v191 offset:16384
	ds_read_b128 v[180:183], v191 offset:17408
	ds_read_b128 v[192:195], v191 offset:18432
	ds_read_b128 v[196:199], v191 offset:19456
	ds_read_b128 v[200:203], v191 offset:20480
	ds_read_b128 v[204:207], v191 offset:21504
	ds_read_b128 v[208:211], v191 offset:22528
	ds_read_b128 v[212:215], v191 offset:23552
	global_load_lds_dwordx4 v[184:185], off
	s_add_i32 m0, s36, 0x2000
	s_add_u32 s36, s46, 0xb0000
	v_lshl_add_u64 v[216:217], s[46:47], 0, v[158:159]
	s_addc_u32 s37, s47, 0
	s_add_i32 s60, s54, s68
	global_load_lds_dwordx4 v[216:217], off
	v_lshl_add_u64 v[218:219], s[36:37], 0, v[154:155]
	s_mov_b32 m0, s60
	v_lshl_add_u64 v[220:221], s[48:49], 0, v[156:157]
	global_load_lds_dwordx4 v[218:219], off
	v_lshl_add_u64 v[218:219], s[36:37], 0, v[158:159]
	s_add_i32 m0, s60, 0x2000
	s_nop 0
	global_load_lds_dwordx4 v[218:219], off
	v_lshl_add_u64 v[218:219], s[48:49], 0, v[152:153]
	s_mov_b32 m0, s74
	s_nop 0
	global_load_lds_dwordx4 v[218:219], off
	s_mov_b32 m0, s66
	s_nop 0
	global_load_lds_dwordx4 v[220:221], off
	s_waitcnt vmcnt(8)
	s_waitcnt lgkmcnt(0)
	s_barrier
; #define PG8_STAGE(bufoff, gbase, voff) do { _Pragma("unroll") for (int _i = 0; _i < 2; ++_i) \
;         __builtin_amdgcn_global_load_lds((const unsigned*)((const char*)(gbase) + (voff)[_i]), (PG8_LAS unsigned*)(lds + (bufoff) + ldsw + _i * 8192), 16, 0, 0); } while (0)
; #define PG8_LDA(dst, b, h) do { _Pragma("unroll") for (int m = 0; m < 4; ++m) _Pragma("unroll") for (int k = 0; k < 2; ++k) dst[m][k] = *(const PG8_LAS bf16x8*)(lds + PG8_SA(b, h) + aoff + m * 2048 + k * 1024); } while (0)
; #define PG8_LDB(dst, b, h) do { _Pragma("unroll") for (int n = 0; n < 2; ++n) _Pragma("unroll") for (int k = 0; k < 2; ++k) dst[n][k] = *(const PG8_LAS bf16x8*)(lds + PG8_SB(b, h) + boff + n * 2048 + k * 1024); } while (0)
; #define PG8_MMA(ai, bj, At, Bt) do { __builtin_amdgcn_s_setprio(1); _Pragma("unroll") for (int m = 0; m < 4; ++m) _Pragma("unroll") for (int n = 0; n < 2; ++n) _Pragma("unroll") for (int k = 0; k < 2; ++k) \
;         acc[ai][bj][m][n] = mma16<F16>(Bt[n][k], At[m][k], acc[ai][bj][m][n]); __builtin_amdgcn_s_setprio(0); } while (0)
; #define PG8_WAIT_V(n) asm volatile("s_waitcnt vmcnt(" #n ")" ::: "memory")
; #define PG8_WAIT_L(n) asm volatile("s_waitcnt lgkmcnt(" #n ")" ::: "memory")
; #define PG8_BAR __builtin_amdgcn_s_barrier()
; #define PG8_SCHED __builtin_amdgcn_sched_barrier(0)
; template <class Epi, class Sched, bool ALIGN_EPI = false, bool SP2 = false, bool F16 = false>
; __device__ __forceinline__ void gemm_phase(PG8_LAS unsigned char* lds, const Gemm g, const Sched& S, const Epi& E, const int wid_in) {
;     ...
;             PG8_WAIT_V(8); PG8_WAIT_L(0); PG8_BAR; PG8_MMA(1, 0, At, B0); PG8_MMA(1, 1, At, B1); PG8_BAR; PG8_SCHED;
;             PG8_LDB(B0, 1, 0); PG8_LDB(B1, 1, 1); PG8_SCHED; PG8_LDA(At, 1, 0); PG8_STAGE(PG8_SA(0, 1), a2 + hstep, voffA);
;             PG8_WAIT_V(8); PG8_WAIT_L(0); PG8_BAR; PG8_MMA(0, 0, At, B0); PG8_MMA(0, 1, At, B1); PG8_BAR; PG8_SCHED;
	s_waitcnt lgkmcnt(0)
	v_mfma_f32_16x16x32_bf16 v[60:63], v[128:131], v[176:179], v[60:63]
	v_mfma_f32_16x16x32_bf16 v[56:59], v[136:139], v[176:179], v[56:59]
	v_mfma_f32_16x16x32_bf16 v[44:47], v[128:131], v[192:195], v[44:47]
	v_mfma_f32_16x16x32_bf16 v[40:43], v[136:139], v[192:195], v[40:43]
	v_mfma_f32_16x16x32_bf16 v[28:31], v[128:131], v[200:203], v[28:31]
	v_mfma_f32_16x16x32_bf16 v[24:27], v[136:139], v[200:203], v[24:27]
	v_mfma_f32_16x16x32_bf16 v[12:15], v[128:131], v[208:211], v[12:15]
	v_mfma_f32_16x16x32_bf16 v[8:11], v[136:139], v[208:211], v[8:11]
	v_mfma_f32_16x16x32_bf16 v[60:63], v[132:135], v[180:183], v[60:63]
	v_mfma_f32_16x16x32_bf16 v[56:59], v[140:143], v[180:183], v[56:59]
	v_mfma_f32_16x16x32_bf16 v[44:47], v[132:135], v[196:199], v[44:47]
	v_mfma_f32_16x16x32_bf16 v[40:43], v[140:143], v[196:199], v[40:43]
	v_mfma_f32_16x16x32_bf16 v[28:31], v[132:135], v[204:207], v[28:31]
	v_mfma_f32_16x16x32_bf16 v[24:27], v[140:143], v[204:207], v[24:27]
	v_mfma_f32_16x16x32_bf16 v[12:15], v[132:135], v[212:215], v[12:15]
	v_mfma_f32_16x16x32_bf16 v[8:11], v[140:143], v[212:215], v[8:11]
	v_mfma_f32_16x16x32_bf16 v[52:55], v[144:147], v[176:179], v[52:55]
	v_mfma_f32_16x16x32_bf16 v[48:51], v[168:171], v[176:179], v[48:51]
	v_mfma_f32_16x16x32_bf16 v[36:39], v[144:147], v[192:195], v[36:39]
	v_mfma_f32_16x16x32_bf16 v[32:35], v[168:171], v[192:195], v[32:35]
	v_mfma_f32_16x16x32_bf16 v[20:23], v[144:147], v[200:203], v[20:23]
	v_mfma_f32_16x16x32_bf16 v[16:19], v[168:171], v[200:203], v[16:19]
	v_mfma_f32_16x16x32_bf16 v[4:7], v[144:147], v[208:211], v[4:7]
	v_mfma_f32_16x16x32_bf16 v[0:3], v[168:171], v[208:211], v[0:3]
	v_mfma_f32_16x16x32_bf16 v[52:55], v[148:151], v[180:183], v[52:55]
	v_mfma_f32_16x16x32_bf16 v[48:51], v[172:175], v[180:183], v[48:51]
	v_mfma_f32_16x16x32_bf16 v[36:39], v[148:151], v[196:199], v[36:39]
	v_mfma_f32_16x16x32_bf16 v[32:35], v[172:175], v[196:199], v[32:35]
	v_mfma_f32_16x16x32_bf16 v[20:23], v[148:151], v[204:207], v[20:23]
	v_mfma_f32_16x16x32_bf16 v[16:19], v[172:175], v[204:207], v[16:19]
	v_mfma_f32_16x16x32_bf16 v[4:7], v[148:151], v[212:215], v[4:7]
	v_mfma_f32_16x16x32_bf16 v[0:3], v[172:175], v[212:215], v[0:3]
	s_barrier
	s_add_i32 s60, 0, 0x18000
	s_add_i32 s61, 0, 0x1c000
	v_add_u32_e32 v140, s60, v188
	v_add_u32_e32 v172, s61, v188
	ds_read_b128 v[128:131], v140
	ds_read_b128 v[132:135], v140 offset:1024
	ds_read_b128 v[136:139], v140 offset:2048
	ds_read_b128 v[140:143], v140 offset:3072
	ds_read_b128 v[144:147], v172
	ds_read_b128 v[148:151], v172 offset:1024
	ds_read_b128 v[168:171], v172 offset:2048
	ds_read_b128 v[172:175], v172 offset:3072
	s_add_u32 s36, s48, 0xb0000
	s_addc_u32 s37, s49, 0
	s_mov_b32 m0, s90
	v_lshl_add_u64 v[222:223], s[36:37], 0, v[152:153]
	ds_read_b128 v[176:179], v191 offset:32768
	ds_read_b128 v[180:183], v191 offset:33792
	ds_read_b128 v[192:195], v191 offset:34816
	ds_read_b128 v[196:199], v191 offset:35840
	ds_read_b128 v[200:203], v191 offset:36864
	ds_read_b128 v[204:207], v191 offset:37888
	ds_read_b128 v[208:211], v191 offset:38912
	ds_read_b128 v[212:215], v191 offset:39936
	global_load_lds_dwordx4 v[222:223], off
	v_lshl_add_u64 v[222:223], s[36:37], 0, v[156:157]
	s_mov_b32 m0, s41
	s_nop 0
	global_load_lds_dwordx4 v[222:223], off
	s_waitcnt vmcnt(8)
	s_waitcnt lgkmcnt(0)
	s_barrier
	s_waitcnt lgkmcnt(0)
	v_mfma_f32_16x16x32_bf16 v[124:127], v[128:131], v[176:179], v[124:127]
	v_mfma_f32_16x16x32_bf16 v[120:123], v[136:139], v[176:179], v[120:123]
	v_mfma_f32_16x16x32_bf16 v[108:111], v[128:131], v[192:195], v[108:111]
	v_mfma_f32_16x16x32_bf16 v[104:107], v[136:139], v[192:195], v[104:107]
	v_mfma_f32_16x16x32_bf16 v[92:95], v[128:131], v[200:203], v[92:95]
	v_mfma_f32_16x16x32_bf16 v[88:91], v[136:139], v[200:203], v[88:91]
	v_mfma_f32_16x16x32_bf16 v[76:79], v[128:131], v[208:211], v[76:79]
	v_mfma_f32_16x16x32_bf16 v[72:75], v[136:139], v[208:211], v[72:75]
	v_mfma_f32_16x16x32_bf16 v[124:127], v[132:135], v[180:183], v[124:127]
	v_mfma_f32_16x16x32_bf16 v[120:123], v[140:143], v[180:183], v[120:123]
	v_mfma_f32_16x16x32_bf16 v[108:111], v[132:135], v[196:199], v[108:111]
	v_mfma_f32_16x16x32_bf16 v[104:107], v[140:143], v[196:199], v[104:107]
	v_mfma_f32_16x16x32_bf16 v[92:95], v[132:135], v[204:207], v[92:95]
	v_mfma_f32_16x16x32_bf16 v[88:91], v[140:143], v[204:207], v[88:91]
	v_mfma_f32_16x16x32_bf16 v[76:79], v[132:135], v[212:215], v[76:79]
	v_mfma_f32_16x16x32_bf16 v[72:75], v[140:143], v[212:215], v[72:75]
	v_mfma_f32_16x16x32_bf16 v[116:119], v[144:147], v[176:179], v[116:119]
	v_mfma_f32_16x16x32_bf16 v[112:115], v[168:171], v[176:179], v[112:115]
	v_mfma_f32_16x16x32_bf16 v[100:103], v[144:147], v[192:195], v[100:103]
	v_mfma_f32_16x16x32_bf16 v[96:99], v[168:171], v[192:195], v[96:99]
	v_mfma_f32_16x16x32_bf16 v[84:87], v[144:147], v[200:203], v[84:87]
	v_mfma_f32_16x16x32_bf16 v[80:83], v[168:171], v[200:203], v[80:83]
	v_mfma_f32_16x16x32_bf16 v[68:71], v[144:147], v[208:211], v[68:71]
	v_mfma_f32_16x16x32_bf16 v[64:67], v[168:171], v[208:211], v[64:67]
	v_mfma_f32_16x16x32_bf16 v[116:119], v[148:151], v[180:183], v[116:119]
	v_mfma_f32_16x16x32_bf16 v[112:115], v[172:175], v[180:183], v[112:115]
	v_mfma_f32_16x16x32_bf16 v[100:103], v[148:151], v[196:199], v[100:103]
	v_mfma_f32_16x16x32_bf16 v[96:99], v[172:175], v[196:199], v[96:99]
	v_mfma_f32_16x16x32_bf16 v[84:87], v[148:151], v[204:207], v[84:87]
	v_mfma_f32_16x16x32_bf16 v[80:83], v[172:175], v[204:207], v[80:83]
	v_mfma_f32_16x16x32_bf16 v[68:71], v[148:151], v[212:215], v[68:71]
	v_mfma_f32_16x16x32_bf16 v[64:67], v[172:175], v[212:215], v[64:67]
	s_barrier
; #define PG8_STAGE(bufoff, gbase, voff) do { _Pragma("unroll") for (int _i = 0; _i < 2; ++_i) \
;         __builtin_amdgcn_global_load_lds((const unsigned*)((const char*)(gbase) + (voff)[_i]), (PG8_LAS unsigned*)(lds + (bufoff) + ldsw + _i * 8192), 16, 0, 0); } while (0)
; #define PG8_LDA(dst, b, h) do { _Pragma("unroll") for (int m = 0; m < 4; ++m) _Pragma("unroll") for (int k = 0; k < 2; ++k) dst[m][k] = *(const PG8_LAS bf16x8*)(lds + PG8_SA(b, h) + aoff + m * 2048 + k * 1024); } while (0)
; #define PG8_MMA(ai, bj, At, Bt) do { __builtin_amdgcn_s_setprio(1); _Pragma("unroll") for (int m = 0; m < 4; ++m) _Pragma("unroll") for (int n = 0; n < 2; ++n) _Pragma("unroll") for (int k = 0; k < 2; ++k) \
;         acc[ai][bj][m][n] = mma16<F16>(Bt[n][k], At[m][k], acc[ai][bj][m][n]); __builtin_amdgcn_s_setprio(0); } while (0)
; #define PG8_WAIT_V(n) asm volatile("s_waitcnt vmcnt(" #n ")" ::: "memory")
; #define PG8_WAIT_L(n) asm volatile("s_waitcnt lgkmcnt(" #n ")" ::: "memory")
; #define PG8_BAR __builtin_amdgcn_s_barrier()
; #define PG8_SCHED __builtin_amdgcn_sched_barrier(0)
; template <class Epi, class Sched, bool ALIGN_EPI = false, bool SP2 = false, bool F16 = false>
; __device__ __forceinline__ void gemm_phase(PG8_LAS unsigned char* lds, const Gemm g, const Sched& S, const Epi& E, const int wid_in) {
;     ...
;             PG8_LDA(At, 1, 1); PG8_STAGE(PG8_SB(1, 0), b3, voffB); PG8_STAGE(PG8_SB(1, 1), b3 + hstep, voffB); PG8_STAGE(PG8_SA(1, 0), a3, voffA);
;             PG8_WAIT_V(8); PG8_WAIT_L(0); PG8_BAR; PG8_MMA(1, 0, At, B0); PG8_MMA(1, 1, At, B1); PG8_BAR; PG8_SCHED;
;     ...
;         if constexpr (ALIGN_EPI) { if (wr == 0) PG8_BAR; }
	s_add_i32 s36, s60, s68
	v_lshl_add_u64 v[184:185], v[184:185], 0, s[30:31]
	s_mov_b32 m0, s36
	ds_read_b128 v[176:179], v191 offset:49152
	ds_read_b128 v[180:183], v191 offset:50176
	ds_read_b128 v[192:195], v191 offset:51200
	ds_read_b128 v[196:199], v191 offset:52224
	ds_read_b128 v[200:203], v191 offset:53248
	ds_read_b128 v[204:207], v191 offset:54272
	ds_read_b128 v[208:211], v191 offset:55296
	ds_read_b128 v[212:215], v191 offset:56320
	global_load_lds_dwordx4 v[184:185], off
	s_add_i32 m0, s36, 0x2000
	s_add_u32 s36, s46, 0xb0080
	v_lshl_add_u64 v[184:185], v[216:217], 0, s[30:31]
	s_addc_u32 s37, s47, 0
	s_add_i32 s46, s61, s68
	global_load_lds_dwordx4 v[184:185], off
	v_lshl_add_u64 v[184:185], s[36:37], 0, v[154:155]
	s_mov_b32 m0, s46
	s_nop 0
	global_load_lds_dwordx4 v[184:185], off
	v_lshl_add_u64 v[184:185], s[36:37], 0, v[158:159]
	s_add_i32 m0, s46, 0x2000
	s_nop 0
	global_load_lds_dwordx4 v[184:185], off
	v_lshl_add_u64 v[184:185], v[218:219], 0, s[30:31]
	s_mov_b32 m0, s75
	s_nop 0
	global_load_lds_dwordx4 v[184:185], off
	v_lshl_add_u64 v[184:185], v[220:221], 0, s[30:31]
	s_mov_b32 m0, s67
	s_nop 0
	global_load_lds_dwordx4 v[184:185], off
	s_waitcnt vmcnt(8)
	s_waitcnt lgkmcnt(0)
	s_barrier
	s_waitcnt lgkmcnt(0)
	v_mfma_f32_16x16x32_bf16 v[60:63], v[128:131], v[176:179], v[60:63]
	v_mfma_f32_16x16x32_bf16 v[56:59], v[136:139], v[176:179], v[56:59]
	v_mfma_f32_16x16x32_bf16 v[44:47], v[128:131], v[192:195], v[44:47]
	v_mfma_f32_16x16x32_bf16 v[40:43], v[136:139], v[192:195], v[40:43]
	v_mfma_f32_16x16x32_bf16 v[28:31], v[128:131], v[200:203], v[28:31]
	v_mfma_f32_16x16x32_bf16 v[24:27], v[136:139], v[200:203], v[24:27]
	v_mfma_f32_16x16x32_bf16 v[12:15], v[128:131], v[208:211], v[12:15]
	v_mfma_f32_16x16x32_bf16 v[8:11], v[136:139], v[208:211], v[8:11]
	v_mfma_f32_16x16x32_bf16 v[60:63], v[132:135], v[180:183], v[60:63]
	v_mfma_f32_16x16x32_bf16 v[56:59], v[140:143], v[180:183], v[56:59]
	v_mfma_f32_16x16x32_bf16 v[44:47], v[132:135], v[196:199], v[44:47]
	v_mfma_f32_16x16x32_bf16 v[40:43], v[140:143], v[196:199], v[40:43]
	v_mfma_f32_16x16x32_bf16 v[28:31], v[132:135], v[204:207], v[28:31]
	v_mfma_f32_16x16x32_bf16 v[24:27], v[140:143], v[204:207], v[24:27]
	v_mfma_f32_16x16x32_bf16 v[12:15], v[132:135], v[212:215], v[12:15]
	v_mfma_f32_16x16x32_bf16 v[8:11], v[140:143], v[212:215], v[8:11]
	v_mfma_f32_16x16x32_bf16 v[52:55], v[144:147], v[176:179], v[52:55]
	v_mfma_f32_16x16x32_bf16 v[48:51], v[168:171], v[176:179], v[48:51]
	v_mfma_f32_16x16x32_bf16 v[36:39], v[144:147], v[192:195], v[36:39]
	v_mfma_f32_16x16x32_bf16 v[32:35], v[168:171], v[192:195], v[32:35]
	v_mfma_f32_16x16x32_bf16 v[20:23], v[144:147], v[200:203], v[20:23]
	v_mfma_f32_16x16x32_bf16 v[16:19], v[168:171], v[200:203], v[16:19]
	v_mfma_f32_16x16x32_bf16 v[4:7], v[144:147], v[208:211], v[4:7]
	v_mfma_f32_16x16x32_bf16 v[0:3], v[168:171], v[208:211], v[0:3]
	v_mfma_f32_16x16x32_bf16 v[52:55], v[148:151], v[180:183], v[52:55]
	v_mfma_f32_16x16x32_bf16 v[48:51], v[172:175], v[180:183], v[48:51]
	v_mfma_f32_16x16x32_bf16 v[36:39], v[148:151], v[196:199], v[36:39]
	v_mfma_f32_16x16x32_bf16 v[32:35], v[172:175], v[196:199], v[32:35]
	v_mfma_f32_16x16x32_bf16 v[20:23], v[148:151], v[204:207], v[20:23]
	v_mfma_f32_16x16x32_bf16 v[16:19], v[172:175], v[204:207], v[16:19]
	v_mfma_f32_16x16x32_bf16 v[4:7], v[148:151], v[212:215], v[4:7]
	v_mfma_f32_16x16x32_bf16 v[0:3], v[172:175], v[212:215], v[0:3]
	s_barrier
	s_add_i32 s59, s59, 2
	s_add_u32 s43, s43, 0x100
	s_addc_u32 s58, s58, 0
	s_cmp_gt_u32 s59, 41
	s_mov_b64 s[36:37], s[44:45]
	s_cbranch_scc0 .LBB0_2040
	s_and_b64 vcc, exec, s[16:17]
	s_cbranch_vccz .LBB0_2043
	s_barrier

; #define PG8_STAGE(bufoff, gbase, voff) do { _Pragma("unroll") for (int _i = 0; _i < 2; ++_i) \
;         __builtin_amdgcn_global_load_lds((const unsigned*)((const char*)(gbase) + (voff)[_i]), (PG8_LAS unsigned*)(lds + (bufoff) + ldsw + _i * 8192), 16, 0, 0); } while (0)
; #define PG8_LDA(dst, b, h) do { _Pragma("unroll") for (int m = 0; m < 4; ++m) _Pragma("unroll") for (int k = 0; k < 2; ++k) dst[m][k] = *(const PG8_LAS bf16x8*)(lds + PG8_SA(b, h) + aoff + m * 2048 + k * 1024); } while (0)
; #define PG8_LDB(dst, b, h) do { _Pragma("unroll") for (int n = 0; n < 2; ++n) _Pragma("unroll") for (int k = 0; k < 2; ++k) dst[n][k] = *(const PG8_LAS bf16x8*)(lds + PG8_SB(b, h) + boff + n * 2048 + k * 1024); } while (0)
; #define PG8_MMA(ai, bj, At, Bt) do { __builtin_amdgcn_s_setprio(1); _Pragma("unroll") for (int m = 0; m < 4; ++m) _Pragma("unroll") for (int n = 0; n < 2; ++n) _Pragma("unroll") for (int k = 0; k < 2; ++k) \
;         acc[ai][bj][m][n] = mma16<F16>(Bt[n][k], At[m][k], acc[ai][bj][m][n]); __builtin_amdgcn_s_setprio(0); } while (0)
; #define PG8_WAIT_V(n) asm volatile("s_waitcnt vmcnt(" #n ")" ::: "memory")
; #define PG8_BAR __builtin_amdgcn_s_barrier()
; template <class Epi, class Sched, bool ALIGN_EPI = false, bool SP2 = false, bool F16 = false>
; __device__ __forceinline__ void gemm_phase(PG8_LAS unsigned char* lds, const Gemm g, const Sched& S, const Epi& E, const int wid_in) {
;     ...
;         for (int t = 0; t < nt; t += 2) {
;             const bool last = (t == nt - 2);
;             const char* a1 = cA + (size_t)(t + 1) * kstep;
;             const char* a2 = last ? nA : cA + (size_t)(t + 2) * kstep; const char* b2 = last ? nB : cB + (size_t)(t + 2) * kstep;
;             const char* a3 = a2 + kstep; const char* b3 = b2 + kstep;
;             if (last && has_next) S.a_ready(nxt);
;             if constexpr (SP2) {
;             PG8_LDB(B0, 0, 0); PG8_LDB(B1, 0, 1); PG8_SCHED; PG8_LDA(At, 0, 0); PG8_STAGE(PG8_SA(1, 1), a1 + hstep, voffA);
;             PG8_WAIT_V(8); PG8_WAIT_L(0); PG8_BAR; PG8_MMA(0, 0, At, B0); PG8_MMA(0, 1, At, B1); PG8_BAR; PG8_SCHED;
;             PG8_LDA(At, 0, 1); PG8_STAGE(PG8_SB(0, 0), b2, voffB); PG8_STAGE(PG8_SB(0, 1), b2 + hstep, voffB); PG8_STAGE(PG8_SA(0, 0), a2, voffA);
;             PG8_WAIT_V(8); PG8_WAIT_L(0); PG8_BAR; PG8_MMA(1, 0, At, B0); PG8_MMA(1, 1, At, B1); PG8_BAR; PG8_SCHED;
.LBB0_2136:
	ds_read_b128 v[112:115], v235
	ds_read_b128 v[116:119], v235 offset:1024
	ds_read_b128 v[128:131], v235 offset:2048
	ds_read_b128 v[132:135], v235 offset:3072
	ds_read_b128 v[144:147], v236
	ds_read_b128 v[148:151], v236 offset:1024
	ds_read_b128 v[152:155], v236 offset:2048
	ds_read_b128 v[156:159], v236 offset:3072
	s_add_u32 s45, s52, 0xfffc0080
	s_addc_u32 s51, s53, -1
	s_cmp_eq_u32 s43, 12
	s_cselect_b32 s57, s14, s51
	s_cselect_b32 s56, s15, s45
	s_cselect_b32 s55, s37, s42
	s_cselect_b32 s54, s40, s41
	s_mov_b32 m0, s91
	v_lshl_add_u64 v[192:193], s[52:53], 0, v[204:205]
	ds_read_b128 v[160:163], v237
	ds_read_b128 v[164:167], v237 offset:1024
	ds_read_b128 v[168:171], v237 offset:2048
	ds_read_b128 v[172:175], v237 offset:3072
	ds_read_b128 v[176:179], v237 offset:4096
	ds_read_b128 v[180:183], v237 offset:5120
	ds_read_b128 v[184:187], v237 offset:6144
	ds_read_b128 v[188:191], v237 offset:7168
	global_load_lds_dwordx4 v[192:193], off
	v_lshl_add_u64 v[192:193], s[52:53], 0, v[206:207]
	s_add_i32 m0, s74, 0xe000
	s_nop 0
	global_load_lds_dwordx4 v[192:193], off
	s_waitcnt vmcnt(8)
	s_waitcnt lgkmcnt(0)
	s_barrier
	s_waitcnt lgkmcnt(0)
	v_mfma_f32_16x16x32_f16 v[140:143], v[112:115], v[160:163], v[140:143]
	v_mfma_f32_16x16x32_f16 v[136:139], v[128:131], v[160:163], v[136:139]
	v_mfma_f32_16x16x32_f16 v[108:111], v[112:115], v[168:171], v[108:111]
	v_mfma_f32_16x16x32_f16 v[104:107], v[128:131], v[168:171], v[104:107]
	v_mfma_f32_16x16x32_f16 v[92:95], v[112:115], v[176:179], v[92:95]
	v_mfma_f32_16x16x32_f16 v[88:91], v[128:131], v[176:179], v[88:91]
	v_mfma_f32_16x16x32_f16 v[76:79], v[112:115], v[184:187], v[76:79]
	v_mfma_f32_16x16x32_f16 v[72:75], v[128:131], v[184:187], v[72:75]
	v_mfma_f32_16x16x32_f16 v[140:143], v[116:119], v[164:167], v[140:143]
	v_mfma_f32_16x16x32_f16 v[136:139], v[132:135], v[164:167], v[136:139]
	v_mfma_f32_16x16x32_f16 v[108:111], v[116:119], v[172:175], v[108:111]
	v_mfma_f32_16x16x32_f16 v[104:107], v[132:135], v[172:175], v[104:107]
	v_mfma_f32_16x16x32_f16 v[92:95], v[116:119], v[180:183], v[92:95]
	v_mfma_f32_16x16x32_f16 v[88:91], v[132:135], v[180:183], v[88:91]
	v_mfma_f32_16x16x32_f16 v[76:79], v[116:119], v[188:191], v[76:79]
	v_mfma_f32_16x16x32_f16 v[72:75], v[132:135], v[188:191], v[72:75]
	v_mfma_f32_16x16x32_f16 v[124:127], v[144:147], v[160:163], v[124:127]
	v_mfma_f32_16x16x32_f16 v[120:123], v[152:155], v[160:163], v[120:123]
	v_mfma_f32_16x16x32_f16 v[100:103], v[144:147], v[168:171], v[100:103]
	v_mfma_f32_16x16x32_f16 v[96:99], v[152:155], v[168:171], v[96:99]
	v_mfma_f32_16x16x32_f16 v[84:87], v[144:147], v[176:179], v[84:87]
	v_mfma_f32_16x16x32_f16 v[80:83], v[152:155], v[176:179], v[80:83]
	v_mfma_f32_16x16x32_f16 v[68:71], v[144:147], v[184:187], v[68:71]
	v_mfma_f32_16x16x32_f16 v[64:67], v[152:155], v[184:187], v[64:67]
	v_mfma_f32_16x16x32_f16 v[124:127], v[148:151], v[164:167], v[124:127]
	v_mfma_f32_16x16x32_f16 v[120:123], v[156:159], v[164:167], v[120:123]
	v_mfma_f32_16x16x32_f16 v[100:103], v[148:151], v[172:175], v[100:103]
	v_mfma_f32_16x16x32_f16 v[96:99], v[156:159], v[172:175], v[96:99]
	v_mfma_f32_16x16x32_f16 v[84:87], v[148:151], v[180:183], v[84:87]
	v_mfma_f32_16x16x32_f16 v[80:83], v[156:159], v[180:183], v[80:83]
	v_mfma_f32_16x16x32_f16 v[68:71], v[148:151], v[188:191], v[68:71]
	v_mfma_f32_16x16x32_f16 v[64:67], v[156:159], v[188:191], v[64:67]
	s_barrier
	s_add_i32 s45, s63, s68
	v_lshl_add_u64 v[192:193], s[54:55], 0, v[198:199]
	s_mov_b32 m0, s45
	ds_read_b128 v[160:163], v237 offset:16384
	ds_read_b128 v[164:167], v237 offset:17408
	ds_read_b128 v[168:171], v237 offset:18432
	ds_read_b128 v[172:175], v237 offset:19456
	ds_read_b128 v[176:179], v237 offset:20480
	ds_read_b128 v[180:183], v237 offset:21504
	ds_read_b128 v[184:187], v237 offset:22528
	ds_read_b128 v[188:191], v237 offset:23552
	global_load_lds_dwordx4 v[192:193], off
	s_add_i32 m0, s45, 0x2000
	s_add_u32 s84, s54, 0x40000
	v_lshl_add_u64 v[194:195], s[54:55], 0, v[202:203]
	s_addc_u32 s85, s55, 0
	s_add_i32 s45, s64, s68
	global_load_lds_dwordx4 v[194:195], off
	v_lshl_add_u64 v[212:213], s[84:85], 0, v[198:199]
	s_mov_b32 m0, s45
	v_lshl_add_u64 v[214:215], s[56:57], 0, v[200:201]
	global_load_lds_dwordx4 v[212:213], off
	v_lshl_add_u64 v[212:213], s[84:85], 0, v[202:203]
	s_add_i32 m0, s45, 0x2000
	s_nop 0
	global_load_lds_dwordx4 v[212:213], off
	v_lshl_add_u64 v[212:213], s[56:57], 0, v[196:197]
	s_mov_b32 m0, s74
	s_nop 0
	global_load_lds_dwordx4 v[212:213], off
	s_mov_b32 m0, s66
	s_nop 0
	global_load_lds_dwordx4 v[214:215], off
	s_waitcnt vmcnt(8)
	s_waitcnt lgkmcnt(0)
	s_barrier
; #define PG8_STAGE(bufoff, gbase, voff) do { _Pragma("unroll") for (int _i = 0; _i < 2; ++_i) \
;         __builtin_amdgcn_global_load_lds((const unsigned*)((const char*)(gbase) + (voff)[_i]), (PG8_LAS unsigned*)(lds + (bufoff) + ldsw + _i * 8192), 16, 0, 0); } while (0)
; #define PG8_LDA(dst, b, h) do { _Pragma("unroll") for (int m = 0; m < 4; ++m) _Pragma("unroll") for (int k = 0; k < 2; ++k) dst[m][k] = *(const PG8_LAS bf16x8*)(lds + PG8_SA(b, h) + aoff + m * 2048 + k * 1024); } while (0)
; #define PG8_LDB(dst, b, h) do { _Pragma("unroll") for (int n = 0; n < 2; ++n) _Pragma("unroll") for (int k = 0; k < 2; ++k) dst[n][k] = *(const PG8_LAS bf16x8*)(lds + PG8_SB(b, h) + boff + n * 2048 + k * 1024); } while (0)
; #define PG8_MMA(ai, bj, At, Bt) do { __builtin_amdgcn_s_setprio(1); _Pragma("unroll") for (int m = 0; m < 4; ++m) _Pragma("unroll") for (int n = 0; n < 2; ++n) _Pragma("unroll") for (int k = 0; k < 2; ++k) \
;         acc[ai][bj][m][n] = mma16<F16>(Bt[n][k], At[m][k], acc[ai][bj][m][n]); __builtin_amdgcn_s_setprio(0); } while (0)
; #define PG8_WAIT_V(n) asm volatile("s_waitcnt vmcnt(" #n ")" ::: "memory")
; #define PG8_WAIT_L(n) asm volatile("s_waitcnt lgkmcnt(" #n ")" ::: "memory")
; #define PG8_BAR __builtin_amdgcn_s_barrier()
; #define PG8_SCHED __builtin_amdgcn_sched_barrier(0)
; template <class Epi, class Sched, bool ALIGN_EPI = false, bool SP2 = false, bool F16 = false>
; __device__ __forceinline__ void gemm_phase(PG8_LAS unsigned char* lds, const Gemm g, const Sched& S, const Epi& E, const int wid_in) {
;     ...
;             PG8_WAIT_V(8); PG8_WAIT_L(0); PG8_BAR; PG8_MMA(1, 0, At, B0); PG8_MMA(1, 1, At, B1); PG8_BAR; PG8_SCHED;
;             PG8_LDB(B0, 1, 0); PG8_LDB(B1, 1, 1); PG8_SCHED; PG8_LDA(At, 1, 0); PG8_STAGE(PG8_SA(0, 1), a2 + hstep, voffA);
;             PG8_WAIT_V(8); PG8_WAIT_L(0); PG8_BAR; PG8_MMA(0, 0, At, B0); PG8_MMA(0, 1, At, B1); PG8_BAR; PG8_SCHED;
	s_waitcnt lgkmcnt(0)
	v_mfma_f32_16x16x32_f16 v[60:63], v[112:115], v[160:163], v[60:63]
	v_mfma_f32_16x16x32_f16 v[56:59], v[128:131], v[160:163], v[56:59]
	v_mfma_f32_16x16x32_f16 v[44:47], v[112:115], v[168:171], v[44:47]
	v_mfma_f32_16x16x32_f16 v[40:43], v[128:131], v[168:171], v[40:43]
	v_mfma_f32_16x16x32_f16 v[28:31], v[112:115], v[176:179], v[28:31]
	v_mfma_f32_16x16x32_f16 v[24:27], v[128:131], v[176:179], v[24:27]
	v_mfma_f32_16x16x32_f16 v[12:15], v[112:115], v[184:187], v[12:15]
	v_mfma_f32_16x16x32_f16 v[8:11], v[128:131], v[184:187], v[8:11]
	v_mfma_f32_16x16x32_f16 v[60:63], v[116:119], v[164:167], v[60:63]
	v_mfma_f32_16x16x32_f16 v[56:59], v[132:135], v[164:167], v[56:59]
	v_mfma_f32_16x16x32_f16 v[44:47], v[116:119], v[172:175], v[44:47]
	v_mfma_f32_16x16x32_f16 v[40:43], v[132:135], v[172:175], v[40:43]
	v_mfma_f32_16x16x32_f16 v[28:31], v[116:119], v[180:183], v[28:31]
	v_mfma_f32_16x16x32_f16 v[24:27], v[132:135], v[180:183], v[24:27]
	v_mfma_f32_16x16x32_f16 v[12:15], v[116:119], v[188:191], v[12:15]
	v_mfma_f32_16x16x32_f16 v[8:11], v[132:135], v[188:191], v[8:11]
	v_mfma_f32_16x16x32_f16 v[52:55], v[144:147], v[160:163], v[52:55]
	v_mfma_f32_16x16x32_f16 v[48:51], v[152:155], v[160:163], v[48:51]
	v_mfma_f32_16x16x32_f16 v[36:39], v[144:147], v[168:171], v[36:39]
	v_mfma_f32_16x16x32_f16 v[32:35], v[152:155], v[168:171], v[32:35]
	v_mfma_f32_16x16x32_f16 v[20:23], v[144:147], v[176:179], v[20:23]
	v_mfma_f32_16x16x32_f16 v[16:19], v[152:155], v[176:179], v[16:19]
	v_mfma_f32_16x16x32_f16 v[4:7], v[144:147], v[184:187], v[4:7]
	v_mfma_f32_16x16x32_f16 v[0:3], v[152:155], v[184:187], v[0:3]
	v_mfma_f32_16x16x32_f16 v[52:55], v[148:151], v[164:167], v[52:55]
	v_mfma_f32_16x16x32_f16 v[48:51], v[156:159], v[164:167], v[48:51]
	v_mfma_f32_16x16x32_f16 v[36:39], v[148:151], v[172:175], v[36:39]
	v_mfma_f32_16x16x32_f16 v[32:35], v[156:159], v[172:175], v[32:35]
	v_mfma_f32_16x16x32_f16 v[20:23], v[148:151], v[180:183], v[20:23]
	v_mfma_f32_16x16x32_f16 v[16:19], v[156:159], v[180:183], v[16:19]
	v_mfma_f32_16x16x32_f16 v[4:7], v[148:151], v[188:191], v[4:7]
	v_mfma_f32_16x16x32_f16 v[0:3], v[156:159], v[188:191], v[0:3]
	s_barrier
	s_add_i32 s45, 0, 0x18000
	s_add_i32 s51, 0, 0x1c000
	v_add_u32_e32 v132, s45, v234
	v_add_u32_e32 v156, s51, v234
	ds_read_b128 v[112:115], v132
	ds_read_b128 v[116:119], v132 offset:1024
	ds_read_b128 v[128:131], v132 offset:2048
	ds_read_b128 v[132:135], v132 offset:3072
	ds_read_b128 v[144:147], v156
	ds_read_b128 v[148:151], v156 offset:1024
	ds_read_b128 v[152:155], v156 offset:2048
	ds_read_b128 v[156:159], v156 offset:3072
	s_add_u32 s56, s56, 0x40000
	s_addc_u32 s57, s57, 0
	s_mov_b32 m0, s90
	v_lshl_add_u64 v[216:217], s[56:57], 0, v[196:197]
	ds_read_b128 v[160:163], v237 offset:32768
	ds_read_b128 v[164:167], v237 offset:33792
	ds_read_b128 v[168:171], v237 offset:34816
	ds_read_b128 v[172:175], v237 offset:35840
	ds_read_b128 v[176:179], v237 offset:36864
	ds_read_b128 v[180:183], v237 offset:37888
	ds_read_b128 v[184:187], v237 offset:38912
	ds_read_b128 v[188:191], v237 offset:39936
	global_load_lds_dwordx4 v[216:217], off
	v_lshl_add_u64 v[216:217], s[56:57], 0, v[200:201]
	s_mov_b32 m0, s59
	s_nop 0
	global_load_lds_dwordx4 v[216:217], off
	s_waitcnt vmcnt(8)
	s_waitcnt lgkmcnt(0)
	s_barrier
	s_waitcnt lgkmcnt(0)
	v_mfma_f32_16x16x32_f16 v[140:143], v[112:115], v[160:163], v[140:143]
	v_mfma_f32_16x16x32_f16 v[136:139], v[128:131], v[160:163], v[136:139]
	v_mfma_f32_16x16x32_f16 v[108:111], v[112:115], v[168:171], v[108:111]
	v_mfma_f32_16x16x32_f16 v[104:107], v[128:131], v[168:171], v[104:107]
	v_mfma_f32_16x16x32_f16 v[92:95], v[112:115], v[176:179], v[92:95]
	v_mfma_f32_16x16x32_f16 v[88:91], v[128:131], v[176:179], v[88:91]
	v_mfma_f32_16x16x32_f16 v[76:79], v[112:115], v[184:187], v[76:79]
	v_mfma_f32_16x16x32_f16 v[72:75], v[128:131], v[184:187], v[72:75]
	v_mfma_f32_16x16x32_f16 v[140:143], v[116:119], v[164:167], v[140:143]
	v_mfma_f32_16x16x32_f16 v[136:139], v[132:135], v[164:167], v[136:139]
	v_mfma_f32_16x16x32_f16 v[108:111], v[116:119], v[172:175], v[108:111]
	v_mfma_f32_16x16x32_f16 v[104:107], v[132:135], v[172:175], v[104:107]
	v_mfma_f32_16x16x32_f16 v[92:95], v[116:119], v[180:183], v[92:95]
	v_mfma_f32_16x16x32_f16 v[88:91], v[132:135], v[180:183], v[88:91]
	v_mfma_f32_16x16x32_f16 v[76:79], v[116:119], v[188:191], v[76:79]
	v_mfma_f32_16x16x32_f16 v[72:75], v[132:135], v[188:191], v[72:75]
	v_mfma_f32_16x16x32_f16 v[124:127], v[144:147], v[160:163], v[124:127]
	v_mfma_f32_16x16x32_f16 v[120:123], v[152:155], v[160:163], v[120:123]
	v_mfma_f32_16x16x32_f16 v[100:103], v[144:147], v[168:171], v[100:103]
	v_mfma_f32_16x16x32_f16 v[96:99], v[152:155], v[168:171], v[96:99]
	v_mfma_f32_16x16x32_f16 v[84:87], v[144:147], v[176:179], v[84:87]
	v_mfma_f32_16x16x32_f16 v[80:83], v[152:155], v[176:179], v[80:83]
	v_mfma_f32_16x16x32_f16 v[68:71], v[144:147], v[184:187], v[68:71]
	v_mfma_f32_16x16x32_f16 v[64:67], v[152:155], v[184:187], v[64:67]
	v_mfma_f32_16x16x32_f16 v[124:127], v[148:151], v[164:167], v[124:127]
	v_mfma_f32_16x16x32_f16 v[120:123], v[156:159], v[164:167], v[120:123]
	v_mfma_f32_16x16x32_f16 v[100:103], v[148:151], v[172:175], v[100:103]
	v_mfma_f32_16x16x32_f16 v[96:99], v[156:159], v[172:175], v[96:99]
	v_mfma_f32_16x16x32_f16 v[84:87], v[148:151], v[180:183], v[84:87]
	v_mfma_f32_16x16x32_f16 v[80:83], v[156:159], v[180:183], v[80:83]
	v_mfma_f32_16x16x32_f16 v[68:71], v[148:151], v[188:191], v[68:71]
	v_mfma_f32_16x16x32_f16 v[64:67], v[156:159], v[188:191], v[64:67]
	s_barrier
; #define PG8_STAGE(bufoff, gbase, voff) do { _Pragma("unroll") for (int _i = 0; _i < 2; ++_i) \
;         __builtin_amdgcn_global_load_lds((const unsigned*)((const char*)(gbase) + (voff)[_i]), (PG8_LAS unsigned*)(lds + (bufoff) + ldsw + _i * 8192), 16, 0, 0); } while (0)
; #define PG8_LDA(dst, b, h) do { _Pragma("unroll") for (int m = 0; m < 4; ++m) _Pragma("unroll") for (int k = 0; k < 2; ++k) dst[m][k] = *(const PG8_LAS bf16x8*)(lds + PG8_SA(b, h) + aoff + m * 2048 + k * 1024); } while (0)
; #define PG8_MMA(ai, bj, At, Bt) do { __builtin_amdgcn_s_setprio(1); _Pragma("unroll") for (int m = 0; m < 4; ++m) _Pragma("unroll") for (int n = 0; n < 2; ++n) _Pragma("unroll") for (int k = 0; k < 2; ++k) \
;         acc[ai][bj][m][n] = mma16<F16>(Bt[n][k], At[m][k], acc[ai][bj][m][n]); __builtin_amdgcn_s_setprio(0); } while (0)
; #define PG8_WAIT_V(n) asm volatile("s_waitcnt vmcnt(" #n ")" ::: "memory")
; #define PG8_WAIT_L(n) asm volatile("s_waitcnt lgkmcnt(" #n ")" ::: "memory")
; #define PG8_BAR __builtin_amdgcn_s_barrier()
; #define PG8_SCHED __builtin_amdgcn_sched_barrier(0)
; template <class Epi, class Sched, bool ALIGN_EPI = false, bool SP2 = false, bool F16 = false>
; __device__ __forceinline__ void gemm_phase(PG8_LAS unsigned char* lds, const Gemm g, const Sched& S, const Epi& E, const int wid_in) {
;     ...
;             PG8_LDA(At, 1, 1); PG8_STAGE(PG8_SB(1, 0), b3, voffB); PG8_STAGE(PG8_SB(1, 1), b3 + hstep, voffB); PG8_STAGE(PG8_SA(1, 0), a3, voffA);
;             PG8_WAIT_V(8); PG8_WAIT_L(0); PG8_BAR; PG8_MMA(1, 0, At, B0); PG8_MMA(1, 1, At, B1); PG8_BAR; PG8_SCHED;
;     ...
;         if constexpr (ALIGN_EPI) { if (wr == 0) PG8_BAR; }
	s_add_i32 s45, s45, s68
	v_lshl_add_u64 v[192:193], v[192:193], 0, s[34:35]
	s_mov_b32 m0, s45
	ds_read_b128 v[160:163], v237 offset:49152
	ds_read_b128 v[164:167], v237 offset:50176
	ds_read_b128 v[168:171], v237 offset:51200
	ds_read_b128 v[172:175], v237 offset:52224
	ds_read_b128 v[176:179], v237 offset:53248
	ds_read_b128 v[180:183], v237 offset:54272
	ds_read_b128 v[184:187], v237 offset:55296
	ds_read_b128 v[188:191], v237 offset:56320
	global_load_lds_dwordx4 v[192:193], off
	s_add_i32 m0, s45, 0x2000
	s_add_u32 s54, s54, 0x40080
	v_lshl_add_u64 v[192:193], v[194:195], 0, s[34:35]
	s_addc_u32 s55, s55, 0
	s_add_i32 s45, s51, s68
	global_load_lds_dwordx4 v[192:193], off
	v_lshl_add_u64 v[192:193], s[54:55], 0, v[198:199]
	s_mov_b32 m0, s45
	s_nop 0
	global_load_lds_dwordx4 v[192:193], off
	v_lshl_add_u64 v[192:193], s[54:55], 0, v[202:203]
	s_add_i32 m0, s45, 0x2000
	s_nop 0
	global_load_lds_dwordx4 v[192:193], off
	v_lshl_add_u64 v[192:193], v[212:213], 0, s[34:35]
	s_mov_b32 m0, s75
	s_nop 0
	global_load_lds_dwordx4 v[192:193], off
	v_lshl_add_u64 v[192:193], v[214:215], 0, s[34:35]
	s_mov_b32 m0, s67
	s_nop 0
	global_load_lds_dwordx4 v[192:193], off
	s_waitcnt vmcnt(8)
	s_waitcnt lgkmcnt(0)
	s_barrier
	s_waitcnt lgkmcnt(0)
	v_mfma_f32_16x16x32_f16 v[60:63], v[112:115], v[160:163], v[60:63]
	v_mfma_f32_16x16x32_f16 v[56:59], v[128:131], v[160:163], v[56:59]
	v_mfma_f32_16x16x32_f16 v[44:47], v[112:115], v[168:171], v[44:47]
	v_mfma_f32_16x16x32_f16 v[40:43], v[128:131], v[168:171], v[40:43]
	v_mfma_f32_16x16x32_f16 v[28:31], v[112:115], v[176:179], v[28:31]
	v_mfma_f32_16x16x32_f16 v[24:27], v[128:131], v[176:179], v[24:27]
	v_mfma_f32_16x16x32_f16 v[12:15], v[112:115], v[184:187], v[12:15]
	v_mfma_f32_16x16x32_f16 v[8:11], v[128:131], v[184:187], v[8:11]
	v_mfma_f32_16x16x32_f16 v[60:63], v[116:119], v[164:167], v[60:63]
	v_mfma_f32_16x16x32_f16 v[56:59], v[132:135], v[164:167], v[56:59]
	v_mfma_f32_16x16x32_f16 v[44:47], v[116:119], v[172:175], v[44:47]
	v_mfma_f32_16x16x32_f16 v[40:43], v[132:135], v[172:175], v[40:43]
	v_mfma_f32_16x16x32_f16 v[28:31], v[116:119], v[180:183], v[28:31]
	v_mfma_f32_16x16x32_f16 v[24:27], v[132:135], v[180:183], v[24:27]
	v_mfma_f32_16x16x32_f16 v[12:15], v[116:119], v[188:191], v[12:15]
	v_mfma_f32_16x16x32_f16 v[8:11], v[132:135], v[188:191], v[8:11]
	v_mfma_f32_16x16x32_f16 v[52:55], v[144:147], v[160:163], v[52:55]
	v_mfma_f32_16x16x32_f16 v[48:51], v[152:155], v[160:163], v[48:51]
	v_mfma_f32_16x16x32_f16 v[36:39], v[144:147], v[168:171], v[36:39]
	v_mfma_f32_16x16x32_f16 v[32:35], v[152:155], v[168:171], v[32:35]
	v_mfma_f32_16x16x32_f16 v[20:23], v[144:147], v[176:179], v[20:23]
	v_mfma_f32_16x16x32_f16 v[16:19], v[152:155], v[176:179], v[16:19]
	v_mfma_f32_16x16x32_f16 v[4:7], v[144:147], v[184:187], v[4:7]
	v_mfma_f32_16x16x32_f16 v[0:3], v[152:155], v[184:187], v[0:3]
	v_mfma_f32_16x16x32_f16 v[52:55], v[148:151], v[164:167], v[52:55]
	v_mfma_f32_16x16x32_f16 v[48:51], v[156:159], v[164:167], v[48:51]
	v_mfma_f32_16x16x32_f16 v[36:39], v[148:151], v[172:175], v[36:39]
	v_mfma_f32_16x16x32_f16 v[32:35], v[156:159], v[172:175], v[32:35]
	v_mfma_f32_16x16x32_f16 v[20:23], v[148:151], v[180:183], v[20:23]
	v_mfma_f32_16x16x32_f16 v[16:19], v[156:159], v[180:183], v[16:19]
	v_mfma_f32_16x16x32_f16 v[4:7], v[148:151], v[188:191], v[4:7]
	v_mfma_f32_16x16x32_f16 v[0:3], v[156:159], v[188:191], v[0:3]
	s_barrier
	s_add_i32 s43, s43, 2
	s_add_u32 s52, s52, 0x100
	s_addc_u32 s53, s53, 0
	s_add_u32 s41, s41, 0x100
	s_addc_u32 s42, s42, 0
	s_cmp_gt_u32 s43, 13
	s_cbranch_scc0 .LBB0_2136
	s_and_b64 vcc, exec, s[16:17]
	s_cbranch_vccz .LBB0_2139
	s_barrier

; #define PG8_STAGE(bufoff, gbase, voff) do { _Pragma("unroll") for (int _i = 0; _i < 2; ++_i) \
;         __builtin_amdgcn_global_load_lds((const unsigned*)((const char*)(gbase) + (voff)[_i]), (PG8_LAS unsigned*)(lds + (bufoff) + ldsw + _i * 8192), 16, 0, 0); } while (0)
; #define PG8_LDA(dst, b, h) do { _Pragma("unroll") for (int m = 0; m < 4; ++m) _Pragma("unroll") for (int k = 0; k < 2; ++k) dst[m][k] = *(const PG8_LAS bf16x8*)(lds + PG8_SA(b, h) + aoff + m * 2048 + k * 1024); } while (0)
; #define PG8_LDB(dst, b, h) do { _Pragma("unroll") for (int n = 0; n < 2; ++n) _Pragma("unroll") for (int k = 0; k < 2; ++k) dst[n][k] = *(const PG8_LAS bf16x8*)(lds + PG8_SB(b, h) + boff + n * 2048 + k * 1024); } while (0)
; #define PG8_MMA(ai, bj, At, Bt) do { __builtin_amdgcn_s_setprio(1); _Pragma("unroll") for (int m = 0; m < 4; ++m) _Pragma("unroll") for (int n = 0; n < 2; ++n) _Pragma("unroll") for (int k = 0; k < 2; ++k) \
;         acc[ai][bj][m][n] = mma16<F16>(Bt[n][k], At[m][k], acc[ai][bj][m][n]); __builtin_amdgcn_s_setprio(0); } while (0)
; #define PG8_WAIT_V(n) asm volatile("s_waitcnt vmcnt(" #n ")" ::: "memory")
; #define PG8_BAR __builtin_amdgcn_s_barrier()
; template <class Epi, class Sched, bool ALIGN_EPI = false, bool SP2 = false, bool F16 = false>
; __device__ __forceinline__ void gemm_phase(PG8_LAS unsigned char* lds, const Gemm g, const Sched& S, const Epi& E, const int wid_in) {
;     ...
;         for (int t = 0; t < nt; t += 2) {
;             const bool last = (t == nt - 2);
;             const char* a1 = cA + (size_t)(t + 1) * kstep;
;             const char* a2 = last ? nA : cA + (size_t)(t + 2) * kstep; const char* b2 = last ? nB : cB + (size_t)(t + 2) * kstep;
;             const char* a3 = a2 + kstep; const char* b3 = b2 + kstep;
;             if (last && has_next) S.a_ready(nxt);
;             if constexpr (SP2) {
;             PG8_LDB(B0, 0, 0); PG8_LDB(B1, 0, 1); PG8_SCHED; PG8_LDA(At, 0, 0); PG8_STAGE(PG8_SA(1, 1), a1 + hstep, voffA);
;             PG8_WAIT_V(8); PG8_WAIT_L(0); PG8_BAR; PG8_MMA(0, 0, At, B0); PG8_MMA(0, 1, At, B1); PG8_BAR; PG8_SCHED;
;             PG8_LDA(At, 0, 1); PG8_STAGE(PG8_SB(0, 0), b2, voffB); PG8_STAGE(PG8_SB(0, 1), b2 + hstep, voffB); PG8_STAGE(PG8_SA(0, 0), a2, voffA);
;             PG8_WAIT_V(8); PG8_WAIT_L(0); PG8_BAR; PG8_MMA(1, 0, At, B0); PG8_MMA(1, 1, At, B1); PG8_BAR; PG8_SCHED;
.LBB0_2226:
	ds_read_b128 v[128:131], v183
	ds_read_b128 v[132:135], v183 offset:1024
	ds_read_b128 v[136:139], v183 offset:2048
	ds_read_b128 v[140:143], v183 offset:3072
	ds_read_b128 v[144:147], v184
	ds_read_b128 v[148:151], v184 offset:1024
	ds_read_b128 v[152:155], v184 offset:2048
	ds_read_b128 v[174:177], v184 offset:3072
	s_add_u32 s43, s48, 0xfffc0080
	s_addc_u32 s50, s49, -1
	s_cmp_eq_u32 s42, 12
	s_cselect_b32 s53, s13, s50
	s_cselect_b32 s52, s23, s43
	s_cselect_b32 s51, s35, s41
	s_cselect_b32 s50, s37, s40
	s_mov_b32 m0, s91
	v_lshl_add_u64 v[178:179], s[48:49], 0, v[166:167]
	ds_read_b128 v[188:191], v185
	ds_read_b128 v[192:195], v185 offset:1024
	ds_read_b128 v[196:199], v185 offset:2048
	ds_read_b128 v[200:203], v185 offset:3072
	ds_read_b128 v[204:207], v185 offset:4096
	ds_read_b128 v[208:211], v185 offset:5120
	ds_read_b128 v[212:215], v185 offset:6144
	ds_read_b128 v[216:219], v185 offset:7168
	global_load_lds_dwordx4 v[178:179], off
	v_lshl_add_u64 v[178:179], s[48:49], 0, v[168:169]
	s_add_i32 m0, s74, 0xe000
	s_nop 0
	global_load_lds_dwordx4 v[178:179], off
	s_waitcnt vmcnt(8)
	s_waitcnt lgkmcnt(0)
	s_barrier
	s_waitcnt lgkmcnt(0)
	v_mfma_f32_16x16x32_f16 v[124:127], v[128:131], v[188:191], v[124:127]
	v_mfma_f32_16x16x32_f16 v[120:123], v[136:139], v[188:191], v[120:123]
	v_mfma_f32_16x16x32_f16 v[108:111], v[128:131], v[196:199], v[108:111]
	v_mfma_f32_16x16x32_f16 v[104:107], v[136:139], v[196:199], v[104:107]
	v_mfma_f32_16x16x32_f16 v[92:95], v[128:131], v[204:207], v[92:95]
	v_mfma_f32_16x16x32_f16 v[88:91], v[136:139], v[204:207], v[88:91]
	v_mfma_f32_16x16x32_f16 v[76:79], v[128:131], v[212:215], v[76:79]
	v_mfma_f32_16x16x32_f16 v[72:75], v[136:139], v[212:215], v[72:75]
	v_mfma_f32_16x16x32_f16 v[124:127], v[132:135], v[192:195], v[124:127]
	v_mfma_f32_16x16x32_f16 v[120:123], v[140:143], v[192:195], v[120:123]
	v_mfma_f32_16x16x32_f16 v[108:111], v[132:135], v[200:203], v[108:111]
	v_mfma_f32_16x16x32_f16 v[104:107], v[140:143], v[200:203], v[104:107]
	v_mfma_f32_16x16x32_f16 v[92:95], v[132:135], v[208:211], v[92:95]
	v_mfma_f32_16x16x32_f16 v[88:91], v[140:143], v[208:211], v[88:91]
	v_mfma_f32_16x16x32_f16 v[76:79], v[132:135], v[216:219], v[76:79]
	v_mfma_f32_16x16x32_f16 v[72:75], v[140:143], v[216:219], v[72:75]
	v_mfma_f32_16x16x32_f16 v[116:119], v[144:147], v[188:191], v[116:119]
	v_mfma_f32_16x16x32_f16 v[112:115], v[152:155], v[188:191], v[112:115]
	v_mfma_f32_16x16x32_f16 v[100:103], v[144:147], v[196:199], v[100:103]
	v_mfma_f32_16x16x32_f16 v[96:99], v[152:155], v[196:199], v[96:99]
	v_mfma_f32_16x16x32_f16 v[84:87], v[144:147], v[204:207], v[84:87]
	v_mfma_f32_16x16x32_f16 v[80:83], v[152:155], v[204:207], v[80:83]
	v_mfma_f32_16x16x32_f16 v[68:71], v[144:147], v[212:215], v[68:71]
	v_mfma_f32_16x16x32_f16 v[64:67], v[152:155], v[212:215], v[64:67]
	v_mfma_f32_16x16x32_f16 v[116:119], v[148:151], v[192:195], v[116:119]
	v_mfma_f32_16x16x32_f16 v[112:115], v[174:177], v[192:195], v[112:115]
	v_mfma_f32_16x16x32_f16 v[100:103], v[148:151], v[200:203], v[100:103]
	v_mfma_f32_16x16x32_f16 v[96:99], v[174:177], v[200:203], v[96:99]
	v_mfma_f32_16x16x32_f16 v[84:87], v[148:151], v[208:211], v[84:87]
	v_mfma_f32_16x16x32_f16 v[80:83], v[174:177], v[208:211], v[80:83]
	v_mfma_f32_16x16x32_f16 v[68:71], v[148:151], v[216:219], v[68:71]
	v_mfma_f32_16x16x32_f16 v[64:67], v[174:177], v[216:219], v[64:67]
	s_barrier
	s_add_i32 s43, s84, s68
	v_lshl_add_u64 v[178:179], s[50:51], 0, v[158:159]
	s_mov_b32 m0, s43
	ds_read_b128 v[188:191], v185 offset:16384
	ds_read_b128 v[192:195], v185 offset:17408
	ds_read_b128 v[196:199], v185 offset:18432
	ds_read_b128 v[200:203], v185 offset:19456
	ds_read_b128 v[204:207], v185 offset:20480
	ds_read_b128 v[208:211], v185 offset:21504
	ds_read_b128 v[212:215], v185 offset:22528
	ds_read_b128 v[216:219], v185 offset:23552
	global_load_lds_dwordx4 v[178:179], off
	s_add_i32 m0, s43, 0x2000
	s_add_u32 s54, s50, 0x40000
	v_lshl_add_u64 v[220:221], s[50:51], 0, v[162:163]
	s_addc_u32 s55, s51, 0
	s_add_i32 s43, s93, s68
	global_load_lds_dwordx4 v[220:221], off
	v_lshl_add_u64 v[222:223], s[54:55], 0, v[158:159]
	s_mov_b32 m0, s43
	v_lshl_add_u64 v[224:225], s[52:53], 0, v[160:161]
	global_load_lds_dwordx4 v[222:223], off
	v_lshl_add_u64 v[222:223], s[54:55], 0, v[162:163]
	s_add_i32 m0, s43, 0x2000
	s_nop 0
	global_load_lds_dwordx4 v[222:223], off
	v_lshl_add_u64 v[222:223], s[52:53], 0, v[156:157]
	s_mov_b32 m0, s74
	s_nop 0
	global_load_lds_dwordx4 v[222:223], off
	s_mov_b32 m0, s66
	s_nop 0
	global_load_lds_dwordx4 v[224:225], off
	s_waitcnt vmcnt(8)
	s_waitcnt lgkmcnt(0)
	s_barrier
; #define PG8_STAGE(bufoff, gbase, voff) do { _Pragma("unroll") for (int _i = 0; _i < 2; ++_i) \
;         __builtin_amdgcn_global_load_lds((const unsigned*)((const char*)(gbase) + (voff)[_i]), (PG8_LAS unsigned*)(lds + (bufoff) + ldsw + _i * 8192), 16, 0, 0); } while (0)
; #define PG8_LDA(dst, b, h) do { _Pragma("unroll") for (int m = 0; m < 4; ++m) _Pragma("unroll") for (int k = 0; k < 2; ++k) dst[m][k] = *(const PG8_LAS bf16x8*)(lds + PG8_SA(b, h) + aoff + m * 2048 + k * 1024); } while (0)
; #define PG8_LDB(dst, b, h) do { _Pragma("unroll") for (int n = 0; n < 2; ++n) _Pragma("unroll") for (int k = 0; k < 2; ++k) dst[n][k] = *(const PG8_LAS bf16x8*)(lds + PG8_SB(b, h) + boff + n * 2048 + k * 1024); } while (0)
; #define PG8_MMA(ai, bj, At, Bt) do { __builtin_amdgcn_s_setprio(1); _Pragma("unroll") for (int m = 0; m < 4; ++m) _Pragma("unroll") for (int n = 0; n < 2; ++n) _Pragma("unroll") for (int k = 0; k < 2; ++k) \
;         acc[ai][bj][m][n] = mma16<F16>(Bt[n][k], At[m][k], acc[ai][bj][m][n]); __builtin_amdgcn_s_setprio(0); } while (0)
; #define PG8_WAIT_V(n) asm volatile("s_waitcnt vmcnt(" #n ")" ::: "memory")
; #define PG8_WAIT_L(n) asm volatile("s_waitcnt lgkmcnt(" #n ")" ::: "memory")
; #define PG8_BAR __builtin_amdgcn_s_barrier()
; #define PG8_SCHED __builtin_amdgcn_sched_barrier(0)
; template <class Epi, class Sched, bool ALIGN_EPI = false, bool SP2 = false, bool F16 = false>
; __device__ __forceinline__ void gemm_phase(PG8_LAS unsigned char* lds, const Gemm g, const Sched& S, const Epi& E, const int wid_in) {
;     ...
;             PG8_WAIT_V(8); PG8_WAIT_L(0); PG8_BAR; PG8_MMA(1, 0, At, B0); PG8_MMA(1, 1, At, B1); PG8_BAR; PG8_SCHED;
;             PG8_LDB(B0, 1, 0); PG8_LDB(B1, 1, 1); PG8_SCHED; PG8_LDA(At, 1, 0); PG8_STAGE(PG8_SA(0, 1), a2 + hstep, voffA);
;             PG8_WAIT_V(8); PG8_WAIT_L(0); PG8_BAR; PG8_MMA(0, 0, At, B0); PG8_MMA(0, 1, At, B1); PG8_BAR; PG8_SCHED;
	s_waitcnt lgkmcnt(0)
	v_mfma_f32_16x16x32_f16 v[60:63], v[128:131], v[188:191], v[60:63]
	v_mfma_f32_16x16x32_f16 v[56:59], v[136:139], v[188:191], v[56:59]
	v_mfma_f32_16x16x32_f16 v[44:47], v[128:131], v[196:199], v[44:47]
	v_mfma_f32_16x16x32_f16 v[40:43], v[136:139], v[196:199], v[40:43]
	v_mfma_f32_16x16x32_f16 v[28:31], v[128:131], v[204:207], v[28:31]
	v_mfma_f32_16x16x32_f16 v[24:27], v[136:139], v[204:207], v[24:27]
	v_mfma_f32_16x16x32_f16 v[12:15], v[128:131], v[212:215], v[12:15]
	v_mfma_f32_16x16x32_f16 v[8:11], v[136:139], v[212:215], v[8:11]
	v_mfma_f32_16x16x32_f16 v[60:63], v[132:135], v[192:195], v[60:63]
	v_mfma_f32_16x16x32_f16 v[56:59], v[140:143], v[192:195], v[56:59]
	v_mfma_f32_16x16x32_f16 v[44:47], v[132:135], v[200:203], v[44:47]
	v_mfma_f32_16x16x32_f16 v[40:43], v[140:143], v[200:203], v[40:43]
	v_mfma_f32_16x16x32_f16 v[28:31], v[132:135], v[208:211], v[28:31]
	v_mfma_f32_16x16x32_f16 v[24:27], v[140:143], v[208:211], v[24:27]
	v_mfma_f32_16x16x32_f16 v[12:15], v[132:135], v[216:219], v[12:15]
	v_mfma_f32_16x16x32_f16 v[8:11], v[140:143], v[216:219], v[8:11]
	v_mfma_f32_16x16x32_f16 v[52:55], v[144:147], v[188:191], v[52:55]
	v_mfma_f32_16x16x32_f16 v[48:51], v[152:155], v[188:191], v[48:51]
	v_mfma_f32_16x16x32_f16 v[36:39], v[144:147], v[196:199], v[36:39]
	v_mfma_f32_16x16x32_f16 v[32:35], v[152:155], v[196:199], v[32:35]
	v_mfma_f32_16x16x32_f16 v[20:23], v[144:147], v[204:207], v[20:23]
	v_mfma_f32_16x16x32_f16 v[16:19], v[152:155], v[204:207], v[16:19]
	v_mfma_f32_16x16x32_f16 v[4:7], v[144:147], v[212:215], v[4:7]
	v_mfma_f32_16x16x32_f16 v[0:3], v[152:155], v[212:215], v[0:3]
	v_mfma_f32_16x16x32_f16 v[52:55], v[148:151], v[192:195], v[52:55]
	v_mfma_f32_16x16x32_f16 v[48:51], v[174:177], v[192:195], v[48:51]
	v_mfma_f32_16x16x32_f16 v[36:39], v[148:151], v[200:203], v[36:39]
	v_mfma_f32_16x16x32_f16 v[32:35], v[174:177], v[200:203], v[32:35]
	v_mfma_f32_16x16x32_f16 v[20:23], v[148:151], v[208:211], v[20:23]
	v_mfma_f32_16x16x32_f16 v[16:19], v[174:177], v[208:211], v[16:19]
	v_mfma_f32_16x16x32_f16 v[4:7], v[148:151], v[216:219], v[4:7]
	v_mfma_f32_16x16x32_f16 v[0:3], v[174:177], v[216:219], v[0:3]
	s_barrier
	s_add_i32 s43, 0, 0x18000
	s_add_i32 s54, 0, 0x1c000
	v_add_u32_e32 v140, s43, v182
	v_add_u32_e32 v165, s54, v182
	ds_read_b128 v[128:131], v140
	ds_read_b128 v[132:135], v140 offset:1024
	ds_read_b128 v[136:139], v140 offset:2048
	ds_read_b128 v[140:143], v140 offset:3072
	ds_read_b128 v[144:147], v165
	ds_read_b128 v[148:151], v165 offset:1024
	ds_read_b128 v[152:155], v165 offset:2048
	ds_read_b128 v[174:177], v165 offset:3072
	s_add_u32 s52, s52, 0x40000
	s_addc_u32 s53, s53, 0
	s_mov_b32 m0, s90
	v_lshl_add_u64 v[226:227], s[52:53], 0, v[156:157]
	ds_read_b128 v[188:191], v185 offset:32768
	ds_read_b128 v[192:195], v185 offset:33792
	ds_read_b128 v[196:199], v185 offset:34816
	ds_read_b128 v[200:203], v185 offset:35840
	ds_read_b128 v[204:207], v185 offset:36864
	ds_read_b128 v[208:211], v185 offset:37888
	ds_read_b128 v[212:215], v185 offset:38912
	ds_read_b128 v[216:219], v185 offset:39936
	global_load_lds_dwordx4 v[226:227], off
	v_lshl_add_u64 v[226:227], s[52:53], 0, v[160:161]
	s_mov_b32 m0, s63
	s_nop 0
	global_load_lds_dwordx4 v[226:227], off
	s_waitcnt vmcnt(8)
	s_waitcnt lgkmcnt(0)
	s_barrier
	s_waitcnt lgkmcnt(0)
	v_mfma_f32_16x16x32_f16 v[124:127], v[128:131], v[188:191], v[124:127]
	v_mfma_f32_16x16x32_f16 v[120:123], v[136:139], v[188:191], v[120:123]
	v_mfma_f32_16x16x32_f16 v[108:111], v[128:131], v[196:199], v[108:111]
	v_mfma_f32_16x16x32_f16 v[104:107], v[136:139], v[196:199], v[104:107]
	v_mfma_f32_16x16x32_f16 v[92:95], v[128:131], v[204:207], v[92:95]
	v_mfma_f32_16x16x32_f16 v[88:91], v[136:139], v[204:207], v[88:91]
	v_mfma_f32_16x16x32_f16 v[76:79], v[128:131], v[212:215], v[76:79]
	v_mfma_f32_16x16x32_f16 v[72:75], v[136:139], v[212:215], v[72:75]
	v_mfma_f32_16x16x32_f16 v[124:127], v[132:135], v[192:195], v[124:127]
	v_mfma_f32_16x16x32_f16 v[120:123], v[140:143], v[192:195], v[120:123]
	v_mfma_f32_16x16x32_f16 v[108:111], v[132:135], v[200:203], v[108:111]
	v_mfma_f32_16x16x32_f16 v[104:107], v[140:143], v[200:203], v[104:107]
	v_mfma_f32_16x16x32_f16 v[92:95], v[132:135], v[208:211], v[92:95]
	v_mfma_f32_16x16x32_f16 v[88:91], v[140:143], v[208:211], v[88:91]
	v_mfma_f32_16x16x32_f16 v[76:79], v[132:135], v[216:219], v[76:79]
	v_mfma_f32_16x16x32_f16 v[72:75], v[140:143], v[216:219], v[72:75]
	v_mfma_f32_16x16x32_f16 v[116:119], v[144:147], v[188:191], v[116:119]
	v_mfma_f32_16x16x32_f16 v[112:115], v[152:155], v[188:191], v[112:115]
	v_mfma_f32_16x16x32_f16 v[100:103], v[144:147], v[196:199], v[100:103]
	v_mfma_f32_16x16x32_f16 v[96:99], v[152:155], v[196:199], v[96:99]
	v_mfma_f32_16x16x32_f16 v[84:87], v[144:147], v[204:207], v[84:87]
	v_mfma_f32_16x16x32_f16 v[80:83], v[152:155], v[204:207], v[80:83]
	v_mfma_f32_16x16x32_f16 v[68:71], v[144:147], v[212:215], v[68:71]
	v_mfma_f32_16x16x32_f16 v[64:67], v[152:155], v[212:215], v[64:67]
	v_mfma_f32_16x16x32_f16 v[116:119], v[148:151], v[192:195], v[116:119]
	v_mfma_f32_16x16x32_f16 v[112:115], v[174:177], v[192:195], v[112:115]
	v_mfma_f32_16x16x32_f16 v[100:103], v[148:151], v[200:203], v[100:103]
	v_mfma_f32_16x16x32_f16 v[96:99], v[174:177], v[200:203], v[96:99]
	v_mfma_f32_16x16x32_f16 v[84:87], v[148:151], v[208:211], v[84:87]
	v_mfma_f32_16x16x32_f16 v[80:83], v[174:177], v[208:211], v[80:83]
	v_mfma_f32_16x16x32_f16 v[68:71], v[148:151], v[216:219], v[68:71]
	v_mfma_f32_16x16x32_f16 v[64:67], v[174:177], v[216:219], v[64:67]
	s_barrier
; #define PG8_STAGE(bufoff, gbase, voff) do { _Pragma("unroll") for (int _i = 0; _i < 2; ++_i) \
;         __builtin_amdgcn_global_load_lds((const unsigned*)((const char*)(gbase) + (voff)[_i]), (PG8_LAS unsigned*)(lds + (bufoff) + ldsw + _i * 8192), 16, 0, 0); } while (0)
; #define PG8_LDA(dst, b, h) do { _Pragma("unroll") for (int m = 0; m < 4; ++m) _Pragma("unroll") for (int k = 0; k < 2; ++k) dst[m][k] = *(const PG8_LAS bf16x8*)(lds + PG8_SA(b, h) + aoff + m * 2048 + k * 1024); } while (0)
; #define PG8_MMA(ai, bj, At, Bt) do { __builtin_amdgcn_s_setprio(1); _Pragma("unroll") for (int m = 0; m < 4; ++m) _Pragma("unroll") for (int n = 0; n < 2; ++n) _Pragma("unroll") for (int k = 0; k < 2; ++k) \
;         acc[ai][bj][m][n] = mma16<F16>(Bt[n][k], At[m][k], acc[ai][bj][m][n]); __builtin_amdgcn_s_setprio(0); } while (0)
; #define PG8_WAIT_V(n) asm volatile("s_waitcnt vmcnt(" #n ")" ::: "memory")
; #define PG8_WAIT_L(n) asm volatile("s_waitcnt lgkmcnt(" #n ")" ::: "memory")
; #define PG8_BAR __builtin_amdgcn_s_barrier()
; #define PG8_SCHED __builtin_amdgcn_sched_barrier(0)
; template <class Epi, class Sched, bool ALIGN_EPI = false, bool SP2 = false, bool F16 = false>
; __device__ __forceinline__ void gemm_phase(PG8_LAS unsigned char* lds, const Gemm g, const Sched& S, const Epi& E, const int wid_in) {
;     ...
;             PG8_LDA(At, 1, 1); PG8_STAGE(PG8_SB(1, 0), b3, voffB); PG8_STAGE(PG8_SB(1, 1), b3 + hstep, voffB); PG8_STAGE(PG8_SA(1, 0), a3, voffA);
;             PG8_WAIT_V(8); PG8_WAIT_L(0); PG8_BAR; PG8_MMA(1, 0, At, B0); PG8_MMA(1, 1, At, B1); PG8_BAR; PG8_SCHED;
;     ...
;         if constexpr (ALIGN_EPI) { if (wr == 0) PG8_BAR; }
	s_add_i32 s43, s43, s68
	v_lshl_add_u64 v[178:179], v[178:179], 0, s[26:27]
	s_mov_b32 m0, s43
	ds_read_b128 v[188:191], v185 offset:49152
	ds_read_b128 v[192:195], v185 offset:50176
	ds_read_b128 v[196:199], v185 offset:51200
	ds_read_b128 v[200:203], v185 offset:52224
	ds_read_b128 v[204:207], v185 offset:53248
	ds_read_b128 v[208:211], v185 offset:54272
	ds_read_b128 v[212:215], v185 offset:55296
	ds_read_b128 v[216:219], v185 offset:56320
	global_load_lds_dwordx4 v[178:179], off
	s_add_i32 m0, s43, 0x2000
	s_add_u32 s50, s50, 0x40080
	v_lshl_add_u64 v[178:179], v[220:221], 0, s[26:27]
	s_addc_u32 s51, s51, 0
	s_add_i32 s43, s54, s68
	global_load_lds_dwordx4 v[178:179], off
	v_lshl_add_u64 v[178:179], s[50:51], 0, v[158:159]
	s_mov_b32 m0, s43
	s_nop 0
	global_load_lds_dwordx4 v[178:179], off
	v_lshl_add_u64 v[178:179], s[50:51], 0, v[162:163]
	s_add_i32 m0, s43, 0x2000
	s_nop 0
	global_load_lds_dwordx4 v[178:179], off
	v_lshl_add_u64 v[178:179], v[222:223], 0, s[26:27]
	s_mov_b32 m0, s75
	s_nop 0
	global_load_lds_dwordx4 v[178:179], off
	v_lshl_add_u64 v[178:179], v[224:225], 0, s[26:27]
	s_mov_b32 m0, s67
	s_nop 0
	global_load_lds_dwordx4 v[178:179], off
	s_waitcnt vmcnt(8)
	s_waitcnt lgkmcnt(0)
	s_barrier
	s_waitcnt lgkmcnt(0)
	v_mfma_f32_16x16x32_f16 v[60:63], v[128:131], v[188:191], v[60:63]
	v_mfma_f32_16x16x32_f16 v[56:59], v[136:139], v[188:191], v[56:59]
	v_mfma_f32_16x16x32_f16 v[44:47], v[128:131], v[196:199], v[44:47]
	v_mfma_f32_16x16x32_f16 v[40:43], v[136:139], v[196:199], v[40:43]
	v_mfma_f32_16x16x32_f16 v[28:31], v[128:131], v[204:207], v[28:31]
	v_mfma_f32_16x16x32_f16 v[24:27], v[136:139], v[204:207], v[24:27]
	v_mfma_f32_16x16x32_f16 v[12:15], v[128:131], v[212:215], v[12:15]
	v_mfma_f32_16x16x32_f16 v[8:11], v[136:139], v[212:215], v[8:11]
	v_mfma_f32_16x16x32_f16 v[60:63], v[132:135], v[192:195], v[60:63]
	v_mfma_f32_16x16x32_f16 v[56:59], v[140:143], v[192:195], v[56:59]
	v_mfma_f32_16x16x32_f16 v[44:47], v[132:135], v[200:203], v[44:47]
	v_mfma_f32_16x16x32_f16 v[40:43], v[140:143], v[200:203], v[40:43]
	v_mfma_f32_16x16x32_f16 v[28:31], v[132:135], v[208:211], v[28:31]
	v_mfma_f32_16x16x32_f16 v[24:27], v[140:143], v[208:211], v[24:27]
	v_mfma_f32_16x16x32_f16 v[12:15], v[132:135], v[216:219], v[12:15]
	v_mfma_f32_16x16x32_f16 v[8:11], v[140:143], v[216:219], v[8:11]
	v_mfma_f32_16x16x32_f16 v[52:55], v[144:147], v[188:191], v[52:55]
	v_mfma_f32_16x16x32_f16 v[48:51], v[152:155], v[188:191], v[48:51]
	v_mfma_f32_16x16x32_f16 v[36:39], v[144:147], v[196:199], v[36:39]
	v_mfma_f32_16x16x32_f16 v[32:35], v[152:155], v[196:199], v[32:35]
	v_mfma_f32_16x16x32_f16 v[20:23], v[144:147], v[204:207], v[20:23]
	v_mfma_f32_16x16x32_f16 v[16:19], v[152:155], v[204:207], v[16:19]
	v_mfma_f32_16x16x32_f16 v[4:7], v[144:147], v[212:215], v[4:7]
	v_mfma_f32_16x16x32_f16 v[0:3], v[152:155], v[212:215], v[0:3]
	v_mfma_f32_16x16x32_f16 v[52:55], v[148:151], v[192:195], v[52:55]
	v_mfma_f32_16x16x32_f16 v[48:51], v[174:177], v[192:195], v[48:51]
	v_mfma_f32_16x16x32_f16 v[36:39], v[148:151], v[200:203], v[36:39]
	v_mfma_f32_16x16x32_f16 v[32:35], v[174:177], v[200:203], v[32:35]
	v_mfma_f32_16x16x32_f16 v[20:23], v[148:151], v[208:211], v[20:23]
	v_mfma_f32_16x16x32_f16 v[16:19], v[174:177], v[208:211], v[16:19]
	v_mfma_f32_16x16x32_f16 v[4:7], v[148:151], v[216:219], v[4:7]
	v_mfma_f32_16x16x32_f16 v[0:3], v[174:177], v[216:219], v[0:3]
	s_barrier
	s_add_i32 s42, s42, 2
	s_add_u32 s48, s48, 0x100
	s_addc_u32 s49, s49, 0
	s_add_u32 s40, s40, 0x100
	s_addc_u32 s41, s41, 0
	s_cmp_gt_u32 s42, 13
	s_cbranch_scc0 .LBB0_2226
	s_and_b64 vcc, exec, s[16:17]
	s_cbranch_vccz .LBB0_2229
	s_barrier

; #define PG8_STAGE(bufoff, gbase, voff) do { _Pragma("unroll") for (int _i = 0; _i < 2; ++_i) \
;         __builtin_amdgcn_global_load_lds((const unsigned*)((const char*)(gbase) + (voff)[_i]), (PG8_LAS unsigned*)(lds + (bufoff) + ldsw + _i * 8192), 16, 0, 0); } while (0)
; #define PG8_LDA(dst, b, h) do { _Pragma("unroll") for (int m = 0; m < 4; ++m) _Pragma("unroll") for (int k = 0; k < 2; ++k) dst[m][k] = *(const PG8_LAS bf16x8*)(lds + PG8_SA(b, h) + aoff + m * 2048 + k * 1024); } while (0)
; #define PG8_LDB(dst, b, h) do { _Pragma("unroll") for (int n = 0; n < 2; ++n) _Pragma("unroll") for (int k = 0; k < 2; ++k) dst[n][k] = *(const PG8_LAS bf16x8*)(lds + PG8_SB(b, h) + boff + n * 2048 + k * 1024); } while (0)
; #define PG8_MMA(ai, bj, At, Bt) do { __builtin_amdgcn_s_setprio(1); _Pragma("unroll") for (int m = 0; m < 4; ++m) _Pragma("unroll") for (int n = 0; n < 2; ++n) _Pragma("unroll") for (int k = 0; k < 2; ++k) \
;         acc[ai][bj][m][n] = mma16<F16>(Bt[n][k], At[m][k], acc[ai][bj][m][n]); __builtin_amdgcn_s_setprio(0); } while (0)
; #define PG8_WAIT_V(n) asm volatile("s_waitcnt vmcnt(" #n ")" ::: "memory")
; #define PG8_BAR __builtin_amdgcn_s_barrier()
; template <class Epi, class Sched, bool ALIGN_EPI = false, bool SP2 = false, bool F16 = false>
; __device__ __forceinline__ void gemm_phase(PG8_LAS unsigned char* lds, const Gemm g, const Sched& S, const Epi& E, const int wid_in) {
;     ...
;         for (int t = 0; t < nt; t += 2) {
;             const bool last = (t == nt - 2);
;             const char* a1 = cA + (size_t)(t + 1) * kstep;
;             const char* a2 = last ? nA : cA + (size_t)(t + 2) * kstep; const char* b2 = last ? nB : cB + (size_t)(t + 2) * kstep;
;             const char* a3 = a2 + kstep; const char* b3 = b2 + kstep;
;             if (last && has_next) S.a_ready(nxt);
;             if constexpr (SP2) {
;             PG8_LDB(B0, 0, 0); PG8_LDB(B1, 0, 1); PG8_SCHED; PG8_LDA(At, 0, 0); PG8_STAGE(PG8_SA(1, 1), a1 + hstep, voffA);
;             PG8_WAIT_V(8); PG8_WAIT_L(0); PG8_BAR; PG8_MMA(0, 0, At, B0); PG8_MMA(0, 1, At, B1); PG8_BAR; PG8_SCHED;
;             PG8_LDA(At, 0, 1); PG8_STAGE(PG8_SB(0, 0), b2, voffB); PG8_STAGE(PG8_SB(0, 1), b2 + hstep, voffB); PG8_STAGE(PG8_SA(0, 0), a2, voffA);
;             PG8_WAIT_V(8); PG8_WAIT_L(0); PG8_BAR; PG8_MMA(1, 0, At, B0); PG8_MMA(1, 1, At, B1); PG8_BAR; PG8_SCHED;
.LBB0_2489:
	ds_read_b128 v[128:131], v189
	ds_read_b128 v[132:135], v189 offset:1024
	ds_read_b128 v[136:139], v189 offset:2048
	ds_read_b128 v[140:143], v189 offset:3072
	ds_read_b128 v[144:147], v190
	ds_read_b128 v[148:151], v190 offset:1024
	ds_read_b128 v[168:171], v190 offset:2048
	ds_read_b128 v[172:175], v190 offset:3072
	s_add_u32 s44, s42, 0xfffc0080
	s_addc_u32 s45, s43, -1
	s_cmp_eq_u32 s59, 12
	s_cselect_b32 s47, s29, s45
	s_cselect_b32 s46, s37, s44
	s_cselect_b32 s45, s27, s58
	s_cselect_b32 s44, s56, s57
	s_mov_b32 m0, s91
	v_lshl_add_u64 v[184:185], s[42:43], 0, v[160:161]
	ds_read_b128 v[176:179], v191
	ds_read_b128 v[180:183], v191 offset:1024
	ds_read_b128 v[192:195], v191 offset:2048
	ds_read_b128 v[196:199], v191 offset:3072
	ds_read_b128 v[200:203], v191 offset:4096
	ds_read_b128 v[204:207], v191 offset:5120
	ds_read_b128 v[208:211], v191 offset:6144
	ds_read_b128 v[212:215], v191 offset:7168
	global_load_lds_dwordx4 v[184:185], off
	v_lshl_add_u64 v[184:185], s[42:43], 0, v[162:163]
	s_add_i32 m0, s74, 0xe000
	s_nop 0
	global_load_lds_dwordx4 v[184:185], off
	s_waitcnt vmcnt(8)
	s_waitcnt lgkmcnt(0)
	s_barrier
	s_waitcnt lgkmcnt(0)
	v_mfma_f32_16x16x32_bf16 v[124:127], v[128:131], v[176:179], v[124:127]
	v_mfma_f32_16x16x32_bf16 v[120:123], v[136:139], v[176:179], v[120:123]
	v_mfma_f32_16x16x32_bf16 v[108:111], v[128:131], v[192:195], v[108:111]
	v_mfma_f32_16x16x32_bf16 v[104:107], v[136:139], v[192:195], v[104:107]
	v_mfma_f32_16x16x32_bf16 v[92:95], v[128:131], v[200:203], v[92:95]
	v_mfma_f32_16x16x32_bf16 v[88:91], v[136:139], v[200:203], v[88:91]
	v_mfma_f32_16x16x32_bf16 v[76:79], v[128:131], v[208:211], v[76:79]
	v_mfma_f32_16x16x32_bf16 v[72:75], v[136:139], v[208:211], v[72:75]
	v_mfma_f32_16x16x32_bf16 v[124:127], v[132:135], v[180:183], v[124:127]
	v_mfma_f32_16x16x32_bf16 v[120:123], v[140:143], v[180:183], v[120:123]
	v_mfma_f32_16x16x32_bf16 v[108:111], v[132:135], v[196:199], v[108:111]
	v_mfma_f32_16x16x32_bf16 v[104:107], v[140:143], v[196:199], v[104:107]
	v_mfma_f32_16x16x32_bf16 v[92:95], v[132:135], v[204:207], v[92:95]
	v_mfma_f32_16x16x32_bf16 v[88:91], v[140:143], v[204:207], v[88:91]
	v_mfma_f32_16x16x32_bf16 v[76:79], v[132:135], v[212:215], v[76:79]
	v_mfma_f32_16x16x32_bf16 v[72:75], v[140:143], v[212:215], v[72:75]
	v_mfma_f32_16x16x32_bf16 v[116:119], v[144:147], v[176:179], v[116:119]
	v_mfma_f32_16x16x32_bf16 v[112:115], v[168:171], v[176:179], v[112:115]
	v_mfma_f32_16x16x32_bf16 v[100:103], v[144:147], v[192:195], v[100:103]
	v_mfma_f32_16x16x32_bf16 v[96:99], v[168:171], v[192:195], v[96:99]
	v_mfma_f32_16x16x32_bf16 v[84:87], v[144:147], v[200:203], v[84:87]
	v_mfma_f32_16x16x32_bf16 v[80:83], v[168:171], v[200:203], v[80:83]
	v_mfma_f32_16x16x32_bf16 v[68:71], v[144:147], v[208:211], v[68:71]
	v_mfma_f32_16x16x32_bf16 v[64:67], v[168:171], v[208:211], v[64:67]
	v_mfma_f32_16x16x32_bf16 v[116:119], v[148:151], v[180:183], v[116:119]
	v_mfma_f32_16x16x32_bf16 v[112:115], v[172:175], v[180:183], v[112:115]
	v_mfma_f32_16x16x32_bf16 v[100:103], v[148:151], v[196:199], v[100:103]
	v_mfma_f32_16x16x32_bf16 v[96:99], v[172:175], v[196:199], v[96:99]
	v_mfma_f32_16x16x32_bf16 v[84:87], v[148:151], v[204:207], v[84:87]
	v_mfma_f32_16x16x32_bf16 v[80:83], v[172:175], v[204:207], v[80:83]
	v_mfma_f32_16x16x32_bf16 v[68:71], v[148:151], v[212:215], v[68:71]
	v_mfma_f32_16x16x32_bf16 v[64:67], v[172:175], v[212:215], v[64:67]
	s_barrier
	s_add_i32 s60, s53, s68
	v_lshl_add_u64 v[184:185], s[44:45], 0, v[154:155]
	s_mov_b32 m0, s60
	ds_read_b128 v[176:179], v191 offset:16384
	ds_read_b128 v[180:183], v191 offset:17408
	ds_read_b128 v[192:195], v191 offset:18432
	ds_read_b128 v[196:199], v191 offset:19456
	ds_read_b128 v[200:203], v191 offset:20480
	ds_read_b128 v[204:207], v191 offset:21504
	ds_read_b128 v[208:211], v191 offset:22528
	ds_read_b128 v[212:215], v191 offset:23552
	global_load_lds_dwordx4 v[184:185], off
	s_add_i32 m0, s60, 0x2000
	s_add_u32 s60, s44, 0x40000
	v_lshl_add_u64 v[216:217], s[44:45], 0, v[158:159]
	s_addc_u32 s61, s45, 0
	s_add_i32 s62, s54, s68
	global_load_lds_dwordx4 v[216:217], off
	v_lshl_add_u64 v[218:219], s[60:61], 0, v[154:155]
	s_mov_b32 m0, s62
	v_lshl_add_u64 v[220:221], s[46:47], 0, v[156:157]
	global_load_lds_dwordx4 v[218:219], off
	v_lshl_add_u64 v[218:219], s[60:61], 0, v[158:159]
	s_add_i32 m0, s62, 0x2000
	s_nop 0
	global_load_lds_dwordx4 v[218:219], off
	v_lshl_add_u64 v[218:219], s[46:47], 0, v[152:153]
	s_mov_b32 m0, s74
	s_nop 0
	global_load_lds_dwordx4 v[218:219], off
	s_mov_b32 m0, s66
	s_nop 0
	global_load_lds_dwordx4 v[220:221], off
	s_waitcnt vmcnt(8)
	s_waitcnt lgkmcnt(0)
	s_barrier
; #define PG8_STAGE(bufoff, gbase, voff) do { _Pragma("unroll") for (int _i = 0; _i < 2; ++_i) \
;         __builtin_amdgcn_global_load_lds((const unsigned*)((const char*)(gbase) + (voff)[_i]), (PG8_LAS unsigned*)(lds + (bufoff) + ldsw + _i * 8192), 16, 0, 0); } while (0)
; #define PG8_LDA(dst, b, h) do { _Pragma("unroll") for (int m = 0; m < 4; ++m) _Pragma("unroll") for (int k = 0; k < 2; ++k) dst[m][k] = *(const PG8_LAS bf16x8*)(lds + PG8_SA(b, h) + aoff + m * 2048 + k * 1024); } while (0)
; #define PG8_LDB(dst, b, h) do { _Pragma("unroll") for (int n = 0; n < 2; ++n) _Pragma("unroll") for (int k = 0; k < 2; ++k) dst[n][k] = *(const PG8_LAS bf16x8*)(lds + PG8_SB(b, h) + boff + n * 2048 + k * 1024); } while (0)
; #define PG8_MMA(ai, bj, At, Bt) do { __builtin_amdgcn_s_setprio(1); _Pragma("unroll") for (int m = 0; m < 4; ++m) _Pragma("unroll") for (int n = 0; n < 2; ++n) _Pragma("unroll") for (int k = 0; k < 2; ++k) \
;         acc[ai][bj][m][n] = mma16<F16>(Bt[n][k], At[m][k], acc[ai][bj][m][n]); __builtin_amdgcn_s_setprio(0); } while (0)
; #define PG8_WAIT_V(n) asm volatile("s_waitcnt vmcnt(" #n ")" ::: "memory")
; #define PG8_WAIT_L(n) asm volatile("s_waitcnt lgkmcnt(" #n ")" ::: "memory")
; #define PG8_BAR __builtin_amdgcn_s_barrier()
; #define PG8_SCHED __builtin_amdgcn_sched_barrier(0)
; template <class Epi, class Sched, bool ALIGN_EPI = false, bool SP2 = false, bool F16 = false>
; __device__ __forceinline__ void gemm_phase(PG8_LAS unsigned char* lds, const Gemm g, const Sched& S, const Epi& E, const int wid_in) {
;     ...
;             PG8_WAIT_V(8); PG8_WAIT_L(0); PG8_BAR; PG8_MMA(1, 0, At, B0); PG8_MMA(1, 1, At, B1); PG8_BAR; PG8_SCHED;
;             PG8_LDB(B0, 1, 0); PG8_LDB(B1, 1, 1); PG8_SCHED; PG8_LDA(At, 1, 0); PG8_STAGE(PG8_SA(0, 1), a2 + hstep, voffA);
;             PG8_WAIT_V(8); PG8_WAIT_L(0); PG8_BAR; PG8_MMA(0, 0, At, B0); PG8_MMA(0, 1, At, B1); PG8_BAR; PG8_SCHED;
	s_waitcnt lgkmcnt(0)
	v_mfma_f32_16x16x32_bf16 v[60:63], v[128:131], v[176:179], v[60:63]
	v_mfma_f32_16x16x32_bf16 v[56:59], v[136:139], v[176:179], v[56:59]
	v_mfma_f32_16x16x32_bf16 v[44:47], v[128:131], v[192:195], v[44:47]
	v_mfma_f32_16x16x32_bf16 v[40:43], v[136:139], v[192:195], v[40:43]
	v_mfma_f32_16x16x32_bf16 v[28:31], v[128:131], v[200:203], v[28:31]
	v_mfma_f32_16x16x32_bf16 v[24:27], v[136:139], v[200:203], v[24:27]
	v_mfma_f32_16x16x32_bf16 v[12:15], v[128:131], v[208:211], v[12:15]
	v_mfma_f32_16x16x32_bf16 v[8:11], v[136:139], v[208:211], v[8:11]
	v_mfma_f32_16x16x32_bf16 v[60:63], v[132:135], v[180:183], v[60:63]
	v_mfma_f32_16x16x32_bf16 v[56:59], v[140:143], v[180:183], v[56:59]
	v_mfma_f32_16x16x32_bf16 v[44:47], v[132:135], v[196:199], v[44:47]
	v_mfma_f32_16x16x32_bf16 v[40:43], v[140:143], v[196:199], v[40:43]
	v_mfma_f32_16x16x32_bf16 v[28:31], v[132:135], v[204:207], v[28:31]
	v_mfma_f32_16x16x32_bf16 v[24:27], v[140:143], v[204:207], v[24:27]
	v_mfma_f32_16x16x32_bf16 v[12:15], v[132:135], v[212:215], v[12:15]
	v_mfma_f32_16x16x32_bf16 v[8:11], v[140:143], v[212:215], v[8:11]
	v_mfma_f32_16x16x32_bf16 v[52:55], v[144:147], v[176:179], v[52:55]
	v_mfma_f32_16x16x32_bf16 v[48:51], v[168:171], v[176:179], v[48:51]
	v_mfma_f32_16x16x32_bf16 v[36:39], v[144:147], v[192:195], v[36:39]
	v_mfma_f32_16x16x32_bf16 v[32:35], v[168:171], v[192:195], v[32:35]
	v_mfma_f32_16x16x32_bf16 v[20:23], v[144:147], v[200:203], v[20:23]
	v_mfma_f32_16x16x32_bf16 v[16:19], v[168:171], v[200:203], v[16:19]
	v_mfma_f32_16x16x32_bf16 v[4:7], v[144:147], v[208:211], v[4:7]
	v_mfma_f32_16x16x32_bf16 v[0:3], v[168:171], v[208:211], v[0:3]
	v_mfma_f32_16x16x32_bf16 v[52:55], v[148:151], v[180:183], v[52:55]
	v_mfma_f32_16x16x32_bf16 v[48:51], v[172:175], v[180:183], v[48:51]
	v_mfma_f32_16x16x32_bf16 v[36:39], v[148:151], v[196:199], v[36:39]
	v_mfma_f32_16x16x32_bf16 v[32:35], v[172:175], v[196:199], v[32:35]
	v_mfma_f32_16x16x32_bf16 v[20:23], v[148:151], v[204:207], v[20:23]
	v_mfma_f32_16x16x32_bf16 v[16:19], v[172:175], v[204:207], v[16:19]
	v_mfma_f32_16x16x32_bf16 v[4:7], v[148:151], v[212:215], v[4:7]
	v_mfma_f32_16x16x32_bf16 v[0:3], v[172:175], v[212:215], v[0:3]
	s_barrier
	s_add_i32 s60, 0, 0x18000
	s_add_i32 s61, 0, 0x1c000
	v_add_u32_e32 v140, s60, v188
	v_add_u32_e32 v172, s61, v188
	ds_read_b128 v[128:131], v140
	ds_read_b128 v[132:135], v140 offset:1024
	ds_read_b128 v[136:139], v140 offset:2048
	ds_read_b128 v[140:143], v140 offset:3072
	ds_read_b128 v[144:147], v172
	ds_read_b128 v[148:151], v172 offset:1024
	ds_read_b128 v[168:171], v172 offset:2048
	ds_read_b128 v[172:175], v172 offset:3072
	s_add_u32 s46, s46, 0x40000
	s_addc_u32 s47, s47, 0
	s_mov_b32 m0, s90
	v_lshl_add_u64 v[222:223], s[46:47], 0, v[152:153]
	ds_read_b128 v[176:179], v191 offset:32768
	ds_read_b128 v[180:183], v191 offset:33792
	ds_read_b128 v[192:195], v191 offset:34816
	ds_read_b128 v[196:199], v191 offset:35840
	ds_read_b128 v[200:203], v191 offset:36864
	ds_read_b128 v[204:207], v191 offset:37888
	ds_read_b128 v[208:211], v191 offset:38912
	ds_read_b128 v[212:215], v191 offset:39936
	global_load_lds_dwordx4 v[222:223], off
	v_lshl_add_u64 v[222:223], s[46:47], 0, v[156:157]
	s_mov_b32 m0, s49
	s_nop 0
	global_load_lds_dwordx4 v[222:223], off
	s_waitcnt vmcnt(8)
	s_waitcnt lgkmcnt(0)
	s_barrier
	s_waitcnt lgkmcnt(0)
	v_mfma_f32_16x16x32_bf16 v[124:127], v[128:131], v[176:179], v[124:127]
	v_mfma_f32_16x16x32_bf16 v[120:123], v[136:139], v[176:179], v[120:123]
	v_mfma_f32_16x16x32_bf16 v[108:111], v[128:131], v[192:195], v[108:111]
	v_mfma_f32_16x16x32_bf16 v[104:107], v[136:139], v[192:195], v[104:107]
	v_mfma_f32_16x16x32_bf16 v[92:95], v[128:131], v[200:203], v[92:95]
	v_mfma_f32_16x16x32_bf16 v[88:91], v[136:139], v[200:203], v[88:91]
	v_mfma_f32_16x16x32_bf16 v[76:79], v[128:131], v[208:211], v[76:79]
	v_mfma_f32_16x16x32_bf16 v[72:75], v[136:139], v[208:211], v[72:75]
	v_mfma_f32_16x16x32_bf16 v[124:127], v[132:135], v[180:183], v[124:127]
	v_mfma_f32_16x16x32_bf16 v[120:123], v[140:143], v[180:183], v[120:123]
	v_mfma_f32_16x16x32_bf16 v[108:111], v[132:135], v[196:199], v[108:111]
	v_mfma_f32_16x16x32_bf16 v[104:107], v[140:143], v[196:199], v[104:107]
	v_mfma_f32_16x16x32_bf16 v[92:95], v[132:135], v[204:207], v[92:95]
	v_mfma_f32_16x16x32_bf16 v[88:91], v[140:143], v[204:207], v[88:91]
	v_mfma_f32_16x16x32_bf16 v[76:79], v[132:135], v[212:215], v[76:79]
	v_mfma_f32_16x16x32_bf16 v[72:75], v[140:143], v[212:215], v[72:75]
	v_mfma_f32_16x16x32_bf16 v[116:119], v[144:147], v[176:179], v[116:119]
	v_mfma_f32_16x16x32_bf16 v[112:115], v[168:171], v[176:179], v[112:115]
	v_mfma_f32_16x16x32_bf16 v[100:103], v[144:147], v[192:195], v[100:103]
	v_mfma_f32_16x16x32_bf16 v[96:99], v[168:171], v[192:195], v[96:99]
	v_mfma_f32_16x16x32_bf16 v[84:87], v[144:147], v[200:203], v[84:87]
	v_mfma_f32_16x16x32_bf16 v[80:83], v[168:171], v[200:203], v[80:83]
	v_mfma_f32_16x16x32_bf16 v[68:71], v[144:147], v[208:211], v[68:71]
	v_mfma_f32_16x16x32_bf16 v[64:67], v[168:171], v[208:211], v[64:67]
	v_mfma_f32_16x16x32_bf16 v[116:119], v[148:151], v[180:183], v[116:119]
	v_mfma_f32_16x16x32_bf16 v[112:115], v[172:175], v[180:183], v[112:115]
	v_mfma_f32_16x16x32_bf16 v[100:103], v[148:151], v[196:199], v[100:103]
	v_mfma_f32_16x16x32_bf16 v[96:99], v[172:175], v[196:199], v[96:99]
	v_mfma_f32_16x16x32_bf16 v[84:87], v[148:151], v[204:207], v[84:87]
	v_mfma_f32_16x16x32_bf16 v[80:83], v[172:175], v[204:207], v[80:83]
	v_mfma_f32_16x16x32_bf16 v[68:71], v[148:151], v[212:215], v[68:71]
	v_mfma_f32_16x16x32_bf16 v[64:67], v[172:175], v[212:215], v[64:67]
	s_barrier
; #define PG8_STAGE(bufoff, gbase, voff) do { _Pragma("unroll") for (int _i = 0; _i < 2; ++_i) \
;         __builtin_amdgcn_global_load_lds((const unsigned*)((const char*)(gbase) + (voff)[_i]), (PG8_LAS unsigned*)(lds + (bufoff) + ldsw + _i * 8192), 16, 0, 0); } while (0)
; #define PG8_LDA(dst, b, h) do { _Pragma("unroll") for (int m = 0; m < 4; ++m) _Pragma("unroll") for (int k = 0; k < 2; ++k) dst[m][k] = *(const PG8_LAS bf16x8*)(lds + PG8_SA(b, h) + aoff + m * 2048 + k * 1024); } while (0)
; #define PG8_MMA(ai, bj, At, Bt) do { __builtin_amdgcn_s_setprio(1); _Pragma("unroll") for (int m = 0; m < 4; ++m) _Pragma("unroll") for (int n = 0; n < 2; ++n) _Pragma("unroll") for (int k = 0; k < 2; ++k) \
;         acc[ai][bj][m][n] = mma16<F16>(Bt[n][k], At[m][k], acc[ai][bj][m][n]); __builtin_amdgcn_s_setprio(0); } while (0)
; #define PG8_WAIT_V(n) asm volatile("s_waitcnt vmcnt(" #n ")" ::: "memory")
; #define PG8_WAIT_L(n) asm volatile("s_waitcnt lgkmcnt(" #n ")" ::: "memory")
; #define PG8_BAR __builtin_amdgcn_s_barrier()
; #define PG8_SCHED __builtin_amdgcn_sched_barrier(0)
; template <class Epi, class Sched, bool ALIGN_EPI = false, bool SP2 = false, bool F16 = false>
; __device__ __forceinline__ void gemm_phase(PG8_LAS unsigned char* lds, const Gemm g, const Sched& S, const Epi& E, const int wid_in) {
;     ...
;             PG8_LDA(At, 1, 1); PG8_STAGE(PG8_SB(1, 0), b3, voffB); PG8_STAGE(PG8_SB(1, 1), b3 + hstep, voffB); PG8_STAGE(PG8_SA(1, 0), a3, voffA);
;             PG8_WAIT_V(8); PG8_WAIT_L(0); PG8_BAR; PG8_MMA(1, 0, At, B0); PG8_MMA(1, 1, At, B1); PG8_BAR; PG8_SCHED;
;     ...
;         if constexpr (ALIGN_EPI) { if (wr == 0) PG8_BAR; }
	s_add_i32 s46, s60, s68
	v_lshl_add_u64 v[184:185], v[184:185], 0, s[24:25]
	s_mov_b32 m0, s46
	ds_read_b128 v[176:179], v191 offset:49152
	ds_read_b128 v[180:183], v191 offset:50176
	ds_read_b128 v[192:195], v191 offset:51200
	ds_read_b128 v[196:199], v191 offset:52224
	ds_read_b128 v[200:203], v191 offset:53248
	ds_read_b128 v[204:207], v191 offset:54272
	ds_read_b128 v[208:211], v191 offset:55296
	ds_read_b128 v[212:215], v191 offset:56320
	global_load_lds_dwordx4 v[184:185], off
	s_add_i32 m0, s46, 0x2000
	s_add_u32 s44, s44, 0x40080
	v_lshl_add_u64 v[184:185], v[216:217], 0, s[24:25]
	s_addc_u32 s45, s45, 0
	s_add_i32 s46, s61, s68
	global_load_lds_dwordx4 v[184:185], off
	v_lshl_add_u64 v[184:185], s[44:45], 0, v[154:155]
	s_mov_b32 m0, s46
	s_nop 0
	global_load_lds_dwordx4 v[184:185], off
	v_lshl_add_u64 v[184:185], s[44:45], 0, v[158:159]
	s_add_i32 m0, s46, 0x2000
	s_nop 0
	global_load_lds_dwordx4 v[184:185], off
	v_lshl_add_u64 v[184:185], v[218:219], 0, s[24:25]
	s_mov_b32 m0, s75
	s_nop 0
	global_load_lds_dwordx4 v[184:185], off
	v_lshl_add_u64 v[184:185], v[220:221], 0, s[24:25]
	s_mov_b32 m0, s67
	s_nop 0
	global_load_lds_dwordx4 v[184:185], off
	s_waitcnt vmcnt(8)
	s_waitcnt lgkmcnt(0)
	s_barrier
	s_waitcnt lgkmcnt(0)
	v_mfma_f32_16x16x32_bf16 v[60:63], v[128:131], v[176:179], v[60:63]
	v_mfma_f32_16x16x32_bf16 v[56:59], v[136:139], v[176:179], v[56:59]
	v_mfma_f32_16x16x32_bf16 v[44:47], v[128:131], v[192:195], v[44:47]
	v_mfma_f32_16x16x32_bf16 v[40:43], v[136:139], v[192:195], v[40:43]
	v_mfma_f32_16x16x32_bf16 v[28:31], v[128:131], v[200:203], v[28:31]
	v_mfma_f32_16x16x32_bf16 v[24:27], v[136:139], v[200:203], v[24:27]
	v_mfma_f32_16x16x32_bf16 v[12:15], v[128:131], v[208:211], v[12:15]
	v_mfma_f32_16x16x32_bf16 v[8:11], v[136:139], v[208:211], v[8:11]
	v_mfma_f32_16x16x32_bf16 v[60:63], v[132:135], v[180:183], v[60:63]
	v_mfma_f32_16x16x32_bf16 v[56:59], v[140:143], v[180:183], v[56:59]
	v_mfma_f32_16x16x32_bf16 v[44:47], v[132:135], v[196:199], v[44:47]
	v_mfma_f32_16x16x32_bf16 v[40:43], v[140:143], v[196:199], v[40:43]
	v_mfma_f32_16x16x32_bf16 v[28:31], v[132:135], v[204:207], v[28:31]
	v_mfma_f32_16x16x32_bf16 v[24:27], v[140:143], v[204:207], v[24:27]
	v_mfma_f32_16x16x32_bf16 v[12:15], v[132:135], v[212:215], v[12:15]
	v_mfma_f32_16x16x32_bf16 v[8:11], v[140:143], v[212:215], v[8:11]
	v_mfma_f32_16x16x32_bf16 v[52:55], v[144:147], v[176:179], v[52:55]
	v_mfma_f32_16x16x32_bf16 v[48:51], v[168:171], v[176:179], v[48:51]
	v_mfma_f32_16x16x32_bf16 v[36:39], v[144:147], v[192:195], v[36:39]
	v_mfma_f32_16x16x32_bf16 v[32:35], v[168:171], v[192:195], v[32:35]
	v_mfma_f32_16x16x32_bf16 v[20:23], v[144:147], v[200:203], v[20:23]
	v_mfma_f32_16x16x32_bf16 v[16:19], v[168:171], v[200:203], v[16:19]
	v_mfma_f32_16x16x32_bf16 v[4:7], v[144:147], v[208:211], v[4:7]
	v_mfma_f32_16x16x32_bf16 v[0:3], v[168:171], v[208:211], v[0:3]
	v_mfma_f32_16x16x32_bf16 v[52:55], v[148:151], v[180:183], v[52:55]
	v_mfma_f32_16x16x32_bf16 v[48:51], v[172:175], v[180:183], v[48:51]
	v_mfma_f32_16x16x32_bf16 v[36:39], v[148:151], v[196:199], v[36:39]
	v_mfma_f32_16x16x32_bf16 v[32:35], v[172:175], v[196:199], v[32:35]
	v_mfma_f32_16x16x32_bf16 v[20:23], v[148:151], v[204:207], v[20:23]
	v_mfma_f32_16x16x32_bf16 v[16:19], v[172:175], v[204:207], v[16:19]
	v_mfma_f32_16x16x32_bf16 v[4:7], v[148:151], v[212:215], v[4:7]
	v_mfma_f32_16x16x32_bf16 v[0:3], v[172:175], v[212:215], v[0:3]
	s_barrier
	s_add_i32 s59, s59, 2
	s_add_u32 s42, s42, 0x100
	s_addc_u32 s43, s43, 0
	s_add_u32 s57, s57, 0x100
	s_addc_u32 s58, s58, 0
	s_cmp_gt_u32 s59, 13
	s_cbranch_scc0 .LBB0_2489
	s_and_b64 vcc, exec, s[16:17]
	s_cbranch_vccz .LBB0_2492
	s_barrier

; #define PG8_STAGE(bufoff, gbase, voff) do { _Pragma("unroll") for (int _i = 0; _i < 2; ++_i) \
;         __builtin_amdgcn_global_load_lds((const unsigned*)((const char*)(gbase) + (voff)[_i]), (PG8_LAS unsigned*)(lds + (bufoff) + ldsw + _i * 8192), 16, 0, 0); } while (0)
; #define PG8_LDA(dst, b, h) do { _Pragma("unroll") for (int m = 0; m < 4; ++m) _Pragma("unroll") for (int k = 0; k < 2; ++k) dst[m][k] = *(const PG8_LAS bf16x8*)(lds + PG8_SA(b, h) + aoff + m * 2048 + k * 1024); } while (0)
; #define PG8_LDB(dst, b, h) do { _Pragma("unroll") for (int n = 0; n < 2; ++n) _Pragma("unroll") for (int k = 0; k < 2; ++k) dst[n][k] = *(const PG8_LAS bf16x8*)(lds + PG8_SB(b, h) + boff + n * 2048 + k * 1024); } while (0)
; #define PG8_MMA(ai, bj, At, Bt) do { __builtin_amdgcn_s_setprio(1); _Pragma("unroll") for (int m = 0; m < 4; ++m) _Pragma("unroll") for (int n = 0; n < 2; ++n) _Pragma("unroll") for (int k = 0; k < 2; ++k) \
;         acc[ai][bj][m][n] = mma16<F16>(Bt[n][k], At[m][k], acc[ai][bj][m][n]); __builtin_amdgcn_s_setprio(0); } while (0)
; #define PG8_WAIT_V(n) asm volatile("s_waitcnt vmcnt(" #n ")" ::: "memory")
; #define PG8_BAR __builtin_amdgcn_s_barrier()
; template <class Epi, class Sched, bool ALIGN_EPI = false, bool SP2 = false, bool F16 = false>
; __device__ __forceinline__ void gemm_phase(PG8_LAS unsigned char* lds, const Gemm g, const Sched& S, const Epi& E, const int wid_in) {
;     ...
;         for (int t = 0; t < nt; t += 2) {
;             const bool last = (t == nt - 2);
;             const char* a1 = cA + (size_t)(t + 1) * kstep;
;             const char* a2 = last ? nA : cA + (size_t)(t + 2) * kstep; const char* b2 = last ? nB : cB + (size_t)(t + 2) * kstep;
;             const char* a3 = a2 + kstep; const char* b3 = b2 + kstep;
;             if (last && has_next) S.a_ready(nxt);
;             if constexpr (SP2) {
;             PG8_LDB(B0, 0, 0); PG8_LDB(B1, 0, 1); PG8_SCHED; PG8_LDA(At, 0, 0); PG8_STAGE(PG8_SA(1, 1), a1 + hstep, voffA);
;             PG8_WAIT_V(8); PG8_WAIT_L(0); PG8_BAR; PG8_MMA(0, 0, At, B0); PG8_MMA(0, 1, At, B1); PG8_BAR; PG8_SCHED;
;             PG8_LDA(At, 0, 1); PG8_STAGE(PG8_SB(0, 0), b2, voffB); PG8_STAGE(PG8_SB(0, 1), b2 + hstep, voffB); PG8_STAGE(PG8_SA(0, 0), a2, voffA);
;             PG8_WAIT_V(8); PG8_WAIT_L(0); PG8_BAR; PG8_MMA(1, 0, At, B0); PG8_MMA(1, 1, At, B1); PG8_BAR; PG8_SCHED;
.LBB0_2566:
	ds_read_b128 v[0:3], v193
	ds_read_b128 v[4:7], v193 offset:1024
	ds_read_b128 v[136:139], v193 offset:2048
	ds_read_b128 v[140:143], v193 offset:3072
	ds_read_b128 v[144:147], v194
	ds_read_b128 v[148:151], v194 offset:1024
	ds_read_b128 v[152:155], v194 offset:2048
	ds_read_b128 v[156:159], v194 offset:3072
	s_add_u32 s42, s36, 0xfffc0080
	s_addc_u32 s43, s37, -1
	s_cmp_eq_u32 s62, 12
	s_cselect_b32 s45, s25, s43
	s_cselect_b32 s44, s35, s42
	s_cselect_b32 s43, s23, s61
	s_cselect_b32 s42, s59, s60
	s_mov_b32 m0, s91
	v_lshl_add_u64 v[188:189], s[36:37], 0, v[168:169]
	ds_read_b128 v[176:179], v195
	ds_read_b128 v[180:183], v195 offset:1024
	ds_read_b128 v[184:187], v195 offset:2048
	ds_read_b128 v[198:201], v195 offset:3072
	ds_read_b128 v[202:205], v195 offset:4096
	ds_read_b128 v[206:209], v195 offset:5120
	ds_read_b128 v[210:213], v195 offset:6144
	ds_read_b128 v[214:217], v195 offset:7168
	global_load_lds_dwordx4 v[188:189], off
	v_lshl_add_u64 v[188:189], s[36:37], 0, v[170:171]
	s_add_i32 m0, s74, 0xe000
	s_nop 0
	global_load_lds_dwordx4 v[188:189], off
	s_waitcnt vmcnt(8)
	s_waitcnt lgkmcnt(0)
	s_barrier
	s_waitcnt lgkmcnt(0)
	v_mfma_f32_16x16x32_f16 v[132:135], v[0:3], v[176:179], v[132:135]
	v_mfma_f32_16x16x32_f16 v[128:131], v[136:139], v[176:179], v[128:131]
	v_mfma_f32_16x16x32_f16 v[116:119], v[0:3], v[184:187], v[116:119]
	v_mfma_f32_16x16x32_f16 v[112:115], v[136:139], v[184:187], v[112:115]
	v_mfma_f32_16x16x32_f16 v[100:103], v[0:3], v[202:205], v[100:103]
	v_mfma_f32_16x16x32_f16 v[96:99], v[136:139], v[202:205], v[96:99]
	v_mfma_f32_16x16x32_f16 v[84:87], v[0:3], v[210:213], v[84:87]
	v_mfma_f32_16x16x32_f16 v[80:83], v[136:139], v[210:213], v[80:83]
	v_mfma_f32_16x16x32_f16 v[132:135], v[4:7], v[180:183], v[132:135]
	v_mfma_f32_16x16x32_f16 v[128:131], v[140:143], v[180:183], v[128:131]
	v_mfma_f32_16x16x32_f16 v[116:119], v[4:7], v[198:201], v[116:119]
	v_mfma_f32_16x16x32_f16 v[112:115], v[140:143], v[198:201], v[112:115]
	v_mfma_f32_16x16x32_f16 v[100:103], v[4:7], v[206:209], v[100:103]
	v_mfma_f32_16x16x32_f16 v[96:99], v[140:143], v[206:209], v[96:99]
	v_mfma_f32_16x16x32_f16 v[84:87], v[4:7], v[214:217], v[84:87]
	v_mfma_f32_16x16x32_f16 v[80:83], v[140:143], v[214:217], v[80:83]
	v_mfma_f32_16x16x32_f16 v[124:127], v[144:147], v[176:179], v[124:127]
	v_mfma_f32_16x16x32_f16 v[120:123], v[152:155], v[176:179], v[120:123]
	v_mfma_f32_16x16x32_f16 v[108:111], v[144:147], v[184:187], v[108:111]
	v_mfma_f32_16x16x32_f16 v[104:107], v[152:155], v[184:187], v[104:107]
	v_mfma_f32_16x16x32_f16 v[92:95], v[144:147], v[202:205], v[92:95]
	v_mfma_f32_16x16x32_f16 v[88:91], v[152:155], v[202:205], v[88:91]
	v_mfma_f32_16x16x32_f16 v[76:79], v[144:147], v[210:213], v[76:79]
	v_mfma_f32_16x16x32_f16 v[72:75], v[152:155], v[210:213], v[72:75]
	v_mfma_f32_16x16x32_f16 v[124:127], v[148:151], v[180:183], v[124:127]
	v_mfma_f32_16x16x32_f16 v[120:123], v[156:159], v[180:183], v[120:123]
	v_mfma_f32_16x16x32_f16 v[108:111], v[148:151], v[198:201], v[108:111]
	v_mfma_f32_16x16x32_f16 v[104:107], v[156:159], v[198:201], v[104:107]
	v_mfma_f32_16x16x32_f16 v[92:95], v[148:151], v[206:209], v[92:95]
	v_mfma_f32_16x16x32_f16 v[88:91], v[156:159], v[206:209], v[88:91]
	v_mfma_f32_16x16x32_f16 v[76:79], v[148:151], v[214:217], v[76:79]
	v_mfma_f32_16x16x32_f16 v[72:75], v[156:159], v[214:217], v[72:75]
	s_barrier
	s_add_i32 s63, s56, s68
	v_lshl_add_u64 v[188:189], s[42:43], 0, v[162:163]
	s_mov_b32 m0, s63
	ds_read_b128 v[176:179], v195 offset:16384
	ds_read_b128 v[180:183], v195 offset:17408
	ds_read_b128 v[184:187], v195 offset:18432
	ds_read_b128 v[198:201], v195 offset:19456
	ds_read_b128 v[202:205], v195 offset:20480
	ds_read_b128 v[206:209], v195 offset:21504
	ds_read_b128 v[210:213], v195 offset:22528
	ds_read_b128 v[214:217], v195 offset:23552
	global_load_lds_dwordx4 v[188:189], off
	s_add_i32 m0, s63, 0x2000
	s_add_u32 s64, s42, 0x40000
	v_lshl_add_u64 v[218:219], s[42:43], 0, v[166:167]
	s_addc_u32 s65, s43, 0
	s_add_i32 s63, s57, s68
	global_load_lds_dwordx4 v[218:219], off
	v_lshl_add_u64 v[220:221], s[64:65], 0, v[162:163]
	s_mov_b32 m0, s63
	v_lshl_add_u64 v[222:223], s[44:45], 0, v[164:165]
	global_load_lds_dwordx4 v[220:221], off
	v_lshl_add_u64 v[220:221], s[64:65], 0, v[166:167]
	s_add_i32 m0, s63, 0x2000
	s_nop 0
	global_load_lds_dwordx4 v[220:221], off
	v_lshl_add_u64 v[220:221], s[44:45], 0, v[160:161]
	s_mov_b32 m0, s74
	s_nop 0
	global_load_lds_dwordx4 v[220:221], off
	s_mov_b32 m0, s66
	s_nop 0
	global_load_lds_dwordx4 v[222:223], off
	s_waitcnt vmcnt(8)
	s_waitcnt lgkmcnt(0)
	s_barrier
; #define PG8_STAGE(bufoff, gbase, voff) do { _Pragma("unroll") for (int _i = 0; _i < 2; ++_i) \
;         __builtin_amdgcn_global_load_lds((const unsigned*)((const char*)(gbase) + (voff)[_i]), (PG8_LAS unsigned*)(lds + (bufoff) + ldsw + _i * 8192), 16, 0, 0); } while (0)
; #define PG8_LDA(dst, b, h) do { _Pragma("unroll") for (int m = 0; m < 4; ++m) _Pragma("unroll") for (int k = 0; k < 2; ++k) dst[m][k] = *(const PG8_LAS bf16x8*)(lds + PG8_SA(b, h) + aoff + m * 2048 + k * 1024); } while (0)
; #define PG8_LDB(dst, b, h) do { _Pragma("unroll") for (int n = 0; n < 2; ++n) _Pragma("unroll") for (int k = 0; k < 2; ++k) dst[n][k] = *(const PG8_LAS bf16x8*)(lds + PG8_SB(b, h) + boff + n * 2048 + k * 1024); } while (0)
; #define PG8_MMA(ai, bj, At, Bt) do { __builtin_amdgcn_s_setprio(1); _Pragma("unroll") for (int m = 0; m < 4; ++m) _Pragma("unroll") for (int n = 0; n < 2; ++n) _Pragma("unroll") for (int k = 0; k < 2; ++k) \
;         acc[ai][bj][m][n] = mma16<F16>(Bt[n][k], At[m][k], acc[ai][bj][m][n]); __builtin_amdgcn_s_setprio(0); } while (0)
; #define PG8_WAIT_V(n) asm volatile("s_waitcnt vmcnt(" #n ")" ::: "memory")
; #define PG8_WAIT_L(n) asm volatile("s_waitcnt lgkmcnt(" #n ")" ::: "memory")
; #define PG8_BAR __builtin_amdgcn_s_barrier()
; #define PG8_SCHED __builtin_amdgcn_sched_barrier(0)
; template <class Epi, class Sched, bool ALIGN_EPI = false, bool SP2 = false, bool F16 = false>
; __device__ __forceinline__ void gemm_phase(PG8_LAS unsigned char* lds, const Gemm g, const Sched& S, const Epi& E, const int wid_in) {
;     ...
;             PG8_WAIT_V(8); PG8_WAIT_L(0); PG8_BAR; PG8_MMA(1, 0, At, B0); PG8_MMA(1, 1, At, B1); PG8_BAR; PG8_SCHED;
;             PG8_LDB(B0, 1, 0); PG8_LDB(B1, 1, 1); PG8_SCHED; PG8_LDA(At, 1, 0); PG8_STAGE(PG8_SA(0, 1), a2 + hstep, voffA);
;             PG8_WAIT_V(8); PG8_WAIT_L(0); PG8_BAR; PG8_MMA(0, 0, At, B0); PG8_MMA(0, 1, At, B1); PG8_BAR; PG8_SCHED;
	s_waitcnt lgkmcnt(0)
	v_mfma_f32_16x16x32_f16 v[68:71], v[0:3], v[176:179], v[68:71]
	v_mfma_f32_16x16x32_f16 v[64:67], v[136:139], v[176:179], v[64:67]
	v_mfma_f32_16x16x32_f16 v[52:55], v[0:3], v[184:187], v[52:55]
	v_mfma_f32_16x16x32_f16 v[48:51], v[136:139], v[184:187], v[48:51]
	v_mfma_f32_16x16x32_f16 v[36:39], v[0:3], v[202:205], v[36:39]
	v_mfma_f32_16x16x32_f16 v[32:35], v[136:139], v[202:205], v[32:35]
	v_mfma_f32_16x16x32_f16 v[0:3], v[0:3], v[210:213], v[20:23]
	v_mfma_f32_16x16x32_f16 v[68:71], v[4:7], v[180:183], v[68:71]
	v_mfma_f32_16x16x32_f16 v[64:67], v[140:143], v[180:183], v[64:67]
	v_mfma_f32_16x16x32_f16 v[52:55], v[4:7], v[198:201], v[52:55]
	v_mfma_f32_16x16x32_f16 v[48:51], v[140:143], v[198:201], v[48:51]
	v_mfma_f32_16x16x32_f16 v[36:39], v[4:7], v[206:209], v[36:39]
	v_mfma_f32_16x16x32_f16 v[32:35], v[140:143], v[206:209], v[32:35]
	v_mfma_f32_16x16x32_f16 v[0:3], v[4:7], v[214:217], v[0:3]
	v_mfma_f32_16x16x32_f16 v[4:7], v[136:139], v[210:213], v[16:19]
	v_mfma_f32_16x16x32_f16 v[4:7], v[140:143], v[214:217], v[4:7]
	v_mfma_f32_16x16x32_f16 v[16:19], v[144:147], v[176:179], v[60:63]
	v_mfma_f32_16x16x32_f16 v[60:63], v[148:151], v[180:183], v[16:19]
	v_mfma_f32_16x16x32_f16 v[16:19], v[152:155], v[176:179], v[56:59]
	v_mfma_f32_16x16x32_f16 v[56:59], v[156:159], v[180:183], v[16:19]
	v_mfma_f32_16x16x32_f16 v[16:19], v[144:147], v[184:187], v[44:47]
	v_mfma_f32_16x16x32_f16 v[44:47], v[148:151], v[198:201], v[16:19]
	v_mfma_f32_16x16x32_f16 v[16:19], v[152:155], v[184:187], v[40:43]
	v_mfma_f32_16x16x32_f16 v[40:43], v[156:159], v[198:201], v[16:19]
	v_mfma_f32_16x16x32_f16 v[16:19], v[144:147], v[202:205], v[28:31]
	v_mfma_f32_16x16x32_f16 v[28:31], v[148:151], v[206:209], v[16:19]
	v_mfma_f32_16x16x32_f16 v[16:19], v[152:155], v[202:205], v[24:27]
	v_mfma_f32_16x16x32_f16 v[12:15], v[144:147], v[210:213], v[12:15]
	v_mfma_f32_16x16x32_f16 v[8:11], v[152:155], v[210:213], v[8:11]
	v_mfma_f32_16x16x32_f16 v[24:27], v[156:159], v[206:209], v[16:19]
	v_mfma_f32_16x16x32_f16 v[12:15], v[148:151], v[214:217], v[12:15]
	v_mfma_f32_16x16x32_f16 v[8:11], v[156:159], v[214:217], v[8:11]
	s_barrier
	s_add_i32 s63, 0, 0x18000
	s_add_i32 s64, 0, 0x1c000
	v_add_u32_e32 v140, s63, v192
	v_add_u32_e32 v156, s64, v192
	ds_read_b128 v[16:19], v140
	ds_read_b128 v[20:23], v140 offset:1024
	ds_read_b128 v[136:139], v140 offset:2048
	ds_read_b128 v[140:143], v140 offset:3072
	ds_read_b128 v[144:147], v156
	ds_read_b128 v[148:151], v156 offset:1024
	ds_read_b128 v[152:155], v156 offset:2048
	ds_read_b128 v[156:159], v156 offset:3072
	s_add_u32 s44, s44, 0x40000
	s_addc_u32 s45, s45, 0
	s_mov_b32 m0, s90
	v_lshl_add_u64 v[224:225], s[44:45], 0, v[160:161]
	ds_read_b128 v[176:179], v195 offset:32768
	ds_read_b128 v[180:183], v195 offset:33792
	ds_read_b128 v[184:187], v195 offset:34816
	ds_read_b128 v[198:201], v195 offset:35840
	ds_read_b128 v[202:205], v195 offset:36864
	ds_read_b128 v[206:209], v195 offset:37888
	ds_read_b128 v[210:213], v195 offset:38912
	ds_read_b128 v[214:217], v195 offset:39936
	global_load_lds_dwordx4 v[224:225], off
	v_lshl_add_u64 v[224:225], s[44:45], 0, v[164:165]
	s_mov_b32 m0, s31
	s_nop 0
	global_load_lds_dwordx4 v[224:225], off
	s_waitcnt vmcnt(8)
	s_waitcnt lgkmcnt(0)
	s_barrier
	s_waitcnt lgkmcnt(0)
	v_mfma_f32_16x16x32_f16 v[132:135], v[16:19], v[176:179], v[132:135]
	v_mfma_f32_16x16x32_f16 v[128:131], v[136:139], v[176:179], v[128:131]
	v_mfma_f32_16x16x32_f16 v[116:119], v[16:19], v[184:187], v[116:119]
	v_mfma_f32_16x16x32_f16 v[112:115], v[136:139], v[184:187], v[112:115]
	v_mfma_f32_16x16x32_f16 v[100:103], v[16:19], v[202:205], v[100:103]
	v_mfma_f32_16x16x32_f16 v[96:99], v[136:139], v[202:205], v[96:99]
	v_mfma_f32_16x16x32_f16 v[84:87], v[16:19], v[210:213], v[84:87]
	v_mfma_f32_16x16x32_f16 v[80:83], v[136:139], v[210:213], v[80:83]
	v_mfma_f32_16x16x32_f16 v[132:135], v[20:23], v[180:183], v[132:135]
	v_mfma_f32_16x16x32_f16 v[128:131], v[140:143], v[180:183], v[128:131]
	v_mfma_f32_16x16x32_f16 v[116:119], v[20:23], v[198:201], v[116:119]
	v_mfma_f32_16x16x32_f16 v[112:115], v[140:143], v[198:201], v[112:115]
	v_mfma_f32_16x16x32_f16 v[100:103], v[20:23], v[206:209], v[100:103]
	v_mfma_f32_16x16x32_f16 v[96:99], v[140:143], v[206:209], v[96:99]
	v_mfma_f32_16x16x32_f16 v[84:87], v[20:23], v[214:217], v[84:87]
	v_mfma_f32_16x16x32_f16 v[80:83], v[140:143], v[214:217], v[80:83]
	v_mfma_f32_16x16x32_f16 v[124:127], v[144:147], v[176:179], v[124:127]
	v_mfma_f32_16x16x32_f16 v[120:123], v[152:155], v[176:179], v[120:123]
	v_mfma_f32_16x16x32_f16 v[108:111], v[144:147], v[184:187], v[108:111]
	v_mfma_f32_16x16x32_f16 v[104:107], v[152:155], v[184:187], v[104:107]
	v_mfma_f32_16x16x32_f16 v[92:95], v[144:147], v[202:205], v[92:95]
	v_mfma_f32_16x16x32_f16 v[88:91], v[152:155], v[202:205], v[88:91]
	v_mfma_f32_16x16x32_f16 v[76:79], v[144:147], v[210:213], v[76:79]
	v_mfma_f32_16x16x32_f16 v[72:75], v[152:155], v[210:213], v[72:75]
	v_mfma_f32_16x16x32_f16 v[124:127], v[148:151], v[180:183], v[124:127]
	v_mfma_f32_16x16x32_f16 v[120:123], v[156:159], v[180:183], v[120:123]
	v_mfma_f32_16x16x32_f16 v[108:111], v[148:151], v[198:201], v[108:111]
	v_mfma_f32_16x16x32_f16 v[104:107], v[156:159], v[198:201], v[104:107]
	v_mfma_f32_16x16x32_f16 v[92:95], v[148:151], v[206:209], v[92:95]
	v_mfma_f32_16x16x32_f16 v[88:91], v[156:159], v[206:209], v[88:91]
	v_mfma_f32_16x16x32_f16 v[76:79], v[148:151], v[214:217], v[76:79]
	v_mfma_f32_16x16x32_f16 v[72:75], v[156:159], v[214:217], v[72:75]
	s_barrier
; #define PG8_STAGE(bufoff, gbase, voff) do { _Pragma("unroll") for (int _i = 0; _i < 2; ++_i) \
;         __builtin_amdgcn_global_load_lds((const unsigned*)((const char*)(gbase) + (voff)[_i]), (PG8_LAS unsigned*)(lds + (bufoff) + ldsw + _i * 8192), 16, 0, 0); } while (0)
; #define PG8_LDA(dst, b, h) do { _Pragma("unroll") for (int m = 0; m < 4; ++m) _Pragma("unroll") for (int k = 0; k < 2; ++k) dst[m][k] = *(const PG8_LAS bf16x8*)(lds + PG8_SA(b, h) + aoff + m * 2048 + k * 1024); } while (0)
; #define PG8_MMA(ai, bj, At, Bt) do { __builtin_amdgcn_s_setprio(1); _Pragma("unroll") for (int m = 0; m < 4; ++m) _Pragma("unroll") for (int n = 0; n < 2; ++n) _Pragma("unroll") for (int k = 0; k < 2; ++k) \
;         acc[ai][bj][m][n] = mma16<F16>(Bt[n][k], At[m][k], acc[ai][bj][m][n]); __builtin_amdgcn_s_setprio(0); } while (0)
; #define PG8_WAIT_V(n) asm volatile("s_waitcnt vmcnt(" #n ")" ::: "memory")
; #define PG8_WAIT_L(n) asm volatile("s_waitcnt lgkmcnt(" #n ")" ::: "memory")
; #define PG8_BAR __builtin_amdgcn_s_barrier()
; #define PG8_SCHED __builtin_amdgcn_sched_barrier(0)
; template <class Epi, class Sched, bool ALIGN_EPI = false, bool SP2 = false, bool F16 = false>
; __device__ __forceinline__ void gemm_phase(PG8_LAS unsigned char* lds, const Gemm g, const Sched& S, const Epi& E, const int wid_in) {
;     ...
;             PG8_LDA(At, 1, 1); PG8_STAGE(PG8_SB(1, 0), b3, voffB); PG8_STAGE(PG8_SB(1, 1), b3 + hstep, voffB); PG8_STAGE(PG8_SA(1, 0), a3, voffA);
;             PG8_WAIT_V(8); PG8_WAIT_L(0); PG8_BAR; PG8_MMA(1, 0, At, B0); PG8_MMA(1, 1, At, B1); PG8_BAR; PG8_SCHED;
;     ...
;         if constexpr (ALIGN_EPI) { if (wr == 0) PG8_BAR; }
	s_add_i32 s44, s63, s68
	v_lshl_add_u64 v[188:189], v[188:189], 0, s[20:21]
	s_mov_b32 m0, s44
	ds_read_b128 v[176:179], v195 offset:49152
	ds_read_b128 v[180:183], v195 offset:50176
	ds_read_b128 v[184:187], v195 offset:51200
	ds_read_b128 v[198:201], v195 offset:52224
	ds_read_b128 v[202:205], v195 offset:53248
	ds_read_b128 v[206:209], v195 offset:54272
	ds_read_b128 v[210:213], v195 offset:55296
	ds_read_b128 v[214:217], v195 offset:56320
	global_load_lds_dwordx4 v[188:189], off
	s_add_i32 m0, s44, 0x2000
	s_add_u32 s42, s42, 0x40080
	v_lshl_add_u64 v[188:189], v[218:219], 0, s[20:21]
	s_addc_u32 s43, s43, 0
	s_add_i32 s44, s64, s68
	global_load_lds_dwordx4 v[188:189], off
	v_lshl_add_u64 v[188:189], s[42:43], 0, v[162:163]
	s_mov_b32 m0, s44
	s_nop 0
	global_load_lds_dwordx4 v[188:189], off
	v_lshl_add_u64 v[188:189], s[42:43], 0, v[166:167]
	s_add_i32 m0, s44, 0x2000
	s_nop 0
	global_load_lds_dwordx4 v[188:189], off
	v_lshl_add_u64 v[188:189], v[220:221], 0, s[20:21]
	s_mov_b32 m0, s75
	s_nop 0
	global_load_lds_dwordx4 v[188:189], off
	v_lshl_add_u64 v[188:189], v[222:223], 0, s[20:21]
	s_mov_b32 m0, s67
	s_nop 0
	global_load_lds_dwordx4 v[188:189], off
	s_waitcnt vmcnt(8)
	s_waitcnt lgkmcnt(0)
	s_barrier
	s_waitcnt lgkmcnt(0)
	v_mfma_f32_16x16x32_f16 v[68:71], v[16:19], v[176:179], v[68:71]
	v_mfma_f32_16x16x32_f16 v[52:55], v[16:19], v[184:187], v[52:55]
	v_mfma_f32_16x16x32_f16 v[36:39], v[16:19], v[202:205], v[36:39]
	v_mfma_f32_16x16x32_f16 v[0:3], v[16:19], v[210:213], v[0:3]
	v_mfma_f32_16x16x32_f16 v[68:71], v[20:23], v[180:183], v[68:71]
	v_mfma_f32_16x16x32_f16 v[64:67], v[136:139], v[176:179], v[64:67]
	v_mfma_f32_16x16x32_f16 v[52:55], v[20:23], v[198:201], v[52:55]
	v_mfma_f32_16x16x32_f16 v[48:51], v[136:139], v[184:187], v[48:51]
	v_mfma_f32_16x16x32_f16 v[36:39], v[20:23], v[206:209], v[36:39]
	v_mfma_f32_16x16x32_f16 v[32:35], v[136:139], v[202:205], v[32:35]
	v_mfma_f32_16x16x32_f16 v[20:23], v[20:23], v[214:217], v[0:3]
	v_mfma_f32_16x16x32_f16 v[0:3], v[136:139], v[210:213], v[4:7]
	v_mfma_f32_16x16x32_f16 v[64:67], v[140:143], v[180:183], v[64:67]
	v_mfma_f32_16x16x32_f16 v[48:51], v[140:143], v[198:201], v[48:51]
	v_mfma_f32_16x16x32_f16 v[32:35], v[140:143], v[206:209], v[32:35]
	v_mfma_f32_16x16x32_f16 v[16:19], v[140:143], v[214:217], v[0:3]
	v_mfma_f32_16x16x32_f16 v[0:3], v[144:147], v[176:179], v[60:63]
	v_mfma_f32_16x16x32_f16 v[60:63], v[148:151], v[180:183], v[0:3]
	v_mfma_f32_16x16x32_f16 v[0:3], v[152:155], v[176:179], v[56:59]
	v_mfma_f32_16x16x32_f16 v[56:59], v[156:159], v[180:183], v[0:3]
	v_mfma_f32_16x16x32_f16 v[0:3], v[144:147], v[184:187], v[44:47]
	v_mfma_f32_16x16x32_f16 v[44:47], v[148:151], v[198:201], v[0:3]
	v_mfma_f32_16x16x32_f16 v[0:3], v[152:155], v[184:187], v[40:43]
	v_mfma_f32_16x16x32_f16 v[40:43], v[156:159], v[198:201], v[0:3]
	v_mfma_f32_16x16x32_f16 v[0:3], v[144:147], v[202:205], v[28:31]
	v_mfma_f32_16x16x32_f16 v[28:31], v[148:151], v[206:209], v[0:3]
	v_mfma_f32_16x16x32_f16 v[0:3], v[152:155], v[202:205], v[24:27]
	v_mfma_f32_16x16x32_f16 v[24:27], v[156:159], v[206:209], v[0:3]
	v_mfma_f32_16x16x32_f16 v[0:3], v[144:147], v[210:213], v[12:15]
	v_mfma_f32_16x16x32_f16 v[12:15], v[148:151], v[214:217], v[0:3]
	v_mfma_f32_16x16x32_f16 v[0:3], v[152:155], v[210:213], v[8:11]
	v_mfma_f32_16x16x32_f16 v[8:11], v[156:159], v[214:217], v[0:3]
	s_barrier
	s_add_i32 s62, s62, 2
	s_add_u32 s36, s36, 0x100
	s_addc_u32 s37, s37, 0
	s_add_u32 s60, s60, 0x100
	s_addc_u32 s61, s61, 0
	s_cmp_gt_u32 s62, 13
	s_cbranch_scc0 .LBB0_2566
	s_and_b64 vcc, exec, s[16:17]
	s_cbranch_vccz .LBB0_2569
	s_barrier

; #define PG8_STAGE(bufoff, gbase, voff) do { _Pragma("unroll") for (int _i = 0; _i < 2; ++_i) \
;         __builtin_amdgcn_global_load_lds((const unsigned*)((const char*)(gbase) + (voff)[_i]), (PG8_LAS unsigned*)(lds + (bufoff) + ldsw + _i * 8192), 16, 0, 0); } while (0)
; #define PG8_LDA(dst, b, h) do { _Pragma("unroll") for (int m = 0; m < 4; ++m) _Pragma("unroll") for (int k = 0; k < 2; ++k) dst[m][k] = *(const PG8_LAS bf16x8*)(lds + PG8_SA(b, h) + aoff + m * 2048 + k * 1024); } while (0)
; #define PG8_LDB(dst, b, h) do { _Pragma("unroll") for (int n = 0; n < 2; ++n) _Pragma("unroll") for (int k = 0; k < 2; ++k) dst[n][k] = *(const PG8_LAS bf16x8*)(lds + PG8_SB(b, h) + boff + n * 2048 + k * 1024); } while (0)
; #define PG8_MMA(ai, bj, At, Bt) do { __builtin_amdgcn_s_setprio(1); _Pragma("unroll") for (int m = 0; m < 4; ++m) _Pragma("unroll") for (int n = 0; n < 2; ++n) _Pragma("unroll") for (int k = 0; k < 2; ++k) \
;         acc[ai][bj][m][n] = mma16<F16>(Bt[n][k], At[m][k], acc[ai][bj][m][n]); __builtin_amdgcn_s_setprio(0); } while (0)
; #define PG8_WAIT_V(n) asm volatile("s_waitcnt vmcnt(" #n ")" ::: "memory")
; #define PG8_BAR __builtin_amdgcn_s_barrier()
; template <class Epi, class Sched, bool ALIGN_EPI = false, bool SP2 = false, bool F16 = false>
; __device__ __forceinline__ void gemm_phase(PG8_LAS unsigned char* lds, const Gemm g, const Sched& S, const Epi& E, const int wid_in) {
;     ...
;         for (int t = 0; t < nt; t += 2) {
;             const bool last = (t == nt - 2);
;             const char* a1 = cA + (size_t)(t + 1) * kstep;
;             const char* a2 = last ? nA : cA + (size_t)(t + 2) * kstep; const char* b2 = last ? nB : cB + (size_t)(t + 2) * kstep;
;             const char* a3 = a2 + kstep; const char* b3 = b2 + kstep;
;             if (last && has_next) S.a_ready(nxt);
;             if constexpr (SP2) {
;             PG8_LDB(B0, 0, 0); PG8_LDB(B1, 0, 1); PG8_SCHED; PG8_LDA(At, 0, 0); PG8_STAGE(PG8_SA(1, 1), a1 + hstep, voffA);
;             PG8_WAIT_V(8); PG8_WAIT_L(0); PG8_BAR; PG8_MMA(0, 0, At, B0); PG8_MMA(0, 1, At, B1); PG8_BAR; PG8_SCHED;
;             PG8_LDA(At, 0, 1); PG8_STAGE(PG8_SB(0, 0), b2, voffB); PG8_STAGE(PG8_SB(0, 1), b2 + hstep, voffB); PG8_STAGE(PG8_SA(0, 0), a2, voffA);
;             PG8_WAIT_V(8); PG8_WAIT_L(0); PG8_BAR; PG8_MMA(1, 0, At, B0); PG8_MMA(1, 1, At, B1); PG8_BAR; PG8_SCHED;
.LBB0_2697:
	ds_read_b128 v[128:131], v189
	ds_read_b128 v[132:135], v189 offset:1024
	ds_read_b128 v[136:139], v189 offset:2048
	ds_read_b128 v[140:143], v189 offset:3072
	ds_read_b128 v[144:147], v190
	ds_read_b128 v[148:151], v190 offset:1024
	ds_read_b128 v[168:171], v190 offset:2048
	ds_read_b128 v[172:175], v190 offset:3072
	s_add_u32 s30, s28, 0x100
	s_addc_u32 s31, s29, 0
	s_cmp_eq_u32 s55, 40
	s_cselect_b32 s37, s11, s31
	s_cselect_b32 s36, s10, s30
	s_cselect_b32 s35, s27, s54
	s_cselect_b32 s34, s26, s53
	s_mov_b32 m0, s91
	v_lshl_add_u64 v[184:185], s[28:29], 0, v[160:161]
	ds_read_b128 v[176:179], v191
	ds_read_b128 v[180:183], v191 offset:1024
	ds_read_b128 v[192:195], v191 offset:2048
	ds_read_b128 v[196:199], v191 offset:3072
	ds_read_b128 v[200:203], v191 offset:4096
	ds_read_b128 v[204:207], v191 offset:5120
	ds_read_b128 v[208:211], v191 offset:6144
	ds_read_b128 v[212:215], v191 offset:7168
	global_load_lds_dwordx4 v[184:185], off
	v_lshl_add_u64 v[184:185], s[28:29], 0, v[162:163]
	s_add_i32 m0, s74, 0xe000
	s_nop 0
	global_load_lds_dwordx4 v[184:185], off
	s_waitcnt vmcnt(8)
	s_waitcnt lgkmcnt(0)
	s_barrier
	s_waitcnt lgkmcnt(0)
	v_mfma_f32_16x16x32_bf16 v[124:127], v[128:131], v[176:179], v[124:127]
	v_mfma_f32_16x16x32_bf16 v[120:123], v[136:139], v[176:179], v[120:123]
	v_mfma_f32_16x16x32_bf16 v[108:111], v[128:131], v[192:195], v[108:111]
	v_mfma_f32_16x16x32_bf16 v[104:107], v[136:139], v[192:195], v[104:107]
	v_mfma_f32_16x16x32_bf16 v[92:95], v[128:131], v[200:203], v[92:95]
	v_mfma_f32_16x16x32_bf16 v[88:91], v[136:139], v[200:203], v[88:91]
	v_mfma_f32_16x16x32_bf16 v[76:79], v[128:131], v[208:211], v[76:79]
	v_mfma_f32_16x16x32_bf16 v[72:75], v[136:139], v[208:211], v[72:75]
	v_mfma_f32_16x16x32_bf16 v[124:127], v[132:135], v[180:183], v[124:127]
	v_mfma_f32_16x16x32_bf16 v[120:123], v[140:143], v[180:183], v[120:123]
	v_mfma_f32_16x16x32_bf16 v[108:111], v[132:135], v[196:199], v[108:111]
	v_mfma_f32_16x16x32_bf16 v[104:107], v[140:143], v[196:199], v[104:107]
	v_mfma_f32_16x16x32_bf16 v[92:95], v[132:135], v[204:207], v[92:95]
	v_mfma_f32_16x16x32_bf16 v[88:91], v[140:143], v[204:207], v[88:91]
	v_mfma_f32_16x16x32_bf16 v[76:79], v[132:135], v[212:215], v[76:79]
	v_mfma_f32_16x16x32_bf16 v[72:75], v[140:143], v[212:215], v[72:75]
	v_mfma_f32_16x16x32_bf16 v[116:119], v[144:147], v[176:179], v[116:119]
	v_mfma_f32_16x16x32_bf16 v[112:115], v[168:171], v[176:179], v[112:115]
	v_mfma_f32_16x16x32_bf16 v[100:103], v[144:147], v[192:195], v[100:103]
	v_mfma_f32_16x16x32_bf16 v[96:99], v[168:171], v[192:195], v[96:99]
	v_mfma_f32_16x16x32_bf16 v[84:87], v[144:147], v[200:203], v[84:87]
	v_mfma_f32_16x16x32_bf16 v[80:83], v[168:171], v[200:203], v[80:83]
	v_mfma_f32_16x16x32_bf16 v[68:71], v[144:147], v[208:211], v[68:71]
	v_mfma_f32_16x16x32_bf16 v[64:67], v[168:171], v[208:211], v[64:67]
	v_mfma_f32_16x16x32_bf16 v[116:119], v[148:151], v[180:183], v[116:119]
	v_mfma_f32_16x16x32_bf16 v[112:115], v[172:175], v[180:183], v[112:115]
	v_mfma_f32_16x16x32_bf16 v[100:103], v[148:151], v[196:199], v[100:103]
	v_mfma_f32_16x16x32_bf16 v[96:99], v[172:175], v[196:199], v[96:99]
	v_mfma_f32_16x16x32_bf16 v[84:87], v[148:151], v[204:207], v[84:87]
	v_mfma_f32_16x16x32_bf16 v[80:83], v[172:175], v[204:207], v[80:83]
	v_mfma_f32_16x16x32_bf16 v[68:71], v[148:151], v[212:215], v[68:71]
	v_mfma_f32_16x16x32_bf16 v[64:67], v[172:175], v[212:215], v[64:67]
	s_barrier
	s_add_i32 s28, s47, s68
	v_lshl_add_u64 v[184:185], s[34:35], 0, v[154:155]
	s_mov_b32 m0, s28
	ds_read_b128 v[176:179], v191 offset:16384
	ds_read_b128 v[180:183], v191 offset:17408
	ds_read_b128 v[192:195], v191 offset:18432
	ds_read_b128 v[196:199], v191 offset:19456
	ds_read_b128 v[200:203], v191 offset:20480
	ds_read_b128 v[204:207], v191 offset:21504
	ds_read_b128 v[208:211], v191 offset:22528
	ds_read_b128 v[212:215], v191 offset:23552
	global_load_lds_dwordx4 v[184:185], off
	s_add_i32 m0, s28, 0x2000
	s_add_u32 s28, s34, 0xb0000
	v_lshl_add_u64 v[216:217], s[34:35], 0, v[158:159]
	s_addc_u32 s29, s35, 0
	s_add_i32 s56, s48, s68
	global_load_lds_dwordx4 v[216:217], off
	v_lshl_add_u64 v[218:219], s[28:29], 0, v[154:155]
	s_mov_b32 m0, s56
	v_lshl_add_u64 v[220:221], s[36:37], 0, v[156:157]
	global_load_lds_dwordx4 v[218:219], off
	v_lshl_add_u64 v[218:219], s[28:29], 0, v[158:159]
	s_add_i32 m0, s56, 0x2000
	s_nop 0
	global_load_lds_dwordx4 v[218:219], off
	v_lshl_add_u64 v[218:219], s[36:37], 0, v[152:153]
	s_mov_b32 m0, s74
	s_nop 0
	global_load_lds_dwordx4 v[218:219], off
	s_mov_b32 m0, s66
	s_nop 0
	global_load_lds_dwordx4 v[220:221], off
	s_waitcnt vmcnt(8)
	s_waitcnt lgkmcnt(0)
	s_barrier
; #define PG8_STAGE(bufoff, gbase, voff) do { _Pragma("unroll") for (int _i = 0; _i < 2; ++_i) \
;         __builtin_amdgcn_global_load_lds((const unsigned*)((const char*)(gbase) + (voff)[_i]), (PG8_LAS unsigned*)(lds + (bufoff) + ldsw + _i * 8192), 16, 0, 0); } while (0)
; #define PG8_LDA(dst, b, h) do { _Pragma("unroll") for (int m = 0; m < 4; ++m) _Pragma("unroll") for (int k = 0; k < 2; ++k) dst[m][k] = *(const PG8_LAS bf16x8*)(lds + PG8_SA(b, h) + aoff + m * 2048 + k * 1024); } while (0)
; #define PG8_LDB(dst, b, h) do { _Pragma("unroll") for (int n = 0; n < 2; ++n) _Pragma("unroll") for (int k = 0; k < 2; ++k) dst[n][k] = *(const PG8_LAS bf16x8*)(lds + PG8_SB(b, h) + boff + n * 2048 + k * 1024); } while (0)
; #define PG8_MMA(ai, bj, At, Bt) do { __builtin_amdgcn_s_setprio(1); _Pragma("unroll") for (int m = 0; m < 4; ++m) _Pragma("unroll") for (int n = 0; n < 2; ++n) _Pragma("unroll") for (int k = 0; k < 2; ++k) \
;         acc[ai][bj][m][n] = mma16<F16>(Bt[n][k], At[m][k], acc[ai][bj][m][n]); __builtin_amdgcn_s_setprio(0); } while (0)
; #define PG8_WAIT_V(n) asm volatile("s_waitcnt vmcnt(" #n ")" ::: "memory")
; #define PG8_WAIT_L(n) asm volatile("s_waitcnt lgkmcnt(" #n ")" ::: "memory")
; #define PG8_BAR __builtin_amdgcn_s_barrier()
; #define PG8_SCHED __builtin_amdgcn_sched_barrier(0)
; template <class Epi, class Sched, bool ALIGN_EPI = false, bool SP2 = false, bool F16 = false>
; __device__ __forceinline__ void gemm_phase(PG8_LAS unsigned char* lds, const Gemm g, const Sched& S, const Epi& E, const int wid_in) {
;     ...
;             PG8_WAIT_V(8); PG8_WAIT_L(0); PG8_BAR; PG8_MMA(1, 0, At, B0); PG8_MMA(1, 1, At, B1); PG8_BAR; PG8_SCHED;
;             PG8_LDB(B0, 1, 0); PG8_LDB(B1, 1, 1); PG8_SCHED; PG8_LDA(At, 1, 0); PG8_STAGE(PG8_SA(0, 1), a2 + hstep, voffA);
;             PG8_WAIT_V(8); PG8_WAIT_L(0); PG8_BAR; PG8_MMA(0, 0, At, B0); PG8_MMA(0, 1, At, B1); PG8_BAR; PG8_SCHED;
	s_waitcnt lgkmcnt(0)
	v_mfma_f32_16x16x32_bf16 v[60:63], v[128:131], v[176:179], v[60:63]
	v_mfma_f32_16x16x32_bf16 v[56:59], v[136:139], v[176:179], v[56:59]
	v_mfma_f32_16x16x32_bf16 v[44:47], v[128:131], v[192:195], v[44:47]
	v_mfma_f32_16x16x32_bf16 v[40:43], v[136:139], v[192:195], v[40:43]
	v_mfma_f32_16x16x32_bf16 v[28:31], v[128:131], v[200:203], v[28:31]
	v_mfma_f32_16x16x32_bf16 v[24:27], v[136:139], v[200:203], v[24:27]
	v_mfma_f32_16x16x32_bf16 v[12:15], v[128:131], v[208:211], v[12:15]
	v_mfma_f32_16x16x32_bf16 v[8:11], v[136:139], v[208:211], v[8:11]
	v_mfma_f32_16x16x32_bf16 v[60:63], v[132:135], v[180:183], v[60:63]
	v_mfma_f32_16x16x32_bf16 v[56:59], v[140:143], v[180:183], v[56:59]
	v_mfma_f32_16x16x32_bf16 v[44:47], v[132:135], v[196:199], v[44:47]
	v_mfma_f32_16x16x32_bf16 v[40:43], v[140:143], v[196:199], v[40:43]
	v_mfma_f32_16x16x32_bf16 v[28:31], v[132:135], v[204:207], v[28:31]
	v_mfma_f32_16x16x32_bf16 v[24:27], v[140:143], v[204:207], v[24:27]
	v_mfma_f32_16x16x32_bf16 v[12:15], v[132:135], v[212:215], v[12:15]
	v_mfma_f32_16x16x32_bf16 v[8:11], v[140:143], v[212:215], v[8:11]
	v_mfma_f32_16x16x32_bf16 v[52:55], v[144:147], v[176:179], v[52:55]
	v_mfma_f32_16x16x32_bf16 v[48:51], v[168:171], v[176:179], v[48:51]
	v_mfma_f32_16x16x32_bf16 v[36:39], v[144:147], v[192:195], v[36:39]
	v_mfma_f32_16x16x32_bf16 v[32:35], v[168:171], v[192:195], v[32:35]
	v_mfma_f32_16x16x32_bf16 v[20:23], v[144:147], v[200:203], v[20:23]
	v_mfma_f32_16x16x32_bf16 v[16:19], v[168:171], v[200:203], v[16:19]
	v_mfma_f32_16x16x32_bf16 v[4:7], v[144:147], v[208:211], v[4:7]
	v_mfma_f32_16x16x32_bf16 v[0:3], v[168:171], v[208:211], v[0:3]
	v_mfma_f32_16x16x32_bf16 v[52:55], v[148:151], v[180:183], v[52:55]
	v_mfma_f32_16x16x32_bf16 v[48:51], v[172:175], v[180:183], v[48:51]
	v_mfma_f32_16x16x32_bf16 v[36:39], v[148:151], v[196:199], v[36:39]
	v_mfma_f32_16x16x32_bf16 v[32:35], v[172:175], v[196:199], v[32:35]
	v_mfma_f32_16x16x32_bf16 v[20:23], v[148:151], v[204:207], v[20:23]
	v_mfma_f32_16x16x32_bf16 v[16:19], v[172:175], v[204:207], v[16:19]
	v_mfma_f32_16x16x32_bf16 v[4:7], v[148:151], v[212:215], v[4:7]
	v_mfma_f32_16x16x32_bf16 v[0:3], v[172:175], v[212:215], v[0:3]
	s_barrier
	s_add_i32 s56, 0, 0x18000
	s_add_i32 s57, 0, 0x1c000
	v_add_u32_e32 v140, s56, v188
	v_add_u32_e32 v172, s57, v188
	ds_read_b128 v[128:131], v140
	ds_read_b128 v[132:135], v140 offset:1024
	ds_read_b128 v[136:139], v140 offset:2048
	ds_read_b128 v[140:143], v140 offset:3072
	ds_read_b128 v[144:147], v172
	ds_read_b128 v[148:151], v172 offset:1024
	ds_read_b128 v[168:171], v172 offset:2048
	ds_read_b128 v[172:175], v172 offset:3072
	s_add_u32 s28, s36, 0xb0000
	s_addc_u32 s29, s37, 0
	s_mov_b32 m0, s90
	v_lshl_add_u64 v[222:223], s[28:29], 0, v[152:153]
	ds_read_b128 v[176:179], v191 offset:32768
	ds_read_b128 v[180:183], v191 offset:33792
	ds_read_b128 v[192:195], v191 offset:34816
	ds_read_b128 v[196:199], v191 offset:35840
	ds_read_b128 v[200:203], v191 offset:36864
	ds_read_b128 v[204:207], v191 offset:37888
	ds_read_b128 v[208:211], v191 offset:38912
	ds_read_b128 v[212:215], v191 offset:39936
	global_load_lds_dwordx4 v[222:223], off
	v_lshl_add_u64 v[222:223], s[28:29], 0, v[156:157]
	s_mov_b32 m0, s43
	s_nop 0
	global_load_lds_dwordx4 v[222:223], off
	s_waitcnt vmcnt(8)
	s_waitcnt lgkmcnt(0)
	s_barrier
	s_waitcnt lgkmcnt(0)
	v_mfma_f32_16x16x32_bf16 v[124:127], v[128:131], v[176:179], v[124:127]
	v_mfma_f32_16x16x32_bf16 v[120:123], v[136:139], v[176:179], v[120:123]
	v_mfma_f32_16x16x32_bf16 v[108:111], v[128:131], v[192:195], v[108:111]
	v_mfma_f32_16x16x32_bf16 v[104:107], v[136:139], v[192:195], v[104:107]
	v_mfma_f32_16x16x32_bf16 v[92:95], v[128:131], v[200:203], v[92:95]
	v_mfma_f32_16x16x32_bf16 v[88:91], v[136:139], v[200:203], v[88:91]
	v_mfma_f32_16x16x32_bf16 v[76:79], v[128:131], v[208:211], v[76:79]
	v_mfma_f32_16x16x32_bf16 v[72:75], v[136:139], v[208:211], v[72:75]
	v_mfma_f32_16x16x32_bf16 v[124:127], v[132:135], v[180:183], v[124:127]
	v_mfma_f32_16x16x32_bf16 v[120:123], v[140:143], v[180:183], v[120:123]
	v_mfma_f32_16x16x32_bf16 v[108:111], v[132:135], v[196:199], v[108:111]
	v_mfma_f32_16x16x32_bf16 v[104:107], v[140:143], v[196:199], v[104:107]
	v_mfma_f32_16x16x32_bf16 v[92:95], v[132:135], v[204:207], v[92:95]
	v_mfma_f32_16x16x32_bf16 v[88:91], v[140:143], v[204:207], v[88:91]
	v_mfma_f32_16x16x32_bf16 v[76:79], v[132:135], v[212:215], v[76:79]
	v_mfma_f32_16x16x32_bf16 v[72:75], v[140:143], v[212:215], v[72:75]
	v_mfma_f32_16x16x32_bf16 v[116:119], v[144:147], v[176:179], v[116:119]
	v_mfma_f32_16x16x32_bf16 v[112:115], v[168:171], v[176:179], v[112:115]
	v_mfma_f32_16x16x32_bf16 v[100:103], v[144:147], v[192:195], v[100:103]
	v_mfma_f32_16x16x32_bf16 v[96:99], v[168:171], v[192:195], v[96:99]
	v_mfma_f32_16x16x32_bf16 v[84:87], v[144:147], v[200:203], v[84:87]
	v_mfma_f32_16x16x32_bf16 v[80:83], v[168:171], v[200:203], v[80:83]
	v_mfma_f32_16x16x32_bf16 v[68:71], v[144:147], v[208:211], v[68:71]
	v_mfma_f32_16x16x32_bf16 v[64:67], v[168:171], v[208:211], v[64:67]
	v_mfma_f32_16x16x32_bf16 v[116:119], v[148:151], v[180:183], v[116:119]
	v_mfma_f32_16x16x32_bf16 v[112:115], v[172:175], v[180:183], v[112:115]
	v_mfma_f32_16x16x32_bf16 v[100:103], v[148:151], v[196:199], v[100:103]
	v_mfma_f32_16x16x32_bf16 v[96:99], v[172:175], v[196:199], v[96:99]
	v_mfma_f32_16x16x32_bf16 v[84:87], v[148:151], v[204:207], v[84:87]
	v_mfma_f32_16x16x32_bf16 v[80:83], v[172:175], v[204:207], v[80:83]
	v_mfma_f32_16x16x32_bf16 v[68:71], v[148:151], v[212:215], v[68:71]
	v_mfma_f32_16x16x32_bf16 v[64:67], v[172:175], v[212:215], v[64:67]
	s_barrier
; #define PG8_STAGE(bufoff, gbase, voff) do { _Pragma("unroll") for (int _i = 0; _i < 2; ++_i) \
;         __builtin_amdgcn_global_load_lds((const unsigned*)((const char*)(gbase) + (voff)[_i]), (PG8_LAS unsigned*)(lds + (bufoff) + ldsw + _i * 8192), 16, 0, 0); } while (0)
; #define PG8_LDA(dst, b, h) do { _Pragma("unroll") for (int m = 0; m < 4; ++m) _Pragma("unroll") for (int k = 0; k < 2; ++k) dst[m][k] = *(const PG8_LAS bf16x8*)(lds + PG8_SA(b, h) + aoff + m * 2048 + k * 1024); } while (0)
; #define PG8_MMA(ai, bj, At, Bt) do { __builtin_amdgcn_s_setprio(1); _Pragma("unroll") for (int m = 0; m < 4; ++m) _Pragma("unroll") for (int n = 0; n < 2; ++n) _Pragma("unroll") for (int k = 0; k < 2; ++k) \
;         acc[ai][bj][m][n] = mma16<F16>(Bt[n][k], At[m][k], acc[ai][bj][m][n]); __builtin_amdgcn_s_setprio(0); } while (0)
; #define PG8_WAIT_V(n) asm volatile("s_waitcnt vmcnt(" #n ")" ::: "memory")
; #define PG8_WAIT_L(n) asm volatile("s_waitcnt lgkmcnt(" #n ")" ::: "memory")
; #define PG8_BAR __builtin_amdgcn_s_barrier()
; #define PG8_SCHED __builtin_amdgcn_sched_barrier(0)
; template <class Epi, class Sched, bool ALIGN_EPI = false, bool SP2 = false, bool F16 = false>
; __device__ __forceinline__ void gemm_phase(PG8_LAS unsigned char* lds, const Gemm g, const Sched& S, const Epi& E, const int wid_in) {
;     ...
;             PG8_LDA(At, 1, 1); PG8_STAGE(PG8_SB(1, 0), b3, voffB); PG8_STAGE(PG8_SB(1, 1), b3 + hstep, voffB); PG8_STAGE(PG8_SA(1, 0), a3, voffA);
;             PG8_WAIT_V(8); PG8_WAIT_L(0); PG8_BAR; PG8_MMA(1, 0, At, B0); PG8_MMA(1, 1, At, B1); PG8_BAR; PG8_SCHED;
;     ...
;         if constexpr (ALIGN_EPI) { if (wr == 0) PG8_BAR; }
	s_add_i32 s28, s56, s68
	v_lshl_add_u64 v[184:185], v[184:185], 0, s[24:25]
	s_mov_b32 m0, s28
	ds_read_b128 v[176:179], v191 offset:49152
	ds_read_b128 v[180:183], v191 offset:50176
	ds_read_b128 v[192:195], v191 offset:51200
	ds_read_b128 v[196:199], v191 offset:52224
	ds_read_b128 v[200:203], v191 offset:53248
	ds_read_b128 v[204:207], v191 offset:54272
	ds_read_b128 v[208:211], v191 offset:55296
	ds_read_b128 v[212:215], v191 offset:56320
	global_load_lds_dwordx4 v[184:185], off
	s_add_i32 m0, s28, 0x2000
	s_add_u32 s28, s34, 0xb0080
	v_lshl_add_u64 v[184:185], v[216:217], 0, s[24:25]
	s_addc_u32 s29, s35, 0
	s_add_i32 s34, s57, s68
	global_load_lds_dwordx4 v[184:185], off
	v_lshl_add_u64 v[184:185], s[28:29], 0, v[154:155]
	s_mov_b32 m0, s34
	s_nop 0
	global_load_lds_dwordx4 v[184:185], off
	v_lshl_add_u64 v[184:185], s[28:29], 0, v[158:159]
	s_add_i32 m0, s34, 0x2000
	s_nop 0
	global_load_lds_dwordx4 v[184:185], off
	v_lshl_add_u64 v[184:185], v[218:219], 0, s[24:25]
	s_mov_b32 m0, s75
	s_nop 0
	global_load_lds_dwordx4 v[184:185], off
	v_lshl_add_u64 v[184:185], v[220:221], 0, s[24:25]
	s_mov_b32 m0, s67
	s_nop 0
	global_load_lds_dwordx4 v[184:185], off
	s_waitcnt vmcnt(8)
	s_waitcnt lgkmcnt(0)
	s_barrier
	s_waitcnt lgkmcnt(0)
	v_mfma_f32_16x16x32_bf16 v[60:63], v[128:131], v[176:179], v[60:63]
	v_mfma_f32_16x16x32_bf16 v[56:59], v[136:139], v[176:179], v[56:59]
	v_mfma_f32_16x16x32_bf16 v[44:47], v[128:131], v[192:195], v[44:47]
	v_mfma_f32_16x16x32_bf16 v[40:43], v[136:139], v[192:195], v[40:43]
	v_mfma_f32_16x16x32_bf16 v[28:31], v[128:131], v[200:203], v[28:31]
	v_mfma_f32_16x16x32_bf16 v[24:27], v[136:139], v[200:203], v[24:27]
	v_mfma_f32_16x16x32_bf16 v[12:15], v[128:131], v[208:211], v[12:15]
	v_mfma_f32_16x16x32_bf16 v[8:11], v[136:139], v[208:211], v[8:11]
	v_mfma_f32_16x16x32_bf16 v[60:63], v[132:135], v[180:183], v[60:63]
	v_mfma_f32_16x16x32_bf16 v[56:59], v[140:143], v[180:183], v[56:59]
	v_mfma_f32_16x16x32_bf16 v[44:47], v[132:135], v[196:199], v[44:47]
	v_mfma_f32_16x16x32_bf16 v[40:43], v[140:143], v[196:199], v[40:43]
	v_mfma_f32_16x16x32_bf16 v[28:31], v[132:135], v[204:207], v[28:31]
	v_mfma_f32_16x16x32_bf16 v[24:27], v[140:143], v[204:207], v[24:27]
	v_mfma_f32_16x16x32_bf16 v[12:15], v[132:135], v[212:215], v[12:15]
	v_mfma_f32_16x16x32_bf16 v[8:11], v[140:143], v[212:215], v[8:11]
	v_mfma_f32_16x16x32_bf16 v[52:55], v[144:147], v[176:179], v[52:55]
	v_mfma_f32_16x16x32_bf16 v[48:51], v[168:171], v[176:179], v[48:51]
	v_mfma_f32_16x16x32_bf16 v[36:39], v[144:147], v[192:195], v[36:39]
	v_mfma_f32_16x16x32_bf16 v[32:35], v[168:171], v[192:195], v[32:35]
	v_mfma_f32_16x16x32_bf16 v[20:23], v[144:147], v[200:203], v[20:23]
	v_mfma_f32_16x16x32_bf16 v[16:19], v[168:171], v[200:203], v[16:19]
	v_mfma_f32_16x16x32_bf16 v[4:7], v[144:147], v[208:211], v[4:7]
	v_mfma_f32_16x16x32_bf16 v[0:3], v[168:171], v[208:211], v[0:3]
	v_mfma_f32_16x16x32_bf16 v[52:55], v[148:151], v[180:183], v[52:55]
	v_mfma_f32_16x16x32_bf16 v[48:51], v[172:175], v[180:183], v[48:51]
	v_mfma_f32_16x16x32_bf16 v[36:39], v[148:151], v[196:199], v[36:39]
	v_mfma_f32_16x16x32_bf16 v[32:35], v[172:175], v[196:199], v[32:35]
	v_mfma_f32_16x16x32_bf16 v[20:23], v[148:151], v[204:207], v[20:23]
	v_mfma_f32_16x16x32_bf16 v[16:19], v[172:175], v[204:207], v[16:19]
	v_mfma_f32_16x16x32_bf16 v[4:7], v[148:151], v[212:215], v[4:7]
	v_mfma_f32_16x16x32_bf16 v[0:3], v[172:175], v[212:215], v[0:3]
	s_barrier
	s_add_i32 s55, s55, 2
	s_add_u32 s53, s53, 0x100
	s_addc_u32 s54, s54, 0
	s_cmp_gt_u32 s55, 41
	s_mov_b64 s[28:29], s[30:31]
	s_cbranch_scc0 .LBB0_2697
	s_and_b64 vcc, exec, s[16:17]
	s_cbranch_vccz .LBB0_2700
	s_barrier

; #define PG8_STAGE(bufoff, gbase, voff) do { _Pragma("unroll") for (int _i = 0; _i < 2; ++_i) \
;         __builtin_amdgcn_global_load_lds((const unsigned*)((const char*)(gbase) + (voff)[_i]), (PG8_LAS unsigned*)(lds + (bufoff) + ldsw + _i * 8192), 16, 0, 0); } while (0)
; #define PG8_LDA(dst, b, h) do { _Pragma("unroll") for (int m = 0; m < 4; ++m) _Pragma("unroll") for (int k = 0; k < 2; ++k) dst[m][k] = *(const PG8_LAS bf16x8*)(lds + PG8_SA(b, h) + aoff + m * 2048 + k * 1024); } while (0)
; #define PG8_LDB(dst, b, h) do { _Pragma("unroll") for (int n = 0; n < 2; ++n) _Pragma("unroll") for (int k = 0; k < 2; ++k) dst[n][k] = *(const PG8_LAS bf16x8*)(lds + PG8_SB(b, h) + boff + n * 2048 + k * 1024); } while (0)
; #define PG8_MMA(ai, bj, At, Bt) do { __builtin_amdgcn_s_setprio(1); _Pragma("unroll") for (int m = 0; m < 4; ++m) _Pragma("unroll") for (int n = 0; n < 2; ++n) _Pragma("unroll") for (int k = 0; k < 2; ++k) \
;         acc[ai][bj][m][n] = mma16<F16>(Bt[n][k], At[m][k], acc[ai][bj][m][n]); __builtin_amdgcn_s_setprio(0); } while (0)
; #define PG8_WAIT_V(n) asm volatile("s_waitcnt vmcnt(" #n ")" ::: "memory")
; #define PG8_WAIT_L(n) asm volatile("s_waitcnt lgkmcnt(" #n ")" ::: "memory")
; #define PG8_BAR __builtin_amdgcn_s_barrier()
; #define PG8_SCHED __builtin_amdgcn_sched_barrier(0)
; template <class Epi, class Sched, bool ALIGN_EPI = false, bool SP2 = false, bool F16 = false>
; __device__ __forceinline__ void gemm_phase(PG8_LAS unsigned char* lds, const Gemm g, const Sched& S, const Epi& E, const int wid_in) {
;     ...
;             PG8_LDB(B0, 0, 0); PG8_LDB(B1, 0, 1); PG8_SCHED; PG8_LDA(At, 0, 0); PG8_STAGE(PG8_SA(1, 1), a1 + hstep, voffA);
;             PG8_WAIT_V(8); PG8_WAIT_L(0); PG8_BAR; PG8_MMA(0, 0, At, B0); PG8_MMA(0, 1, At, B1); PG8_BAR; PG8_SCHED;
;             PG8_LDA(At, 0, 1); PG8_STAGE(PG8_SB(0, 0), b2, voffB); PG8_STAGE(PG8_SB(0, 1), b2 + hstep, voffB); PG8_STAGE(PG8_SA(0, 0), a2, voffA);
;             PG8_WAIT_V(8); PG8_WAIT_L(0); PG8_BAR; PG8_MMA(1, 0, At, B0); PG8_MMA(1, 1, At, B1); PG8_BAR; PG8_SCHED;
.LBB0_2793:
	ds_read_b128 v[112:115], v235
	ds_read_b128 v[116:119], v235 offset:1024
	ds_read_b128 v[128:131], v235 offset:2048
	ds_read_b128 v[132:135], v235 offset:3072
	ds_read_b128 v[144:147], v236
	ds_read_b128 v[148:151], v236 offset:1024
	ds_read_b128 v[152:155], v236 offset:2048
	ds_read_b128 v[156:159], v236 offset:3072
	s_add_u32 s44, s42, 0xfffc0080
	s_addc_u32 s45, s43, -1
	s_cmp_eq_u32 s59, 12
	s_cselect_b32 s47, s14, s45
	s_cselect_b32 s46, s15, s44
	s_cselect_b32 s45, s29, s58
	s_cselect_b32 s44, s31, s41
	s_mov_b32 m0, s91
	v_lshl_add_u64 v[192:193], s[42:43], 0, v[204:205]
	ds_read_b128 v[160:163], v237
	ds_read_b128 v[164:167], v237 offset:1024
	ds_read_b128 v[168:171], v237 offset:2048
	ds_read_b128 v[172:175], v237 offset:3072
	ds_read_b128 v[176:179], v237 offset:4096
	ds_read_b128 v[180:183], v237 offset:5120
	ds_read_b128 v[184:187], v237 offset:6144
	ds_read_b128 v[188:191], v237 offset:7168
	global_load_lds_dwordx4 v[192:193], off
	v_lshl_add_u64 v[192:193], s[42:43], 0, v[206:207]
	s_add_i32 m0, s74, 0xe000
	s_nop 0
	global_load_lds_dwordx4 v[192:193], off
	s_waitcnt vmcnt(8)
	s_waitcnt lgkmcnt(0)
	s_barrier
	s_waitcnt lgkmcnt(0)
	v_mfma_f32_16x16x32_f16 v[140:143], v[112:115], v[160:163], v[140:143]
	v_mfma_f32_16x16x32_f16 v[136:139], v[128:131], v[160:163], v[136:139]
	v_mfma_f32_16x16x32_f16 v[108:111], v[112:115], v[168:171], v[108:111]
	v_mfma_f32_16x16x32_f16 v[104:107], v[128:131], v[168:171], v[104:107]
	v_mfma_f32_16x16x32_f16 v[92:95], v[112:115], v[176:179], v[92:95]
	v_mfma_f32_16x16x32_f16 v[88:91], v[128:131], v[176:179], v[88:91]
	v_mfma_f32_16x16x32_f16 v[76:79], v[112:115], v[184:187], v[76:79]
	v_mfma_f32_16x16x32_f16 v[72:75], v[128:131], v[184:187], v[72:75]
	v_mfma_f32_16x16x32_f16 v[140:143], v[116:119], v[164:167], v[140:143]
	v_mfma_f32_16x16x32_f16 v[136:139], v[132:135], v[164:167], v[136:139]
	v_mfma_f32_16x16x32_f16 v[108:111], v[116:119], v[172:175], v[108:111]
	v_mfma_f32_16x16x32_f16 v[104:107], v[132:135], v[172:175], v[104:107]
	v_mfma_f32_16x16x32_f16 v[92:95], v[116:119], v[180:183], v[92:95]
	v_mfma_f32_16x16x32_f16 v[88:91], v[132:135], v[180:183], v[88:91]
	v_mfma_f32_16x16x32_f16 v[76:79], v[116:119], v[188:191], v[76:79]
	v_mfma_f32_16x16x32_f16 v[72:75], v[132:135], v[188:191], v[72:75]
	v_mfma_f32_16x16x32_f16 v[124:127], v[144:147], v[160:163], v[124:127]
	v_mfma_f32_16x16x32_f16 v[120:123], v[152:155], v[160:163], v[120:123]
	v_mfma_f32_16x16x32_f16 v[100:103], v[144:147], v[168:171], v[100:103]
	v_mfma_f32_16x16x32_f16 v[96:99], v[152:155], v[168:171], v[96:99]
	v_mfma_f32_16x16x32_f16 v[84:87], v[144:147], v[176:179], v[84:87]
	v_mfma_f32_16x16x32_f16 v[80:83], v[152:155], v[176:179], v[80:83]
	v_mfma_f32_16x16x32_f16 v[68:71], v[144:147], v[184:187], v[68:71]
	v_mfma_f32_16x16x32_f16 v[64:67], v[152:155], v[184:187], v[64:67]
	v_mfma_f32_16x16x32_f16 v[124:127], v[148:151], v[164:167], v[124:127]
	v_mfma_f32_16x16x32_f16 v[120:123], v[156:159], v[164:167], v[120:123]
	v_mfma_f32_16x16x32_f16 v[100:103], v[148:151], v[172:175], v[100:103]
	v_mfma_f32_16x16x32_f16 v[96:99], v[156:159], v[172:175], v[96:99]
	v_mfma_f32_16x16x32_f16 v[84:87], v[148:151], v[180:183], v[84:87]
	v_mfma_f32_16x16x32_f16 v[80:83], v[156:159], v[180:183], v[80:83]
	v_mfma_f32_16x16x32_f16 v[68:71], v[148:151], v[188:191], v[68:71]
	v_mfma_f32_16x16x32_f16 v[64:67], v[156:159], v[188:191], v[64:67]
	s_barrier
	s_add_i32 s60, s55, s68
	v_lshl_add_u64 v[192:193], s[44:45], 0, v[198:199]
	s_mov_b32 m0, s60
	ds_read_b128 v[160:163], v237 offset:16384
	ds_read_b128 v[164:167], v237 offset:17408
	ds_read_b128 v[168:171], v237 offset:18432
	ds_read_b128 v[172:175], v237 offset:19456
	ds_read_b128 v[176:179], v237 offset:20480
	ds_read_b128 v[180:183], v237 offset:21504
	ds_read_b128 v[184:187], v237 offset:22528
	ds_read_b128 v[188:191], v237 offset:23552
	global_load_lds_dwordx4 v[192:193], off
	s_add_i32 m0, s60, 0x2000
	s_add_u32 s60, s44, 0x40000
	v_lshl_add_u64 v[194:195], s[44:45], 0, v[202:203]
	s_addc_u32 s61, s45, 0
	s_add_i32 s62, s56, s68
	global_load_lds_dwordx4 v[194:195], off
	v_lshl_add_u64 v[212:213], s[60:61], 0, v[198:199]
	s_mov_b32 m0, s62
	v_lshl_add_u64 v[214:215], s[46:47], 0, v[200:201]
	global_load_lds_dwordx4 v[212:213], off
	v_lshl_add_u64 v[212:213], s[60:61], 0, v[202:203]
	s_add_i32 m0, s62, 0x2000
	s_nop 0
	global_load_lds_dwordx4 v[212:213], off
	v_lshl_add_u64 v[212:213], s[46:47], 0, v[196:197]
	s_mov_b32 m0, s74
	s_nop 0
	global_load_lds_dwordx4 v[212:213], off
	s_mov_b32 m0, s66
	s_nop 0
	global_load_lds_dwordx4 v[214:215], off
	s_waitcnt vmcnt(8)
	s_waitcnt lgkmcnt(0)
	s_barrier
; #define PG8_STAGE(bufoff, gbase, voff) do { _Pragma("unroll") for (int _i = 0; _i < 2; ++_i) \
;         __builtin_amdgcn_global_load_lds((const unsigned*)((const char*)(gbase) + (voff)[_i]), (PG8_LAS unsigned*)(lds + (bufoff) + ldsw + _i * 8192), 16, 0, 0); } while (0)
; #define PG8_LDA(dst, b, h) do { _Pragma("unroll") for (int m = 0; m < 4; ++m) _Pragma("unroll") for (int k = 0; k < 2; ++k) dst[m][k] = *(const PG8_LAS bf16x8*)(lds + PG8_SA(b, h) + aoff + m * 2048 + k * 1024); } while (0)
; #define PG8_LDB(dst, b, h) do { _Pragma("unroll") for (int n = 0; n < 2; ++n) _Pragma("unroll") for (int k = 0; k < 2; ++k) dst[n][k] = *(const PG8_LAS bf16x8*)(lds + PG8_SB(b, h) + boff + n * 2048 + k * 1024); } while (0)
; #define PG8_MMA(ai, bj, At, Bt) do { __builtin_amdgcn_s_setprio(1); _Pragma("unroll") for (int m = 0; m < 4; ++m) _Pragma("unroll") for (int n = 0; n < 2; ++n) _Pragma("unroll") for (int k = 0; k < 2; ++k) \
;         acc[ai][bj][m][n] = mma16<F16>(Bt[n][k], At[m][k], acc[ai][bj][m][n]); __builtin_amdgcn_s_setprio(0); } while (0)
; #define PG8_WAIT_V(n) asm volatile("s_waitcnt vmcnt(" #n ")" ::: "memory")
; #define PG8_WAIT_L(n) asm volatile("s_waitcnt lgkmcnt(" #n ")" ::: "memory")
; #define PG8_BAR __builtin_amdgcn_s_barrier()
; #define PG8_SCHED __builtin_amdgcn_sched_barrier(0)
; template <class Epi, class Sched, bool ALIGN_EPI = false, bool SP2 = false, bool F16 = false>
; __device__ __forceinline__ void gemm_phase(PG8_LAS unsigned char* lds, const Gemm g, const Sched& S, const Epi& E, const int wid_in) {
;     ...
;             PG8_WAIT_V(8); PG8_WAIT_L(0); PG8_BAR; PG8_MMA(1, 0, At, B0); PG8_MMA(1, 1, At, B1); PG8_BAR; PG8_SCHED;
;             PG8_LDB(B0, 1, 0); PG8_LDB(B1, 1, 1); PG8_SCHED; PG8_LDA(At, 1, 0); PG8_STAGE(PG8_SA(0, 1), a2 + hstep, voffA);
;             PG8_WAIT_V(8); PG8_WAIT_L(0); PG8_BAR; PG8_MMA(0, 0, At, B0); PG8_MMA(0, 1, At, B1); PG8_BAR; PG8_SCHED;
	s_waitcnt lgkmcnt(0)
	v_mfma_f32_16x16x32_f16 v[60:63], v[112:115], v[160:163], v[60:63]
	v_mfma_f32_16x16x32_f16 v[56:59], v[128:131], v[160:163], v[56:59]
	v_mfma_f32_16x16x32_f16 v[44:47], v[112:115], v[168:171], v[44:47]
	v_mfma_f32_16x16x32_f16 v[40:43], v[128:131], v[168:171], v[40:43]
	v_mfma_f32_16x16x32_f16 v[28:31], v[112:115], v[176:179], v[28:31]
	v_mfma_f32_16x16x32_f16 v[24:27], v[128:131], v[176:179], v[24:27]
	v_mfma_f32_16x16x32_f16 v[12:15], v[112:115], v[184:187], v[12:15]
	v_mfma_f32_16x16x32_f16 v[8:11], v[128:131], v[184:187], v[8:11]
	v_mfma_f32_16x16x32_f16 v[60:63], v[116:119], v[164:167], v[60:63]
	v_mfma_f32_16x16x32_f16 v[56:59], v[132:135], v[164:167], v[56:59]
	v_mfma_f32_16x16x32_f16 v[44:47], v[116:119], v[172:175], v[44:47]
	v_mfma_f32_16x16x32_f16 v[40:43], v[132:135], v[172:175], v[40:43]
	v_mfma_f32_16x16x32_f16 v[28:31], v[116:119], v[180:183], v[28:31]
	v_mfma_f32_16x16x32_f16 v[24:27], v[132:135], v[180:183], v[24:27]
	v_mfma_f32_16x16x32_f16 v[12:15], v[116:119], v[188:191], v[12:15]
	v_mfma_f32_16x16x32_f16 v[8:11], v[132:135], v[188:191], v[8:11]
	v_mfma_f32_16x16x32_f16 v[52:55], v[144:147], v[160:163], v[52:55]
	v_mfma_f32_16x16x32_f16 v[48:51], v[152:155], v[160:163], v[48:51]
	v_mfma_f32_16x16x32_f16 v[36:39], v[144:147], v[168:171], v[36:39]
	v_mfma_f32_16x16x32_f16 v[32:35], v[152:155], v[168:171], v[32:35]
	v_mfma_f32_16x16x32_f16 v[20:23], v[144:147], v[176:179], v[20:23]
	v_mfma_f32_16x16x32_f16 v[16:19], v[152:155], v[176:179], v[16:19]
	v_mfma_f32_16x16x32_f16 v[4:7], v[144:147], v[184:187], v[4:7]
	v_mfma_f32_16x16x32_f16 v[0:3], v[152:155], v[184:187], v[0:3]
	v_mfma_f32_16x16x32_f16 v[52:55], v[148:151], v[164:167], v[52:55]
	v_mfma_f32_16x16x32_f16 v[48:51], v[156:159], v[164:167], v[48:51]
	v_mfma_f32_16x16x32_f16 v[36:39], v[148:151], v[172:175], v[36:39]
	v_mfma_f32_16x16x32_f16 v[32:35], v[156:159], v[172:175], v[32:35]
	v_mfma_f32_16x16x32_f16 v[20:23], v[148:151], v[180:183], v[20:23]
	v_mfma_f32_16x16x32_f16 v[16:19], v[156:159], v[180:183], v[16:19]
	v_mfma_f32_16x16x32_f16 v[4:7], v[148:151], v[188:191], v[4:7]
	v_mfma_f32_16x16x32_f16 v[0:3], v[156:159], v[188:191], v[0:3]
	s_barrier
	s_add_i32 s60, 0, 0x18000
	s_add_i32 s61, 0, 0x1c000
	v_add_u32_e32 v132, s60, v234
	v_add_u32_e32 v156, s61, v234
	ds_read_b128 v[112:115], v132
	ds_read_b128 v[116:119], v132 offset:1024
	ds_read_b128 v[128:131], v132 offset:2048
	ds_read_b128 v[132:135], v132 offset:3072
	ds_read_b128 v[144:147], v156
	ds_read_b128 v[148:151], v156 offset:1024
	ds_read_b128 v[152:155], v156 offset:2048
	ds_read_b128 v[156:159], v156 offset:3072
	s_add_u32 s46, s46, 0x40000
	s_addc_u32 s47, s47, 0
	s_mov_b32 m0, s90
	v_lshl_add_u64 v[216:217], s[46:47], 0, v[196:197]
	ds_read_b128 v[160:163], v237 offset:32768
	ds_read_b128 v[164:167], v237 offset:33792
	ds_read_b128 v[168:171], v237 offset:34816
	ds_read_b128 v[172:175], v237 offset:35840
	ds_read_b128 v[176:179], v237 offset:36864
	ds_read_b128 v[180:183], v237 offset:37888
	ds_read_b128 v[184:187], v237 offset:38912
	ds_read_b128 v[188:191], v237 offset:39936
	global_load_lds_dwordx4 v[216:217], off
	v_lshl_add_u64 v[216:217], s[46:47], 0, v[200:201]
	s_mov_b32 m0, s51
	s_nop 0
	global_load_lds_dwordx4 v[216:217], off
	s_waitcnt vmcnt(8)
	s_waitcnt lgkmcnt(0)
	s_barrier
	s_waitcnt lgkmcnt(0)
	v_mfma_f32_16x16x32_f16 v[140:143], v[112:115], v[160:163], v[140:143]
	v_mfma_f32_16x16x32_f16 v[136:139], v[128:131], v[160:163], v[136:139]
	v_mfma_f32_16x16x32_f16 v[108:111], v[112:115], v[168:171], v[108:111]
	v_mfma_f32_16x16x32_f16 v[104:107], v[128:131], v[168:171], v[104:107]
	v_mfma_f32_16x16x32_f16 v[92:95], v[112:115], v[176:179], v[92:95]
	v_mfma_f32_16x16x32_f16 v[88:91], v[128:131], v[176:179], v[88:91]
	v_mfma_f32_16x16x32_f16 v[76:79], v[112:115], v[184:187], v[76:79]
	v_mfma_f32_16x16x32_f16 v[72:75], v[128:131], v[184:187], v[72:75]
	v_mfma_f32_16x16x32_f16 v[140:143], v[116:119], v[164:167], v[140:143]
	v_mfma_f32_16x16x32_f16 v[136:139], v[132:135], v[164:167], v[136:139]
	v_mfma_f32_16x16x32_f16 v[108:111], v[116:119], v[172:175], v[108:111]
	v_mfma_f32_16x16x32_f16 v[104:107], v[132:135], v[172:175], v[104:107]
	v_mfma_f32_16x16x32_f16 v[92:95], v[116:119], v[180:183], v[92:95]
	v_mfma_f32_16x16x32_f16 v[88:91], v[132:135], v[180:183], v[88:91]
	v_mfma_f32_16x16x32_f16 v[76:79], v[116:119], v[188:191], v[76:79]
	v_mfma_f32_16x16x32_f16 v[72:75], v[132:135], v[188:191], v[72:75]
	v_mfma_f32_16x16x32_f16 v[124:127], v[144:147], v[160:163], v[124:127]
	v_mfma_f32_16x16x32_f16 v[120:123], v[152:155], v[160:163], v[120:123]
	v_mfma_f32_16x16x32_f16 v[100:103], v[144:147], v[168:171], v[100:103]
	v_mfma_f32_16x16x32_f16 v[96:99], v[152:155], v[168:171], v[96:99]
	v_mfma_f32_16x16x32_f16 v[84:87], v[144:147], v[176:179], v[84:87]
	v_mfma_f32_16x16x32_f16 v[80:83], v[152:155], v[176:179], v[80:83]
	v_mfma_f32_16x16x32_f16 v[68:71], v[144:147], v[184:187], v[68:71]
	v_mfma_f32_16x16x32_f16 v[64:67], v[152:155], v[184:187], v[64:67]
	v_mfma_f32_16x16x32_f16 v[124:127], v[148:151], v[164:167], v[124:127]
	v_mfma_f32_16x16x32_f16 v[120:123], v[156:159], v[164:167], v[120:123]
	v_mfma_f32_16x16x32_f16 v[100:103], v[148:151], v[172:175], v[100:103]
	v_mfma_f32_16x16x32_f16 v[96:99], v[156:159], v[172:175], v[96:99]
	v_mfma_f32_16x16x32_f16 v[84:87], v[148:151], v[180:183], v[84:87]
	v_mfma_f32_16x16x32_f16 v[80:83], v[156:159], v[180:183], v[80:83]
	v_mfma_f32_16x16x32_f16 v[68:71], v[148:151], v[188:191], v[68:71]
	v_mfma_f32_16x16x32_f16 v[64:67], v[156:159], v[188:191], v[64:67]
	s_barrier
; #define PG8_STAGE(bufoff, gbase, voff) do { _Pragma("unroll") for (int _i = 0; _i < 2; ++_i) \
;         __builtin_amdgcn_global_load_lds((const unsigned*)((const char*)(gbase) + (voff)[_i]), (PG8_LAS unsigned*)(lds + (bufoff) + ldsw + _i * 8192), 16, 0, 0); } while (0)
; #define PG8_LDA(dst, b, h) do { _Pragma("unroll") for (int m = 0; m < 4; ++m) _Pragma("unroll") for (int k = 0; k < 2; ++k) dst[m][k] = *(const PG8_LAS bf16x8*)(lds + PG8_SA(b, h) + aoff + m * 2048 + k * 1024); } while (0)
; #define PG8_MMA(ai, bj, At, Bt) do { __builtin_amdgcn_s_setprio(1); _Pragma("unroll") for (int m = 0; m < 4; ++m) _Pragma("unroll") for (int n = 0; n < 2; ++n) _Pragma("unroll") for (int k = 0; k < 2; ++k) \
;         acc[ai][bj][m][n] = mma16<F16>(Bt[n][k], At[m][k], acc[ai][bj][m][n]); __builtin_amdgcn_s_setprio(0); } while (0)
; #define PG8_WAIT_V(n) asm volatile("s_waitcnt vmcnt(" #n ")" ::: "memory")
; #define PG8_WAIT_L(n) asm volatile("s_waitcnt lgkmcnt(" #n ")" ::: "memory")
; #define PG8_BAR __builtin_amdgcn_s_barrier()
; #define PG8_SCHED __builtin_amdgcn_sched_barrier(0)
; template <class Epi, class Sched, bool ALIGN_EPI = false, bool SP2 = false, bool F16 = false>
; __device__ __forceinline__ void gemm_phase(PG8_LAS unsigned char* lds, const Gemm g, const Sched& S, const Epi& E, const int wid_in) {
;     ...
;             PG8_LDA(At, 1, 1); PG8_STAGE(PG8_SB(1, 0), b3, voffB); PG8_STAGE(PG8_SB(1, 1), b3 + hstep, voffB); PG8_STAGE(PG8_SA(1, 0), a3, voffA);
;             PG8_WAIT_V(8); PG8_WAIT_L(0); PG8_BAR; PG8_MMA(1, 0, At, B0); PG8_MMA(1, 1, At, B1); PG8_BAR; PG8_SCHED;
;     ...
;         if constexpr (ALIGN_EPI) { if (wr == 0) PG8_BAR; }
	s_add_i32 s46, s60, s68
	v_lshl_add_u64 v[192:193], v[192:193], 0, s[26:27]
	s_mov_b32 m0, s46
	ds_read_b128 v[160:163], v237 offset:49152
	ds_read_b128 v[164:167], v237 offset:50176
	ds_read_b128 v[168:171], v237 offset:51200
	ds_read_b128 v[172:175], v237 offset:52224
	ds_read_b128 v[176:179], v237 offset:53248
	ds_read_b128 v[180:183], v237 offset:54272
	ds_read_b128 v[184:187], v237 offset:55296
	ds_read_b128 v[188:191], v237 offset:56320
	global_load_lds_dwordx4 v[192:193], off
	s_add_i32 m0, s46, 0x2000
	s_add_u32 s44, s44, 0x40080
	v_lshl_add_u64 v[192:193], v[194:195], 0, s[26:27]
	s_addc_u32 s45, s45, 0
	s_add_i32 s46, s61, s68
	global_load_lds_dwordx4 v[192:193], off
	v_lshl_add_u64 v[192:193], s[44:45], 0, v[198:199]
	s_mov_b32 m0, s46
	s_nop 0
	global_load_lds_dwordx4 v[192:193], off
	v_lshl_add_u64 v[192:193], s[44:45], 0, v[202:203]
	s_add_i32 m0, s46, 0x2000
	s_nop 0
	global_load_lds_dwordx4 v[192:193], off
	v_lshl_add_u64 v[192:193], v[212:213], 0, s[26:27]
	s_mov_b32 m0, s75
	s_nop 0
	global_load_lds_dwordx4 v[192:193], off
	v_lshl_add_u64 v[192:193], v[214:215], 0, s[26:27]
	s_mov_b32 m0, s67
	s_nop 0
	global_load_lds_dwordx4 v[192:193], off
	s_waitcnt vmcnt(8)
	s_waitcnt lgkmcnt(0)
	s_barrier
	s_waitcnt lgkmcnt(0)
	v_mfma_f32_16x16x32_f16 v[60:63], v[112:115], v[160:163], v[60:63]
	v_mfma_f32_16x16x32_f16 v[56:59], v[128:131], v[160:163], v[56:59]
	v_mfma_f32_16x16x32_f16 v[44:47], v[112:115], v[168:171], v[44:47]
	v_mfma_f32_16x16x32_f16 v[40:43], v[128:131], v[168:171], v[40:43]
	v_mfma_f32_16x16x32_f16 v[28:31], v[112:115], v[176:179], v[28:31]
	v_mfma_f32_16x16x32_f16 v[24:27], v[128:131], v[176:179], v[24:27]
	v_mfma_f32_16x16x32_f16 v[12:15], v[112:115], v[184:187], v[12:15]
	v_mfma_f32_16x16x32_f16 v[8:11], v[128:131], v[184:187], v[8:11]
	v_mfma_f32_16x16x32_f16 v[60:63], v[116:119], v[164:167], v[60:63]
	v_mfma_f32_16x16x32_f16 v[56:59], v[132:135], v[164:167], v[56:59]
	v_mfma_f32_16x16x32_f16 v[44:47], v[116:119], v[172:175], v[44:47]
	v_mfma_f32_16x16x32_f16 v[40:43], v[132:135], v[172:175], v[40:43]
	v_mfma_f32_16x16x32_f16 v[28:31], v[116:119], v[180:183], v[28:31]
	v_mfma_f32_16x16x32_f16 v[24:27], v[132:135], v[180:183], v[24:27]
	v_mfma_f32_16x16x32_f16 v[12:15], v[116:119], v[188:191], v[12:15]
	v_mfma_f32_16x16x32_f16 v[8:11], v[132:135], v[188:191], v[8:11]
	v_mfma_f32_16x16x32_f16 v[52:55], v[144:147], v[160:163], v[52:55]
	v_mfma_f32_16x16x32_f16 v[48:51], v[152:155], v[160:163], v[48:51]
	v_mfma_f32_16x16x32_f16 v[36:39], v[144:147], v[168:171], v[36:39]
	v_mfma_f32_16x16x32_f16 v[32:35], v[152:155], v[168:171], v[32:35]
	v_mfma_f32_16x16x32_f16 v[20:23], v[144:147], v[176:179], v[20:23]
	v_mfma_f32_16x16x32_f16 v[16:19], v[152:155], v[176:179], v[16:19]
	v_mfma_f32_16x16x32_f16 v[4:7], v[144:147], v[184:187], v[4:7]
	v_mfma_f32_16x16x32_f16 v[0:3], v[152:155], v[184:187], v[0:3]
	v_mfma_f32_16x16x32_f16 v[52:55], v[148:151], v[164:167], v[52:55]
	v_mfma_f32_16x16x32_f16 v[48:51], v[156:159], v[164:167], v[48:51]
	v_mfma_f32_16x16x32_f16 v[36:39], v[148:151], v[172:175], v[36:39]
	v_mfma_f32_16x16x32_f16 v[32:35], v[156:159], v[172:175], v[32:35]
	v_mfma_f32_16x16x32_f16 v[20:23], v[148:151], v[180:183], v[20:23]
	v_mfma_f32_16x16x32_f16 v[16:19], v[156:159], v[180:183], v[16:19]
	v_mfma_f32_16x16x32_f16 v[4:7], v[148:151], v[188:191], v[4:7]
	v_mfma_f32_16x16x32_f16 v[0:3], v[156:159], v[188:191], v[0:3]
	s_barrier
	s_add_i32 s59, s59, 2
	s_add_u32 s42, s42, 0x100
	s_addc_u32 s43, s43, 0
	s_add_u32 s41, s41, 0x100
	s_addc_u32 s58, s58, 0
	s_cmp_gt_u32 s59, 13
	s_cbranch_scc0 .LBB0_2793
	s_and_b64 vcc, exec, s[16:17]
	s_cbranch_vccz .LBB0_2796
	s_barrier
